# v56 + operand-stationary (snake) MFMA order in K-loops: consecutive MFMAs share SrcA or SrcB
# baseline (speedup 1.0000x reference)
; #define PG8_STAGE(bufoff, gbase, voff) do { _Pragma("unroll") for (int _i = 0; _i < 2; ++_i) \
;         __builtin_amdgcn_global_load_lds((const unsigned*)((const char*)(gbase) + (voff)[_i]), (LAS unsigned*)(lds + (bufoff) + ldsw + _i * 8192), 16, 0, 0); } while (0)
; #define PG8_LDA(dst, b, h) do { _Pragma("unroll") for (int m = 0; m < 4; ++m) _Pragma("unroll") for (int k = 0; k < 2; ++k) dst[m][k] = *(const LAS bf16x8*)(lds + PG8_SA(b, h) + aoff + m * 2048 + k * 1024); } while (0)
; #define PG8_LDB(dst, b, h) do { _Pragma("unroll") for (int n = 0; n < 2; ++n) _Pragma("unroll") for (int k = 0; k < 2; ++k) dst[n][k] = *(const LAS bf16x8*)(lds + PG8_SB(b, h) + boff + n * 2048 + k * 1024); } while (0)
; #define PG8_MMA(ai, bj, At, Bt) do { __builtin_amdgcn_s_setprio(1); _Pragma("unroll") for (int m = 0; m < 4; ++m) _Pragma("unroll") for (int n = 0; n < 2; ++n) _Pragma("unroll") for (int k = 0; k < 2; ++k) \
;         acc[ai][bj][m][n] = __builtin_amdgcn_mfma_f32_16x16x32_bf16(Bt[n][k], At[m][k], acc[ai][bj][m][n], 0, 0, 0); __builtin_amdgcn_s_setprio(0); } while (0)
; template <class Epi>
; __device__ __forceinline__ void gemm_phase(LAS unsigned char* lds, const Gemm g, const StaticOrder& S, const Epi& E) {
;     ...
;         const bool has_next = S.next(ui + 1, nxt);
;         const char* nA = has_next ? (const char*)g.A + (size_t)(nxt.pm >> 5) * aslab + (size_t)(nxt.pm & 31) * tstepA : cA; const char* nB = has_next ? (const char*)g.Bt + (size_t)nxt.pn * tstepB : cB;
;         for (int t = 0; t < nt; t += 2) {
;             const bool last = (t == nt - 2);
;             const char* a1 = cA + (size_t)(t + 1) * kstep;
;             const char* a2 = last ? nA : cA + (size_t)(t + 2) * kstep; const char* b2 = last ? nB : cB + (size_t)(t + 2) * kstep;
;             const char* a3 = a2 + kstep; const char* b3 = b2 + kstep;
;             PG8_LDB(B0, 0, 0); PG8_LDB(B1, 0, 1); PG8_SCHED; PG8_LDA(At, 0, 0); PG8_STAGE(PG8_SA(1, 1), a1 + hstepA, voffA);
;             PG8_WAIT_V(8); PG8_WAIT_L(0); PG8_BAR; PG8_MMA(0, 0, At, B0); PG8_MMA(0, 1, At, B1); PG8_BAR; PG8_SCHED;
;             PG8_LDA(At, 0, 1); PG8_STAGE(PG8_SB(0, 0), b2, voffB); PG8_STAGE(PG8_SB(0, 1), b2 + hstepB, voffB); PG8_STAGE(PG8_SA(0, 0), a2, voffA);
;             PG8_WAIT_V(8); PG8_WAIT_L(0); PG8_BAR; PG8_MMA(1, 0, At, B0); PG8_MMA(1, 1, At, B1); PG8_BAR; PG8_SCHED;
.LBB0_152:
	s_ashr_i32 s20, s56, 5
	s_ashr_i32 s21, s20, 31
	s_lshl_b64 s[20:21], s[20:21], 24
	v_readlane_b32 s22, v235, 38
	v_readlane_b32 s23, v235, 39
	s_add_u32 s19, s22, s20
	s_addc_u32 s21, s23, s21
	s_lshl_b32 s20, s56, 19
	s_and_b32 s20, s20, 0xf80000
	s_add_u32 s20, s19, s20
	s_addc_u32 s21, s21, 0
	s_and_b64 s[22:23], s[0:1], exec
	s_cselect_b32 s58, s21, s25
	s_cselect_b32 s59, s20, s24
	s_ashr_i32 s19, s18, 31
	s_lshl_b64 s[22:23], s[18:19], 19
	s_add_u32 s22, s6, s22
	s_addc_u32 s23, s7, s23
	s_and_b64 s[26:27], s[0:1], exec
	s_cselect_b32 s19, s23, s3
	s_cselect_b32 s60, s22, s2
	s_add_u32 s24, s24, 0x40080
	s_addc_u32 s25, s25, 0
	s_add_u32 s61, s2, 0x100
	s_addc_u32 s62, s3, 0
	s_mov_b32 s63, -2
	ds_read_b128 v[154:157], v149
	ds_read_b128 v[158:161], v149 offset:1024
	ds_read_b128 v[162:165], v149 offset:2048
	ds_read_b128 v[166:169], v149 offset:3072
	ds_read_b128 v[170:173], v150
	ds_read_b128 v[174:177], v150 offset:1024
	ds_read_b128 v[178:181], v150 offset:2048
	ds_read_b128 v[182:185], v150 offset:3072
	s_add_u32 s2, s24, 0xfffc0080
	s_addc_u32 s3, s25, -1
	s_cmp_eq_u32 s63, 12
	s_cselect_b32 s27, s58, s3
	s_cselect_b32 s26, s59, s2
	s_cselect_b32 s3, s19, s62
	s_cselect_b32 s2, s60, s61
	v_lshl_add_u64 v[144:145], s[24:25], 0, v[136:137]
	s_add_i32 m0, s42, 0xc000
	ds_read_b128 v[190:193], v151
	ds_read_b128 v[198:201], v151 offset:1024
	ds_read_b128 v[202:205], v151 offset:2048
	ds_read_b128 v[206:209], v151 offset:3072
	ds_read_b128 v[210:213], v151 offset:4096
	ds_read_b128 v[214:217], v151 offset:5120
	ds_read_b128 v[218:221], v151 offset:6144
	ds_read_b128 v[222:225], v151 offset:7168
	global_load_lds_dwordx4 v[144:145], off
	v_lshl_add_u64 v[144:145], s[24:25], 0, v[140:141]
	s_add_i32 m0, s42, 0xe000
	s_nop 0
	global_load_lds_dwordx4 v[144:145], off
	s_waitcnt vmcnt(8)
	s_waitcnt lgkmcnt(0)
	s_barrier
	s_waitcnt lgkmcnt(0)
	v_mfma_f32_16x16x32_bf16 v[116:119], v[154:157], v[190:193], 0
	v_mfma_f32_16x16x32_bf16 v[108:111], v[162:165], v[190:193], 0
	v_mfma_f32_16x16x32_bf16 v[100:103], v[162:165], v[202:205], 0
	v_mfma_f32_16x16x32_bf16 v[104:107], v[154:157], v[202:205], 0
	v_mfma_f32_16x16x32_bf16 v[92:95], v[154:157], v[210:213], 0
	v_mfma_f32_16x16x32_bf16 v[84:87], v[162:165], v[210:213], 0
	v_mfma_f32_16x16x32_bf16 v[68:71], v[162:165], v[218:221], 0
	v_mfma_f32_16x16x32_bf16 v[76:79], v[154:157], v[218:221], 0
	v_mfma_f32_16x16x32_bf16 v[116:119], v[158:161], v[198:201], v[116:119]
	v_mfma_f32_16x16x32_bf16 v[108:111], v[166:169], v[198:201], v[108:111]
	v_mfma_f32_16x16x32_bf16 v[100:103], v[166:169], v[206:209], v[100:103]
	v_mfma_f32_16x16x32_bf16 v[104:107], v[158:161], v[206:209], v[104:107]
	v_mfma_f32_16x16x32_bf16 v[92:95], v[158:161], v[214:217], v[92:95]
	v_mfma_f32_16x16x32_bf16 v[84:87], v[166:169], v[214:217], v[84:87]
	v_mfma_f32_16x16x32_bf16 v[68:71], v[166:169], v[222:225], v[68:71]
	v_mfma_f32_16x16x32_bf16 v[76:79], v[158:161], v[222:225], v[76:79]
	v_mfma_f32_16x16x32_bf16 v[124:127], v[170:173], v[190:193], 0
	v_mfma_f32_16x16x32_bf16 v[120:123], v[178:181], v[190:193], 0
	v_mfma_f32_16x16x32_bf16 v[96:99], v[178:181], v[202:205], 0
	v_mfma_f32_16x16x32_bf16 v[112:115], v[170:173], v[202:205], 0
	v_mfma_f32_16x16x32_bf16 v[88:91], v[170:173], v[210:213], 0
	v_mfma_f32_16x16x32_bf16 v[80:83], v[178:181], v[210:213], 0
	v_mfma_f32_16x16x32_bf16 v[64:67], v[178:181], v[218:221], 0
	v_mfma_f32_16x16x32_bf16 v[72:75], v[170:173], v[218:221], 0
	v_mfma_f32_16x16x32_bf16 v[124:127], v[174:177], v[198:201], v[124:127]
	v_mfma_f32_16x16x32_bf16 v[120:123], v[182:185], v[198:201], v[120:123]
	v_mfma_f32_16x16x32_bf16 v[96:99], v[182:185], v[206:209], v[96:99]
	v_mfma_f32_16x16x32_bf16 v[112:115], v[174:177], v[206:209], v[112:115]
	v_mfma_f32_16x16x32_bf16 v[88:91], v[174:177], v[214:217], v[88:91]
	v_mfma_f32_16x16x32_bf16 v[80:83], v[182:185], v[214:217], v[80:83]
	v_mfma_f32_16x16x32_bf16 v[64:67], v[182:185], v[222:225], v[64:67]
	v_mfma_f32_16x16x32_bf16 v[72:75], v[174:177], v[222:225], v[72:75]
	s_barrier
	s_add_i32 s64, s53, s40
	v_lshl_add_u64 v[144:145], s[2:3], 0, v[128:129]
	s_mov_b32 m0, s64
	ds_read_b128 v[190:193], v151 offset:16384
	ds_read_b128 v[198:201], v151 offset:17408
	ds_read_b128 v[202:205], v151 offset:18432
	ds_read_b128 v[206:209], v151 offset:19456
	ds_read_b128 v[210:213], v151 offset:20480
	ds_read_b128 v[214:217], v151 offset:21504
	ds_read_b128 v[218:221], v151 offset:22528
	ds_read_b128 v[222:225], v151 offset:23552
	global_load_lds_dwordx4 v[144:145], off
	s_add_i32 m0, s64, 0x2000
	s_add_u32 s64, s2, 0x40000
	v_lshl_add_u64 v[186:187], s[2:3], 0, v[130:131]
	s_addc_u32 s65, s3, 0
	s_add_i32 s66, s54, s40
	global_load_lds_dwordx4 v[186:187], off
	v_lshl_add_u64 v[194:195], s[64:65], 0, v[128:129]
	s_mov_b32 m0, s66
	v_lshl_add_u64 v[226:227], s[26:27], 0, v[132:133]
	global_load_lds_dwordx4 v[194:195], off
	v_lshl_add_u64 v[194:195], s[64:65], 0, v[130:131]
	s_add_i32 m0, s66, 0x2000
	s_nop 0
	global_load_lds_dwordx4 v[194:195], off
	v_lshl_add_u64 v[194:195], s[26:27], 0, v[134:135]
	s_mov_b32 m0, s42
	s_nop 0
	global_load_lds_dwordx4 v[194:195], off
	s_mov_b32 m0, s43
	s_nop 0
	global_load_lds_dwordx4 v[226:227], off
	s_waitcnt vmcnt(8)
	s_waitcnt lgkmcnt(0)
	s_barrier
; #define PG8_STAGE(bufoff, gbase, voff) do { _Pragma("unroll") for (int _i = 0; _i < 2; ++_i) \
;         __builtin_amdgcn_global_load_lds((const unsigned*)((const char*)(gbase) + (voff)[_i]), (LAS unsigned*)(lds + (bufoff) + ldsw + _i * 8192), 16, 0, 0); } while (0)
; #define PG8_LDA(dst, b, h) do { _Pragma("unroll") for (int m = 0; m < 4; ++m) _Pragma("unroll") for (int k = 0; k < 2; ++k) dst[m][k] = *(const LAS bf16x8*)(lds + PG8_SA(b, h) + aoff + m * 2048 + k * 1024); } while (0)
; #define PG8_LDB(dst, b, h) do { _Pragma("unroll") for (int n = 0; n < 2; ++n) _Pragma("unroll") for (int k = 0; k < 2; ++k) dst[n][k] = *(const LAS bf16x8*)(lds + PG8_SB(b, h) + boff + n * 2048 + k * 1024); } while (0)
; #define PG8_MMA(ai, bj, At, Bt) do { __builtin_amdgcn_s_setprio(1); _Pragma("unroll") for (int m = 0; m < 4; ++m) _Pragma("unroll") for (int n = 0; n < 2; ++n) _Pragma("unroll") for (int k = 0; k < 2; ++k) \
;         acc[ai][bj][m][n] = __builtin_amdgcn_mfma_f32_16x16x32_bf16(Bt[n][k], At[m][k], acc[ai][bj][m][n], 0, 0, 0); __builtin_amdgcn_s_setprio(0); } while (0)
; #define PG8_WAIT_V(n) asm volatile("s_waitcnt vmcnt(" #n ")" ::: "memory")
; #define PG8_WAIT_L(n) asm volatile("s_waitcnt lgkmcnt(" #n ")" ::: "memory")
; #define PG8_BAR __builtin_amdgcn_s_barrier()
; #define PG8_SCHED __builtin_amdgcn_sched_barrier(0)
; template <class Epi>
; __device__ __forceinline__ void gemm_phase(LAS unsigned char* lds, const Gemm g, const StaticOrder& S, const Epi& E) {
;     ...
;             PG8_WAIT_V(8); PG8_WAIT_L(0); PG8_BAR; PG8_MMA(1, 0, At, B0); PG8_MMA(1, 1, At, B1); PG8_BAR; PG8_SCHED;
;             PG8_LDB(B0, 1, 0); PG8_LDB(B1, 1, 1); PG8_SCHED; PG8_LDA(At, 1, 0); PG8_STAGE(PG8_SA(0, 1), a2 + hstepA, voffA);
;             PG8_WAIT_V(8); PG8_WAIT_L(0); PG8_BAR; PG8_MMA(0, 0, At, B0); PG8_MMA(0, 1, At, B1); PG8_BAR; PG8_SCHED;
	s_waitcnt lgkmcnt(0)
	v_mfma_f32_16x16x32_bf16 v[60:63], v[154:157], v[190:193], 0
	v_mfma_f32_16x16x32_bf16 v[52:55], v[162:165], v[190:193], 0
	v_mfma_f32_16x16x32_bf16 v[36:39], v[162:165], v[202:205], 0
	v_mfma_f32_16x16x32_bf16 v[44:47], v[154:157], v[202:205], 0
	v_mfma_f32_16x16x32_bf16 v[28:31], v[154:157], v[210:213], 0
	v_mfma_f32_16x16x32_bf16 v[20:23], v[162:165], v[210:213], 0
	v_mfma_f32_16x16x32_bf16 v[4:7], v[162:165], v[218:221], 0
	v_mfma_f32_16x16x32_bf16 v[12:15], v[154:157], v[218:221], 0
	v_mfma_f32_16x16x32_bf16 v[60:63], v[158:161], v[198:201], v[60:63]
	v_mfma_f32_16x16x32_bf16 v[52:55], v[166:169], v[198:201], v[52:55]
	v_mfma_f32_16x16x32_bf16 v[36:39], v[166:169], v[206:209], v[36:39]
	v_mfma_f32_16x16x32_bf16 v[44:47], v[158:161], v[206:209], v[44:47]
	v_mfma_f32_16x16x32_bf16 v[28:31], v[158:161], v[214:217], v[28:31]
	v_mfma_f32_16x16x32_bf16 v[20:23], v[166:169], v[214:217], v[20:23]
	v_mfma_f32_16x16x32_bf16 v[4:7], v[166:169], v[222:225], v[4:7]
	v_mfma_f32_16x16x32_bf16 v[12:15], v[158:161], v[222:225], v[12:15]
	v_mfma_f32_16x16x32_bf16 v[56:59], v[170:173], v[190:193], 0
	v_mfma_f32_16x16x32_bf16 v[48:51], v[178:181], v[190:193], 0
	v_mfma_f32_16x16x32_bf16 v[32:35], v[178:181], v[202:205], 0
	v_mfma_f32_16x16x32_bf16 v[40:43], v[170:173], v[202:205], 0
	v_mfma_f32_16x16x32_bf16 v[24:27], v[170:173], v[210:213], 0
	v_mfma_f32_16x16x32_bf16 v[16:19], v[178:181], v[210:213], 0
	v_mfma_f32_16x16x32_bf16 v[0:3], v[178:181], v[218:221], 0
	v_mfma_f32_16x16x32_bf16 v[8:11], v[170:173], v[218:221], 0
	v_mfma_f32_16x16x32_bf16 v[56:59], v[174:177], v[198:201], v[56:59]
	v_mfma_f32_16x16x32_bf16 v[48:51], v[182:185], v[198:201], v[48:51]
	v_mfma_f32_16x16x32_bf16 v[32:35], v[182:185], v[206:209], v[32:35]
	v_mfma_f32_16x16x32_bf16 v[40:43], v[174:177], v[206:209], v[40:43]
	v_mfma_f32_16x16x32_bf16 v[24:27], v[174:177], v[214:217], v[24:27]
	v_mfma_f32_16x16x32_bf16 v[16:19], v[182:185], v[214:217], v[16:19]
	v_mfma_f32_16x16x32_bf16 v[0:3], v[182:185], v[222:225], v[0:3]
	v_mfma_f32_16x16x32_bf16 v[8:11], v[174:177], v[222:225], v[8:11]
	s_barrier
	s_add_i32 s64, 0, 0x18000
	v_add_u32_e32 v138, s64, v147
	s_add_i32 s65, 0, 0x1c000
	ds_read_b128 v[154:157], v138
	ds_read_b128 v[158:161], v138 offset:1024
	ds_read_b128 v[162:165], v138 offset:2048
	ds_read_b128 v[166:169], v138 offset:3072
	v_add_u32_e32 v138, s65, v147
	ds_read_b128 v[170:173], v138
	ds_read_b128 v[174:177], v138 offset:1024
	ds_read_b128 v[178:181], v138 offset:2048
	ds_read_b128 v[182:185], v138 offset:3072
	s_add_u32 s26, s26, 0x40000
	s_addc_u32 s27, s27, 0
	s_mov_b32 m0, s44
	v_lshl_add_u64 v[228:229], s[26:27], 0, v[134:135]
	ds_read_b128 v[190:193], v151 offset:32768
	ds_read_b128 v[198:201], v151 offset:33792
	ds_read_b128 v[202:205], v151 offset:34816
	ds_read_b128 v[206:209], v151 offset:35840
	ds_read_b128 v[210:213], v151 offset:36864
	ds_read_b128 v[214:217], v151 offset:37888
	ds_read_b128 v[218:221], v151 offset:38912
	ds_read_b128 v[222:225], v151 offset:39936
	global_load_lds_dwordx4 v[228:229], off
	v_lshl_add_u64 v[228:229], s[26:27], 0, v[132:133]
	s_mov_b32 m0, s45
	s_nop 0
	global_load_lds_dwordx4 v[228:229], off
	s_waitcnt vmcnt(8)
	s_waitcnt lgkmcnt(0)
	s_barrier
	s_waitcnt lgkmcnt(0)
	v_mfma_f32_16x16x32_bf16 v[116:119], v[154:157], v[190:193], v[116:119]
	v_mfma_f32_16x16x32_bf16 v[108:111], v[162:165], v[190:193], v[108:111]
	v_mfma_f32_16x16x32_bf16 v[100:103], v[162:165], v[202:205], v[100:103]
	v_mfma_f32_16x16x32_bf16 v[104:107], v[154:157], v[202:205], v[104:107]
	v_mfma_f32_16x16x32_bf16 v[92:95], v[154:157], v[210:213], v[92:95]
	v_mfma_f32_16x16x32_bf16 v[84:87], v[162:165], v[210:213], v[84:87]
	v_mfma_f32_16x16x32_bf16 v[68:71], v[162:165], v[218:221], v[68:71]
	v_mfma_f32_16x16x32_bf16 v[76:79], v[154:157], v[218:221], v[76:79]
	v_mfma_f32_16x16x32_bf16 v[116:119], v[158:161], v[198:201], v[116:119]
	v_mfma_f32_16x16x32_bf16 v[108:111], v[166:169], v[198:201], v[108:111]
	v_mfma_f32_16x16x32_bf16 v[100:103], v[166:169], v[206:209], v[100:103]
	v_mfma_f32_16x16x32_bf16 v[104:107], v[158:161], v[206:209], v[104:107]
	v_mfma_f32_16x16x32_bf16 v[92:95], v[158:161], v[214:217], v[92:95]
	v_mfma_f32_16x16x32_bf16 v[84:87], v[166:169], v[214:217], v[84:87]
	v_mfma_f32_16x16x32_bf16 v[68:71], v[166:169], v[222:225], v[68:71]
	v_mfma_f32_16x16x32_bf16 v[76:79], v[158:161], v[222:225], v[76:79]
	v_mfma_f32_16x16x32_bf16 v[124:127], v[170:173], v[190:193], v[124:127]
	v_mfma_f32_16x16x32_bf16 v[120:123], v[178:181], v[190:193], v[120:123]
	v_mfma_f32_16x16x32_bf16 v[96:99], v[178:181], v[202:205], v[96:99]
	v_mfma_f32_16x16x32_bf16 v[112:115], v[170:173], v[202:205], v[112:115]
	v_mfma_f32_16x16x32_bf16 v[88:91], v[170:173], v[210:213], v[88:91]
	v_mfma_f32_16x16x32_bf16 v[80:83], v[178:181], v[210:213], v[80:83]
	v_mfma_f32_16x16x32_bf16 v[64:67], v[178:181], v[218:221], v[64:67]
	v_mfma_f32_16x16x32_bf16 v[72:75], v[170:173], v[218:221], v[72:75]
	v_mfma_f32_16x16x32_bf16 v[124:127], v[174:177], v[198:201], v[124:127]
	v_mfma_f32_16x16x32_bf16 v[120:123], v[182:185], v[198:201], v[120:123]
	v_mfma_f32_16x16x32_bf16 v[96:99], v[182:185], v[206:209], v[96:99]
	v_mfma_f32_16x16x32_bf16 v[112:115], v[174:177], v[206:209], v[112:115]
	v_mfma_f32_16x16x32_bf16 v[88:91], v[174:177], v[214:217], v[88:91]
	v_mfma_f32_16x16x32_bf16 v[80:83], v[182:185], v[214:217], v[80:83]
	v_mfma_f32_16x16x32_bf16 v[64:67], v[182:185], v[222:225], v[64:67]
	v_mfma_f32_16x16x32_bf16 v[72:75], v[174:177], v[222:225], v[72:75]
	s_barrier
; #define PG8_STAGE(bufoff, gbase, voff) do { _Pragma("unroll") for (int _i = 0; _i < 2; ++_i) \
;         __builtin_amdgcn_global_load_lds((const unsigned*)((const char*)(gbase) + (voff)[_i]), (LAS unsigned*)(lds + (bufoff) + ldsw + _i * 8192), 16, 0, 0); } while (0)
; #define PG8_LDA(dst, b, h) do { _Pragma("unroll") for (int m = 0; m < 4; ++m) _Pragma("unroll") for (int k = 0; k < 2; ++k) dst[m][k] = *(const LAS bf16x8*)(lds + PG8_SA(b, h) + aoff + m * 2048 + k * 1024); } while (0)
; #define PG8_LDB(dst, b, h) do { _Pragma("unroll") for (int n = 0; n < 2; ++n) _Pragma("unroll") for (int k = 0; k < 2; ++k) dst[n][k] = *(const LAS bf16x8*)(lds + PG8_SB(b, h) + boff + n * 2048 + k * 1024); } while (0)
; #define PG8_MMA(ai, bj, At, Bt) do { __builtin_amdgcn_s_setprio(1); _Pragma("unroll") for (int m = 0; m < 4; ++m) _Pragma("unroll") for (int n = 0; n < 2; ++n) _Pragma("unroll") for (int k = 0; k < 2; ++k) \
;         acc[ai][bj][m][n] = __builtin_amdgcn_mfma_f32_16x16x32_bf16(Bt[n][k], At[m][k], acc[ai][bj][m][n], 0, 0, 0); __builtin_amdgcn_s_setprio(0); } while (0)
; #define PG8_WAIT_V(n) asm volatile("s_waitcnt vmcnt(" #n ")" ::: "memory")
; #define PG8_WAIT_L(n) asm volatile("s_waitcnt lgkmcnt(" #n ")" ::: "memory")
; #define PG8_BAR __builtin_amdgcn_s_barrier()
; #define PG8_SCHED __builtin_amdgcn_sched_barrier(0)
; template <class Epi>
; __device__ __forceinline__ void gemm_phase(LAS unsigned char* lds, const Gemm g, const StaticOrder& S, const Epi& E) {
;     ...
;             PG8_LDB(B0, 0, 0); PG8_LDB(B1, 0, 1); PG8_SCHED; PG8_LDA(At, 0, 0); PG8_STAGE(PG8_SA(1, 1), a1 + hstepA, voffA);
;     ...
;             PG8_LDA(At, 1, 1); PG8_STAGE(PG8_SB(1, 0), b3, voffB); PG8_STAGE(PG8_SB(1, 1), b3 + hstepB, voffB); PG8_STAGE(PG8_SA(1, 0), a3, voffA);
;             PG8_WAIT_V(8); PG8_WAIT_L(0); PG8_BAR; PG8_MMA(1, 0, At, B0); PG8_MMA(1, 1, At, B1); PG8_BAR; PG8_SCHED;
;         }
	s_add_i32 s26, s64, s40
	v_lshl_add_u64 v[144:145], v[144:145], 0, s[14:15]
	s_mov_b32 m0, s26
	ds_read_b128 v[190:193], v151 offset:49152
	ds_read_b128 v[198:201], v151 offset:50176
	ds_read_b128 v[202:205], v151 offset:51200
	ds_read_b128 v[206:209], v151 offset:52224
	ds_read_b128 v[210:213], v151 offset:53248
	ds_read_b128 v[214:217], v151 offset:54272
	ds_read_b128 v[218:221], v151 offset:55296
	ds_read_b128 v[222:225], v151 offset:56320
	global_load_lds_dwordx4 v[144:145], off
	s_add_i32 m0, s26, 0x2000
	s_add_u32 s2, s2, 0x40080
	v_lshl_add_u64 v[144:145], v[186:187], 0, s[14:15]
	s_addc_u32 s3, s3, 0
	s_add_i32 s26, s65, s40
	global_load_lds_dwordx4 v[144:145], off
	v_lshl_add_u64 v[144:145], s[2:3], 0, v[128:129]
	s_mov_b32 m0, s26
	s_nop 0
	global_load_lds_dwordx4 v[144:145], off
	v_lshl_add_u64 v[144:145], s[2:3], 0, v[130:131]
	s_add_i32 m0, s26, 0x2000
	s_nop 0
	global_load_lds_dwordx4 v[144:145], off
	v_lshl_add_u64 v[144:145], v[194:195], 0, s[14:15]
	s_mov_b32 m0, s49
	s_nop 0
	global_load_lds_dwordx4 v[144:145], off
	v_lshl_add_u64 v[144:145], v[226:227], 0, s[14:15]
	s_mov_b32 m0, s50
	s_nop 0
	global_load_lds_dwordx4 v[144:145], off
	s_waitcnt vmcnt(8)
	s_waitcnt lgkmcnt(0)
	s_barrier
	s_waitcnt lgkmcnt(0)
	v_mfma_f32_16x16x32_bf16 v[60:63], v[154:157], v[190:193], v[60:63]
	v_mfma_f32_16x16x32_bf16 v[52:55], v[162:165], v[190:193], v[52:55]
	v_mfma_f32_16x16x32_bf16 v[36:39], v[162:165], v[202:205], v[36:39]
	v_mfma_f32_16x16x32_bf16 v[44:47], v[154:157], v[202:205], v[44:47]
	v_mfma_f32_16x16x32_bf16 v[28:31], v[154:157], v[210:213], v[28:31]
	v_mfma_f32_16x16x32_bf16 v[20:23], v[162:165], v[210:213], v[20:23]
	v_mfma_f32_16x16x32_bf16 v[4:7], v[162:165], v[218:221], v[4:7]
	v_mfma_f32_16x16x32_bf16 v[12:15], v[154:157], v[218:221], v[12:15]
	v_mfma_f32_16x16x32_bf16 v[60:63], v[158:161], v[198:201], v[60:63]
	v_mfma_f32_16x16x32_bf16 v[52:55], v[166:169], v[198:201], v[52:55]
	v_mfma_f32_16x16x32_bf16 v[36:39], v[166:169], v[206:209], v[36:39]
	v_mfma_f32_16x16x32_bf16 v[44:47], v[158:161], v[206:209], v[44:47]
	v_mfma_f32_16x16x32_bf16 v[28:31], v[158:161], v[214:217], v[28:31]
	v_mfma_f32_16x16x32_bf16 v[20:23], v[166:169], v[214:217], v[20:23]
	v_mfma_f32_16x16x32_bf16 v[4:7], v[166:169], v[222:225], v[4:7]
	v_mfma_f32_16x16x32_bf16 v[12:15], v[158:161], v[222:225], v[12:15]
	v_mfma_f32_16x16x32_bf16 v[56:59], v[170:173], v[190:193], v[56:59]
	v_mfma_f32_16x16x32_bf16 v[48:51], v[178:181], v[190:193], v[48:51]
	v_mfma_f32_16x16x32_bf16 v[32:35], v[178:181], v[202:205], v[32:35]
	v_mfma_f32_16x16x32_bf16 v[40:43], v[170:173], v[202:205], v[40:43]
	v_mfma_f32_16x16x32_bf16 v[24:27], v[170:173], v[210:213], v[24:27]
	v_mfma_f32_16x16x32_bf16 v[16:19], v[178:181], v[210:213], v[16:19]
	v_mfma_f32_16x16x32_bf16 v[0:3], v[178:181], v[218:221], v[0:3]
	v_mfma_f32_16x16x32_bf16 v[8:11], v[170:173], v[218:221], v[8:11]
	v_mfma_f32_16x16x32_bf16 v[56:59], v[174:177], v[198:201], v[56:59]
	v_mfma_f32_16x16x32_bf16 v[48:51], v[182:185], v[198:201], v[48:51]
	v_mfma_f32_16x16x32_bf16 v[32:35], v[182:185], v[206:209], v[32:35]
	v_mfma_f32_16x16x32_bf16 v[40:43], v[174:177], v[206:209], v[40:43]
	v_mfma_f32_16x16x32_bf16 v[24:27], v[174:177], v[214:217], v[24:27]
	v_mfma_f32_16x16x32_bf16 v[16:19], v[182:185], v[214:217], v[16:19]
	v_mfma_f32_16x16x32_bf16 v[0:3], v[182:185], v[222:225], v[0:3]
	v_mfma_f32_16x16x32_bf16 v[8:11], v[174:177], v[222:225], v[8:11]
	s_barrier
	s_add_i32 s63, s63, 2
	s_add_u32 s24, s24, 0x100
	s_addc_u32 s25, s25, 0
	s_add_u32 s61, s61, 0x100
	s_addc_u32 s62, s62, 0
	s_cmp_gt_u32 s63, 13
	s_cbranch_scc0 .LBB0_153
.LBB0_153:
	ds_read_b128 v[154:157], v149
	ds_read_b128 v[158:161], v149 offset:1024
	ds_read_b128 v[162:165], v149 offset:2048
	ds_read_b128 v[166:169], v149 offset:3072
	ds_read_b128 v[170:173], v150
	ds_read_b128 v[174:177], v150 offset:1024
	ds_read_b128 v[178:181], v150 offset:2048
	ds_read_b128 v[182:185], v150 offset:3072
	s_add_u32 s2, s24, 0xfffc0080
	s_addc_u32 s3, s25, -1
	s_cmp_eq_u32 s63, 12
	s_cselect_b32 s27, s58, s3
	s_cselect_b32 s26, s59, s2
	s_cselect_b32 s3, s19, s62
	s_cselect_b32 s2, s60, s61
	v_lshl_add_u64 v[144:145], s[24:25], 0, v[136:137]
	s_add_i32 m0, s42, 0xc000
	ds_read_b128 v[190:193], v151
	ds_read_b128 v[198:201], v151 offset:1024
	ds_read_b128 v[202:205], v151 offset:2048
	ds_read_b128 v[206:209], v151 offset:3072
	ds_read_b128 v[210:213], v151 offset:4096
	ds_read_b128 v[214:217], v151 offset:5120
	ds_read_b128 v[218:221], v151 offset:6144
	ds_read_b128 v[222:225], v151 offset:7168
	global_load_lds_dwordx4 v[144:145], off
	v_lshl_add_u64 v[144:145], s[24:25], 0, v[140:141]
	s_add_i32 m0, s42, 0xe000
	s_nop 0
	global_load_lds_dwordx4 v[144:145], off
	s_waitcnt vmcnt(8)
	s_waitcnt lgkmcnt(0)
	s_barrier
; #define PG8_STAGE(bufoff, gbase, voff) do { _Pragma("unroll") for (int _i = 0; _i < 2; ++_i) \
;         __builtin_amdgcn_global_load_lds((const unsigned*)((const char*)(gbase) + (voff)[_i]), (LAS unsigned*)(lds + (bufoff) + ldsw + _i * 8192), 16, 0, 0); } while (0)
; #define PG8_LDA(dst, b, h) do { _Pragma("unroll") for (int m = 0; m < 4; ++m) _Pragma("unroll") for (int k = 0; k < 2; ++k) dst[m][k] = *(const LAS bf16x8*)(lds + PG8_SA(b, h) + aoff + m * 2048 + k * 1024); } while (0)
; #define PG8_LDB(dst, b, h) do { _Pragma("unroll") for (int n = 0; n < 2; ++n) _Pragma("unroll") for (int k = 0; k < 2; ++k) dst[n][k] = *(const LAS bf16x8*)(lds + PG8_SB(b, h) + boff + n * 2048 + k * 1024); } while (0)
; #define PG8_MMA(ai, bj, At, Bt) do { __builtin_amdgcn_s_setprio(1); _Pragma("unroll") for (int m = 0; m < 4; ++m) _Pragma("unroll") for (int n = 0; n < 2; ++n) _Pragma("unroll") for (int k = 0; k < 2; ++k) \
;         acc[ai][bj][m][n] = __builtin_amdgcn_mfma_f32_16x16x32_bf16(Bt[n][k], At[m][k], acc[ai][bj][m][n], 0, 0, 0); __builtin_amdgcn_s_setprio(0); } while (0)
; #define PG8_WAIT_V(n) asm volatile("s_waitcnt vmcnt(" #n ")" ::: "memory")
; #define PG8_WAIT_L(n) asm volatile("s_waitcnt lgkmcnt(" #n ")" ::: "memory")
; #define PG8_BAR __builtin_amdgcn_s_barrier()
; #define PG8_SCHED __builtin_amdgcn_sched_barrier(0)
; template <class Epi>
; __device__ __forceinline__ void gemm_phase(LAS unsigned char* lds, const Gemm g, const StaticOrder& S, const Epi& E) {
;     ...
;             PG8_LDB(B0, 0, 0); PG8_LDB(B1, 0, 1); PG8_SCHED; PG8_LDA(At, 0, 0); PG8_STAGE(PG8_SA(1, 1), a1 + hstepA, voffA);
;             PG8_WAIT_V(8); PG8_WAIT_L(0); PG8_BAR; PG8_MMA(0, 0, At, B0); PG8_MMA(0, 1, At, B1); PG8_BAR; PG8_SCHED;
;             PG8_LDA(At, 0, 1); PG8_STAGE(PG8_SB(0, 0), b2, voffB); PG8_STAGE(PG8_SB(0, 1), b2 + hstepB, voffB); PG8_STAGE(PG8_SA(0, 0), a2, voffA);
;             PG8_WAIT_V(8); PG8_WAIT_L(0); PG8_BAR; PG8_MMA(1, 0, At, B0); PG8_MMA(1, 1, At, B1); PG8_BAR; PG8_SCHED;
;             PG8_LDB(B0, 1, 0); PG8_LDB(B1, 1, 1); PG8_SCHED; PG8_LDA(At, 1, 0); PG8_STAGE(PG8_SA(0, 1), a2 + hstepA, voffA);
;             PG8_WAIT_V(8); PG8_WAIT_L(0); PG8_BAR; PG8_MMA(0, 0, At, B0); PG8_MMA(0, 1, At, B1); PG8_BAR; PG8_SCHED;
	s_waitcnt lgkmcnt(0)
	v_mfma_f32_16x16x32_bf16 v[116:119], v[154:157], v[190:193], v[116:119]
	v_mfma_f32_16x16x32_bf16 v[108:111], v[162:165], v[190:193], v[108:111]
	v_mfma_f32_16x16x32_bf16 v[100:103], v[162:165], v[202:205], v[100:103]
	v_mfma_f32_16x16x32_bf16 v[104:107], v[154:157], v[202:205], v[104:107]
	v_mfma_f32_16x16x32_bf16 v[92:95], v[154:157], v[210:213], v[92:95]
	v_mfma_f32_16x16x32_bf16 v[84:87], v[162:165], v[210:213], v[84:87]
	v_mfma_f32_16x16x32_bf16 v[68:71], v[162:165], v[218:221], v[68:71]
	v_mfma_f32_16x16x32_bf16 v[76:79], v[154:157], v[218:221], v[76:79]
	v_mfma_f32_16x16x32_bf16 v[116:119], v[158:161], v[198:201], v[116:119]
	v_mfma_f32_16x16x32_bf16 v[108:111], v[166:169], v[198:201], v[108:111]
	v_mfma_f32_16x16x32_bf16 v[100:103], v[166:169], v[206:209], v[100:103]
	v_mfma_f32_16x16x32_bf16 v[104:107], v[158:161], v[206:209], v[104:107]
	v_mfma_f32_16x16x32_bf16 v[92:95], v[158:161], v[214:217], v[92:95]
	v_mfma_f32_16x16x32_bf16 v[84:87], v[166:169], v[214:217], v[84:87]
	v_mfma_f32_16x16x32_bf16 v[68:71], v[166:169], v[222:225], v[68:71]
	v_mfma_f32_16x16x32_bf16 v[76:79], v[158:161], v[222:225], v[76:79]
	v_mfma_f32_16x16x32_bf16 v[124:127], v[170:173], v[190:193], v[124:127]
	v_mfma_f32_16x16x32_bf16 v[120:123], v[178:181], v[190:193], v[120:123]
	v_mfma_f32_16x16x32_bf16 v[96:99], v[178:181], v[202:205], v[96:99]
	v_mfma_f32_16x16x32_bf16 v[112:115], v[170:173], v[202:205], v[112:115]
	v_mfma_f32_16x16x32_bf16 v[88:91], v[170:173], v[210:213], v[88:91]
	v_mfma_f32_16x16x32_bf16 v[80:83], v[178:181], v[210:213], v[80:83]
	v_mfma_f32_16x16x32_bf16 v[64:67], v[178:181], v[218:221], v[64:67]
	v_mfma_f32_16x16x32_bf16 v[72:75], v[170:173], v[218:221], v[72:75]
	v_mfma_f32_16x16x32_bf16 v[124:127], v[174:177], v[198:201], v[124:127]
	v_mfma_f32_16x16x32_bf16 v[120:123], v[182:185], v[198:201], v[120:123]
	v_mfma_f32_16x16x32_bf16 v[96:99], v[182:185], v[206:209], v[96:99]
	v_mfma_f32_16x16x32_bf16 v[112:115], v[174:177], v[206:209], v[112:115]
	v_mfma_f32_16x16x32_bf16 v[88:91], v[174:177], v[214:217], v[88:91]
	v_mfma_f32_16x16x32_bf16 v[80:83], v[182:185], v[214:217], v[80:83]
	v_mfma_f32_16x16x32_bf16 v[64:67], v[182:185], v[222:225], v[64:67]
	v_mfma_f32_16x16x32_bf16 v[72:75], v[174:177], v[222:225], v[72:75]
	s_barrier
	s_add_i32 s64, s53, s40
	v_lshl_add_u64 v[144:145], s[2:3], 0, v[128:129]
	s_mov_b32 m0, s64
	ds_read_b128 v[190:193], v151 offset:16384
	ds_read_b128 v[198:201], v151 offset:17408
	ds_read_b128 v[202:205], v151 offset:18432
	ds_read_b128 v[206:209], v151 offset:19456
	ds_read_b128 v[210:213], v151 offset:20480
	ds_read_b128 v[214:217], v151 offset:21504
	ds_read_b128 v[218:221], v151 offset:22528
	ds_read_b128 v[222:225], v151 offset:23552
	global_load_lds_dwordx4 v[144:145], off
	s_add_i32 m0, s64, 0x2000
	s_add_u32 s64, s2, 0x40000
	v_lshl_add_u64 v[186:187], s[2:3], 0, v[130:131]
	s_addc_u32 s65, s3, 0
	s_add_i32 s66, s54, s40
	global_load_lds_dwordx4 v[186:187], off
	v_lshl_add_u64 v[194:195], s[64:65], 0, v[128:129]
	s_mov_b32 m0, s66
	v_lshl_add_u64 v[226:227], s[26:27], 0, v[132:133]
	global_load_lds_dwordx4 v[194:195], off
	v_lshl_add_u64 v[194:195], s[64:65], 0, v[130:131]
	s_add_i32 m0, s66, 0x2000
	s_nop 0
	global_load_lds_dwordx4 v[194:195], off
	v_lshl_add_u64 v[194:195], s[26:27], 0, v[134:135]
	s_mov_b32 m0, s42
	s_nop 0
	global_load_lds_dwordx4 v[194:195], off
	s_mov_b32 m0, s43
	s_nop 0
	global_load_lds_dwordx4 v[226:227], off
	s_waitcnt vmcnt(8)
	s_waitcnt lgkmcnt(0)
	s_barrier
	s_waitcnt lgkmcnt(0)
	v_mfma_f32_16x16x32_bf16 v[60:63], v[154:157], v[190:193], v[60:63]
	v_mfma_f32_16x16x32_bf16 v[52:55], v[162:165], v[190:193], v[52:55]
	v_mfma_f32_16x16x32_bf16 v[36:39], v[162:165], v[202:205], v[36:39]
	v_mfma_f32_16x16x32_bf16 v[44:47], v[154:157], v[202:205], v[44:47]
	v_mfma_f32_16x16x32_bf16 v[28:31], v[154:157], v[210:213], v[28:31]
	v_mfma_f32_16x16x32_bf16 v[20:23], v[162:165], v[210:213], v[20:23]
	v_mfma_f32_16x16x32_bf16 v[4:7], v[162:165], v[218:221], v[4:7]
	v_mfma_f32_16x16x32_bf16 v[12:15], v[154:157], v[218:221], v[12:15]
	v_mfma_f32_16x16x32_bf16 v[60:63], v[158:161], v[198:201], v[60:63]
	v_mfma_f32_16x16x32_bf16 v[52:55], v[166:169], v[198:201], v[52:55]
	v_mfma_f32_16x16x32_bf16 v[36:39], v[166:169], v[206:209], v[36:39]
	v_mfma_f32_16x16x32_bf16 v[44:47], v[158:161], v[206:209], v[44:47]
	v_mfma_f32_16x16x32_bf16 v[28:31], v[158:161], v[214:217], v[28:31]
	v_mfma_f32_16x16x32_bf16 v[20:23], v[166:169], v[214:217], v[20:23]
	v_mfma_f32_16x16x32_bf16 v[4:7], v[166:169], v[222:225], v[4:7]
	v_mfma_f32_16x16x32_bf16 v[12:15], v[158:161], v[222:225], v[12:15]
	v_mfma_f32_16x16x32_bf16 v[56:59], v[170:173], v[190:193], v[56:59]
	v_mfma_f32_16x16x32_bf16 v[48:51], v[178:181], v[190:193], v[48:51]
	v_mfma_f32_16x16x32_bf16 v[32:35], v[178:181], v[202:205], v[32:35]
	v_mfma_f32_16x16x32_bf16 v[40:43], v[170:173], v[202:205], v[40:43]
	v_mfma_f32_16x16x32_bf16 v[24:27], v[170:173], v[210:213], v[24:27]
	v_mfma_f32_16x16x32_bf16 v[16:19], v[178:181], v[210:213], v[16:19]
	v_mfma_f32_16x16x32_bf16 v[0:3], v[178:181], v[218:221], v[0:3]
	v_mfma_f32_16x16x32_bf16 v[8:11], v[170:173], v[218:221], v[8:11]
	v_mfma_f32_16x16x32_bf16 v[56:59], v[174:177], v[198:201], v[56:59]
	v_mfma_f32_16x16x32_bf16 v[48:51], v[182:185], v[198:201], v[48:51]
	v_mfma_f32_16x16x32_bf16 v[32:35], v[182:185], v[206:209], v[32:35]
	v_mfma_f32_16x16x32_bf16 v[40:43], v[174:177], v[206:209], v[40:43]
	v_mfma_f32_16x16x32_bf16 v[24:27], v[174:177], v[214:217], v[24:27]
	v_mfma_f32_16x16x32_bf16 v[16:19], v[182:185], v[214:217], v[16:19]
	v_mfma_f32_16x16x32_bf16 v[0:3], v[182:185], v[222:225], v[0:3]
	v_mfma_f32_16x16x32_bf16 v[8:11], v[174:177], v[222:225], v[8:11]
	s_barrier
; #define PG8_STAGE(bufoff, gbase, voff) do { _Pragma("unroll") for (int _i = 0; _i < 2; ++_i) \
;         __builtin_amdgcn_global_load_lds((const unsigned*)((const char*)(gbase) + (voff)[_i]), (LAS unsigned*)(lds + (bufoff) + ldsw + _i * 8192), 16, 0, 0); } while (0)
; #define PG8_LDA(dst, b, h) do { _Pragma("unroll") for (int m = 0; m < 4; ++m) _Pragma("unroll") for (int k = 0; k < 2; ++k) dst[m][k] = *(const LAS bf16x8*)(lds + PG8_SA(b, h) + aoff + m * 2048 + k * 1024); } while (0)
; #define PG8_LDB(dst, b, h) do { _Pragma("unroll") for (int n = 0; n < 2; ++n) _Pragma("unroll") for (int k = 0; k < 2; ++k) dst[n][k] = *(const LAS bf16x8*)(lds + PG8_SB(b, h) + boff + n * 2048 + k * 1024); } while (0)
; #define PG8_MMA(ai, bj, At, Bt) do { __builtin_amdgcn_s_setprio(1); _Pragma("unroll") for (int m = 0; m < 4; ++m) _Pragma("unroll") for (int n = 0; n < 2; ++n) _Pragma("unroll") for (int k = 0; k < 2; ++k) \
;         acc[ai][bj][m][n] = __builtin_amdgcn_mfma_f32_16x16x32_bf16(Bt[n][k], At[m][k], acc[ai][bj][m][n], 0, 0, 0); __builtin_amdgcn_s_setprio(0); } while (0)
; #define PG8_WAIT_V(n) asm volatile("s_waitcnt vmcnt(" #n ")" ::: "memory")
; #define PG8_WAIT_L(n) asm volatile("s_waitcnt lgkmcnt(" #n ")" ::: "memory")
; #define PG8_BAR __builtin_amdgcn_s_barrier()
; #define PG8_SCHED __builtin_amdgcn_sched_barrier(0)
; template <class Epi>
; __device__ __forceinline__ void gemm_phase(LAS unsigned char* lds, const Gemm g, const StaticOrder& S, const Epi& E) {
;     ...
;             PG8_LDB(B0, 1, 0); PG8_LDB(B1, 1, 1); PG8_SCHED; PG8_LDA(At, 1, 0); PG8_STAGE(PG8_SA(0, 1), a2 + hstepA, voffA);
;             PG8_WAIT_V(8); PG8_WAIT_L(0); PG8_BAR; PG8_MMA(0, 0, At, B0); PG8_MMA(0, 1, At, B1); PG8_BAR; PG8_SCHED;
	s_add_i32 s64, 0, 0x18000
	v_add_u32_e32 v138, s64, v147
	s_add_i32 s65, 0, 0x1c000
	ds_read_b128 v[154:157], v138
	ds_read_b128 v[158:161], v138 offset:1024
	ds_read_b128 v[162:165], v138 offset:2048
	ds_read_b128 v[166:169], v138 offset:3072
	v_add_u32_e32 v138, s65, v147
	ds_read_b128 v[170:173], v138
	ds_read_b128 v[174:177], v138 offset:1024
	ds_read_b128 v[178:181], v138 offset:2048
	ds_read_b128 v[182:185], v138 offset:3072
	s_add_u32 s26, s26, 0x40000
	s_addc_u32 s27, s27, 0
	s_mov_b32 m0, s44
	v_lshl_add_u64 v[228:229], s[26:27], 0, v[134:135]
	ds_read_b128 v[190:193], v151 offset:32768
	ds_read_b128 v[198:201], v151 offset:33792
	ds_read_b128 v[202:205], v151 offset:34816
	ds_read_b128 v[206:209], v151 offset:35840
	ds_read_b128 v[210:213], v151 offset:36864
	ds_read_b128 v[214:217], v151 offset:37888
	ds_read_b128 v[218:221], v151 offset:38912
	ds_read_b128 v[222:225], v151 offset:39936
	global_load_lds_dwordx4 v[228:229], off
	v_lshl_add_u64 v[228:229], s[26:27], 0, v[132:133]
	s_mov_b32 m0, s45
	s_nop 0
	global_load_lds_dwordx4 v[228:229], off
	s_waitcnt vmcnt(8)
	s_waitcnt lgkmcnt(0)
	s_barrier
	s_waitcnt lgkmcnt(0)
	v_mfma_f32_16x16x32_bf16 v[116:119], v[154:157], v[190:193], v[116:119]
	v_mfma_f32_16x16x32_bf16 v[108:111], v[162:165], v[190:193], v[108:111]
	v_mfma_f32_16x16x32_bf16 v[100:103], v[162:165], v[202:205], v[100:103]
	v_mfma_f32_16x16x32_bf16 v[104:107], v[154:157], v[202:205], v[104:107]
	v_mfma_f32_16x16x32_bf16 v[92:95], v[154:157], v[210:213], v[92:95]
	v_mfma_f32_16x16x32_bf16 v[84:87], v[162:165], v[210:213], v[84:87]
	v_mfma_f32_16x16x32_bf16 v[68:71], v[162:165], v[218:221], v[68:71]
	v_mfma_f32_16x16x32_bf16 v[76:79], v[154:157], v[218:221], v[76:79]
	v_mfma_f32_16x16x32_bf16 v[116:119], v[158:161], v[198:201], v[116:119]
	v_mfma_f32_16x16x32_bf16 v[108:111], v[166:169], v[198:201], v[108:111]
	v_mfma_f32_16x16x32_bf16 v[100:103], v[166:169], v[206:209], v[100:103]
	v_mfma_f32_16x16x32_bf16 v[104:107], v[158:161], v[206:209], v[104:107]
	v_mfma_f32_16x16x32_bf16 v[92:95], v[158:161], v[214:217], v[92:95]
	v_mfma_f32_16x16x32_bf16 v[84:87], v[166:169], v[214:217], v[84:87]
	v_mfma_f32_16x16x32_bf16 v[68:71], v[166:169], v[222:225], v[68:71]
	v_mfma_f32_16x16x32_bf16 v[76:79], v[158:161], v[222:225], v[76:79]
	v_mfma_f32_16x16x32_bf16 v[124:127], v[170:173], v[190:193], v[124:127]
	v_mfma_f32_16x16x32_bf16 v[120:123], v[178:181], v[190:193], v[120:123]
	v_mfma_f32_16x16x32_bf16 v[96:99], v[178:181], v[202:205], v[96:99]
	v_mfma_f32_16x16x32_bf16 v[112:115], v[170:173], v[202:205], v[112:115]
	v_mfma_f32_16x16x32_bf16 v[88:91], v[170:173], v[210:213], v[88:91]
	v_mfma_f32_16x16x32_bf16 v[80:83], v[178:181], v[210:213], v[80:83]
	v_mfma_f32_16x16x32_bf16 v[64:67], v[178:181], v[218:221], v[64:67]
	v_mfma_f32_16x16x32_bf16 v[72:75], v[170:173], v[218:221], v[72:75]
	v_mfma_f32_16x16x32_bf16 v[124:127], v[174:177], v[198:201], v[124:127]
	v_mfma_f32_16x16x32_bf16 v[120:123], v[182:185], v[198:201], v[120:123]
	v_mfma_f32_16x16x32_bf16 v[96:99], v[182:185], v[206:209], v[96:99]
	v_mfma_f32_16x16x32_bf16 v[112:115], v[174:177], v[206:209], v[112:115]
	v_mfma_f32_16x16x32_bf16 v[88:91], v[174:177], v[214:217], v[88:91]
	v_mfma_f32_16x16x32_bf16 v[80:83], v[182:185], v[214:217], v[80:83]
	v_mfma_f32_16x16x32_bf16 v[64:67], v[182:185], v[222:225], v[64:67]
	v_mfma_f32_16x16x32_bf16 v[72:75], v[174:177], v[222:225], v[72:75]
	s_barrier
; #define PG8_STAGE(bufoff, gbase, voff) do { _Pragma("unroll") for (int _i = 0; _i < 2; ++_i) \
;         __builtin_amdgcn_global_load_lds((const unsigned*)((const char*)(gbase) + (voff)[_i]), (LAS unsigned*)(lds + (bufoff) + ldsw + _i * 8192), 16, 0, 0); } while (0)
; #define PG8_LDA(dst, b, h) do { _Pragma("unroll") for (int m = 0; m < 4; ++m) _Pragma("unroll") for (int k = 0; k < 2; ++k) dst[m][k] = *(const LAS bf16x8*)(lds + PG8_SA(b, h) + aoff + m * 2048 + k * 1024); } while (0)
; #define PG8_MMA(ai, bj, At, Bt) do { __builtin_amdgcn_s_setprio(1); _Pragma("unroll") for (int m = 0; m < 4; ++m) _Pragma("unroll") for (int n = 0; n < 2; ++n) _Pragma("unroll") for (int k = 0; k < 2; ++k) \
;         acc[ai][bj][m][n] = __builtin_amdgcn_mfma_f32_16x16x32_bf16(Bt[n][k], At[m][k], acc[ai][bj][m][n], 0, 0, 0); __builtin_amdgcn_s_setprio(0); } while (0)
; #define PG8_WAIT_V(n) asm volatile("s_waitcnt vmcnt(" #n ")" ::: "memory")
; #define PG8_WAIT_L(n) asm volatile("s_waitcnt lgkmcnt(" #n ")" ::: "memory")
; #define PG8_BAR __builtin_amdgcn_s_barrier()
; #define PG8_SCHED __builtin_amdgcn_sched_barrier(0)
; template <class Epi>
; __device__ __forceinline__ void gemm_phase(LAS unsigned char* lds, const Gemm g, const StaticOrder& S, const Epi& E) {
;     ...
;             PG8_LDA(At, 1, 1); PG8_STAGE(PG8_SB(1, 0), b3, voffB); PG8_STAGE(PG8_SB(1, 1), b3 + hstepB, voffB); PG8_STAGE(PG8_SA(1, 0), a3, voffA);
;             PG8_WAIT_V(8); PG8_WAIT_L(0); PG8_BAR; PG8_MMA(1, 0, At, B0); PG8_MMA(1, 1, At, B1); PG8_BAR; PG8_SCHED;
;         }
;         if (wr == 0) PG8_BAR;
	s_add_i32 s26, s64, s40
	v_lshl_add_u64 v[144:145], v[144:145], 0, s[14:15]
	s_mov_b32 m0, s26
	ds_read_b128 v[190:193], v151 offset:49152
	ds_read_b128 v[198:201], v151 offset:50176
	ds_read_b128 v[202:205], v151 offset:51200
	ds_read_b128 v[206:209], v151 offset:52224
	ds_read_b128 v[210:213], v151 offset:53248
	ds_read_b128 v[214:217], v151 offset:54272
	ds_read_b128 v[218:221], v151 offset:55296
	ds_read_b128 v[222:225], v151 offset:56320
	global_load_lds_dwordx4 v[144:145], off
	s_add_i32 m0, s26, 0x2000
	s_add_u32 s2, s2, 0x40080
	v_lshl_add_u64 v[144:145], v[186:187], 0, s[14:15]
	s_addc_u32 s3, s3, 0
	s_add_i32 s26, s65, s40
	global_load_lds_dwordx4 v[144:145], off
	v_lshl_add_u64 v[144:145], s[2:3], 0, v[128:129]
	s_mov_b32 m0, s26
	s_nop 0
	global_load_lds_dwordx4 v[144:145], off
	v_lshl_add_u64 v[144:145], s[2:3], 0, v[130:131]
	s_add_i32 m0, s26, 0x2000
	s_nop 0
	global_load_lds_dwordx4 v[144:145], off
	v_lshl_add_u64 v[144:145], v[194:195], 0, s[14:15]
	s_mov_b32 m0, s49
	s_nop 0
	global_load_lds_dwordx4 v[144:145], off
	v_lshl_add_u64 v[144:145], v[226:227], 0, s[14:15]
	s_mov_b32 m0, s50
	s_nop 0
	global_load_lds_dwordx4 v[144:145], off
	s_waitcnt vmcnt(8)
	s_waitcnt lgkmcnt(0)
	s_barrier
	s_waitcnt lgkmcnt(0)
	v_mfma_f32_16x16x32_bf16 v[60:63], v[154:157], v[190:193], v[60:63]
	v_mfma_f32_16x16x32_bf16 v[52:55], v[162:165], v[190:193], v[52:55]
	v_mfma_f32_16x16x32_bf16 v[36:39], v[162:165], v[202:205], v[36:39]
	v_mfma_f32_16x16x32_bf16 v[44:47], v[154:157], v[202:205], v[44:47]
	v_mfma_f32_16x16x32_bf16 v[28:31], v[154:157], v[210:213], v[28:31]
	v_mfma_f32_16x16x32_bf16 v[20:23], v[162:165], v[210:213], v[20:23]
	v_mfma_f32_16x16x32_bf16 v[4:7], v[162:165], v[218:221], v[4:7]
	v_mfma_f32_16x16x32_bf16 v[12:15], v[154:157], v[218:221], v[12:15]
	v_mfma_f32_16x16x32_bf16 v[60:63], v[158:161], v[198:201], v[60:63]
	v_mfma_f32_16x16x32_bf16 v[52:55], v[166:169], v[198:201], v[52:55]
	v_mfma_f32_16x16x32_bf16 v[36:39], v[166:169], v[206:209], v[36:39]
	v_mfma_f32_16x16x32_bf16 v[44:47], v[158:161], v[206:209], v[44:47]
	v_mfma_f32_16x16x32_bf16 v[28:31], v[158:161], v[214:217], v[28:31]
	v_mfma_f32_16x16x32_bf16 v[20:23], v[166:169], v[214:217], v[20:23]
	v_mfma_f32_16x16x32_bf16 v[4:7], v[166:169], v[222:225], v[4:7]
	v_mfma_f32_16x16x32_bf16 v[12:15], v[158:161], v[222:225], v[12:15]
	v_mfma_f32_16x16x32_bf16 v[56:59], v[170:173], v[190:193], v[56:59]
	v_mfma_f32_16x16x32_bf16 v[48:51], v[178:181], v[190:193], v[48:51]
	v_mfma_f32_16x16x32_bf16 v[32:35], v[178:181], v[202:205], v[32:35]
	v_mfma_f32_16x16x32_bf16 v[40:43], v[170:173], v[202:205], v[40:43]
	v_mfma_f32_16x16x32_bf16 v[24:27], v[170:173], v[210:213], v[24:27]
	v_mfma_f32_16x16x32_bf16 v[16:19], v[178:181], v[210:213], v[16:19]
	v_mfma_f32_16x16x32_bf16 v[0:3], v[178:181], v[218:221], v[0:3]
	v_mfma_f32_16x16x32_bf16 v[8:11], v[170:173], v[218:221], v[8:11]
	v_mfma_f32_16x16x32_bf16 v[56:59], v[174:177], v[198:201], v[56:59]
	v_mfma_f32_16x16x32_bf16 v[48:51], v[182:185], v[198:201], v[48:51]
	v_mfma_f32_16x16x32_bf16 v[32:35], v[182:185], v[206:209], v[32:35]
	v_mfma_f32_16x16x32_bf16 v[40:43], v[174:177], v[206:209], v[40:43]
	v_mfma_f32_16x16x32_bf16 v[24:27], v[174:177], v[214:217], v[24:27]
	v_mfma_f32_16x16x32_bf16 v[16:19], v[182:185], v[214:217], v[16:19]
	v_mfma_f32_16x16x32_bf16 v[0:3], v[182:185], v[222:225], v[0:3]
	v_mfma_f32_16x16x32_bf16 v[8:11], v[174:177], v[222:225], v[8:11]
	s_barrier
	s_add_i32 s63, s63, 2
	s_add_u32 s24, s24, 0x100
	s_addc_u32 s25, s25, 0
	s_add_u32 s61, s61, 0x100
	s_addc_u32 s62, s62, 0
	s_cmp_gt_u32 s63, 13
	s_cbranch_scc0 .LBB0_153
	s_and_b64 vcc, exec, s[16:17]
	s_cbranch_vccz .LBB0_156
	s_barrier

; #define PG8_STAGE(bufoff, gbase, voff) do { _Pragma("unroll") for (int _i = 0; _i < 2; ++_i) \
;         __builtin_amdgcn_global_load_lds((const unsigned*)((const char*)(gbase) + (voff)[_i]), (LAS unsigned*)(lds + (bufoff) + ldsw + _i * 8192), 16, 0, 0); } while (0)
; #define PG8_LDA(dst, b, h) do { _Pragma("unroll") for (int m = 0; m < 4; ++m) _Pragma("unroll") for (int k = 0; k < 2; ++k) dst[m][k] = *(const LAS bf16x8*)(lds + PG8_SA(b, h) + aoff + m * 2048 + k * 1024); } while (0)
; #define PG8_LDB(dst, b, h) do { _Pragma("unroll") for (int n = 0; n < 2; ++n) _Pragma("unroll") for (int k = 0; k < 2; ++k) dst[n][k] = *(const LAS bf16x8*)(lds + PG8_SB(b, h) + boff + n * 2048 + k * 1024); } while (0)
; #define PG8_MMA(ai, bj, At, Bt) do { __builtin_amdgcn_s_setprio(1); _Pragma("unroll") for (int m = 0; m < 4; ++m) _Pragma("unroll") for (int n = 0; n < 2; ++n) _Pragma("unroll") for (int k = 0; k < 2; ++k) \
;         acc[ai][bj][m][n] = __builtin_amdgcn_mfma_f32_16x16x32_bf16(Bt[n][k], At[m][k], acc[ai][bj][m][n], 0, 0, 0); __builtin_amdgcn_s_setprio(0); } while (0)
; #define PG8_WAIT_V(n) asm volatile("s_waitcnt vmcnt(" #n ")" ::: "memory")
; template <class Epi>
; __device__ __forceinline__ void gemm_phase(LAS unsigned char* lds, const Gemm g, const StaticOrder& S, const Epi& E) {
;     ...
;         const char* nA = has_next ? (const char*)g.A + (size_t)(nxt.pm >> 5) * aslab + (size_t)(nxt.pm & 31) * tstepA : cA; const char* nB = has_next ? (const char*)g.Bt + (size_t)nxt.pn * tstepB : cB;
;         for (int t = 0; t < nt; t += 2) {
;             const bool last = (t == nt - 2);
;             const char* a1 = cA + (size_t)(t + 1) * kstep;
;             const char* a2 = last ? nA : cA + (size_t)(t + 2) * kstep; const char* b2 = last ? nB : cB + (size_t)(t + 2) * kstep;
;             const char* a3 = a2 + kstep; const char* b3 = b2 + kstep;
;             PG8_LDB(B0, 0, 0); PG8_LDB(B1, 0, 1); PG8_SCHED; PG8_LDA(At, 0, 0); PG8_STAGE(PG8_SA(1, 1), a1 + hstepA, voffA);
;             PG8_WAIT_V(8); PG8_WAIT_L(0); PG8_BAR; PG8_MMA(0, 0, At, B0); PG8_MMA(0, 1, At, B1); PG8_BAR; PG8_SCHED;
;             PG8_LDA(At, 0, 1); PG8_STAGE(PG8_SB(0, 0), b2, voffB); PG8_STAGE(PG8_SB(0, 1), b2 + hstepB, voffB); PG8_STAGE(PG8_SA(0, 0), a2, voffA);
;             PG8_WAIT_V(8); PG8_WAIT_L(0); PG8_BAR; PG8_MMA(1, 0, At, B0); PG8_MMA(1, 1, At, B1); PG8_BAR; PG8_SCHED;
.LBB0_256:
	s_add_u32 s50, s8, 0x100
	s_addc_u32 s51, s9, 0
	s_mov_b32 s52, -2
	s_waitcnt lgkmcnt(0)
	ds_read_b128 v[128:131], v187
	ds_read_b128 v[132:135], v187 offset:1024
	ds_read_b128 v[136:139], v187 offset:2048
	ds_read_b128 v[140:143], v187 offset:3072
	ds_read_b128 v[144:147], v188
	ds_read_b128 v[148:151], v188 offset:1024
	ds_read_b128 v[166:169], v188 offset:2048
	ds_read_b128 v[170:173], v188 offset:3072
	s_add_u32 s8, s2, 0x100
	s_addc_u32 s9, s3, 0
	s_cmp_eq_u32 s52, 40
	s_cselect_b32 s31, s1, s9
	s_cselect_b32 s30, s0, s8
	s_cselect_b32 s27, s25, s51
	s_cselect_b32 s26, s24, s50
	v_lshl_add_u64 v[182:183], s[2:3], 0, v[160:161]
	s_add_i32 m0, s35, 0xc000
	ds_read_b128 v[174:177], v190
	ds_read_b128 v[178:181], v190 offset:1024
	ds_read_b128 v[192:195], v190 offset:2048
	ds_read_b128 v[198:201], v190 offset:3072
	ds_read_b128 v[202:205], v190 offset:4096
	ds_read_b128 v[206:209], v190 offset:5120
	ds_read_b128 v[210:213], v190 offset:6144
	ds_read_b128 v[214:217], v190 offset:7168
	global_load_lds_dwordx4 v[182:183], off
	v_lshl_add_u64 v[182:183], s[2:3], 0, v[162:163]
	s_add_i32 m0, s35, 0xe000
	s_nop 0
	global_load_lds_dwordx4 v[182:183], off
	s_waitcnt vmcnt(8)
	s_waitcnt lgkmcnt(0)
	s_barrier
	s_waitcnt lgkmcnt(0)
	v_mfma_f32_16x16x32_bf16 v[124:127], v[128:131], v[174:177], 0
	v_mfma_f32_16x16x32_bf16 v[120:123], v[136:139], v[174:177], 0
	v_mfma_f32_16x16x32_bf16 v[104:107], v[136:139], v[192:195], 0
	v_mfma_f32_16x16x32_bf16 v[108:111], v[128:131], v[192:195], 0
	v_mfma_f32_16x16x32_bf16 v[92:95], v[128:131], v[202:205], 0
	v_mfma_f32_16x16x32_bf16 v[88:91], v[136:139], v[202:205], 0
	v_mfma_f32_16x16x32_bf16 v[72:75], v[136:139], v[210:213], 0
	v_mfma_f32_16x16x32_bf16 v[76:79], v[128:131], v[210:213], 0
	v_mfma_f32_16x16x32_bf16 v[124:127], v[132:135], v[178:181], v[124:127]
	v_mfma_f32_16x16x32_bf16 v[120:123], v[140:143], v[178:181], v[120:123]
	v_mfma_f32_16x16x32_bf16 v[104:107], v[140:143], v[198:201], v[104:107]
	v_mfma_f32_16x16x32_bf16 v[108:111], v[132:135], v[198:201], v[108:111]
	v_mfma_f32_16x16x32_bf16 v[92:95], v[132:135], v[206:209], v[92:95]
	v_mfma_f32_16x16x32_bf16 v[88:91], v[140:143], v[206:209], v[88:91]
	v_mfma_f32_16x16x32_bf16 v[72:75], v[140:143], v[214:217], v[72:75]
	v_mfma_f32_16x16x32_bf16 v[76:79], v[132:135], v[214:217], v[76:79]
	v_mfma_f32_16x16x32_bf16 v[116:119], v[144:147], v[174:177], 0
	v_mfma_f32_16x16x32_bf16 v[112:115], v[166:169], v[174:177], 0
	v_mfma_f32_16x16x32_bf16 v[96:99], v[166:169], v[192:195], 0
	v_mfma_f32_16x16x32_bf16 v[100:103], v[144:147], v[192:195], 0
	v_mfma_f32_16x16x32_bf16 v[84:87], v[144:147], v[202:205], 0
	v_mfma_f32_16x16x32_bf16 v[80:83], v[166:169], v[202:205], 0
	v_mfma_f32_16x16x32_bf16 v[64:67], v[166:169], v[210:213], 0
	v_mfma_f32_16x16x32_bf16 v[68:71], v[144:147], v[210:213], 0
	v_mfma_f32_16x16x32_bf16 v[116:119], v[148:151], v[178:181], v[116:119]
	v_mfma_f32_16x16x32_bf16 v[112:115], v[170:173], v[178:181], v[112:115]
	v_mfma_f32_16x16x32_bf16 v[96:99], v[170:173], v[198:201], v[96:99]
	v_mfma_f32_16x16x32_bf16 v[100:103], v[148:151], v[198:201], v[100:103]
	v_mfma_f32_16x16x32_bf16 v[84:87], v[148:151], v[206:209], v[84:87]
	v_mfma_f32_16x16x32_bf16 v[80:83], v[170:173], v[206:209], v[80:83]
	v_mfma_f32_16x16x32_bf16 v[64:67], v[170:173], v[214:217], v[64:67]
	v_mfma_f32_16x16x32_bf16 v[68:71], v[148:151], v[214:217], v[68:71]
	s_barrier
	s_add_i32 s2, s45, s34
	v_lshl_add_u64 v[182:183], s[26:27], 0, v[154:155]
	s_mov_b32 m0, s2
	ds_read_b128 v[174:177], v190 offset:16384
	ds_read_b128 v[178:181], v190 offset:17408
	ds_read_b128 v[192:195], v190 offset:18432
	ds_read_b128 v[198:201], v190 offset:19456
	ds_read_b128 v[202:205], v190 offset:20480
	ds_read_b128 v[206:209], v190 offset:21504
	ds_read_b128 v[210:213], v190 offset:22528
	ds_read_b128 v[214:217], v190 offset:23552
	global_load_lds_dwordx4 v[182:183], off
	s_add_i32 m0, s2, 0x2000
	s_add_u32 s2, s26, 0xb0000
	v_lshl_add_u64 v[218:219], s[26:27], 0, v[158:159]
	s_addc_u32 s3, s27, 0
	s_add_i32 s53, s46, s34
	global_load_lds_dwordx4 v[218:219], off
	v_lshl_add_u64 v[220:221], s[2:3], 0, v[154:155]
	s_mov_b32 m0, s53
	v_lshl_add_u64 v[222:223], s[30:31], 0, v[156:157]
	global_load_lds_dwordx4 v[220:221], off
	v_lshl_add_u64 v[220:221], s[2:3], 0, v[158:159]
	s_add_i32 m0, s53, 0x2000
	s_nop 0
	global_load_lds_dwordx4 v[220:221], off
	v_lshl_add_u64 v[220:221], s[30:31], 0, v[152:153]
	s_mov_b32 m0, s35
	s_nop 0
	global_load_lds_dwordx4 v[220:221], off
	s_mov_b32 m0, s36
	s_nop 0
	global_load_lds_dwordx4 v[222:223], off
	s_waitcnt vmcnt(8)
	s_waitcnt lgkmcnt(0)
	s_barrier
; #define PG8_STAGE(bufoff, gbase, voff) do { _Pragma("unroll") for (int _i = 0; _i < 2; ++_i) \
;         __builtin_amdgcn_global_load_lds((const unsigned*)((const char*)(gbase) + (voff)[_i]), (LAS unsigned*)(lds + (bufoff) + ldsw + _i * 8192), 16, 0, 0); } while (0)
; #define PG8_LDA(dst, b, h) do { _Pragma("unroll") for (int m = 0; m < 4; ++m) _Pragma("unroll") for (int k = 0; k < 2; ++k) dst[m][k] = *(const LAS bf16x8*)(lds + PG8_SA(b, h) + aoff + m * 2048 + k * 1024); } while (0)
; #define PG8_LDB(dst, b, h) do { _Pragma("unroll") for (int n = 0; n < 2; ++n) _Pragma("unroll") for (int k = 0; k < 2; ++k) dst[n][k] = *(const LAS bf16x8*)(lds + PG8_SB(b, h) + boff + n * 2048 + k * 1024); } while (0)
; #define PG8_MMA(ai, bj, At, Bt) do { __builtin_amdgcn_s_setprio(1); _Pragma("unroll") for (int m = 0; m < 4; ++m) _Pragma("unroll") for (int n = 0; n < 2; ++n) _Pragma("unroll") for (int k = 0; k < 2; ++k) \
;         acc[ai][bj][m][n] = __builtin_amdgcn_mfma_f32_16x16x32_bf16(Bt[n][k], At[m][k], acc[ai][bj][m][n], 0, 0, 0); __builtin_amdgcn_s_setprio(0); } while (0)
; #define PG8_WAIT_V(n) asm volatile("s_waitcnt vmcnt(" #n ")" ::: "memory")
; #define PG8_WAIT_L(n) asm volatile("s_waitcnt lgkmcnt(" #n ")" ::: "memory")
; #define PG8_BAR __builtin_amdgcn_s_barrier()
; #define PG8_SCHED __builtin_amdgcn_sched_barrier(0)
; template <class Epi>
; __device__ __forceinline__ void gemm_phase(LAS unsigned char* lds, const Gemm g, const StaticOrder& S, const Epi& E) {
;     ...
;             PG8_WAIT_V(8); PG8_WAIT_L(0); PG8_BAR; PG8_MMA(1, 0, At, B0); PG8_MMA(1, 1, At, B1); PG8_BAR; PG8_SCHED;
;             PG8_LDB(B0, 1, 0); PG8_LDB(B1, 1, 1); PG8_SCHED; PG8_LDA(At, 1, 0); PG8_STAGE(PG8_SA(0, 1), a2 + hstepA, voffA);
;             PG8_WAIT_V(8); PG8_WAIT_L(0); PG8_BAR; PG8_MMA(0, 0, At, B0); PG8_MMA(0, 1, At, B1); PG8_BAR; PG8_SCHED;
	s_waitcnt lgkmcnt(0)
	v_mfma_f32_16x16x32_bf16 v[60:63], v[128:131], v[174:177], 0
	v_mfma_f32_16x16x32_bf16 v[56:59], v[136:139], v[174:177], 0
	v_mfma_f32_16x16x32_bf16 v[40:43], v[136:139], v[192:195], 0
	v_mfma_f32_16x16x32_bf16 v[44:47], v[128:131], v[192:195], 0
	v_mfma_f32_16x16x32_bf16 v[28:31], v[128:131], v[202:205], 0
	v_mfma_f32_16x16x32_bf16 v[24:27], v[136:139], v[202:205], 0
	v_mfma_f32_16x16x32_bf16 v[8:11], v[136:139], v[210:213], 0
	v_mfma_f32_16x16x32_bf16 v[12:15], v[128:131], v[210:213], 0
	v_mfma_f32_16x16x32_bf16 v[60:63], v[132:135], v[178:181], v[60:63]
	v_mfma_f32_16x16x32_bf16 v[56:59], v[140:143], v[178:181], v[56:59]
	v_mfma_f32_16x16x32_bf16 v[40:43], v[140:143], v[198:201], v[40:43]
	v_mfma_f32_16x16x32_bf16 v[44:47], v[132:135], v[198:201], v[44:47]
	v_mfma_f32_16x16x32_bf16 v[28:31], v[132:135], v[206:209], v[28:31]
	v_mfma_f32_16x16x32_bf16 v[24:27], v[140:143], v[206:209], v[24:27]
	v_mfma_f32_16x16x32_bf16 v[8:11], v[140:143], v[214:217], v[8:11]
	v_mfma_f32_16x16x32_bf16 v[12:15], v[132:135], v[214:217], v[12:15]
	v_mfma_f32_16x16x32_bf16 v[52:55], v[144:147], v[174:177], 0
	v_mfma_f32_16x16x32_bf16 v[48:51], v[166:169], v[174:177], 0
	v_mfma_f32_16x16x32_bf16 v[32:35], v[166:169], v[192:195], 0
	v_mfma_f32_16x16x32_bf16 v[36:39], v[144:147], v[192:195], 0
	v_mfma_f32_16x16x32_bf16 v[20:23], v[144:147], v[202:205], 0
	v_mfma_f32_16x16x32_bf16 v[16:19], v[166:169], v[202:205], 0
	v_mfma_f32_16x16x32_bf16 v[0:3], v[166:169], v[210:213], 0
	v_mfma_f32_16x16x32_bf16 v[4:7], v[144:147], v[210:213], 0
	v_mfma_f32_16x16x32_bf16 v[52:55], v[148:151], v[178:181], v[52:55]
	v_mfma_f32_16x16x32_bf16 v[48:51], v[170:173], v[178:181], v[48:51]
	v_mfma_f32_16x16x32_bf16 v[32:35], v[170:173], v[198:201], v[32:35]
	v_mfma_f32_16x16x32_bf16 v[36:39], v[148:151], v[198:201], v[36:39]
	v_mfma_f32_16x16x32_bf16 v[20:23], v[148:151], v[206:209], v[20:23]
	v_mfma_f32_16x16x32_bf16 v[16:19], v[170:173], v[206:209], v[16:19]
	v_mfma_f32_16x16x32_bf16 v[0:3], v[170:173], v[214:217], v[0:3]
	v_mfma_f32_16x16x32_bf16 v[4:7], v[148:151], v[214:217], v[4:7]
	s_barrier
	s_add_i32 s53, 0, 0x18000
	s_add_i32 s54, 0, 0x1c000
	v_add_u32_e32 v140, s53, v185
	v_add_u32_e32 v170, s54, v185
	ds_read_b128 v[128:131], v140
	ds_read_b128 v[132:135], v140 offset:1024
	ds_read_b128 v[136:139], v140 offset:2048
	ds_read_b128 v[140:143], v140 offset:3072
	ds_read_b128 v[144:147], v170
	ds_read_b128 v[148:151], v170 offset:1024
	ds_read_b128 v[166:169], v170 offset:2048
	ds_read_b128 v[170:173], v170 offset:3072
	s_add_u32 s2, s30, 0xb4000
	s_addc_u32 s3, s31, 0
	s_mov_b32 m0, s37
	v_lshl_add_u64 v[224:225], s[2:3], 0, v[152:153]
	ds_read_b128 v[174:177], v190 offset:32768
	ds_read_b128 v[178:181], v190 offset:33792
	ds_read_b128 v[192:195], v190 offset:34816
	ds_read_b128 v[198:201], v190 offset:35840
	ds_read_b128 v[202:205], v190 offset:36864
	ds_read_b128 v[206:209], v190 offset:37888
	ds_read_b128 v[210:213], v190 offset:38912
	ds_read_b128 v[214:217], v190 offset:39936
	global_load_lds_dwordx4 v[224:225], off
	v_lshl_add_u64 v[224:225], s[2:3], 0, v[156:157]
	s_mov_b32 m0, s38
	s_nop 0
	global_load_lds_dwordx4 v[224:225], off
	s_waitcnt vmcnt(8)
	s_waitcnt lgkmcnt(0)
	s_barrier
	s_waitcnt lgkmcnt(0)
	v_mfma_f32_16x16x32_bf16 v[124:127], v[128:131], v[174:177], v[124:127]
	v_mfma_f32_16x16x32_bf16 v[120:123], v[136:139], v[174:177], v[120:123]
	v_mfma_f32_16x16x32_bf16 v[104:107], v[136:139], v[192:195], v[104:107]
	v_mfma_f32_16x16x32_bf16 v[108:111], v[128:131], v[192:195], v[108:111]
	v_mfma_f32_16x16x32_bf16 v[92:95], v[128:131], v[202:205], v[92:95]
	v_mfma_f32_16x16x32_bf16 v[88:91], v[136:139], v[202:205], v[88:91]
	v_mfma_f32_16x16x32_bf16 v[72:75], v[136:139], v[210:213], v[72:75]
	v_mfma_f32_16x16x32_bf16 v[76:79], v[128:131], v[210:213], v[76:79]
	v_mfma_f32_16x16x32_bf16 v[124:127], v[132:135], v[178:181], v[124:127]
	v_mfma_f32_16x16x32_bf16 v[120:123], v[140:143], v[178:181], v[120:123]
	v_mfma_f32_16x16x32_bf16 v[104:107], v[140:143], v[198:201], v[104:107]
	v_mfma_f32_16x16x32_bf16 v[108:111], v[132:135], v[198:201], v[108:111]
	v_mfma_f32_16x16x32_bf16 v[92:95], v[132:135], v[206:209], v[92:95]
	v_mfma_f32_16x16x32_bf16 v[88:91], v[140:143], v[206:209], v[88:91]
	v_mfma_f32_16x16x32_bf16 v[72:75], v[140:143], v[214:217], v[72:75]
	v_mfma_f32_16x16x32_bf16 v[76:79], v[132:135], v[214:217], v[76:79]
	v_mfma_f32_16x16x32_bf16 v[116:119], v[144:147], v[174:177], v[116:119]
	v_mfma_f32_16x16x32_bf16 v[112:115], v[166:169], v[174:177], v[112:115]
	v_mfma_f32_16x16x32_bf16 v[96:99], v[166:169], v[192:195], v[96:99]
	v_mfma_f32_16x16x32_bf16 v[100:103], v[144:147], v[192:195], v[100:103]
	v_mfma_f32_16x16x32_bf16 v[84:87], v[144:147], v[202:205], v[84:87]
	v_mfma_f32_16x16x32_bf16 v[80:83], v[166:169], v[202:205], v[80:83]
	v_mfma_f32_16x16x32_bf16 v[64:67], v[166:169], v[210:213], v[64:67]
	v_mfma_f32_16x16x32_bf16 v[68:71], v[144:147], v[210:213], v[68:71]
	v_mfma_f32_16x16x32_bf16 v[116:119], v[148:151], v[178:181], v[116:119]
	v_mfma_f32_16x16x32_bf16 v[112:115], v[170:173], v[178:181], v[112:115]
	v_mfma_f32_16x16x32_bf16 v[96:99], v[170:173], v[198:201], v[96:99]
	v_mfma_f32_16x16x32_bf16 v[100:103], v[148:151], v[198:201], v[100:103]
	v_mfma_f32_16x16x32_bf16 v[84:87], v[148:151], v[206:209], v[84:87]
	v_mfma_f32_16x16x32_bf16 v[80:83], v[170:173], v[206:209], v[80:83]
	v_mfma_f32_16x16x32_bf16 v[64:67], v[170:173], v[214:217], v[64:67]
	v_mfma_f32_16x16x32_bf16 v[68:71], v[148:151], v[214:217], v[68:71]
	s_barrier
; #define PG8_STAGE(bufoff, gbase, voff) do { _Pragma("unroll") for (int _i = 0; _i < 2; ++_i) \
;         __builtin_amdgcn_global_load_lds((const unsigned*)((const char*)(gbase) + (voff)[_i]), (LAS unsigned*)(lds + (bufoff) + ldsw + _i * 8192), 16, 0, 0); } while (0)
; #define PG8_LDA(dst, b, h) do { _Pragma("unroll") for (int m = 0; m < 4; ++m) _Pragma("unroll") for (int k = 0; k < 2; ++k) dst[m][k] = *(const LAS bf16x8*)(lds + PG8_SA(b, h) + aoff + m * 2048 + k * 1024); } while (0)
; #define PG8_LDB(dst, b, h) do { _Pragma("unroll") for (int n = 0; n < 2; ++n) _Pragma("unroll") for (int k = 0; k < 2; ++k) dst[n][k] = *(const LAS bf16x8*)(lds + PG8_SB(b, h) + boff + n * 2048 + k * 1024); } while (0)
; #define PG8_WAIT_V(n) asm volatile("s_waitcnt vmcnt(" #n ")" ::: "memory")
; #define PG8_WAIT_L(n) asm volatile("s_waitcnt lgkmcnt(" #n ")" ::: "memory")
; template <class Epi>
; __device__ __forceinline__ void gemm_phase(LAS unsigned char* lds, const Gemm g, const StaticOrder& S, const Epi& E) {
;     ...
;         for (int t = 0; t < nt; t += 2) {
;             const bool last = (t == nt - 2);
;             const char* a1 = cA + (size_t)(t + 1) * kstep;
;             const char* a2 = last ? nA : cA + (size_t)(t + 2) * kstep; const char* b2 = last ? nB : cB + (size_t)(t + 2) * kstep;
;             const char* a3 = a2 + kstep; const char* b3 = b2 + kstep;
;             PG8_LDB(B0, 0, 0); PG8_LDB(B1, 0, 1); PG8_SCHED; PG8_LDA(At, 0, 0); PG8_STAGE(PG8_SA(1, 1), a1 + hstepA, voffA);
;             PG8_WAIT_V(8); PG8_WAIT_L(0); PG8_BAR; PG8_MMA(0, 0, At, B0); PG8_MMA(0, 1, At, B1); PG8_BAR; PG8_SCHED;
;             PG8_LDA(At, 0, 1); PG8_STAGE(PG8_SB(0, 0), b2, voffB); PG8_STAGE(PG8_SB(0, 1), b2 + hstepB, voffB); PG8_STAGE(PG8_SA(0, 0), a2, voffA);
;             PG8_WAIT_V(8); PG8_WAIT_L(0); PG8_BAR; PG8_MMA(1, 0, At, B0); PG8_MMA(1, 1, At, B1); PG8_BAR; PG8_SCHED;
;             PG8_LDB(B0, 1, 0); PG8_LDB(B1, 1, 1); PG8_SCHED; PG8_LDA(At, 1, 0); PG8_STAGE(PG8_SA(0, 1), a2 + hstepA, voffA);
;             PG8_WAIT_V(8); PG8_WAIT_L(0); PG8_BAR; PG8_MMA(0, 0, At, B0); PG8_MMA(0, 1, At, B1); PG8_BAR; PG8_SCHED;
;             PG8_LDA(At, 1, 1); PG8_STAGE(PG8_SB(1, 0), b3, voffB); PG8_STAGE(PG8_SB(1, 1), b3 + hstepB, voffB); PG8_STAGE(PG8_SA(1, 0), a3, voffA);
;             PG8_WAIT_V(8); PG8_WAIT_L(0); PG8_BAR; PG8_MMA(1, 0, At, B0); PG8_MMA(1, 1, At, B1); PG8_BAR; PG8_SCHED;
	s_add_i32 s2, s53, s34
	v_lshl_add_u64 v[182:183], v[182:183], 0, s[20:21]
	s_mov_b32 m0, s2
	ds_read_b128 v[174:177], v190 offset:49152
	ds_read_b128 v[178:181], v190 offset:50176
	ds_read_b128 v[192:195], v190 offset:51200
	ds_read_b128 v[198:201], v190 offset:52224
	ds_read_b128 v[202:205], v190 offset:53248
	ds_read_b128 v[206:209], v190 offset:54272
	ds_read_b128 v[210:213], v190 offset:55296
	ds_read_b128 v[214:217], v190 offset:56320
	global_load_lds_dwordx4 v[182:183], off
	s_add_i32 m0, s2, 0x2000
	s_add_u32 s2, s26, 0xb0080
	v_lshl_add_u64 v[182:183], v[218:219], 0, s[20:21]
	s_addc_u32 s3, s27, 0
	s_add_i32 s26, s54, s34
	global_load_lds_dwordx4 v[182:183], off
	v_lshl_add_u64 v[182:183], s[2:3], 0, v[154:155]
	s_mov_b32 m0, s26
	s_nop 0
	global_load_lds_dwordx4 v[182:183], off
	v_lshl_add_u64 v[182:183], s[2:3], 0, v[158:159]
	s_add_i32 m0, s26, 0x2000
	s_nop 0
	global_load_lds_dwordx4 v[182:183], off
	v_lshl_add_u64 v[182:183], v[220:221], 0, s[20:21]
	s_mov_b32 m0, s40
	s_nop 0
	global_load_lds_dwordx4 v[182:183], off
	v_lshl_add_u64 v[182:183], v[222:223], 0, s[20:21]
	s_mov_b32 m0, s41
	s_nop 0
	global_load_lds_dwordx4 v[182:183], off
	s_waitcnt vmcnt(8)
	s_waitcnt lgkmcnt(0)
	s_barrier
	s_waitcnt lgkmcnt(0)
	v_mfma_f32_16x16x32_bf16 v[60:63], v[128:131], v[174:177], v[60:63]
	v_mfma_f32_16x16x32_bf16 v[56:59], v[136:139], v[174:177], v[56:59]
	v_mfma_f32_16x16x32_bf16 v[40:43], v[136:139], v[192:195], v[40:43]
	v_mfma_f32_16x16x32_bf16 v[44:47], v[128:131], v[192:195], v[44:47]
	v_mfma_f32_16x16x32_bf16 v[28:31], v[128:131], v[202:205], v[28:31]
	v_mfma_f32_16x16x32_bf16 v[24:27], v[136:139], v[202:205], v[24:27]
	v_mfma_f32_16x16x32_bf16 v[8:11], v[136:139], v[210:213], v[8:11]
	v_mfma_f32_16x16x32_bf16 v[12:15], v[128:131], v[210:213], v[12:15]
	v_mfma_f32_16x16x32_bf16 v[60:63], v[132:135], v[178:181], v[60:63]
	v_mfma_f32_16x16x32_bf16 v[56:59], v[140:143], v[178:181], v[56:59]
	v_mfma_f32_16x16x32_bf16 v[40:43], v[140:143], v[198:201], v[40:43]
	v_mfma_f32_16x16x32_bf16 v[44:47], v[132:135], v[198:201], v[44:47]
	v_mfma_f32_16x16x32_bf16 v[28:31], v[132:135], v[206:209], v[28:31]
	v_mfma_f32_16x16x32_bf16 v[24:27], v[140:143], v[206:209], v[24:27]
	v_mfma_f32_16x16x32_bf16 v[8:11], v[140:143], v[214:217], v[8:11]
	v_mfma_f32_16x16x32_bf16 v[12:15], v[132:135], v[214:217], v[12:15]
	v_mfma_f32_16x16x32_bf16 v[52:55], v[144:147], v[174:177], v[52:55]
	v_mfma_f32_16x16x32_bf16 v[48:51], v[166:169], v[174:177], v[48:51]
	v_mfma_f32_16x16x32_bf16 v[32:35], v[166:169], v[192:195], v[32:35]
	v_mfma_f32_16x16x32_bf16 v[36:39], v[144:147], v[192:195], v[36:39]
	v_mfma_f32_16x16x32_bf16 v[20:23], v[144:147], v[202:205], v[20:23]
	v_mfma_f32_16x16x32_bf16 v[16:19], v[166:169], v[202:205], v[16:19]
	v_mfma_f32_16x16x32_bf16 v[0:3], v[166:169], v[210:213], v[0:3]
	v_mfma_f32_16x16x32_bf16 v[4:7], v[144:147], v[210:213], v[4:7]
	v_mfma_f32_16x16x32_bf16 v[52:55], v[148:151], v[178:181], v[52:55]
	v_mfma_f32_16x16x32_bf16 v[48:51], v[170:173], v[178:181], v[48:51]
	v_mfma_f32_16x16x32_bf16 v[32:35], v[170:173], v[198:201], v[32:35]
	v_mfma_f32_16x16x32_bf16 v[36:39], v[148:151], v[198:201], v[36:39]
	v_mfma_f32_16x16x32_bf16 v[20:23], v[148:151], v[206:209], v[20:23]
	v_mfma_f32_16x16x32_bf16 v[16:19], v[170:173], v[206:209], v[16:19]
	v_mfma_f32_16x16x32_bf16 v[0:3], v[170:173], v[214:217], v[0:3]
	v_mfma_f32_16x16x32_bf16 v[4:7], v[148:151], v[214:217], v[4:7]
	s_barrier
	s_add_i32 s52, s52, 2
	s_add_u32 s50, s50, 0x100
	s_addc_u32 s51, s51, 0
	s_cmp_gt_u32 s52, 41
	s_mov_b64 s[2:3], s[8:9]
	s_cbranch_scc0 .LBB0_257
.LBB0_257:
	ds_read_b128 v[128:131], v187
	ds_read_b128 v[132:135], v187 offset:1024
	ds_read_b128 v[136:139], v187 offset:2048
	ds_read_b128 v[140:143], v187 offset:3072
	ds_read_b128 v[144:147], v188
	ds_read_b128 v[148:151], v188 offset:1024
	ds_read_b128 v[166:169], v188 offset:2048
	ds_read_b128 v[170:173], v188 offset:3072
	s_add_u32 s8, s2, 0x100
	s_addc_u32 s9, s3, 0
	s_cmp_eq_u32 s52, 40
	s_cselect_b32 s31, s1, s9
	s_cselect_b32 s30, s0, s8
	s_cselect_b32 s27, s25, s51
	s_cselect_b32 s26, s24, s50
	v_lshl_add_u64 v[182:183], s[2:3], 0, v[160:161]
	s_add_i32 m0, s35, 0xc000
	ds_read_b128 v[174:177], v190
	ds_read_b128 v[178:181], v190 offset:1024
	ds_read_b128 v[192:195], v190 offset:2048
	ds_read_b128 v[198:201], v190 offset:3072
	ds_read_b128 v[202:205], v190 offset:4096
	ds_read_b128 v[206:209], v190 offset:5120
	ds_read_b128 v[210:213], v190 offset:6144
	ds_read_b128 v[214:217], v190 offset:7168
	global_load_lds_dwordx4 v[182:183], off
	v_lshl_add_u64 v[182:183], s[2:3], 0, v[162:163]
	s_add_i32 m0, s35, 0xe000
	s_nop 0
	global_load_lds_dwordx4 v[182:183], off
	s_waitcnt vmcnt(8)
	s_waitcnt lgkmcnt(0)
	s_barrier
; #define PG8_STAGE(bufoff, gbase, voff) do { _Pragma("unroll") for (int _i = 0; _i < 2; ++_i) \
;         __builtin_amdgcn_global_load_lds((const unsigned*)((const char*)(gbase) + (voff)[_i]), (LAS unsigned*)(lds + (bufoff) + ldsw + _i * 8192), 16, 0, 0); } while (0)
; #define PG8_LDA(dst, b, h) do { _Pragma("unroll") for (int m = 0; m < 4; ++m) _Pragma("unroll") for (int k = 0; k < 2; ++k) dst[m][k] = *(const LAS bf16x8*)(lds + PG8_SA(b, h) + aoff + m * 2048 + k * 1024); } while (0)
; #define PG8_LDB(dst, b, h) do { _Pragma("unroll") for (int n = 0; n < 2; ++n) _Pragma("unroll") for (int k = 0; k < 2; ++k) dst[n][k] = *(const LAS bf16x8*)(lds + PG8_SB(b, h) + boff + n * 2048 + k * 1024); } while (0)
; #define PG8_MMA(ai, bj, At, Bt) do { __builtin_amdgcn_s_setprio(1); _Pragma("unroll") for (int m = 0; m < 4; ++m) _Pragma("unroll") for (int n = 0; n < 2; ++n) _Pragma("unroll") for (int k = 0; k < 2; ++k) \
;         acc[ai][bj][m][n] = __builtin_amdgcn_mfma_f32_16x16x32_bf16(Bt[n][k], At[m][k], acc[ai][bj][m][n], 0, 0, 0); __builtin_amdgcn_s_setprio(0); } while (0)
; #define PG8_WAIT_V(n) asm volatile("s_waitcnt vmcnt(" #n ")" ::: "memory")
; #define PG8_WAIT_L(n) asm volatile("s_waitcnt lgkmcnt(" #n ")" ::: "memory")
; #define PG8_BAR __builtin_amdgcn_s_barrier()
; #define PG8_SCHED __builtin_amdgcn_sched_barrier(0)
; template <class Epi>
; __device__ __forceinline__ void gemm_phase(LAS unsigned char* lds, const Gemm g, const StaticOrder& S, const Epi& E) {
;     ...
;             PG8_WAIT_V(8); PG8_WAIT_L(0); PG8_BAR; PG8_MMA(0, 0, At, B0); PG8_MMA(0, 1, At, B1); PG8_BAR; PG8_SCHED;
;             PG8_LDA(At, 0, 1); PG8_STAGE(PG8_SB(0, 0), b2, voffB); PG8_STAGE(PG8_SB(0, 1), b2 + hstepB, voffB); PG8_STAGE(PG8_SA(0, 0), a2, voffA);
;             PG8_WAIT_V(8); PG8_WAIT_L(0); PG8_BAR; PG8_MMA(1, 0, At, B0); PG8_MMA(1, 1, At, B1); PG8_BAR; PG8_SCHED;
;             PG8_LDB(B0, 1, 0); PG8_LDB(B1, 1, 1); PG8_SCHED; PG8_LDA(At, 1, 0); PG8_STAGE(PG8_SA(0, 1), a2 + hstepA, voffA);
	s_waitcnt lgkmcnt(0)
	v_mfma_f32_16x16x32_bf16 v[124:127], v[128:131], v[174:177], v[124:127]
	v_mfma_f32_16x16x32_bf16 v[120:123], v[136:139], v[174:177], v[120:123]
	v_mfma_f32_16x16x32_bf16 v[104:107], v[136:139], v[192:195], v[104:107]
	v_mfma_f32_16x16x32_bf16 v[108:111], v[128:131], v[192:195], v[108:111]
	v_mfma_f32_16x16x32_bf16 v[92:95], v[128:131], v[202:205], v[92:95]
	v_mfma_f32_16x16x32_bf16 v[88:91], v[136:139], v[202:205], v[88:91]
	v_mfma_f32_16x16x32_bf16 v[72:75], v[136:139], v[210:213], v[72:75]
	v_mfma_f32_16x16x32_bf16 v[76:79], v[128:131], v[210:213], v[76:79]
	v_mfma_f32_16x16x32_bf16 v[124:127], v[132:135], v[178:181], v[124:127]
	v_mfma_f32_16x16x32_bf16 v[120:123], v[140:143], v[178:181], v[120:123]
	v_mfma_f32_16x16x32_bf16 v[104:107], v[140:143], v[198:201], v[104:107]
	v_mfma_f32_16x16x32_bf16 v[108:111], v[132:135], v[198:201], v[108:111]
	v_mfma_f32_16x16x32_bf16 v[92:95], v[132:135], v[206:209], v[92:95]
	v_mfma_f32_16x16x32_bf16 v[88:91], v[140:143], v[206:209], v[88:91]
	v_mfma_f32_16x16x32_bf16 v[72:75], v[140:143], v[214:217], v[72:75]
	v_mfma_f32_16x16x32_bf16 v[76:79], v[132:135], v[214:217], v[76:79]
	v_mfma_f32_16x16x32_bf16 v[116:119], v[144:147], v[174:177], v[116:119]
	v_mfma_f32_16x16x32_bf16 v[112:115], v[166:169], v[174:177], v[112:115]
	v_mfma_f32_16x16x32_bf16 v[96:99], v[166:169], v[192:195], v[96:99]
	v_mfma_f32_16x16x32_bf16 v[100:103], v[144:147], v[192:195], v[100:103]
	v_mfma_f32_16x16x32_bf16 v[84:87], v[144:147], v[202:205], v[84:87]
	v_mfma_f32_16x16x32_bf16 v[80:83], v[166:169], v[202:205], v[80:83]
	v_mfma_f32_16x16x32_bf16 v[64:67], v[166:169], v[210:213], v[64:67]
	v_mfma_f32_16x16x32_bf16 v[68:71], v[144:147], v[210:213], v[68:71]
	v_mfma_f32_16x16x32_bf16 v[116:119], v[148:151], v[178:181], v[116:119]
	v_mfma_f32_16x16x32_bf16 v[112:115], v[170:173], v[178:181], v[112:115]
	v_mfma_f32_16x16x32_bf16 v[96:99], v[170:173], v[198:201], v[96:99]
	v_mfma_f32_16x16x32_bf16 v[100:103], v[148:151], v[198:201], v[100:103]
	v_mfma_f32_16x16x32_bf16 v[84:87], v[148:151], v[206:209], v[84:87]
	v_mfma_f32_16x16x32_bf16 v[80:83], v[170:173], v[206:209], v[80:83]
	v_mfma_f32_16x16x32_bf16 v[64:67], v[170:173], v[214:217], v[64:67]
	v_mfma_f32_16x16x32_bf16 v[68:71], v[148:151], v[214:217], v[68:71]
	s_barrier
	s_add_i32 s2, s45, s34
	v_lshl_add_u64 v[182:183], s[26:27], 0, v[154:155]
	s_mov_b32 m0, s2
	ds_read_b128 v[174:177], v190 offset:16384
	ds_read_b128 v[178:181], v190 offset:17408
	ds_read_b128 v[192:195], v190 offset:18432
	ds_read_b128 v[198:201], v190 offset:19456
	ds_read_b128 v[202:205], v190 offset:20480
	ds_read_b128 v[206:209], v190 offset:21504
	ds_read_b128 v[210:213], v190 offset:22528
	ds_read_b128 v[214:217], v190 offset:23552
	global_load_lds_dwordx4 v[182:183], off
	s_add_i32 m0, s2, 0x2000
	s_add_u32 s2, s26, 0xb0000
	v_lshl_add_u64 v[218:219], s[26:27], 0, v[158:159]
	s_addc_u32 s3, s27, 0
	s_add_i32 s53, s46, s34
	global_load_lds_dwordx4 v[218:219], off
	v_lshl_add_u64 v[220:221], s[2:3], 0, v[154:155]
	s_mov_b32 m0, s53
	v_lshl_add_u64 v[222:223], s[30:31], 0, v[156:157]
	global_load_lds_dwordx4 v[220:221], off
	v_lshl_add_u64 v[220:221], s[2:3], 0, v[158:159]
	s_add_i32 m0, s53, 0x2000
	s_nop 0
	global_load_lds_dwordx4 v[220:221], off
	v_lshl_add_u64 v[220:221], s[30:31], 0, v[152:153]
	s_mov_b32 m0, s35
	s_nop 0
	global_load_lds_dwordx4 v[220:221], off
	s_mov_b32 m0, s36
	s_nop 0
	global_load_lds_dwordx4 v[222:223], off
	s_waitcnt vmcnt(8)
	s_waitcnt lgkmcnt(0)
	s_barrier
	s_waitcnt lgkmcnt(0)
	v_mfma_f32_16x16x32_bf16 v[60:63], v[128:131], v[174:177], v[60:63]
	v_mfma_f32_16x16x32_bf16 v[56:59], v[136:139], v[174:177], v[56:59]
	v_mfma_f32_16x16x32_bf16 v[40:43], v[136:139], v[192:195], v[40:43]
	v_mfma_f32_16x16x32_bf16 v[44:47], v[128:131], v[192:195], v[44:47]
	v_mfma_f32_16x16x32_bf16 v[28:31], v[128:131], v[202:205], v[28:31]
	v_mfma_f32_16x16x32_bf16 v[24:27], v[136:139], v[202:205], v[24:27]
	v_mfma_f32_16x16x32_bf16 v[8:11], v[136:139], v[210:213], v[8:11]
	v_mfma_f32_16x16x32_bf16 v[12:15], v[128:131], v[210:213], v[12:15]
	v_mfma_f32_16x16x32_bf16 v[60:63], v[132:135], v[178:181], v[60:63]
	v_mfma_f32_16x16x32_bf16 v[56:59], v[140:143], v[178:181], v[56:59]
	v_mfma_f32_16x16x32_bf16 v[40:43], v[140:143], v[198:201], v[40:43]
	v_mfma_f32_16x16x32_bf16 v[44:47], v[132:135], v[198:201], v[44:47]
	v_mfma_f32_16x16x32_bf16 v[28:31], v[132:135], v[206:209], v[28:31]
	v_mfma_f32_16x16x32_bf16 v[24:27], v[140:143], v[206:209], v[24:27]
	v_mfma_f32_16x16x32_bf16 v[8:11], v[140:143], v[214:217], v[8:11]
	v_mfma_f32_16x16x32_bf16 v[12:15], v[132:135], v[214:217], v[12:15]
	v_mfma_f32_16x16x32_bf16 v[52:55], v[144:147], v[174:177], v[52:55]
	v_mfma_f32_16x16x32_bf16 v[48:51], v[166:169], v[174:177], v[48:51]
	v_mfma_f32_16x16x32_bf16 v[32:35], v[166:169], v[192:195], v[32:35]
	v_mfma_f32_16x16x32_bf16 v[36:39], v[144:147], v[192:195], v[36:39]
	v_mfma_f32_16x16x32_bf16 v[20:23], v[144:147], v[202:205], v[20:23]
	v_mfma_f32_16x16x32_bf16 v[16:19], v[166:169], v[202:205], v[16:19]
	v_mfma_f32_16x16x32_bf16 v[0:3], v[166:169], v[210:213], v[0:3]
	v_mfma_f32_16x16x32_bf16 v[4:7], v[144:147], v[210:213], v[4:7]
	v_mfma_f32_16x16x32_bf16 v[52:55], v[148:151], v[178:181], v[52:55]
	v_mfma_f32_16x16x32_bf16 v[48:51], v[170:173], v[178:181], v[48:51]
	v_mfma_f32_16x16x32_bf16 v[32:35], v[170:173], v[198:201], v[32:35]
	v_mfma_f32_16x16x32_bf16 v[36:39], v[148:151], v[198:201], v[36:39]
	v_mfma_f32_16x16x32_bf16 v[20:23], v[148:151], v[206:209], v[20:23]
	v_mfma_f32_16x16x32_bf16 v[16:19], v[170:173], v[206:209], v[16:19]
	v_mfma_f32_16x16x32_bf16 v[0:3], v[170:173], v[214:217], v[0:3]
	v_mfma_f32_16x16x32_bf16 v[4:7], v[148:151], v[214:217], v[4:7]
	s_barrier
; #define PG8_STAGE(bufoff, gbase, voff) do { _Pragma("unroll") for (int _i = 0; _i < 2; ++_i) \
;         __builtin_amdgcn_global_load_lds((const unsigned*)((const char*)(gbase) + (voff)[_i]), (LAS unsigned*)(lds + (bufoff) + ldsw + _i * 8192), 16, 0, 0); } while (0)
; #define PG8_LDA(dst, b, h) do { _Pragma("unroll") for (int m = 0; m < 4; ++m) _Pragma("unroll") for (int k = 0; k < 2; ++k) dst[m][k] = *(const LAS bf16x8*)(lds + PG8_SA(b, h) + aoff + m * 2048 + k * 1024); } while (0)
; #define PG8_LDB(dst, b, h) do { _Pragma("unroll") for (int n = 0; n < 2; ++n) _Pragma("unroll") for (int k = 0; k < 2; ++k) dst[n][k] = *(const LAS bf16x8*)(lds + PG8_SB(b, h) + boff + n * 2048 + k * 1024); } while (0)
; #define PG8_MMA(ai, bj, At, Bt) do { __builtin_amdgcn_s_setprio(1); _Pragma("unroll") for (int m = 0; m < 4; ++m) _Pragma("unroll") for (int n = 0; n < 2; ++n) _Pragma("unroll") for (int k = 0; k < 2; ++k) \
;         acc[ai][bj][m][n] = __builtin_amdgcn_mfma_f32_16x16x32_bf16(Bt[n][k], At[m][k], acc[ai][bj][m][n], 0, 0, 0); __builtin_amdgcn_s_setprio(0); } while (0)
; #define PG8_WAIT_V(n) asm volatile("s_waitcnt vmcnt(" #n ")" ::: "memory")
; #define PG8_WAIT_L(n) asm volatile("s_waitcnt lgkmcnt(" #n ")" ::: "memory")
; #define PG8_BAR __builtin_amdgcn_s_barrier()
; #define PG8_SCHED __builtin_amdgcn_sched_barrier(0)
; template <class Epi>
; __device__ __forceinline__ void gemm_phase(LAS unsigned char* lds, const Gemm g, const StaticOrder& S, const Epi& E) {
;     ...
;             PG8_LDB(B0, 1, 0); PG8_LDB(B1, 1, 1); PG8_SCHED; PG8_LDA(At, 1, 0); PG8_STAGE(PG8_SA(0, 1), a2 + hstepA, voffA);
;             PG8_WAIT_V(8); PG8_WAIT_L(0); PG8_BAR; PG8_MMA(0, 0, At, B0); PG8_MMA(0, 1, At, B1); PG8_BAR; PG8_SCHED;
	s_add_i32 s53, 0, 0x18000
	s_add_i32 s54, 0, 0x1c000
	v_add_u32_e32 v140, s53, v185
	v_add_u32_e32 v170, s54, v185
	ds_read_b128 v[128:131], v140
	ds_read_b128 v[132:135], v140 offset:1024
	ds_read_b128 v[136:139], v140 offset:2048
	ds_read_b128 v[140:143], v140 offset:3072
	ds_read_b128 v[144:147], v170
	ds_read_b128 v[148:151], v170 offset:1024
	ds_read_b128 v[166:169], v170 offset:2048
	ds_read_b128 v[170:173], v170 offset:3072
	s_add_u32 s2, s30, 0xb4000
	s_addc_u32 s3, s31, 0
	s_mov_b32 m0, s37
	v_lshl_add_u64 v[224:225], s[2:3], 0, v[152:153]
	ds_read_b128 v[174:177], v190 offset:32768
	ds_read_b128 v[178:181], v190 offset:33792
	ds_read_b128 v[192:195], v190 offset:34816
	ds_read_b128 v[198:201], v190 offset:35840
	ds_read_b128 v[202:205], v190 offset:36864
	ds_read_b128 v[206:209], v190 offset:37888
	ds_read_b128 v[210:213], v190 offset:38912
	ds_read_b128 v[214:217], v190 offset:39936
	global_load_lds_dwordx4 v[224:225], off
	v_lshl_add_u64 v[224:225], s[2:3], 0, v[156:157]
	s_mov_b32 m0, s38
	s_nop 0
	global_load_lds_dwordx4 v[224:225], off
	s_waitcnt vmcnt(8)
	s_waitcnt lgkmcnt(0)
	s_barrier
	s_waitcnt lgkmcnt(0)
	v_mfma_f32_16x16x32_bf16 v[124:127], v[128:131], v[174:177], v[124:127]
	v_mfma_f32_16x16x32_bf16 v[120:123], v[136:139], v[174:177], v[120:123]
	v_mfma_f32_16x16x32_bf16 v[104:107], v[136:139], v[192:195], v[104:107]
	v_mfma_f32_16x16x32_bf16 v[108:111], v[128:131], v[192:195], v[108:111]
	v_mfma_f32_16x16x32_bf16 v[92:95], v[128:131], v[202:205], v[92:95]
	v_mfma_f32_16x16x32_bf16 v[88:91], v[136:139], v[202:205], v[88:91]
	v_mfma_f32_16x16x32_bf16 v[72:75], v[136:139], v[210:213], v[72:75]
	v_mfma_f32_16x16x32_bf16 v[76:79], v[128:131], v[210:213], v[76:79]
	v_mfma_f32_16x16x32_bf16 v[124:127], v[132:135], v[178:181], v[124:127]
	v_mfma_f32_16x16x32_bf16 v[120:123], v[140:143], v[178:181], v[120:123]
	v_mfma_f32_16x16x32_bf16 v[104:107], v[140:143], v[198:201], v[104:107]
	v_mfma_f32_16x16x32_bf16 v[108:111], v[132:135], v[198:201], v[108:111]
	v_mfma_f32_16x16x32_bf16 v[92:95], v[132:135], v[206:209], v[92:95]
	v_mfma_f32_16x16x32_bf16 v[88:91], v[140:143], v[206:209], v[88:91]
	v_mfma_f32_16x16x32_bf16 v[72:75], v[140:143], v[214:217], v[72:75]
	v_mfma_f32_16x16x32_bf16 v[76:79], v[132:135], v[214:217], v[76:79]
	v_mfma_f32_16x16x32_bf16 v[116:119], v[144:147], v[174:177], v[116:119]
	v_mfma_f32_16x16x32_bf16 v[112:115], v[166:169], v[174:177], v[112:115]
	v_mfma_f32_16x16x32_bf16 v[96:99], v[166:169], v[192:195], v[96:99]
	v_mfma_f32_16x16x32_bf16 v[100:103], v[144:147], v[192:195], v[100:103]
	v_mfma_f32_16x16x32_bf16 v[84:87], v[144:147], v[202:205], v[84:87]
	v_mfma_f32_16x16x32_bf16 v[80:83], v[166:169], v[202:205], v[80:83]
	v_mfma_f32_16x16x32_bf16 v[64:67], v[166:169], v[210:213], v[64:67]
	v_mfma_f32_16x16x32_bf16 v[68:71], v[144:147], v[210:213], v[68:71]
	v_mfma_f32_16x16x32_bf16 v[116:119], v[148:151], v[178:181], v[116:119]
	v_mfma_f32_16x16x32_bf16 v[112:115], v[170:173], v[178:181], v[112:115]
	v_mfma_f32_16x16x32_bf16 v[96:99], v[170:173], v[198:201], v[96:99]
	v_mfma_f32_16x16x32_bf16 v[100:103], v[148:151], v[198:201], v[100:103]
	v_mfma_f32_16x16x32_bf16 v[84:87], v[148:151], v[206:209], v[84:87]
	v_mfma_f32_16x16x32_bf16 v[80:83], v[170:173], v[206:209], v[80:83]
	v_mfma_f32_16x16x32_bf16 v[64:67], v[170:173], v[214:217], v[64:67]
	v_mfma_f32_16x16x32_bf16 v[68:71], v[148:151], v[214:217], v[68:71]
	s_barrier
; #define PG8_STAGE(bufoff, gbase, voff) do { _Pragma("unroll") for (int _i = 0; _i < 2; ++_i) \
;         __builtin_amdgcn_global_load_lds((const unsigned*)((const char*)(gbase) + (voff)[_i]), (LAS unsigned*)(lds + (bufoff) + ldsw + _i * 8192), 16, 0, 0); } while (0)
; #define PG8_LDA(dst, b, h) do { _Pragma("unroll") for (int m = 0; m < 4; ++m) _Pragma("unroll") for (int k = 0; k < 2; ++k) dst[m][k] = *(const LAS bf16x8*)(lds + PG8_SA(b, h) + aoff + m * 2048 + k * 1024); } while (0)
; #define PG8_MMA(ai, bj, At, Bt) do { __builtin_amdgcn_s_setprio(1); _Pragma("unroll") for (int m = 0; m < 4; ++m) _Pragma("unroll") for (int n = 0; n < 2; ++n) _Pragma("unroll") for (int k = 0; k < 2; ++k) \
;         acc[ai][bj][m][n] = __builtin_amdgcn_mfma_f32_16x16x32_bf16(Bt[n][k], At[m][k], acc[ai][bj][m][n], 0, 0, 0); __builtin_amdgcn_s_setprio(0); } while (0)
; #define PG8_WAIT_V(n) asm volatile("s_waitcnt vmcnt(" #n ")" ::: "memory")
; #define PG8_WAIT_L(n) asm volatile("s_waitcnt lgkmcnt(" #n ")" ::: "memory")
; #define PG8_BAR __builtin_amdgcn_s_barrier()
; #define PG8_SCHED __builtin_amdgcn_sched_barrier(0)
; template <class Epi>
; __device__ __forceinline__ void gemm_phase(LAS unsigned char* lds, const Gemm g, const StaticOrder& S, const Epi& E) {
;     ...
;             PG8_LDA(At, 1, 1); PG8_STAGE(PG8_SB(1, 0), b3, voffB); PG8_STAGE(PG8_SB(1, 1), b3 + hstepB, voffB); PG8_STAGE(PG8_SA(1, 0), a3, voffA);
;             PG8_WAIT_V(8); PG8_WAIT_L(0); PG8_BAR; PG8_MMA(1, 0, At, B0); PG8_MMA(1, 1, At, B1); PG8_BAR; PG8_SCHED;
;         }
;         if (wr == 0) PG8_BAR;
	s_add_i32 s2, s53, s34
	v_lshl_add_u64 v[182:183], v[182:183], 0, s[20:21]
	s_mov_b32 m0, s2
	ds_read_b128 v[174:177], v190 offset:49152
	ds_read_b128 v[178:181], v190 offset:50176
	ds_read_b128 v[192:195], v190 offset:51200
	ds_read_b128 v[198:201], v190 offset:52224
	ds_read_b128 v[202:205], v190 offset:53248
	ds_read_b128 v[206:209], v190 offset:54272
	ds_read_b128 v[210:213], v190 offset:55296
	ds_read_b128 v[214:217], v190 offset:56320
	global_load_lds_dwordx4 v[182:183], off
	s_add_i32 m0, s2, 0x2000
	s_add_u32 s2, s26, 0xb0080
	v_lshl_add_u64 v[182:183], v[218:219], 0, s[20:21]
	s_addc_u32 s3, s27, 0
	s_add_i32 s26, s54, s34
	global_load_lds_dwordx4 v[182:183], off
	v_lshl_add_u64 v[182:183], s[2:3], 0, v[154:155]
	s_mov_b32 m0, s26
	s_nop 0
	global_load_lds_dwordx4 v[182:183], off
	v_lshl_add_u64 v[182:183], s[2:3], 0, v[158:159]
	s_add_i32 m0, s26, 0x2000
	s_nop 0
	global_load_lds_dwordx4 v[182:183], off
	v_lshl_add_u64 v[182:183], v[220:221], 0, s[20:21]
	s_mov_b32 m0, s40
	s_nop 0
	global_load_lds_dwordx4 v[182:183], off
	v_lshl_add_u64 v[182:183], v[222:223], 0, s[20:21]
	s_mov_b32 m0, s41
	s_nop 0
	global_load_lds_dwordx4 v[182:183], off
	s_waitcnt vmcnt(8)
	s_waitcnt lgkmcnt(0)
	s_barrier
	s_waitcnt lgkmcnt(0)
	v_mfma_f32_16x16x32_bf16 v[60:63], v[128:131], v[174:177], v[60:63]
	v_mfma_f32_16x16x32_bf16 v[56:59], v[136:139], v[174:177], v[56:59]
	v_mfma_f32_16x16x32_bf16 v[40:43], v[136:139], v[192:195], v[40:43]
	v_mfma_f32_16x16x32_bf16 v[44:47], v[128:131], v[192:195], v[44:47]
	v_mfma_f32_16x16x32_bf16 v[28:31], v[128:131], v[202:205], v[28:31]
	v_mfma_f32_16x16x32_bf16 v[24:27], v[136:139], v[202:205], v[24:27]
	v_mfma_f32_16x16x32_bf16 v[8:11], v[136:139], v[210:213], v[8:11]
	v_mfma_f32_16x16x32_bf16 v[12:15], v[128:131], v[210:213], v[12:15]
	v_mfma_f32_16x16x32_bf16 v[60:63], v[132:135], v[178:181], v[60:63]
	v_mfma_f32_16x16x32_bf16 v[56:59], v[140:143], v[178:181], v[56:59]
	v_mfma_f32_16x16x32_bf16 v[40:43], v[140:143], v[198:201], v[40:43]
	v_mfma_f32_16x16x32_bf16 v[44:47], v[132:135], v[198:201], v[44:47]
	v_mfma_f32_16x16x32_bf16 v[28:31], v[132:135], v[206:209], v[28:31]
	v_mfma_f32_16x16x32_bf16 v[24:27], v[140:143], v[206:209], v[24:27]
	v_mfma_f32_16x16x32_bf16 v[8:11], v[140:143], v[214:217], v[8:11]
	v_mfma_f32_16x16x32_bf16 v[12:15], v[132:135], v[214:217], v[12:15]
	v_mfma_f32_16x16x32_bf16 v[52:55], v[144:147], v[174:177], v[52:55]
	v_mfma_f32_16x16x32_bf16 v[48:51], v[166:169], v[174:177], v[48:51]
	v_mfma_f32_16x16x32_bf16 v[32:35], v[166:169], v[192:195], v[32:35]
	v_mfma_f32_16x16x32_bf16 v[36:39], v[144:147], v[192:195], v[36:39]
	v_mfma_f32_16x16x32_bf16 v[20:23], v[144:147], v[202:205], v[20:23]
	v_mfma_f32_16x16x32_bf16 v[16:19], v[166:169], v[202:205], v[16:19]
	v_mfma_f32_16x16x32_bf16 v[0:3], v[166:169], v[210:213], v[0:3]
	v_mfma_f32_16x16x32_bf16 v[4:7], v[144:147], v[210:213], v[4:7]
	v_mfma_f32_16x16x32_bf16 v[52:55], v[148:151], v[178:181], v[52:55]
	v_mfma_f32_16x16x32_bf16 v[48:51], v[170:173], v[178:181], v[48:51]
	v_mfma_f32_16x16x32_bf16 v[32:35], v[170:173], v[198:201], v[32:35]
	v_mfma_f32_16x16x32_bf16 v[36:39], v[148:151], v[198:201], v[36:39]
	v_mfma_f32_16x16x32_bf16 v[20:23], v[148:151], v[206:209], v[20:23]
	v_mfma_f32_16x16x32_bf16 v[16:19], v[170:173], v[206:209], v[16:19]
	v_mfma_f32_16x16x32_bf16 v[0:3], v[170:173], v[214:217], v[0:3]
	v_mfma_f32_16x16x32_bf16 v[4:7], v[148:151], v[214:217], v[4:7]
	s_barrier
	s_add_i32 s52, s52, 2
	s_add_u32 s50, s50, 0x100
	s_addc_u32 s51, s51, 0
	s_cmp_gt_u32 s52, 41
	s_mov_b64 s[2:3], s[8:9]
	s_cbranch_scc0 .LBB0_257
	s_and_b64 vcc, exec, s[22:23]
	s_cbranch_vccz .LBB0_260
	s_barrier

; #define PG8_STAGE(bufoff, gbase, voff) do { _Pragma("unroll") for (int _i = 0; _i < 2; ++_i) \
;         __builtin_amdgcn_global_load_lds((const unsigned*)((const char*)(gbase) + (voff)[_i]), (LAS unsigned*)(lds + (bufoff) + ldsw + _i * 8192), 16, 0, 0); } while (0)
; #define PG8_LDA(dst, b, h) do { _Pragma("unroll") for (int m = 0; m < 4; ++m) _Pragma("unroll") for (int k = 0; k < 2; ++k) dst[m][k] = *(const LAS bf16x8*)(lds + PG8_SA(b, h) + aoff + m * 2048 + k * 1024); } while (0)
; #define PG8_LDB(dst, b, h) do { _Pragma("unroll") for (int n = 0; n < 2; ++n) _Pragma("unroll") for (int k = 0; k < 2; ++k) dst[n][k] = *(const LAS bf16x8*)(lds + PG8_SB(b, h) + boff + n * 2048 + k * 1024); } while (0)
; #define PG8_MMA(ai, bj, At, Bt) do { __builtin_amdgcn_s_setprio(1); _Pragma("unroll") for (int m = 0; m < 4; ++m) _Pragma("unroll") for (int n = 0; n < 2; ++n) _Pragma("unroll") for (int k = 0; k < 2; ++k) \
;         acc[ai][bj][m][n] = __builtin_amdgcn_mfma_f32_16x16x32_bf16(Bt[n][k], At[m][k], acc[ai][bj][m][n], 0, 0, 0); __builtin_amdgcn_s_setprio(0); } while (0)
; #define PG8_WAIT_V(n) asm volatile("s_waitcnt vmcnt(" #n ")" ::: "memory")
; #define PG8_WAIT_L(n) asm volatile("s_waitcnt lgkmcnt(" #n ")" ::: "memory")
; #define PG8_BAR __builtin_amdgcn_s_barrier()
; #define PG8_SCHED __builtin_amdgcn_sched_barrier(0)
; template <class Epi>
; __device__ __forceinline__ void gemm_phase(LAS unsigned char* lds, const Gemm g, const StaticOrder& S, const Epi& E) {
;     ...
;         const char* nA = has_next ? (const char*)g.A + (size_t)(nxt.pm >> 5) * aslab + (size_t)(nxt.pm & 31) * tstepA : cA; const char* nB = has_next ? (const char*)g.Bt + (size_t)nxt.pn * tstepB : cB;
;         for (int t = 0; t < nt; t += 2) {
;             const bool last = (t == nt - 2);
;             const char* a1 = cA + (size_t)(t + 1) * kstep;
;             const char* a2 = last ? nA : cA + (size_t)(t + 2) * kstep; const char* b2 = last ? nB : cB + (size_t)(t + 2) * kstep;
;             const char* a3 = a2 + kstep; const char* b3 = b2 + kstep;
;             PG8_LDB(B0, 0, 0); PG8_LDB(B1, 0, 1); PG8_SCHED; PG8_LDA(At, 0, 0); PG8_STAGE(PG8_SA(1, 1), a1 + hstepA, voffA);
;             PG8_WAIT_V(8); PG8_WAIT_L(0); PG8_BAR; PG8_MMA(0, 0, At, B0); PG8_MMA(0, 1, At, B1); PG8_BAR; PG8_SCHED;
.LBB0_378:
	s_ashr_i32 s18, s42, 5
	s_ashr_i32 s19, s18, 31
	s_lshl_b64 s[18:19], s[18:19], 24
	v_readlane_b32 s20, v235, 38
	v_readlane_b32 s21, v235, 39
	s_add_u32 s17, s20, s18
	s_addc_u32 s19, s21, s19
	s_lshl_b32 s18, s42, 19
	s_and_b32 s18, s18, 0xf80000
	s_add_u32 s18, s17, s18
	s_addc_u32 s19, s19, 0
	s_and_b64 s[20:21], s[4:5], exec
	s_cselect_b32 s44, s19, s23
	s_cselect_b32 s45, s18, s22
	s_ashr_i32 s17, s16, 31
	s_lshl_b64 s[20:21], s[16:17], 19
	s_add_u32 s20, s10, s20
	s_addc_u32 s21, s11, s21
	s_and_b64 s[24:25], s[4:5], exec
	s_cselect_b32 s17, s21, s3
	s_cselect_b32 s46, s20, s2
	s_add_u32 s22, s22, 0x40080
	s_addc_u32 s23, s23, 0
	s_add_u32 s47, s2, 0x100
	s_addc_u32 s48, s3, 0
	s_mov_b32 s49, -2
	ds_read_b128 v[128:131], v198
	ds_read_b128 v[132:135], v198 offset:1024
	ds_read_b128 v[136:139], v198 offset:2048
	ds_read_b128 v[140:143], v198 offset:3072
	ds_read_b128 v[144:147], v199
	ds_read_b128 v[148:151], v199 offset:1024
	ds_read_b128 v[170:173], v199 offset:2048
	ds_read_b128 v[174:177], v199 offset:3072
	s_add_u32 s2, s22, 0xfffc0080
	s_addc_u32 s3, s23, -1
	s_cmp_eq_u32 s49, 12
	s_cselect_b32 s25, s44, s3
	s_cselect_b32 s24, s45, s2
	s_cselect_b32 s3, s17, s48
	s_cselect_b32 s2, s46, s47
	v_lshl_add_u64 v[186:187], s[22:23], 0, v[164:165]
	s_add_i32 m0, s28, 0xc000
	ds_read_b128 v[178:181], v200
	ds_read_b128 v[182:185], v200 offset:1024
	ds_read_b128 v[204:207], v200 offset:2048
	ds_read_b128 v[208:211], v200 offset:3072
	ds_read_b128 v[212:215], v200 offset:4096
	ds_read_b128 v[216:219], v200 offset:5120
	ds_read_b128 v[220:223], v200 offset:6144
	ds_read_b128 v[224:227], v200 offset:7168
	global_load_lds_dwordx4 v[186:187], off
	v_lshl_add_u64 v[186:187], s[22:23], 0, v[166:167]
	s_add_i32 m0, s28, 0xe000
	s_nop 0
	global_load_lds_dwordx4 v[186:187], off
	s_waitcnt vmcnt(8)
	s_waitcnt lgkmcnt(0)
	s_barrier
	s_waitcnt lgkmcnt(0)
	v_mfma_f32_16x16x32_bf16 v[124:127], v[128:131], v[178:181], 0
	v_mfma_f32_16x16x32_bf16 v[120:123], v[136:139], v[178:181], 0
	v_mfma_f32_16x16x32_bf16 v[104:107], v[136:139], v[204:207], 0
	v_mfma_f32_16x16x32_bf16 v[108:111], v[128:131], v[204:207], 0
	v_mfma_f32_16x16x32_bf16 v[92:95], v[128:131], v[212:215], 0
	v_mfma_f32_16x16x32_bf16 v[88:91], v[136:139], v[212:215], 0
	v_mfma_f32_16x16x32_bf16 v[72:75], v[136:139], v[220:223], 0
	v_mfma_f32_16x16x32_bf16 v[76:79], v[128:131], v[220:223], 0
	v_mfma_f32_16x16x32_bf16 v[124:127], v[132:135], v[182:185], v[124:127]
	v_mfma_f32_16x16x32_bf16 v[120:123], v[140:143], v[182:185], v[120:123]
	v_mfma_f32_16x16x32_bf16 v[104:107], v[140:143], v[208:211], v[104:107]
	v_mfma_f32_16x16x32_bf16 v[108:111], v[132:135], v[208:211], v[108:111]
	v_mfma_f32_16x16x32_bf16 v[92:95], v[132:135], v[216:219], v[92:95]
	v_mfma_f32_16x16x32_bf16 v[88:91], v[140:143], v[216:219], v[88:91]
	v_mfma_f32_16x16x32_bf16 v[72:75], v[140:143], v[224:227], v[72:75]
	v_mfma_f32_16x16x32_bf16 v[76:79], v[132:135], v[224:227], v[76:79]
	v_mfma_f32_16x16x32_bf16 v[116:119], v[144:147], v[178:181], 0
	v_mfma_f32_16x16x32_bf16 v[112:115], v[170:173], v[178:181], 0
	v_mfma_f32_16x16x32_bf16 v[96:99], v[170:173], v[204:207], 0
	v_mfma_f32_16x16x32_bf16 v[100:103], v[144:147], v[204:207], 0
	v_mfma_f32_16x16x32_bf16 v[84:87], v[144:147], v[212:215], 0
	v_mfma_f32_16x16x32_bf16 v[80:83], v[170:173], v[212:215], 0
	v_mfma_f32_16x16x32_bf16 v[64:67], v[170:173], v[220:223], 0
	v_mfma_f32_16x16x32_bf16 v[68:71], v[144:147], v[220:223], 0
	v_mfma_f32_16x16x32_bf16 v[116:119], v[148:151], v[182:185], v[116:119]
	v_mfma_f32_16x16x32_bf16 v[112:115], v[174:177], v[182:185], v[112:115]
	v_mfma_f32_16x16x32_bf16 v[96:99], v[174:177], v[208:211], v[96:99]
	v_mfma_f32_16x16x32_bf16 v[100:103], v[148:151], v[208:211], v[100:103]
	v_mfma_f32_16x16x32_bf16 v[84:87], v[148:151], v[216:219], v[84:87]
	v_mfma_f32_16x16x32_bf16 v[80:83], v[174:177], v[216:219], v[80:83]
	v_mfma_f32_16x16x32_bf16 v[64:67], v[174:177], v[224:227], v[64:67]
	v_mfma_f32_16x16x32_bf16 v[68:71], v[148:151], v[224:227], v[68:71]
	s_barrier
	s_add_i32 s50, s39, s26
	v_lshl_add_u64 v[186:187], s[2:3], 0, v[156:157]
	s_mov_b32 m0, s50
	ds_read_b128 v[178:181], v200 offset:16384
	ds_read_b128 v[182:185], v200 offset:17408
	ds_read_b128 v[204:207], v200 offset:18432
	ds_read_b128 v[208:211], v200 offset:19456
	ds_read_b128 v[212:215], v200 offset:20480
	ds_read_b128 v[216:219], v200 offset:21504
	ds_read_b128 v[220:223], v200 offset:22528
	ds_read_b128 v[224:227], v200 offset:23552
	global_load_lds_dwordx4 v[186:187], off
	s_add_i32 m0, s50, 0x2000
	s_add_u32 s50, s2, 0x40000
	v_lshl_add_u64 v[190:191], s[2:3], 0, v[152:153]
	s_addc_u32 s51, s3, 0
	s_add_i32 s52, s40, s26
	global_load_lds_dwordx4 v[190:191], off
	v_lshl_add_u64 v[228:229], s[50:51], 0, v[156:157]
	s_mov_b32 m0, s52
	v_lshl_add_u64 v[230:231], s[24:25], 0, v[154:155]
	global_load_lds_dwordx4 v[228:229], off
	v_lshl_add_u64 v[228:229], s[50:51], 0, v[152:153]
	s_add_i32 m0, s52, 0x2000
	s_nop 0
	global_load_lds_dwordx4 v[228:229], off
	v_lshl_add_u64 v[228:229], s[24:25], 0, v[158:159]
	s_mov_b32 m0, s28
	s_nop 0
	global_load_lds_dwordx4 v[228:229], off
	s_mov_b32 m0, s29
	s_nop 0
	global_load_lds_dwordx4 v[230:231], off
	s_waitcnt vmcnt(8)
	s_waitcnt lgkmcnt(0)
	s_barrier
; #define PG8_STAGE(bufoff, gbase, voff) do { _Pragma("unroll") for (int _i = 0; _i < 2; ++_i) \
;         __builtin_amdgcn_global_load_lds((const unsigned*)((const char*)(gbase) + (voff)[_i]), (LAS unsigned*)(lds + (bufoff) + ldsw + _i * 8192), 16, 0, 0); } while (0)
; #define PG8_LDA(dst, b, h) do { _Pragma("unroll") for (int m = 0; m < 4; ++m) _Pragma("unroll") for (int k = 0; k < 2; ++k) dst[m][k] = *(const LAS bf16x8*)(lds + PG8_SA(b, h) + aoff + m * 2048 + k * 1024); } while (0)
; #define PG8_LDB(dst, b, h) do { _Pragma("unroll") for (int n = 0; n < 2; ++n) _Pragma("unroll") for (int k = 0; k < 2; ++k) dst[n][k] = *(const LAS bf16x8*)(lds + PG8_SB(b, h) + boff + n * 2048 + k * 1024); } while (0)
; #define PG8_MMA(ai, bj, At, Bt) do { __builtin_amdgcn_s_setprio(1); _Pragma("unroll") for (int m = 0; m < 4; ++m) _Pragma("unroll") for (int n = 0; n < 2; ++n) _Pragma("unroll") for (int k = 0; k < 2; ++k) \
;         acc[ai][bj][m][n] = __builtin_amdgcn_mfma_f32_16x16x32_bf16(Bt[n][k], At[m][k], acc[ai][bj][m][n], 0, 0, 0); __builtin_amdgcn_s_setprio(0); } while (0)
; #define PG8_WAIT_V(n) asm volatile("s_waitcnt vmcnt(" #n ")" ::: "memory")
; #define PG8_WAIT_L(n) asm volatile("s_waitcnt lgkmcnt(" #n ")" ::: "memory")
; #define PG8_BAR __builtin_amdgcn_s_barrier()
; #define PG8_SCHED __builtin_amdgcn_sched_barrier(0)
; template <class Epi>
; __device__ __forceinline__ void gemm_phase(LAS unsigned char* lds, const Gemm g, const StaticOrder& S, const Epi& E) {
;     ...
;             PG8_WAIT_V(8); PG8_WAIT_L(0); PG8_BAR; PG8_MMA(0, 0, At, B0); PG8_MMA(0, 1, At, B1); PG8_BAR; PG8_SCHED;
;             PG8_LDA(At, 0, 1); PG8_STAGE(PG8_SB(0, 0), b2, voffB); PG8_STAGE(PG8_SB(0, 1), b2 + hstepB, voffB); PG8_STAGE(PG8_SA(0, 0), a2, voffA);
;             PG8_WAIT_V(8); PG8_WAIT_L(0); PG8_BAR; PG8_MMA(1, 0, At, B0); PG8_MMA(1, 1, At, B1); PG8_BAR; PG8_SCHED;
;             PG8_LDB(B0, 1, 0); PG8_LDB(B1, 1, 1); PG8_SCHED; PG8_LDA(At, 1, 0); PG8_STAGE(PG8_SA(0, 1), a2 + hstepA, voffA);
;             PG8_WAIT_V(8); PG8_WAIT_L(0); PG8_BAR; PG8_MMA(0, 0, At, B0); PG8_MMA(0, 1, At, B1); PG8_BAR; PG8_SCHED;
	s_waitcnt lgkmcnt(0)
	v_mfma_f32_16x16x32_bf16 v[60:63], v[128:131], v[178:181], 0
	v_mfma_f32_16x16x32_bf16 v[56:59], v[136:139], v[178:181], 0
	v_mfma_f32_16x16x32_bf16 v[40:43], v[136:139], v[204:207], 0
	v_mfma_f32_16x16x32_bf16 v[44:47], v[128:131], v[204:207], 0
	v_mfma_f32_16x16x32_bf16 v[28:31], v[128:131], v[212:215], 0
	v_mfma_f32_16x16x32_bf16 v[24:27], v[136:139], v[212:215], 0
	v_mfma_f32_16x16x32_bf16 v[8:11], v[136:139], v[220:223], 0
	v_mfma_f32_16x16x32_bf16 v[12:15], v[128:131], v[220:223], 0
	v_mfma_f32_16x16x32_bf16 v[60:63], v[132:135], v[182:185], v[60:63]
	v_mfma_f32_16x16x32_bf16 v[56:59], v[140:143], v[182:185], v[56:59]
	v_mfma_f32_16x16x32_bf16 v[40:43], v[140:143], v[208:211], v[40:43]
	v_mfma_f32_16x16x32_bf16 v[44:47], v[132:135], v[208:211], v[44:47]
	v_mfma_f32_16x16x32_bf16 v[28:31], v[132:135], v[216:219], v[28:31]
	v_mfma_f32_16x16x32_bf16 v[24:27], v[140:143], v[216:219], v[24:27]
	v_mfma_f32_16x16x32_bf16 v[8:11], v[140:143], v[224:227], v[8:11]
	v_mfma_f32_16x16x32_bf16 v[12:15], v[132:135], v[224:227], v[12:15]
	v_mfma_f32_16x16x32_bf16 v[52:55], v[144:147], v[178:181], 0
	v_mfma_f32_16x16x32_bf16 v[48:51], v[170:173], v[178:181], 0
	v_mfma_f32_16x16x32_bf16 v[32:35], v[170:173], v[204:207], 0
	v_mfma_f32_16x16x32_bf16 v[36:39], v[144:147], v[204:207], 0
	v_mfma_f32_16x16x32_bf16 v[20:23], v[144:147], v[212:215], 0
	v_mfma_f32_16x16x32_bf16 v[16:19], v[170:173], v[212:215], 0
	v_mfma_f32_16x16x32_bf16 v[0:3], v[170:173], v[220:223], 0
	v_mfma_f32_16x16x32_bf16 v[4:7], v[144:147], v[220:223], 0
	v_mfma_f32_16x16x32_bf16 v[52:55], v[148:151], v[182:185], v[52:55]
	v_mfma_f32_16x16x32_bf16 v[48:51], v[174:177], v[182:185], v[48:51]
	v_mfma_f32_16x16x32_bf16 v[32:35], v[174:177], v[208:211], v[32:35]
	v_mfma_f32_16x16x32_bf16 v[36:39], v[148:151], v[208:211], v[36:39]
	v_mfma_f32_16x16x32_bf16 v[20:23], v[148:151], v[216:219], v[20:23]
	v_mfma_f32_16x16x32_bf16 v[16:19], v[174:177], v[216:219], v[16:19]
	v_mfma_f32_16x16x32_bf16 v[0:3], v[174:177], v[224:227], v[0:3]
	v_mfma_f32_16x16x32_bf16 v[4:7], v[148:151], v[224:227], v[4:7]
	s_barrier
	s_add_i32 s50, 0, 0x18000
	s_add_i32 s51, 0, 0x1c000
	v_add_u32_e32 v140, s50, v195
	v_add_u32_e32 v160, s51, v195
	ds_read_b128 v[128:131], v140
	ds_read_b128 v[132:135], v140 offset:1024
	ds_read_b128 v[136:139], v140 offset:2048
	ds_read_b128 v[140:143], v140 offset:3072
	ds_read_b128 v[144:147], v160
	ds_read_b128 v[148:151], v160 offset:1024
	ds_read_b128 v[170:173], v160 offset:2048
	ds_read_b128 v[174:177], v160 offset:3072
	s_add_u32 s24, s24, 0x40000
	s_addc_u32 s25, s25, 0
	s_mov_b32 m0, s30
	v_lshl_add_u64 v[232:233], s[24:25], 0, v[158:159]
	ds_read_b128 v[178:181], v200 offset:32768
	ds_read_b128 v[182:185], v200 offset:33792
	ds_read_b128 v[204:207], v200 offset:34816
	ds_read_b128 v[208:211], v200 offset:35840
	ds_read_b128 v[212:215], v200 offset:36864
	ds_read_b128 v[216:219], v200 offset:37888
	ds_read_b128 v[220:223], v200 offset:38912
	ds_read_b128 v[224:227], v200 offset:39936
	global_load_lds_dwordx4 v[232:233], off
	v_lshl_add_u64 v[232:233], s[24:25], 0, v[154:155]
	s_mov_b32 m0, s31
	s_nop 0
	global_load_lds_dwordx4 v[232:233], off
	s_waitcnt vmcnt(8)
	s_waitcnt lgkmcnt(0)
	s_barrier
	s_waitcnt lgkmcnt(0)
	v_mfma_f32_16x16x32_bf16 v[124:127], v[128:131], v[178:181], v[124:127]
	v_mfma_f32_16x16x32_bf16 v[120:123], v[136:139], v[178:181], v[120:123]
	v_mfma_f32_16x16x32_bf16 v[104:107], v[136:139], v[204:207], v[104:107]
	v_mfma_f32_16x16x32_bf16 v[108:111], v[128:131], v[204:207], v[108:111]
	v_mfma_f32_16x16x32_bf16 v[92:95], v[128:131], v[212:215], v[92:95]
	v_mfma_f32_16x16x32_bf16 v[88:91], v[136:139], v[212:215], v[88:91]
	v_mfma_f32_16x16x32_bf16 v[72:75], v[136:139], v[220:223], v[72:75]
	v_mfma_f32_16x16x32_bf16 v[76:79], v[128:131], v[220:223], v[76:79]
	v_mfma_f32_16x16x32_bf16 v[124:127], v[132:135], v[182:185], v[124:127]
	v_mfma_f32_16x16x32_bf16 v[120:123], v[140:143], v[182:185], v[120:123]
	v_mfma_f32_16x16x32_bf16 v[104:107], v[140:143], v[208:211], v[104:107]
	v_mfma_f32_16x16x32_bf16 v[108:111], v[132:135], v[208:211], v[108:111]
	v_mfma_f32_16x16x32_bf16 v[92:95], v[132:135], v[216:219], v[92:95]
	v_mfma_f32_16x16x32_bf16 v[88:91], v[140:143], v[216:219], v[88:91]
	v_mfma_f32_16x16x32_bf16 v[72:75], v[140:143], v[224:227], v[72:75]
	v_mfma_f32_16x16x32_bf16 v[76:79], v[132:135], v[224:227], v[76:79]
	v_mfma_f32_16x16x32_bf16 v[116:119], v[144:147], v[178:181], v[116:119]
	v_mfma_f32_16x16x32_bf16 v[112:115], v[170:173], v[178:181], v[112:115]
	v_mfma_f32_16x16x32_bf16 v[96:99], v[170:173], v[204:207], v[96:99]
	v_mfma_f32_16x16x32_bf16 v[100:103], v[144:147], v[204:207], v[100:103]
	v_mfma_f32_16x16x32_bf16 v[84:87], v[144:147], v[212:215], v[84:87]
	v_mfma_f32_16x16x32_bf16 v[80:83], v[170:173], v[212:215], v[80:83]
	v_mfma_f32_16x16x32_bf16 v[64:67], v[170:173], v[220:223], v[64:67]
	v_mfma_f32_16x16x32_bf16 v[68:71], v[144:147], v[220:223], v[68:71]
	v_mfma_f32_16x16x32_bf16 v[116:119], v[148:151], v[182:185], v[116:119]
	v_mfma_f32_16x16x32_bf16 v[112:115], v[174:177], v[182:185], v[112:115]
	v_mfma_f32_16x16x32_bf16 v[96:99], v[174:177], v[208:211], v[96:99]
	v_mfma_f32_16x16x32_bf16 v[100:103], v[148:151], v[208:211], v[100:103]
	v_mfma_f32_16x16x32_bf16 v[84:87], v[148:151], v[216:219], v[84:87]
	v_mfma_f32_16x16x32_bf16 v[80:83], v[174:177], v[216:219], v[80:83]
	v_mfma_f32_16x16x32_bf16 v[64:67], v[174:177], v[224:227], v[64:67]
	v_mfma_f32_16x16x32_bf16 v[68:71], v[148:151], v[224:227], v[68:71]
	s_barrier
; #define PG8_STAGE(bufoff, gbase, voff) do { _Pragma("unroll") for (int _i = 0; _i < 2; ++_i) \
;         __builtin_amdgcn_global_load_lds((const unsigned*)((const char*)(gbase) + (voff)[_i]), (LAS unsigned*)(lds + (bufoff) + ldsw + _i * 8192), 16, 0, 0); } while (0)
; #define PG8_LDA(dst, b, h) do { _Pragma("unroll") for (int m = 0; m < 4; ++m) _Pragma("unroll") for (int k = 0; k < 2; ++k) dst[m][k] = *(const LAS bf16x8*)(lds + PG8_SA(b, h) + aoff + m * 2048 + k * 1024); } while (0)
; #define PG8_LDB(dst, b, h) do { _Pragma("unroll") for (int n = 0; n < 2; ++n) _Pragma("unroll") for (int k = 0; k < 2; ++k) dst[n][k] = *(const LAS bf16x8*)(lds + PG8_SB(b, h) + boff + n * 2048 + k * 1024); } while (0)
; #define PG8_WAIT_V(n) asm volatile("s_waitcnt vmcnt(" #n ")" ::: "memory")
; #define PG8_WAIT_L(n) asm volatile("s_waitcnt lgkmcnt(" #n ")" ::: "memory")
; template <class Epi>
; __device__ __forceinline__ void gemm_phase(LAS unsigned char* lds, const Gemm g, const StaticOrder& S, const Epi& E) {
;     ...
;         for (int t = 0; t < nt; t += 2) {
;             const bool last = (t == nt - 2);
;             const char* a1 = cA + (size_t)(t + 1) * kstep;
;             const char* a2 = last ? nA : cA + (size_t)(t + 2) * kstep; const char* b2 = last ? nB : cB + (size_t)(t + 2) * kstep;
;             const char* a3 = a2 + kstep; const char* b3 = b2 + kstep;
;             PG8_LDB(B0, 0, 0); PG8_LDB(B1, 0, 1); PG8_SCHED; PG8_LDA(At, 0, 0); PG8_STAGE(PG8_SA(1, 1), a1 + hstepA, voffA);
;             PG8_WAIT_V(8); PG8_WAIT_L(0); PG8_BAR; PG8_MMA(0, 0, At, B0); PG8_MMA(0, 1, At, B1); PG8_BAR; PG8_SCHED;
;             PG8_LDA(At, 0, 1); PG8_STAGE(PG8_SB(0, 0), b2, voffB); PG8_STAGE(PG8_SB(0, 1), b2 + hstepB, voffB); PG8_STAGE(PG8_SA(0, 0), a2, voffA);
;             PG8_WAIT_V(8); PG8_WAIT_L(0); PG8_BAR; PG8_MMA(1, 0, At, B0); PG8_MMA(1, 1, At, B1); PG8_BAR; PG8_SCHED;
;             PG8_LDB(B0, 1, 0); PG8_LDB(B1, 1, 1); PG8_SCHED; PG8_LDA(At, 1, 0); PG8_STAGE(PG8_SA(0, 1), a2 + hstepA, voffA);
;             PG8_WAIT_V(8); PG8_WAIT_L(0); PG8_BAR; PG8_MMA(0, 0, At, B0); PG8_MMA(0, 1, At, B1); PG8_BAR; PG8_SCHED;
;             PG8_LDA(At, 1, 1); PG8_STAGE(PG8_SB(1, 0), b3, voffB); PG8_STAGE(PG8_SB(1, 1), b3 + hstepB, voffB); PG8_STAGE(PG8_SA(1, 0), a3, voffA);
;             PG8_WAIT_V(8); PG8_WAIT_L(0); PG8_BAR; PG8_MMA(1, 0, At, B0); PG8_MMA(1, 1, At, B1); PG8_BAR; PG8_SCHED;
	s_add_i32 s24, s50, s26
	v_lshl_add_u64 v[186:187], v[186:187], 0, s[6:7]
	s_mov_b32 m0, s24
	ds_read_b128 v[178:181], v200 offset:49152
	ds_read_b128 v[182:185], v200 offset:50176
	ds_read_b128 v[204:207], v200 offset:51200
	ds_read_b128 v[208:211], v200 offset:52224
	ds_read_b128 v[212:215], v200 offset:53248
	ds_read_b128 v[216:219], v200 offset:54272
	ds_read_b128 v[220:223], v200 offset:55296
	ds_read_b128 v[224:227], v200 offset:56320
	global_load_lds_dwordx4 v[186:187], off
	s_add_i32 m0, s24, 0x2000
	s_add_u32 s2, s2, 0x40080
	v_lshl_add_u64 v[186:187], v[190:191], 0, s[6:7]
	s_addc_u32 s3, s3, 0
	s_add_i32 s24, s51, s26
	global_load_lds_dwordx4 v[186:187], off
	v_lshl_add_u64 v[186:187], s[2:3], 0, v[156:157]
	s_mov_b32 m0, s24
	s_nop 0
	global_load_lds_dwordx4 v[186:187], off
	v_lshl_add_u64 v[186:187], s[2:3], 0, v[152:153]
	s_add_i32 m0, s24, 0x2000
	s_nop 0
	global_load_lds_dwordx4 v[186:187], off
	v_lshl_add_u64 v[186:187], v[228:229], 0, s[6:7]
	s_mov_b32 m0, s35
	s_nop 0
	global_load_lds_dwordx4 v[186:187], off
	v_lshl_add_u64 v[186:187], v[230:231], 0, s[6:7]
	s_mov_b32 m0, s36
	s_nop 0
	global_load_lds_dwordx4 v[186:187], off
	s_waitcnt vmcnt(8)
	s_waitcnt lgkmcnt(0)
	s_barrier
	s_waitcnt lgkmcnt(0)
	v_mfma_f32_16x16x32_bf16 v[60:63], v[128:131], v[178:181], v[60:63]
	v_mfma_f32_16x16x32_bf16 v[56:59], v[136:139], v[178:181], v[56:59]
	v_mfma_f32_16x16x32_bf16 v[40:43], v[136:139], v[204:207], v[40:43]
	v_mfma_f32_16x16x32_bf16 v[44:47], v[128:131], v[204:207], v[44:47]
	v_mfma_f32_16x16x32_bf16 v[28:31], v[128:131], v[212:215], v[28:31]
	v_mfma_f32_16x16x32_bf16 v[24:27], v[136:139], v[212:215], v[24:27]
	v_mfma_f32_16x16x32_bf16 v[8:11], v[136:139], v[220:223], v[8:11]
	v_mfma_f32_16x16x32_bf16 v[12:15], v[128:131], v[220:223], v[12:15]
	v_mfma_f32_16x16x32_bf16 v[60:63], v[132:135], v[182:185], v[60:63]
	v_mfma_f32_16x16x32_bf16 v[56:59], v[140:143], v[182:185], v[56:59]
	v_mfma_f32_16x16x32_bf16 v[40:43], v[140:143], v[208:211], v[40:43]
	v_mfma_f32_16x16x32_bf16 v[44:47], v[132:135], v[208:211], v[44:47]
	v_mfma_f32_16x16x32_bf16 v[28:31], v[132:135], v[216:219], v[28:31]
	v_mfma_f32_16x16x32_bf16 v[24:27], v[140:143], v[216:219], v[24:27]
	v_mfma_f32_16x16x32_bf16 v[8:11], v[140:143], v[224:227], v[8:11]
	v_mfma_f32_16x16x32_bf16 v[12:15], v[132:135], v[224:227], v[12:15]
	v_mfma_f32_16x16x32_bf16 v[52:55], v[144:147], v[178:181], v[52:55]
	v_mfma_f32_16x16x32_bf16 v[48:51], v[170:173], v[178:181], v[48:51]
	v_mfma_f32_16x16x32_bf16 v[32:35], v[170:173], v[204:207], v[32:35]
	v_mfma_f32_16x16x32_bf16 v[36:39], v[144:147], v[204:207], v[36:39]
	v_mfma_f32_16x16x32_bf16 v[20:23], v[144:147], v[212:215], v[20:23]
	v_mfma_f32_16x16x32_bf16 v[16:19], v[170:173], v[212:215], v[16:19]
	v_mfma_f32_16x16x32_bf16 v[0:3], v[170:173], v[220:223], v[0:3]
	v_mfma_f32_16x16x32_bf16 v[4:7], v[144:147], v[220:223], v[4:7]
	v_mfma_f32_16x16x32_bf16 v[52:55], v[148:151], v[182:185], v[52:55]
	v_mfma_f32_16x16x32_bf16 v[48:51], v[174:177], v[182:185], v[48:51]
	v_mfma_f32_16x16x32_bf16 v[32:35], v[174:177], v[208:211], v[32:35]
	v_mfma_f32_16x16x32_bf16 v[36:39], v[148:151], v[208:211], v[36:39]
	v_mfma_f32_16x16x32_bf16 v[20:23], v[148:151], v[216:219], v[20:23]
	v_mfma_f32_16x16x32_bf16 v[16:19], v[174:177], v[216:219], v[16:19]
	v_mfma_f32_16x16x32_bf16 v[0:3], v[174:177], v[224:227], v[0:3]
	v_mfma_f32_16x16x32_bf16 v[4:7], v[148:151], v[224:227], v[4:7]
	s_barrier
	s_add_i32 s49, s49, 2
	s_add_u32 s22, s22, 0x100
	s_addc_u32 s23, s23, 0
	s_add_u32 s47, s47, 0x100
	s_addc_u32 s48, s48, 0
	s_cmp_gt_u32 s49, 13
	s_cbranch_scc0 .LBB0_379
.LBB0_379:
	ds_read_b128 v[128:131], v198
	ds_read_b128 v[132:135], v198 offset:1024
	ds_read_b128 v[136:139], v198 offset:2048
	ds_read_b128 v[140:143], v198 offset:3072
	ds_read_b128 v[144:147], v199
	ds_read_b128 v[148:151], v199 offset:1024
	ds_read_b128 v[170:173], v199 offset:2048
	ds_read_b128 v[174:177], v199 offset:3072
	s_add_u32 s2, s22, 0xfffc0080
	s_addc_u32 s3, s23, -1
	s_cmp_eq_u32 s49, 12
	s_cselect_b32 s25, s44, s3
	s_cselect_b32 s24, s45, s2
	s_cselect_b32 s3, s17, s48
	s_cselect_b32 s2, s46, s47
	v_lshl_add_u64 v[186:187], s[22:23], 0, v[164:165]
	s_add_i32 m0, s28, 0xc000
	ds_read_b128 v[178:181], v200
	ds_read_b128 v[182:185], v200 offset:1024
	ds_read_b128 v[204:207], v200 offset:2048
	ds_read_b128 v[208:211], v200 offset:3072
	ds_read_b128 v[212:215], v200 offset:4096
	ds_read_b128 v[216:219], v200 offset:5120
	ds_read_b128 v[220:223], v200 offset:6144
	ds_read_b128 v[224:227], v200 offset:7168
	global_load_lds_dwordx4 v[186:187], off
	v_lshl_add_u64 v[186:187], s[22:23], 0, v[166:167]
	s_add_i32 m0, s28, 0xe000
	s_nop 0
	global_load_lds_dwordx4 v[186:187], off
	s_waitcnt vmcnt(8)
	s_waitcnt lgkmcnt(0)
	s_barrier
; #define PG8_STAGE(bufoff, gbase, voff) do { _Pragma("unroll") for (int _i = 0; _i < 2; ++_i) \
;         __builtin_amdgcn_global_load_lds((const unsigned*)((const char*)(gbase) + (voff)[_i]), (LAS unsigned*)(lds + (bufoff) + ldsw + _i * 8192), 16, 0, 0); } while (0)
; #define PG8_LDA(dst, b, h) do { _Pragma("unroll") for (int m = 0; m < 4; ++m) _Pragma("unroll") for (int k = 0; k < 2; ++k) dst[m][k] = *(const LAS bf16x8*)(lds + PG8_SA(b, h) + aoff + m * 2048 + k * 1024); } while (0)
; #define PG8_MMA(ai, bj, At, Bt) do { __builtin_amdgcn_s_setprio(1); _Pragma("unroll") for (int m = 0; m < 4; ++m) _Pragma("unroll") for (int n = 0; n < 2; ++n) _Pragma("unroll") for (int k = 0; k < 2; ++k) \
;         acc[ai][bj][m][n] = __builtin_amdgcn_mfma_f32_16x16x32_bf16(Bt[n][k], At[m][k], acc[ai][bj][m][n], 0, 0, 0); __builtin_amdgcn_s_setprio(0); } while (0)
; #define PG8_WAIT_V(n) asm volatile("s_waitcnt vmcnt(" #n ")" ::: "memory")
; #define PG8_WAIT_L(n) asm volatile("s_waitcnt lgkmcnt(" #n ")" ::: "memory")
; #define PG8_BAR __builtin_amdgcn_s_barrier()
; #define PG8_SCHED __builtin_amdgcn_sched_barrier(0)
; template <class Epi>
; __device__ __forceinline__ void gemm_phase(LAS unsigned char* lds, const Gemm g, const StaticOrder& S, const Epi& E) {
;     ...
;             PG8_WAIT_V(8); PG8_WAIT_L(0); PG8_BAR; PG8_MMA(0, 0, At, B0); PG8_MMA(0, 1, At, B1); PG8_BAR; PG8_SCHED;
;             PG8_LDA(At, 0, 1); PG8_STAGE(PG8_SB(0, 0), b2, voffB); PG8_STAGE(PG8_SB(0, 1), b2 + hstepB, voffB); PG8_STAGE(PG8_SA(0, 0), a2, voffA);
;             PG8_WAIT_V(8); PG8_WAIT_L(0); PG8_BAR; PG8_MMA(1, 0, At, B0); PG8_MMA(1, 1, At, B1); PG8_BAR; PG8_SCHED;
	s_waitcnt lgkmcnt(0)
	v_mfma_f32_16x16x32_bf16 v[124:127], v[128:131], v[178:181], v[124:127]
	v_mfma_f32_16x16x32_bf16 v[120:123], v[136:139], v[178:181], v[120:123]
	v_mfma_f32_16x16x32_bf16 v[104:107], v[136:139], v[204:207], v[104:107]
	v_mfma_f32_16x16x32_bf16 v[108:111], v[128:131], v[204:207], v[108:111]
	v_mfma_f32_16x16x32_bf16 v[92:95], v[128:131], v[212:215], v[92:95]
	v_mfma_f32_16x16x32_bf16 v[88:91], v[136:139], v[212:215], v[88:91]
	v_mfma_f32_16x16x32_bf16 v[72:75], v[136:139], v[220:223], v[72:75]
	v_mfma_f32_16x16x32_bf16 v[76:79], v[128:131], v[220:223], v[76:79]
	v_mfma_f32_16x16x32_bf16 v[124:127], v[132:135], v[182:185], v[124:127]
	v_mfma_f32_16x16x32_bf16 v[120:123], v[140:143], v[182:185], v[120:123]
	v_mfma_f32_16x16x32_bf16 v[104:107], v[140:143], v[208:211], v[104:107]
	v_mfma_f32_16x16x32_bf16 v[108:111], v[132:135], v[208:211], v[108:111]
	v_mfma_f32_16x16x32_bf16 v[92:95], v[132:135], v[216:219], v[92:95]
	v_mfma_f32_16x16x32_bf16 v[88:91], v[140:143], v[216:219], v[88:91]
	v_mfma_f32_16x16x32_bf16 v[72:75], v[140:143], v[224:227], v[72:75]
	v_mfma_f32_16x16x32_bf16 v[76:79], v[132:135], v[224:227], v[76:79]
	v_mfma_f32_16x16x32_bf16 v[116:119], v[144:147], v[178:181], v[116:119]
	v_mfma_f32_16x16x32_bf16 v[112:115], v[170:173], v[178:181], v[112:115]
	v_mfma_f32_16x16x32_bf16 v[96:99], v[170:173], v[204:207], v[96:99]
	v_mfma_f32_16x16x32_bf16 v[100:103], v[144:147], v[204:207], v[100:103]
	v_mfma_f32_16x16x32_bf16 v[84:87], v[144:147], v[212:215], v[84:87]
	v_mfma_f32_16x16x32_bf16 v[80:83], v[170:173], v[212:215], v[80:83]
	v_mfma_f32_16x16x32_bf16 v[64:67], v[170:173], v[220:223], v[64:67]
	v_mfma_f32_16x16x32_bf16 v[68:71], v[144:147], v[220:223], v[68:71]
	v_mfma_f32_16x16x32_bf16 v[116:119], v[148:151], v[182:185], v[116:119]
	v_mfma_f32_16x16x32_bf16 v[112:115], v[174:177], v[182:185], v[112:115]
	v_mfma_f32_16x16x32_bf16 v[96:99], v[174:177], v[208:211], v[96:99]
	v_mfma_f32_16x16x32_bf16 v[100:103], v[148:151], v[208:211], v[100:103]
	v_mfma_f32_16x16x32_bf16 v[84:87], v[148:151], v[216:219], v[84:87]
	v_mfma_f32_16x16x32_bf16 v[80:83], v[174:177], v[216:219], v[80:83]
	v_mfma_f32_16x16x32_bf16 v[64:67], v[174:177], v[224:227], v[64:67]
	v_mfma_f32_16x16x32_bf16 v[68:71], v[148:151], v[224:227], v[68:71]
	s_barrier
	s_add_i32 s50, s39, s26
	v_lshl_add_u64 v[186:187], s[2:3], 0, v[156:157]
	s_mov_b32 m0, s50
	ds_read_b128 v[178:181], v200 offset:16384
	ds_read_b128 v[182:185], v200 offset:17408
	ds_read_b128 v[204:207], v200 offset:18432
	ds_read_b128 v[208:211], v200 offset:19456
	ds_read_b128 v[212:215], v200 offset:20480
	ds_read_b128 v[216:219], v200 offset:21504
	ds_read_b128 v[220:223], v200 offset:22528
	ds_read_b128 v[224:227], v200 offset:23552
	global_load_lds_dwordx4 v[186:187], off
	s_add_i32 m0, s50, 0x2000
	s_add_u32 s50, s2, 0x40000
	v_lshl_add_u64 v[190:191], s[2:3], 0, v[152:153]
	s_addc_u32 s51, s3, 0
	s_add_i32 s52, s40, s26
	global_load_lds_dwordx4 v[190:191], off
	v_lshl_add_u64 v[228:229], s[50:51], 0, v[156:157]
	s_mov_b32 m0, s52
	v_lshl_add_u64 v[230:231], s[24:25], 0, v[154:155]
	global_load_lds_dwordx4 v[228:229], off
	v_lshl_add_u64 v[228:229], s[50:51], 0, v[152:153]
	s_add_i32 m0, s52, 0x2000
	s_nop 0
	global_load_lds_dwordx4 v[228:229], off
	v_lshl_add_u64 v[228:229], s[24:25], 0, v[158:159]
	s_mov_b32 m0, s28
	s_nop 0
	global_load_lds_dwordx4 v[228:229], off
	s_mov_b32 m0, s29
	s_nop 0
	global_load_lds_dwordx4 v[230:231], off
	s_waitcnt vmcnt(8)
	s_waitcnt lgkmcnt(0)
	s_barrier
	s_waitcnt lgkmcnt(0)
	v_mfma_f32_16x16x32_bf16 v[60:63], v[128:131], v[178:181], v[60:63]
	v_mfma_f32_16x16x32_bf16 v[56:59], v[136:139], v[178:181], v[56:59]
	v_mfma_f32_16x16x32_bf16 v[40:43], v[136:139], v[204:207], v[40:43]
	v_mfma_f32_16x16x32_bf16 v[44:47], v[128:131], v[204:207], v[44:47]
	v_mfma_f32_16x16x32_bf16 v[28:31], v[128:131], v[212:215], v[28:31]
	v_mfma_f32_16x16x32_bf16 v[24:27], v[136:139], v[212:215], v[24:27]
	v_mfma_f32_16x16x32_bf16 v[8:11], v[136:139], v[220:223], v[8:11]
	v_mfma_f32_16x16x32_bf16 v[12:15], v[128:131], v[220:223], v[12:15]
	v_mfma_f32_16x16x32_bf16 v[60:63], v[132:135], v[182:185], v[60:63]
	v_mfma_f32_16x16x32_bf16 v[56:59], v[140:143], v[182:185], v[56:59]
	v_mfma_f32_16x16x32_bf16 v[40:43], v[140:143], v[208:211], v[40:43]
	v_mfma_f32_16x16x32_bf16 v[44:47], v[132:135], v[208:211], v[44:47]
	v_mfma_f32_16x16x32_bf16 v[28:31], v[132:135], v[216:219], v[28:31]
	v_mfma_f32_16x16x32_bf16 v[24:27], v[140:143], v[216:219], v[24:27]
	v_mfma_f32_16x16x32_bf16 v[8:11], v[140:143], v[224:227], v[8:11]
	v_mfma_f32_16x16x32_bf16 v[12:15], v[132:135], v[224:227], v[12:15]
	v_mfma_f32_16x16x32_bf16 v[52:55], v[144:147], v[178:181], v[52:55]
	v_mfma_f32_16x16x32_bf16 v[48:51], v[170:173], v[178:181], v[48:51]
	v_mfma_f32_16x16x32_bf16 v[32:35], v[170:173], v[204:207], v[32:35]
	v_mfma_f32_16x16x32_bf16 v[36:39], v[144:147], v[204:207], v[36:39]
	v_mfma_f32_16x16x32_bf16 v[20:23], v[144:147], v[212:215], v[20:23]
	v_mfma_f32_16x16x32_bf16 v[16:19], v[170:173], v[212:215], v[16:19]
	v_mfma_f32_16x16x32_bf16 v[0:3], v[170:173], v[220:223], v[0:3]
	v_mfma_f32_16x16x32_bf16 v[4:7], v[144:147], v[220:223], v[4:7]
	v_mfma_f32_16x16x32_bf16 v[52:55], v[148:151], v[182:185], v[52:55]
	v_mfma_f32_16x16x32_bf16 v[48:51], v[174:177], v[182:185], v[48:51]
	v_mfma_f32_16x16x32_bf16 v[32:35], v[174:177], v[208:211], v[32:35]
	v_mfma_f32_16x16x32_bf16 v[36:39], v[148:151], v[208:211], v[36:39]
	v_mfma_f32_16x16x32_bf16 v[20:23], v[148:151], v[216:219], v[20:23]
	v_mfma_f32_16x16x32_bf16 v[16:19], v[174:177], v[216:219], v[16:19]
	v_mfma_f32_16x16x32_bf16 v[0:3], v[174:177], v[224:227], v[0:3]
	v_mfma_f32_16x16x32_bf16 v[4:7], v[148:151], v[224:227], v[4:7]
	s_barrier
; #define PG8_STAGE(bufoff, gbase, voff) do { _Pragma("unroll") for (int _i = 0; _i < 2; ++_i) \
;         __builtin_amdgcn_global_load_lds((const unsigned*)((const char*)(gbase) + (voff)[_i]), (LAS unsigned*)(lds + (bufoff) + ldsw + _i * 8192), 16, 0, 0); } while (0)
; #define PG8_LDA(dst, b, h) do { _Pragma("unroll") for (int m = 0; m < 4; ++m) _Pragma("unroll") for (int k = 0; k < 2; ++k) dst[m][k] = *(const LAS bf16x8*)(lds + PG8_SA(b, h) + aoff + m * 2048 + k * 1024); } while (0)
; #define PG8_LDB(dst, b, h) do { _Pragma("unroll") for (int n = 0; n < 2; ++n) _Pragma("unroll") for (int k = 0; k < 2; ++k) dst[n][k] = *(const LAS bf16x8*)(lds + PG8_SB(b, h) + boff + n * 2048 + k * 1024); } while (0)
; #define PG8_MMA(ai, bj, At, Bt) do { __builtin_amdgcn_s_setprio(1); _Pragma("unroll") for (int m = 0; m < 4; ++m) _Pragma("unroll") for (int n = 0; n < 2; ++n) _Pragma("unroll") for (int k = 0; k < 2; ++k) \
;         acc[ai][bj][m][n] = __builtin_amdgcn_mfma_f32_16x16x32_bf16(Bt[n][k], At[m][k], acc[ai][bj][m][n], 0, 0, 0); __builtin_amdgcn_s_setprio(0); } while (0)
; #define PG8_WAIT_V(n) asm volatile("s_waitcnt vmcnt(" #n ")" ::: "memory")
; #define PG8_WAIT_L(n) asm volatile("s_waitcnt lgkmcnt(" #n ")" ::: "memory")
; #define PG8_BAR __builtin_amdgcn_s_barrier()
; #define PG8_SCHED __builtin_amdgcn_sched_barrier(0)
; template <class Epi>
; __device__ __forceinline__ void gemm_phase(LAS unsigned char* lds, const Gemm g, const StaticOrder& S, const Epi& E) {
;     ...
;             PG8_LDB(B0, 1, 0); PG8_LDB(B1, 1, 1); PG8_SCHED; PG8_LDA(At, 1, 0); PG8_STAGE(PG8_SA(0, 1), a2 + hstepA, voffA);
;             PG8_WAIT_V(8); PG8_WAIT_L(0); PG8_BAR; PG8_MMA(0, 0, At, B0); PG8_MMA(0, 1, At, B1); PG8_BAR; PG8_SCHED;
	s_add_i32 s50, 0, 0x18000
	s_add_i32 s51, 0, 0x1c000
	v_add_u32_e32 v140, s50, v195
	v_add_u32_e32 v160, s51, v195
	ds_read_b128 v[128:131], v140
	ds_read_b128 v[132:135], v140 offset:1024
	ds_read_b128 v[136:139], v140 offset:2048
	ds_read_b128 v[140:143], v140 offset:3072
	ds_read_b128 v[144:147], v160
	ds_read_b128 v[148:151], v160 offset:1024
	ds_read_b128 v[170:173], v160 offset:2048
	ds_read_b128 v[174:177], v160 offset:3072
	s_add_u32 s24, s24, 0x40000
	s_addc_u32 s25, s25, 0
	s_mov_b32 m0, s30
	v_lshl_add_u64 v[232:233], s[24:25], 0, v[158:159]
	ds_read_b128 v[178:181], v200 offset:32768
	ds_read_b128 v[182:185], v200 offset:33792
	ds_read_b128 v[204:207], v200 offset:34816
	ds_read_b128 v[208:211], v200 offset:35840
	ds_read_b128 v[212:215], v200 offset:36864
	ds_read_b128 v[216:219], v200 offset:37888
	ds_read_b128 v[220:223], v200 offset:38912
	ds_read_b128 v[224:227], v200 offset:39936
	global_load_lds_dwordx4 v[232:233], off
	v_lshl_add_u64 v[232:233], s[24:25], 0, v[154:155]
	s_mov_b32 m0, s31
	s_nop 0
	global_load_lds_dwordx4 v[232:233], off
	s_waitcnt vmcnt(8)
	s_waitcnt lgkmcnt(0)
	s_barrier
	s_waitcnt lgkmcnt(0)
	v_mfma_f32_16x16x32_bf16 v[124:127], v[128:131], v[178:181], v[124:127]
	v_mfma_f32_16x16x32_bf16 v[120:123], v[136:139], v[178:181], v[120:123]
	v_mfma_f32_16x16x32_bf16 v[104:107], v[136:139], v[204:207], v[104:107]
	v_mfma_f32_16x16x32_bf16 v[108:111], v[128:131], v[204:207], v[108:111]
	v_mfma_f32_16x16x32_bf16 v[92:95], v[128:131], v[212:215], v[92:95]
	v_mfma_f32_16x16x32_bf16 v[88:91], v[136:139], v[212:215], v[88:91]
	v_mfma_f32_16x16x32_bf16 v[72:75], v[136:139], v[220:223], v[72:75]
	v_mfma_f32_16x16x32_bf16 v[76:79], v[128:131], v[220:223], v[76:79]
	v_mfma_f32_16x16x32_bf16 v[124:127], v[132:135], v[182:185], v[124:127]
	v_mfma_f32_16x16x32_bf16 v[120:123], v[140:143], v[182:185], v[120:123]
	v_mfma_f32_16x16x32_bf16 v[104:107], v[140:143], v[208:211], v[104:107]
	v_mfma_f32_16x16x32_bf16 v[108:111], v[132:135], v[208:211], v[108:111]
	v_mfma_f32_16x16x32_bf16 v[92:95], v[132:135], v[216:219], v[92:95]
	v_mfma_f32_16x16x32_bf16 v[88:91], v[140:143], v[216:219], v[88:91]
	v_mfma_f32_16x16x32_bf16 v[72:75], v[140:143], v[224:227], v[72:75]
	v_mfma_f32_16x16x32_bf16 v[76:79], v[132:135], v[224:227], v[76:79]
	v_mfma_f32_16x16x32_bf16 v[116:119], v[144:147], v[178:181], v[116:119]
	v_mfma_f32_16x16x32_bf16 v[112:115], v[170:173], v[178:181], v[112:115]
	v_mfma_f32_16x16x32_bf16 v[96:99], v[170:173], v[204:207], v[96:99]
	v_mfma_f32_16x16x32_bf16 v[100:103], v[144:147], v[204:207], v[100:103]
	v_mfma_f32_16x16x32_bf16 v[84:87], v[144:147], v[212:215], v[84:87]
	v_mfma_f32_16x16x32_bf16 v[80:83], v[170:173], v[212:215], v[80:83]
	v_mfma_f32_16x16x32_bf16 v[64:67], v[170:173], v[220:223], v[64:67]
	v_mfma_f32_16x16x32_bf16 v[68:71], v[144:147], v[220:223], v[68:71]
	v_mfma_f32_16x16x32_bf16 v[116:119], v[148:151], v[182:185], v[116:119]
	v_mfma_f32_16x16x32_bf16 v[112:115], v[174:177], v[182:185], v[112:115]
	v_mfma_f32_16x16x32_bf16 v[96:99], v[174:177], v[208:211], v[96:99]
	v_mfma_f32_16x16x32_bf16 v[100:103], v[148:151], v[208:211], v[100:103]
	v_mfma_f32_16x16x32_bf16 v[84:87], v[148:151], v[216:219], v[84:87]
	v_mfma_f32_16x16x32_bf16 v[80:83], v[174:177], v[216:219], v[80:83]
	v_mfma_f32_16x16x32_bf16 v[64:67], v[174:177], v[224:227], v[64:67]
	v_mfma_f32_16x16x32_bf16 v[68:71], v[148:151], v[224:227], v[68:71]
	s_barrier
; #define PG8_STAGE(bufoff, gbase, voff) do { _Pragma("unroll") for (int _i = 0; _i < 2; ++_i) \
;         __builtin_amdgcn_global_load_lds((const unsigned*)((const char*)(gbase) + (voff)[_i]), (LAS unsigned*)(lds + (bufoff) + ldsw + _i * 8192), 16, 0, 0); } while (0)
; #define PG8_LDA(dst, b, h) do { _Pragma("unroll") for (int m = 0; m < 4; ++m) _Pragma("unroll") for (int k = 0; k < 2; ++k) dst[m][k] = *(const LAS bf16x8*)(lds + PG8_SA(b, h) + aoff + m * 2048 + k * 1024); } while (0)
; #define PG8_MMA(ai, bj, At, Bt) do { __builtin_amdgcn_s_setprio(1); _Pragma("unroll") for (int m = 0; m < 4; ++m) _Pragma("unroll") for (int n = 0; n < 2; ++n) _Pragma("unroll") for (int k = 0; k < 2; ++k) \
;         acc[ai][bj][m][n] = __builtin_amdgcn_mfma_f32_16x16x32_bf16(Bt[n][k], At[m][k], acc[ai][bj][m][n], 0, 0, 0); __builtin_amdgcn_s_setprio(0); } while (0)
; #define PG8_WAIT_V(n) asm volatile("s_waitcnt vmcnt(" #n ")" ::: "memory")
; #define PG8_WAIT_L(n) asm volatile("s_waitcnt lgkmcnt(" #n ")" ::: "memory")
; #define PG8_BAR __builtin_amdgcn_s_barrier()
; #define PG8_SCHED __builtin_amdgcn_sched_barrier(0)
; template <class Epi>
; __device__ __forceinline__ void gemm_phase(LAS unsigned char* lds, const Gemm g, const StaticOrder& S, const Epi& E) {
;     ...
;             PG8_LDA(At, 1, 1); PG8_STAGE(PG8_SB(1, 0), b3, voffB); PG8_STAGE(PG8_SB(1, 1), b3 + hstepB, voffB); PG8_STAGE(PG8_SA(1, 0), a3, voffA);
;             PG8_WAIT_V(8); PG8_WAIT_L(0); PG8_BAR; PG8_MMA(1, 0, At, B0); PG8_MMA(1, 1, At, B1); PG8_BAR; PG8_SCHED;
;         }
;         if (wr == 0) PG8_BAR;
	s_add_i32 s24, s50, s26
	v_lshl_add_u64 v[186:187], v[186:187], 0, s[6:7]
	s_mov_b32 m0, s24
	ds_read_b128 v[178:181], v200 offset:49152
	ds_read_b128 v[182:185], v200 offset:50176
	ds_read_b128 v[204:207], v200 offset:51200
	ds_read_b128 v[208:211], v200 offset:52224
	ds_read_b128 v[212:215], v200 offset:53248
	ds_read_b128 v[216:219], v200 offset:54272
	ds_read_b128 v[220:223], v200 offset:55296
	ds_read_b128 v[224:227], v200 offset:56320
	global_load_lds_dwordx4 v[186:187], off
	s_add_i32 m0, s24, 0x2000
	s_add_u32 s2, s2, 0x40080
	v_lshl_add_u64 v[186:187], v[190:191], 0, s[6:7]
	s_addc_u32 s3, s3, 0
	s_add_i32 s24, s51, s26
	global_load_lds_dwordx4 v[186:187], off
	v_lshl_add_u64 v[186:187], s[2:3], 0, v[156:157]
	s_mov_b32 m0, s24
	s_nop 0
	global_load_lds_dwordx4 v[186:187], off
	v_lshl_add_u64 v[186:187], s[2:3], 0, v[152:153]
	s_add_i32 m0, s24, 0x2000
	s_nop 0
	global_load_lds_dwordx4 v[186:187], off
	v_lshl_add_u64 v[186:187], v[228:229], 0, s[6:7]
	s_mov_b32 m0, s35
	s_nop 0
	global_load_lds_dwordx4 v[186:187], off
	v_lshl_add_u64 v[186:187], v[230:231], 0, s[6:7]
	s_mov_b32 m0, s36
	s_nop 0
	global_load_lds_dwordx4 v[186:187], off
	s_waitcnt vmcnt(8)
	s_waitcnt lgkmcnt(0)
	s_barrier
	s_waitcnt lgkmcnt(0)
	v_mfma_f32_16x16x32_bf16 v[60:63], v[128:131], v[178:181], v[60:63]
	v_mfma_f32_16x16x32_bf16 v[56:59], v[136:139], v[178:181], v[56:59]
	v_mfma_f32_16x16x32_bf16 v[40:43], v[136:139], v[204:207], v[40:43]
	v_mfma_f32_16x16x32_bf16 v[44:47], v[128:131], v[204:207], v[44:47]
	v_mfma_f32_16x16x32_bf16 v[28:31], v[128:131], v[212:215], v[28:31]
	v_mfma_f32_16x16x32_bf16 v[24:27], v[136:139], v[212:215], v[24:27]
	v_mfma_f32_16x16x32_bf16 v[8:11], v[136:139], v[220:223], v[8:11]
	v_mfma_f32_16x16x32_bf16 v[12:15], v[128:131], v[220:223], v[12:15]
	v_mfma_f32_16x16x32_bf16 v[60:63], v[132:135], v[182:185], v[60:63]
	v_mfma_f32_16x16x32_bf16 v[56:59], v[140:143], v[182:185], v[56:59]
	v_mfma_f32_16x16x32_bf16 v[40:43], v[140:143], v[208:211], v[40:43]
	v_mfma_f32_16x16x32_bf16 v[44:47], v[132:135], v[208:211], v[44:47]
	v_mfma_f32_16x16x32_bf16 v[28:31], v[132:135], v[216:219], v[28:31]
	v_mfma_f32_16x16x32_bf16 v[24:27], v[140:143], v[216:219], v[24:27]
	v_mfma_f32_16x16x32_bf16 v[8:11], v[140:143], v[224:227], v[8:11]
	v_mfma_f32_16x16x32_bf16 v[12:15], v[132:135], v[224:227], v[12:15]
	v_mfma_f32_16x16x32_bf16 v[52:55], v[144:147], v[178:181], v[52:55]
	v_mfma_f32_16x16x32_bf16 v[48:51], v[170:173], v[178:181], v[48:51]
	v_mfma_f32_16x16x32_bf16 v[32:35], v[170:173], v[204:207], v[32:35]
	v_mfma_f32_16x16x32_bf16 v[36:39], v[144:147], v[204:207], v[36:39]
	v_mfma_f32_16x16x32_bf16 v[20:23], v[144:147], v[212:215], v[20:23]
	v_mfma_f32_16x16x32_bf16 v[16:19], v[170:173], v[212:215], v[16:19]
	v_mfma_f32_16x16x32_bf16 v[0:3], v[170:173], v[220:223], v[0:3]
	v_mfma_f32_16x16x32_bf16 v[4:7], v[144:147], v[220:223], v[4:7]
	v_mfma_f32_16x16x32_bf16 v[52:55], v[148:151], v[182:185], v[52:55]
	v_mfma_f32_16x16x32_bf16 v[48:51], v[174:177], v[182:185], v[48:51]
	v_mfma_f32_16x16x32_bf16 v[32:35], v[174:177], v[208:211], v[32:35]
	v_mfma_f32_16x16x32_bf16 v[36:39], v[148:151], v[208:211], v[36:39]
	v_mfma_f32_16x16x32_bf16 v[20:23], v[148:151], v[216:219], v[20:23]
	v_mfma_f32_16x16x32_bf16 v[16:19], v[174:177], v[216:219], v[16:19]
	v_mfma_f32_16x16x32_bf16 v[0:3], v[174:177], v[224:227], v[0:3]
	v_mfma_f32_16x16x32_bf16 v[4:7], v[148:151], v[224:227], v[4:7]
	s_barrier
	s_add_i32 s49, s49, 2
	s_add_u32 s22, s22, 0x100
	s_addc_u32 s23, s23, 0
	s_add_u32 s47, s47, 0x100
	s_addc_u32 s48, s48, 0
	s_cmp_gt_u32 s49, 13
	s_cbranch_scc0 .LBB0_379
	s_and_b64 vcc, exec, s[8:9]
	s_cbranch_vccz .LBB0_382
	s_barrier

; #define PG8_STAGE(bufoff, gbase, voff) do { _Pragma("unroll") for (int _i = 0; _i < 2; ++_i) \
;         __builtin_amdgcn_global_load_lds((const unsigned*)((const char*)(gbase) + (voff)[_i]), (LAS unsigned*)(lds + (bufoff) + ldsw + _i * 8192), 16, 0, 0); } while (0)
; #define PG8_LDA(dst, b, h) do { _Pragma("unroll") for (int m = 0; m < 4; ++m) _Pragma("unroll") for (int k = 0; k < 2; ++k) dst[m][k] = *(const LAS bf16x8*)(lds + PG8_SA(b, h) + aoff + m * 2048 + k * 1024); } while (0)
; #define PG8_LDB(dst, b, h) do { _Pragma("unroll") for (int n = 0; n < 2; ++n) _Pragma("unroll") for (int k = 0; k < 2; ++k) dst[n][k] = *(const LAS bf16x8*)(lds + PG8_SB(b, h) + boff + n * 2048 + k * 1024); } while (0)
; #define PG8_MMA(ai, bj, At, Bt) do { __builtin_amdgcn_s_setprio(1); _Pragma("unroll") for (int m = 0; m < 4; ++m) _Pragma("unroll") for (int n = 0; n < 2; ++n) _Pragma("unroll") for (int k = 0; k < 2; ++k) \
;         acc[ai][bj][m][n] = __builtin_amdgcn_mfma_f32_16x16x32_bf16(Bt[n][k], At[m][k], acc[ai][bj][m][n], 0, 0, 0); __builtin_amdgcn_s_setprio(0); } while (0)
; #define PG8_WAIT_V(n) asm volatile("s_waitcnt vmcnt(" #n ")" ::: "memory")
; #define PG8_WAIT_L(n) asm volatile("s_waitcnt lgkmcnt(" #n ")" ::: "memory")
; #define PG8_BAR __builtin_amdgcn_s_barrier()
; #define PG8_SCHED __builtin_amdgcn_sched_barrier(0)
; template <class Epi>
; __device__ __forceinline__ void gemm_phase(LAS unsigned char* lds, const Gemm g, const StaticOrder& S, const Epi& E) {
;     ...
;         const char* nA = has_next ? (const char*)g.A + (size_t)(nxt.pm >> 5) * aslab + (size_t)(nxt.pm & 31) * tstepA : cA; const char* nB = has_next ? (const char*)g.Bt + (size_t)nxt.pn * tstepB : cB;
;         for (int t = 0; t < nt; t += 2) {
;             const bool last = (t == nt - 2);
;             const char* a1 = cA + (size_t)(t + 1) * kstep;
;             const char* a2 = last ? nA : cA + (size_t)(t + 2) * kstep; const char* b2 = last ? nB : cB + (size_t)(t + 2) * kstep;
;             const char* a3 = a2 + kstep; const char* b3 = b2 + kstep;
;             PG8_LDB(B0, 0, 0); PG8_LDB(B1, 0, 1); PG8_SCHED; PG8_LDA(At, 0, 0); PG8_STAGE(PG8_SA(1, 1), a1 + hstepA, voffA);
;             PG8_WAIT_V(8); PG8_WAIT_L(0); PG8_BAR; PG8_MMA(0, 0, At, B0); PG8_MMA(0, 1, At, B1); PG8_BAR; PG8_SCHED;
.LBB0_696:
	s_ashr_i32 s14, s38, 5
	s_ashr_i32 s15, s14, 31
	s_lshl_b64 s[14:15], s[14:15], 24
	s_add_u32 s13, s24, s14
	s_addc_u32 s15, s25, s15
	s_lshl_b32 s14, s38, 19
	s_and_b32 s14, s14, 0xf80000
	s_add_u32 s14, s13, s14
	s_addc_u32 s15, s15, 0
	s_and_b64 s[16:17], s[4:5], exec
	s_cselect_b32 s41, s15, s19
	s_cselect_b32 s42, s14, s18
	s_ashr_i32 s13, s12, 31
	s_lshl_b64 s[16:17], s[12:13], 18
	v_readlane_b32 s20, v235, 25
	v_readlane_b32 s21, v235, 26
	s_add_u32 s16, s20, s16
	s_addc_u32 s17, s21, s17
	s_and_b64 s[20:21], s[4:5], exec
	s_cselect_b32 s13, s17, s3
	s_cselect_b32 s43, s16, s2
	s_add_u32 s18, s18, 0x40080
	s_addc_u32 s19, s19, 0
	s_add_u32 s44, s2, 0x100
	s_addc_u32 s45, s3, 0
	s_mov_b32 s46, -2
	s_waitcnt vmcnt(0)
	ds_read_b128 v[142:145], v151
	ds_read_b128 v[154:157], v151 offset:1024
	ds_read_b128 v[158:161], v151 offset:2048
	ds_read_b128 v[162:165], v151 offset:3072
	ds_read_b128 v[166:169], v152
	ds_read_b128 v[170:173], v152 offset:1024
	ds_read_b128 v[174:177], v152 offset:2048
	ds_read_b128 v[178:181], v152 offset:3072
	s_add_u32 s2, s18, 0xfffc0080
	s_addc_u32 s3, s19, -1
	s_cmp_eq_u32 s46, 4
	s_cselect_b32 s21, s41, s3
	s_cselect_b32 s20, s42, s2
	s_cselect_b32 s3, s13, s45
	s_cselect_b32 s2, s43, s44
	v_lshl_add_u64 v[146:147], s[18:19], 0, v[136:137]
	s_add_i32 m0, s23, 0xc000
	ds_read_b128 v[182:185], v153
	ds_read_b128 v[190:193], v153 offset:1024
	ds_read_b128 v[198:201], v153 offset:2048
	ds_read_b128 v[202:205], v153 offset:3072
	ds_read_b128 v[206:209], v153 offset:4096
	ds_read_b128 v[210:213], v153 offset:5120
	ds_read_b128 v[214:217], v153 offset:6144
	ds_read_b128 v[218:221], v153 offset:7168
	global_load_lds_dwordx4 v[146:147], off
	v_lshl_add_u64 v[146:147], s[18:19], 0, v[138:139]
	s_add_i32 m0, s23, 0xe000
	s_nop 0
	global_load_lds_dwordx4 v[146:147], off
	s_waitcnt vmcnt(8)
	s_waitcnt lgkmcnt(0)
	s_barrier
	s_waitcnt lgkmcnt(0)
	v_mfma_f32_16x16x32_bf16 v[124:127], v[142:145], v[182:185], 0
	v_mfma_f32_16x16x32_bf16 v[120:123], v[158:161], v[182:185], 0
	v_mfma_f32_16x16x32_bf16 v[112:115], v[158:161], v[198:201], 0
	v_mfma_f32_16x16x32_bf16 v[116:119], v[142:145], v[198:201], 0
	v_mfma_f32_16x16x32_bf16 v[96:99], v[142:145], v[206:209], 0
	v_mfma_f32_16x16x32_bf16 v[88:91], v[158:161], v[206:209], 0
	v_mfma_f32_16x16x32_bf16 v[72:75], v[158:161], v[214:217], 0
	v_mfma_f32_16x16x32_bf16 v[80:83], v[142:145], v[214:217], 0
	v_mfma_f32_16x16x32_bf16 v[124:127], v[154:157], v[190:193], v[124:127]
	v_mfma_f32_16x16x32_bf16 v[120:123], v[162:165], v[190:193], v[120:123]
	v_mfma_f32_16x16x32_bf16 v[112:115], v[162:165], v[202:205], v[112:115]
	v_mfma_f32_16x16x32_bf16 v[116:119], v[154:157], v[202:205], v[116:119]
	v_mfma_f32_16x16x32_bf16 v[96:99], v[154:157], v[210:213], v[96:99]
	v_mfma_f32_16x16x32_bf16 v[88:91], v[162:165], v[210:213], v[88:91]
	v_mfma_f32_16x16x32_bf16 v[72:75], v[162:165], v[218:221], v[72:75]
	v_mfma_f32_16x16x32_bf16 v[80:83], v[154:157], v[218:221], v[80:83]
	v_mfma_f32_16x16x32_bf16 v[108:111], v[166:169], v[182:185], 0
	v_mfma_f32_16x16x32_bf16 v[104:107], v[174:177], v[182:185], 0
	v_mfma_f32_16x16x32_bf16 v[92:95], v[174:177], v[198:201], 0
	v_mfma_f32_16x16x32_bf16 v[100:103], v[166:169], v[198:201], 0
	v_mfma_f32_16x16x32_bf16 v[84:87], v[166:169], v[206:209], 0
	v_mfma_f32_16x16x32_bf16 v[76:79], v[174:177], v[206:209], 0
	v_mfma_f32_16x16x32_bf16 v[64:67], v[174:177], v[214:217], 0
	v_mfma_f32_16x16x32_bf16 v[68:71], v[166:169], v[214:217], 0
	v_mfma_f32_16x16x32_bf16 v[108:111], v[170:173], v[190:193], v[108:111]
	v_mfma_f32_16x16x32_bf16 v[104:107], v[178:181], v[190:193], v[104:107]
	v_mfma_f32_16x16x32_bf16 v[92:95], v[178:181], v[202:205], v[92:95]
	v_mfma_f32_16x16x32_bf16 v[100:103], v[170:173], v[202:205], v[100:103]
	v_mfma_f32_16x16x32_bf16 v[84:87], v[170:173], v[210:213], v[84:87]
	v_mfma_f32_16x16x32_bf16 v[76:79], v[178:181], v[210:213], v[76:79]
	v_mfma_f32_16x16x32_bf16 v[64:67], v[178:181], v[218:221], v[64:67]
	v_mfma_f32_16x16x32_bf16 v[68:71], v[170:173], v[218:221], v[68:71]
	s_barrier
	s_add_i32 s47, s35, s22
	v_lshl_add_u64 v[146:147], s[2:3], 0, v[130:131]
	s_mov_b32 m0, s47
	ds_read_b128 v[182:185], v153 offset:16384
	ds_read_b128 v[190:193], v153 offset:17408
	ds_read_b128 v[198:201], v153 offset:18432
	ds_read_b128 v[202:205], v153 offset:19456
	ds_read_b128 v[206:209], v153 offset:20480
	ds_read_b128 v[210:213], v153 offset:21504
	ds_read_b128 v[214:217], v153 offset:22528
	ds_read_b128 v[218:221], v153 offset:23552
	global_load_lds_dwordx4 v[146:147], off
	s_add_i32 m0, s47, 0x2000
	s_add_u32 s48, s2, 0x20000
	v_lshl_add_u64 v[186:187], s[2:3], 0, v[134:135]
	s_addc_u32 s49, s3, 0
	s_add_i32 s47, s36, s22
	global_load_lds_dwordx4 v[186:187], off
	v_lshl_add_u64 v[194:195], s[48:49], 0, v[130:131]
	s_mov_b32 m0, s47
	v_lshl_add_u64 v[222:223], s[20:21], 0, v[132:133]
	global_load_lds_dwordx4 v[194:195], off
	v_lshl_add_u64 v[194:195], s[48:49], 0, v[134:135]
	s_add_i32 m0, s47, 0x2000
	s_nop 0
	global_load_lds_dwordx4 v[194:195], off
	v_lshl_add_u64 v[194:195], s[20:21], 0, v[128:129]
	s_mov_b32 m0, s23
	s_nop 0
	global_load_lds_dwordx4 v[194:195], off
	s_mov_b32 m0, s26
	s_nop 0
	global_load_lds_dwordx4 v[222:223], off
	s_waitcnt vmcnt(8)
	s_waitcnt lgkmcnt(0)
	s_barrier
; #define PG8_STAGE(bufoff, gbase, voff) do { _Pragma("unroll") for (int _i = 0; _i < 2; ++_i) \
;         __builtin_amdgcn_global_load_lds((const unsigned*)((const char*)(gbase) + (voff)[_i]), (LAS unsigned*)(lds + (bufoff) + ldsw + _i * 8192), 16, 0, 0); } while (0)
; #define PG8_LDA(dst, b, h) do { _Pragma("unroll") for (int m = 0; m < 4; ++m) _Pragma("unroll") for (int k = 0; k < 2; ++k) dst[m][k] = *(const LAS bf16x8*)(lds + PG8_SA(b, h) + aoff + m * 2048 + k * 1024); } while (0)
; #define PG8_LDB(dst, b, h) do { _Pragma("unroll") for (int n = 0; n < 2; ++n) _Pragma("unroll") for (int k = 0; k < 2; ++k) dst[n][k] = *(const LAS bf16x8*)(lds + PG8_SB(b, h) + boff + n * 2048 + k * 1024); } while (0)
; #define PG8_MMA(ai, bj, At, Bt) do { __builtin_amdgcn_s_setprio(1); _Pragma("unroll") for (int m = 0; m < 4; ++m) _Pragma("unroll") for (int n = 0; n < 2; ++n) _Pragma("unroll") for (int k = 0; k < 2; ++k) \
;         acc[ai][bj][m][n] = __builtin_amdgcn_mfma_f32_16x16x32_bf16(Bt[n][k], At[m][k], acc[ai][bj][m][n], 0, 0, 0); __builtin_amdgcn_s_setprio(0); } while (0)
; #define PG8_WAIT_V(n) asm volatile("s_waitcnt vmcnt(" #n ")" ::: "memory")
; #define PG8_WAIT_L(n) asm volatile("s_waitcnt lgkmcnt(" #n ")" ::: "memory")
; #define PG8_BAR __builtin_amdgcn_s_barrier()
; #define PG8_SCHED __builtin_amdgcn_sched_barrier(0)
; template <class Epi>
; __device__ __forceinline__ void gemm_phase(LAS unsigned char* lds, const Gemm g, const StaticOrder& S, const Epi& E) {
;     ...
;             PG8_WAIT_V(8); PG8_WAIT_L(0); PG8_BAR; PG8_MMA(0, 0, At, B0); PG8_MMA(0, 1, At, B1); PG8_BAR; PG8_SCHED;
;             PG8_LDA(At, 0, 1); PG8_STAGE(PG8_SB(0, 0), b2, voffB); PG8_STAGE(PG8_SB(0, 1), b2 + hstepB, voffB); PG8_STAGE(PG8_SA(0, 0), a2, voffA);
;             PG8_WAIT_V(8); PG8_WAIT_L(0); PG8_BAR; PG8_MMA(1, 0, At, B0); PG8_MMA(1, 1, At, B1); PG8_BAR; PG8_SCHED;
;             PG8_LDB(B0, 1, 0); PG8_LDB(B1, 1, 1); PG8_SCHED; PG8_LDA(At, 1, 0); PG8_STAGE(PG8_SA(0, 1), a2 + hstepA, voffA);
;             PG8_WAIT_V(8); PG8_WAIT_L(0); PG8_BAR; PG8_MMA(0, 0, At, B0); PG8_MMA(0, 1, At, B1); PG8_BAR; PG8_SCHED;
	s_waitcnt lgkmcnt(0)
	v_mfma_f32_16x16x32_bf16 v[60:63], v[142:145], v[182:185], 0
	v_mfma_f32_16x16x32_bf16 v[56:59], v[158:161], v[182:185], 0
	v_mfma_f32_16x16x32_bf16 v[40:43], v[158:161], v[198:201], 0
	v_mfma_f32_16x16x32_bf16 v[48:51], v[142:145], v[198:201], 0
	v_mfma_f32_16x16x32_bf16 v[32:35], v[142:145], v[206:209], 0
	v_mfma_f32_16x16x32_bf16 v[24:27], v[158:161], v[206:209], 0
	v_mfma_f32_16x16x32_bf16 v[8:11], v[158:161], v[214:217], 0
	v_mfma_f32_16x16x32_bf16 v[16:19], v[142:145], v[214:217], 0
	v_mfma_f32_16x16x32_bf16 v[60:63], v[154:157], v[190:193], v[60:63]
	v_mfma_f32_16x16x32_bf16 v[56:59], v[162:165], v[190:193], v[56:59]
	v_mfma_f32_16x16x32_bf16 v[40:43], v[162:165], v[202:205], v[40:43]
	v_mfma_f32_16x16x32_bf16 v[48:51], v[154:157], v[202:205], v[48:51]
	v_mfma_f32_16x16x32_bf16 v[32:35], v[154:157], v[210:213], v[32:35]
	v_mfma_f32_16x16x32_bf16 v[24:27], v[162:165], v[210:213], v[24:27]
	v_mfma_f32_16x16x32_bf16 v[8:11], v[162:165], v[218:221], v[8:11]
	v_mfma_f32_16x16x32_bf16 v[16:19], v[154:157], v[218:221], v[16:19]
	v_mfma_f32_16x16x32_bf16 v[52:55], v[166:169], v[182:185], 0
	v_mfma_f32_16x16x32_bf16 v[44:47], v[174:177], v[182:185], 0
	v_mfma_f32_16x16x32_bf16 v[28:31], v[174:177], v[198:201], 0
	v_mfma_f32_16x16x32_bf16 v[36:39], v[166:169], v[198:201], 0
	v_mfma_f32_16x16x32_bf16 v[20:23], v[166:169], v[206:209], 0
	v_mfma_f32_16x16x32_bf16 v[12:15], v[174:177], v[206:209], 0
	v_mfma_f32_16x16x32_bf16 v[0:3], v[174:177], v[214:217], 0
	v_mfma_f32_16x16x32_bf16 v[4:7], v[166:169], v[214:217], 0
	v_mfma_f32_16x16x32_bf16 v[52:55], v[170:173], v[190:193], v[52:55]
	v_mfma_f32_16x16x32_bf16 v[44:47], v[178:181], v[190:193], v[44:47]
	v_mfma_f32_16x16x32_bf16 v[28:31], v[178:181], v[202:205], v[28:31]
	v_mfma_f32_16x16x32_bf16 v[36:39], v[170:173], v[202:205], v[36:39]
	v_mfma_f32_16x16x32_bf16 v[20:23], v[170:173], v[210:213], v[20:23]
	v_mfma_f32_16x16x32_bf16 v[12:15], v[178:181], v[210:213], v[12:15]
	v_mfma_f32_16x16x32_bf16 v[0:3], v[178:181], v[218:221], v[0:3]
	v_mfma_f32_16x16x32_bf16 v[4:7], v[170:173], v[218:221], v[4:7]
	s_barrier
	s_add_i32 s47, 0, 0x18000
	s_add_i32 s48, 0, 0x1c000
	v_add_u32_e32 v162, s47, v149
	v_add_u32_e32 v178, s48, v149
	ds_read_b128 v[142:145], v162
	ds_read_b128 v[154:157], v162 offset:1024
	ds_read_b128 v[158:161], v162 offset:2048
	ds_read_b128 v[162:165], v162 offset:3072
	ds_read_b128 v[166:169], v178
	ds_read_b128 v[170:173], v178 offset:1024
	ds_read_b128 v[174:177], v178 offset:2048
	ds_read_b128 v[178:181], v178 offset:3072
	s_add_u32 s20, s20, 0x40000
	s_addc_u32 s21, s21, 0
	s_mov_b32 m0, s27
	v_lshl_add_u64 v[224:225], s[20:21], 0, v[128:129]
	ds_read_b128 v[182:185], v153 offset:32768
	ds_read_b128 v[190:193], v153 offset:33792
	ds_read_b128 v[198:201], v153 offset:34816
	ds_read_b128 v[202:205], v153 offset:35840
	ds_read_b128 v[206:209], v153 offset:36864
	ds_read_b128 v[210:213], v153 offset:37888
	ds_read_b128 v[214:217], v153 offset:38912
	ds_read_b128 v[218:221], v153 offset:39936
	global_load_lds_dwordx4 v[224:225], off
	v_lshl_add_u64 v[224:225], s[20:21], 0, v[132:133]
	s_mov_b32 m0, s28
	s_nop 0
	global_load_lds_dwordx4 v[224:225], off
	s_waitcnt vmcnt(8)
	s_waitcnt lgkmcnt(0)
	s_barrier
	s_waitcnt lgkmcnt(0)
	v_mfma_f32_16x16x32_bf16 v[124:127], v[142:145], v[182:185], v[124:127]
	v_mfma_f32_16x16x32_bf16 v[120:123], v[158:161], v[182:185], v[120:123]
	v_mfma_f32_16x16x32_bf16 v[112:115], v[158:161], v[198:201], v[112:115]
	v_mfma_f32_16x16x32_bf16 v[116:119], v[142:145], v[198:201], v[116:119]
	v_mfma_f32_16x16x32_bf16 v[96:99], v[142:145], v[206:209], v[96:99]
	v_mfma_f32_16x16x32_bf16 v[88:91], v[158:161], v[206:209], v[88:91]
	v_mfma_f32_16x16x32_bf16 v[72:75], v[158:161], v[214:217], v[72:75]
	v_mfma_f32_16x16x32_bf16 v[80:83], v[142:145], v[214:217], v[80:83]
	v_mfma_f32_16x16x32_bf16 v[124:127], v[154:157], v[190:193], v[124:127]
	v_mfma_f32_16x16x32_bf16 v[120:123], v[162:165], v[190:193], v[120:123]
	v_mfma_f32_16x16x32_bf16 v[112:115], v[162:165], v[202:205], v[112:115]
	v_mfma_f32_16x16x32_bf16 v[116:119], v[154:157], v[202:205], v[116:119]
	v_mfma_f32_16x16x32_bf16 v[96:99], v[154:157], v[210:213], v[96:99]
	v_mfma_f32_16x16x32_bf16 v[88:91], v[162:165], v[210:213], v[88:91]
	v_mfma_f32_16x16x32_bf16 v[72:75], v[162:165], v[218:221], v[72:75]
	v_mfma_f32_16x16x32_bf16 v[80:83], v[154:157], v[218:221], v[80:83]
	v_mfma_f32_16x16x32_bf16 v[108:111], v[166:169], v[182:185], v[108:111]
	v_mfma_f32_16x16x32_bf16 v[104:107], v[174:177], v[182:185], v[104:107]
	v_mfma_f32_16x16x32_bf16 v[92:95], v[174:177], v[198:201], v[92:95]
	v_mfma_f32_16x16x32_bf16 v[100:103], v[166:169], v[198:201], v[100:103]
	v_mfma_f32_16x16x32_bf16 v[84:87], v[166:169], v[206:209], v[84:87]
	v_mfma_f32_16x16x32_bf16 v[76:79], v[174:177], v[206:209], v[76:79]
	v_mfma_f32_16x16x32_bf16 v[64:67], v[174:177], v[214:217], v[64:67]
	v_mfma_f32_16x16x32_bf16 v[68:71], v[166:169], v[214:217], v[68:71]
	v_mfma_f32_16x16x32_bf16 v[108:111], v[170:173], v[190:193], v[108:111]
	v_mfma_f32_16x16x32_bf16 v[104:107], v[178:181], v[190:193], v[104:107]
	v_mfma_f32_16x16x32_bf16 v[92:95], v[178:181], v[202:205], v[92:95]
	v_mfma_f32_16x16x32_bf16 v[100:103], v[170:173], v[202:205], v[100:103]
	v_mfma_f32_16x16x32_bf16 v[84:87], v[170:173], v[210:213], v[84:87]
	v_mfma_f32_16x16x32_bf16 v[76:79], v[178:181], v[210:213], v[76:79]
	v_mfma_f32_16x16x32_bf16 v[64:67], v[178:181], v[218:221], v[64:67]
	v_mfma_f32_16x16x32_bf16 v[68:71], v[170:173], v[218:221], v[68:71]
	s_barrier
; #define PG8_STAGE(bufoff, gbase, voff) do { _Pragma("unroll") for (int _i = 0; _i < 2; ++_i) \
;         __builtin_amdgcn_global_load_lds((const unsigned*)((const char*)(gbase) + (voff)[_i]), (LAS unsigned*)(lds + (bufoff) + ldsw + _i * 8192), 16, 0, 0); } while (0)
; #define PG8_LDA(dst, b, h) do { _Pragma("unroll") for (int m = 0; m < 4; ++m) _Pragma("unroll") for (int k = 0; k < 2; ++k) dst[m][k] = *(const LAS bf16x8*)(lds + PG8_SA(b, h) + aoff + m * 2048 + k * 1024); } while (0)
; #define PG8_LDB(dst, b, h) do { _Pragma("unroll") for (int n = 0; n < 2; ++n) _Pragma("unroll") for (int k = 0; k < 2; ++k) dst[n][k] = *(const LAS bf16x8*)(lds + PG8_SB(b, h) + boff + n * 2048 + k * 1024); } while (0)
; #define PG8_WAIT_V(n) asm volatile("s_waitcnt vmcnt(" #n ")" ::: "memory")
; #define PG8_WAIT_L(n) asm volatile("s_waitcnt lgkmcnt(" #n ")" ::: "memory")
; template <class Epi>
; __device__ __forceinline__ void gemm_phase(LAS unsigned char* lds, const Gemm g, const StaticOrder& S, const Epi& E) {
;     ...
;         for (int t = 0; t < nt; t += 2) {
;             const bool last = (t == nt - 2);
;             const char* a1 = cA + (size_t)(t + 1) * kstep;
;             const char* a2 = last ? nA : cA + (size_t)(t + 2) * kstep; const char* b2 = last ? nB : cB + (size_t)(t + 2) * kstep;
;             const char* a3 = a2 + kstep; const char* b3 = b2 + kstep;
;             PG8_LDB(B0, 0, 0); PG8_LDB(B1, 0, 1); PG8_SCHED; PG8_LDA(At, 0, 0); PG8_STAGE(PG8_SA(1, 1), a1 + hstepA, voffA);
;             PG8_WAIT_V(8); PG8_WAIT_L(0); PG8_BAR; PG8_MMA(0, 0, At, B0); PG8_MMA(0, 1, At, B1); PG8_BAR; PG8_SCHED;
;             PG8_LDA(At, 0, 1); PG8_STAGE(PG8_SB(0, 0), b2, voffB); PG8_STAGE(PG8_SB(0, 1), b2 + hstepB, voffB); PG8_STAGE(PG8_SA(0, 0), a2, voffA);
;             PG8_WAIT_V(8); PG8_WAIT_L(0); PG8_BAR; PG8_MMA(1, 0, At, B0); PG8_MMA(1, 1, At, B1); PG8_BAR; PG8_SCHED;
;             PG8_LDB(B0, 1, 0); PG8_LDB(B1, 1, 1); PG8_SCHED; PG8_LDA(At, 1, 0); PG8_STAGE(PG8_SA(0, 1), a2 + hstepA, voffA);
;             PG8_WAIT_V(8); PG8_WAIT_L(0); PG8_BAR; PG8_MMA(0, 0, At, B0); PG8_MMA(0, 1, At, B1); PG8_BAR; PG8_SCHED;
;             PG8_LDA(At, 1, 1); PG8_STAGE(PG8_SB(1, 0), b3, voffB); PG8_STAGE(PG8_SB(1, 1), b3 + hstepB, voffB); PG8_STAGE(PG8_SA(1, 0), a3, voffA);
;             PG8_WAIT_V(8); PG8_WAIT_L(0); PG8_BAR; PG8_MMA(1, 0, At, B0); PG8_MMA(1, 1, At, B1); PG8_BAR; PG8_SCHED;
	s_add_i32 s20, s47, s22
	v_lshl_add_u64 v[146:147], v[146:147], 0, s[8:9]
	s_mov_b32 m0, s20
	ds_read_b128 v[182:185], v153 offset:49152
	ds_read_b128 v[190:193], v153 offset:50176
	ds_read_b128 v[198:201], v153 offset:51200
	ds_read_b128 v[202:205], v153 offset:52224
	ds_read_b128 v[206:209], v153 offset:53248
	ds_read_b128 v[210:213], v153 offset:54272
	ds_read_b128 v[214:217], v153 offset:55296
	ds_read_b128 v[218:221], v153 offset:56320
	global_load_lds_dwordx4 v[146:147], off
	s_add_i32 m0, s20, 0x2000
	s_add_u32 s2, s2, 0x20080
	v_lshl_add_u64 v[146:147], v[186:187], 0, s[8:9]
	s_addc_u32 s3, s3, 0
	s_add_i32 s20, s48, s22
	global_load_lds_dwordx4 v[146:147], off
	v_lshl_add_u64 v[146:147], s[2:3], 0, v[130:131]
	s_mov_b32 m0, s20
	s_nop 0
	global_load_lds_dwordx4 v[146:147], off
	v_lshl_add_u64 v[146:147], s[2:3], 0, v[134:135]
	s_add_i32 m0, s20, 0x2000
	s_nop 0
	global_load_lds_dwordx4 v[146:147], off
	v_lshl_add_u64 v[146:147], v[194:195], 0, s[8:9]
	s_mov_b32 m0, s30
	s_nop 0
	global_load_lds_dwordx4 v[146:147], off
	v_lshl_add_u64 v[146:147], v[222:223], 0, s[8:9]
	s_mov_b32 m0, s31
	s_nop 0
	global_load_lds_dwordx4 v[146:147], off
	s_waitcnt vmcnt(8)
	s_waitcnt lgkmcnt(0)
	s_barrier
	s_waitcnt lgkmcnt(0)
	v_mfma_f32_16x16x32_bf16 v[60:63], v[142:145], v[182:185], v[60:63]
	v_mfma_f32_16x16x32_bf16 v[56:59], v[158:161], v[182:185], v[56:59]
	v_mfma_f32_16x16x32_bf16 v[40:43], v[158:161], v[198:201], v[40:43]
	v_mfma_f32_16x16x32_bf16 v[48:51], v[142:145], v[198:201], v[48:51]
	v_mfma_f32_16x16x32_bf16 v[32:35], v[142:145], v[206:209], v[32:35]
	v_mfma_f32_16x16x32_bf16 v[24:27], v[158:161], v[206:209], v[24:27]
	v_mfma_f32_16x16x32_bf16 v[8:11], v[158:161], v[214:217], v[8:11]
	v_mfma_f32_16x16x32_bf16 v[16:19], v[142:145], v[214:217], v[16:19]
	v_mfma_f32_16x16x32_bf16 v[60:63], v[154:157], v[190:193], v[60:63]
	v_mfma_f32_16x16x32_bf16 v[56:59], v[162:165], v[190:193], v[56:59]
	v_mfma_f32_16x16x32_bf16 v[40:43], v[162:165], v[202:205], v[40:43]
	v_mfma_f32_16x16x32_bf16 v[48:51], v[154:157], v[202:205], v[48:51]
	v_mfma_f32_16x16x32_bf16 v[32:35], v[154:157], v[210:213], v[32:35]
	v_mfma_f32_16x16x32_bf16 v[24:27], v[162:165], v[210:213], v[24:27]
	v_mfma_f32_16x16x32_bf16 v[8:11], v[162:165], v[218:221], v[8:11]
	v_mfma_f32_16x16x32_bf16 v[16:19], v[154:157], v[218:221], v[16:19]
	v_mfma_f32_16x16x32_bf16 v[52:55], v[166:169], v[182:185], v[52:55]
	v_mfma_f32_16x16x32_bf16 v[44:47], v[174:177], v[182:185], v[44:47]
	v_mfma_f32_16x16x32_bf16 v[28:31], v[174:177], v[198:201], v[28:31]
	v_mfma_f32_16x16x32_bf16 v[36:39], v[166:169], v[198:201], v[36:39]
	v_mfma_f32_16x16x32_bf16 v[20:23], v[166:169], v[206:209], v[20:23]
	v_mfma_f32_16x16x32_bf16 v[12:15], v[174:177], v[206:209], v[12:15]
	v_mfma_f32_16x16x32_bf16 v[0:3], v[174:177], v[214:217], v[0:3]
	v_mfma_f32_16x16x32_bf16 v[4:7], v[166:169], v[214:217], v[4:7]
	v_mfma_f32_16x16x32_bf16 v[52:55], v[170:173], v[190:193], v[52:55]
	v_mfma_f32_16x16x32_bf16 v[44:47], v[178:181], v[190:193], v[44:47]
	v_mfma_f32_16x16x32_bf16 v[28:31], v[178:181], v[202:205], v[28:31]
	v_mfma_f32_16x16x32_bf16 v[36:39], v[170:173], v[202:205], v[36:39]
	v_mfma_f32_16x16x32_bf16 v[20:23], v[170:173], v[210:213], v[20:23]
	v_mfma_f32_16x16x32_bf16 v[12:15], v[178:181], v[210:213], v[12:15]
	v_mfma_f32_16x16x32_bf16 v[0:3], v[178:181], v[218:221], v[0:3]
	v_mfma_f32_16x16x32_bf16 v[4:7], v[170:173], v[218:221], v[4:7]
	s_barrier
	s_add_i32 s46, s46, 2
	s_add_u32 s18, s18, 0x100
	s_addc_u32 s19, s19, 0
	s_add_u32 s44, s44, 0x100
	s_addc_u32 s45, s45, 0
	s_cmp_gt_u32 s46, 5
	s_cbranch_scc0 .LBB0_697
.LBB0_697:
	ds_read_b128 v[142:145], v151
	ds_read_b128 v[154:157], v151 offset:1024
	ds_read_b128 v[158:161], v151 offset:2048
	ds_read_b128 v[162:165], v151 offset:3072
	ds_read_b128 v[166:169], v152
	ds_read_b128 v[170:173], v152 offset:1024
	ds_read_b128 v[174:177], v152 offset:2048
	ds_read_b128 v[178:181], v152 offset:3072
	s_add_u32 s2, s18, 0xfffc0080
	s_addc_u32 s3, s19, -1
	s_cmp_eq_u32 s46, 4
	s_cselect_b32 s21, s41, s3
	s_cselect_b32 s20, s42, s2
	s_cselect_b32 s3, s13, s45
	s_cselect_b32 s2, s43, s44
	v_lshl_add_u64 v[146:147], s[18:19], 0, v[136:137]
	s_add_i32 m0, s23, 0xc000
	ds_read_b128 v[182:185], v153
	ds_read_b128 v[190:193], v153 offset:1024
	ds_read_b128 v[198:201], v153 offset:2048
	ds_read_b128 v[202:205], v153 offset:3072
	ds_read_b128 v[206:209], v153 offset:4096
	ds_read_b128 v[210:213], v153 offset:5120
	ds_read_b128 v[214:217], v153 offset:6144
	ds_read_b128 v[218:221], v153 offset:7168
	global_load_lds_dwordx4 v[146:147], off
	v_lshl_add_u64 v[146:147], s[18:19], 0, v[138:139]
	s_add_i32 m0, s23, 0xe000
	s_nop 0
	global_load_lds_dwordx4 v[146:147], off
	s_waitcnt vmcnt(8)
	s_waitcnt lgkmcnt(0)
	s_barrier
; #define PG8_STAGE(bufoff, gbase, voff) do { _Pragma("unroll") for (int _i = 0; _i < 2; ++_i) \
;         __builtin_amdgcn_global_load_lds((const unsigned*)((const char*)(gbase) + (voff)[_i]), (LAS unsigned*)(lds + (bufoff) + ldsw + _i * 8192), 16, 0, 0); } while (0)
; #define PG8_LDA(dst, b, h) do { _Pragma("unroll") for (int m = 0; m < 4; ++m) _Pragma("unroll") for (int k = 0; k < 2; ++k) dst[m][k] = *(const LAS bf16x8*)(lds + PG8_SA(b, h) + aoff + m * 2048 + k * 1024); } while (0)
; #define PG8_MMA(ai, bj, At, Bt) do { __builtin_amdgcn_s_setprio(1); _Pragma("unroll") for (int m = 0; m < 4; ++m) _Pragma("unroll") for (int n = 0; n < 2; ++n) _Pragma("unroll") for (int k = 0; k < 2; ++k) \
;         acc[ai][bj][m][n] = __builtin_amdgcn_mfma_f32_16x16x32_bf16(Bt[n][k], At[m][k], acc[ai][bj][m][n], 0, 0, 0); __builtin_amdgcn_s_setprio(0); } while (0)
; #define PG8_WAIT_V(n) asm volatile("s_waitcnt vmcnt(" #n ")" ::: "memory")
; #define PG8_WAIT_L(n) asm volatile("s_waitcnt lgkmcnt(" #n ")" ::: "memory")
; #define PG8_BAR __builtin_amdgcn_s_barrier()
; #define PG8_SCHED __builtin_amdgcn_sched_barrier(0)
; template <class Epi>
; __device__ __forceinline__ void gemm_phase(LAS unsigned char* lds, const Gemm g, const StaticOrder& S, const Epi& E) {
;     ...
;             PG8_WAIT_V(8); PG8_WAIT_L(0); PG8_BAR; PG8_MMA(0, 0, At, B0); PG8_MMA(0, 1, At, B1); PG8_BAR; PG8_SCHED;
;             PG8_LDA(At, 0, 1); PG8_STAGE(PG8_SB(0, 0), b2, voffB); PG8_STAGE(PG8_SB(0, 1), b2 + hstepB, voffB); PG8_STAGE(PG8_SA(0, 0), a2, voffA);
;             PG8_WAIT_V(8); PG8_WAIT_L(0); PG8_BAR; PG8_MMA(1, 0, At, B0); PG8_MMA(1, 1, At, B1); PG8_BAR; PG8_SCHED;
	s_waitcnt lgkmcnt(0)
	v_mfma_f32_16x16x32_bf16 v[124:127], v[142:145], v[182:185], v[124:127]
	v_mfma_f32_16x16x32_bf16 v[120:123], v[158:161], v[182:185], v[120:123]
	v_mfma_f32_16x16x32_bf16 v[112:115], v[158:161], v[198:201], v[112:115]
	v_mfma_f32_16x16x32_bf16 v[116:119], v[142:145], v[198:201], v[116:119]
	v_mfma_f32_16x16x32_bf16 v[96:99], v[142:145], v[206:209], v[96:99]
	v_mfma_f32_16x16x32_bf16 v[88:91], v[158:161], v[206:209], v[88:91]
	v_mfma_f32_16x16x32_bf16 v[72:75], v[158:161], v[214:217], v[72:75]
	v_mfma_f32_16x16x32_bf16 v[80:83], v[142:145], v[214:217], v[80:83]
	v_mfma_f32_16x16x32_bf16 v[124:127], v[154:157], v[190:193], v[124:127]
	v_mfma_f32_16x16x32_bf16 v[120:123], v[162:165], v[190:193], v[120:123]
	v_mfma_f32_16x16x32_bf16 v[112:115], v[162:165], v[202:205], v[112:115]
	v_mfma_f32_16x16x32_bf16 v[116:119], v[154:157], v[202:205], v[116:119]
	v_mfma_f32_16x16x32_bf16 v[96:99], v[154:157], v[210:213], v[96:99]
	v_mfma_f32_16x16x32_bf16 v[88:91], v[162:165], v[210:213], v[88:91]
	v_mfma_f32_16x16x32_bf16 v[72:75], v[162:165], v[218:221], v[72:75]
	v_mfma_f32_16x16x32_bf16 v[80:83], v[154:157], v[218:221], v[80:83]
	v_mfma_f32_16x16x32_bf16 v[108:111], v[166:169], v[182:185], v[108:111]
	v_mfma_f32_16x16x32_bf16 v[104:107], v[174:177], v[182:185], v[104:107]
	v_mfma_f32_16x16x32_bf16 v[92:95], v[174:177], v[198:201], v[92:95]
	v_mfma_f32_16x16x32_bf16 v[100:103], v[166:169], v[198:201], v[100:103]
	v_mfma_f32_16x16x32_bf16 v[84:87], v[166:169], v[206:209], v[84:87]
	v_mfma_f32_16x16x32_bf16 v[76:79], v[174:177], v[206:209], v[76:79]
	v_mfma_f32_16x16x32_bf16 v[64:67], v[174:177], v[214:217], v[64:67]
	v_mfma_f32_16x16x32_bf16 v[68:71], v[166:169], v[214:217], v[68:71]
	v_mfma_f32_16x16x32_bf16 v[108:111], v[170:173], v[190:193], v[108:111]
	v_mfma_f32_16x16x32_bf16 v[104:107], v[178:181], v[190:193], v[104:107]
	v_mfma_f32_16x16x32_bf16 v[92:95], v[178:181], v[202:205], v[92:95]
	v_mfma_f32_16x16x32_bf16 v[100:103], v[170:173], v[202:205], v[100:103]
	v_mfma_f32_16x16x32_bf16 v[84:87], v[170:173], v[210:213], v[84:87]
	v_mfma_f32_16x16x32_bf16 v[76:79], v[178:181], v[210:213], v[76:79]
	v_mfma_f32_16x16x32_bf16 v[64:67], v[178:181], v[218:221], v[64:67]
	v_mfma_f32_16x16x32_bf16 v[68:71], v[170:173], v[218:221], v[68:71]
	s_barrier
	s_add_i32 s47, s35, s22
	v_lshl_add_u64 v[146:147], s[2:3], 0, v[130:131]
	s_mov_b32 m0, s47
	ds_read_b128 v[182:185], v153 offset:16384
	ds_read_b128 v[190:193], v153 offset:17408
	ds_read_b128 v[198:201], v153 offset:18432
	ds_read_b128 v[202:205], v153 offset:19456
	ds_read_b128 v[206:209], v153 offset:20480
	ds_read_b128 v[210:213], v153 offset:21504
	ds_read_b128 v[214:217], v153 offset:22528
	ds_read_b128 v[218:221], v153 offset:23552
	global_load_lds_dwordx4 v[146:147], off
	s_add_i32 m0, s47, 0x2000
	s_add_u32 s48, s2, 0x20000
	v_lshl_add_u64 v[186:187], s[2:3], 0, v[134:135]
	s_addc_u32 s49, s3, 0
	s_add_i32 s47, s36, s22
	global_load_lds_dwordx4 v[186:187], off
	v_lshl_add_u64 v[194:195], s[48:49], 0, v[130:131]
	s_mov_b32 m0, s47
	v_lshl_add_u64 v[222:223], s[20:21], 0, v[132:133]
	global_load_lds_dwordx4 v[194:195], off
	v_lshl_add_u64 v[194:195], s[48:49], 0, v[134:135]
	s_add_i32 m0, s47, 0x2000
	s_nop 0
	global_load_lds_dwordx4 v[194:195], off
	v_lshl_add_u64 v[194:195], s[20:21], 0, v[128:129]
	s_mov_b32 m0, s23
	s_nop 0
	global_load_lds_dwordx4 v[194:195], off
	s_mov_b32 m0, s26
	s_nop 0
	global_load_lds_dwordx4 v[222:223], off
	s_waitcnt vmcnt(8)
	s_waitcnt lgkmcnt(0)
	s_barrier
	s_waitcnt lgkmcnt(0)
	v_mfma_f32_16x16x32_bf16 v[60:63], v[142:145], v[182:185], v[60:63]
	v_mfma_f32_16x16x32_bf16 v[56:59], v[158:161], v[182:185], v[56:59]
	v_mfma_f32_16x16x32_bf16 v[40:43], v[158:161], v[198:201], v[40:43]
	v_mfma_f32_16x16x32_bf16 v[48:51], v[142:145], v[198:201], v[48:51]
	v_mfma_f32_16x16x32_bf16 v[32:35], v[142:145], v[206:209], v[32:35]
	v_mfma_f32_16x16x32_bf16 v[24:27], v[158:161], v[206:209], v[24:27]
	v_mfma_f32_16x16x32_bf16 v[8:11], v[158:161], v[214:217], v[8:11]
	v_mfma_f32_16x16x32_bf16 v[16:19], v[142:145], v[214:217], v[16:19]
	v_mfma_f32_16x16x32_bf16 v[60:63], v[154:157], v[190:193], v[60:63]
	v_mfma_f32_16x16x32_bf16 v[56:59], v[162:165], v[190:193], v[56:59]
	v_mfma_f32_16x16x32_bf16 v[40:43], v[162:165], v[202:205], v[40:43]
	v_mfma_f32_16x16x32_bf16 v[48:51], v[154:157], v[202:205], v[48:51]
	v_mfma_f32_16x16x32_bf16 v[32:35], v[154:157], v[210:213], v[32:35]
	v_mfma_f32_16x16x32_bf16 v[24:27], v[162:165], v[210:213], v[24:27]
	v_mfma_f32_16x16x32_bf16 v[8:11], v[162:165], v[218:221], v[8:11]
	v_mfma_f32_16x16x32_bf16 v[16:19], v[154:157], v[218:221], v[16:19]
	v_mfma_f32_16x16x32_bf16 v[52:55], v[166:169], v[182:185], v[52:55]
	v_mfma_f32_16x16x32_bf16 v[44:47], v[174:177], v[182:185], v[44:47]
	v_mfma_f32_16x16x32_bf16 v[28:31], v[174:177], v[198:201], v[28:31]
	v_mfma_f32_16x16x32_bf16 v[36:39], v[166:169], v[198:201], v[36:39]
	v_mfma_f32_16x16x32_bf16 v[20:23], v[166:169], v[206:209], v[20:23]
	v_mfma_f32_16x16x32_bf16 v[12:15], v[174:177], v[206:209], v[12:15]
	v_mfma_f32_16x16x32_bf16 v[0:3], v[174:177], v[214:217], v[0:3]
	v_mfma_f32_16x16x32_bf16 v[4:7], v[166:169], v[214:217], v[4:7]
	v_mfma_f32_16x16x32_bf16 v[52:55], v[170:173], v[190:193], v[52:55]
	v_mfma_f32_16x16x32_bf16 v[44:47], v[178:181], v[190:193], v[44:47]
	v_mfma_f32_16x16x32_bf16 v[28:31], v[178:181], v[202:205], v[28:31]
	v_mfma_f32_16x16x32_bf16 v[36:39], v[170:173], v[202:205], v[36:39]
	v_mfma_f32_16x16x32_bf16 v[20:23], v[170:173], v[210:213], v[20:23]
	v_mfma_f32_16x16x32_bf16 v[12:15], v[178:181], v[210:213], v[12:15]
	v_mfma_f32_16x16x32_bf16 v[0:3], v[178:181], v[218:221], v[0:3]
	v_mfma_f32_16x16x32_bf16 v[4:7], v[170:173], v[218:221], v[4:7]
	s_barrier
; #define PG8_STAGE(bufoff, gbase, voff) do { _Pragma("unroll") for (int _i = 0; _i < 2; ++_i) \
;         __builtin_amdgcn_global_load_lds((const unsigned*)((const char*)(gbase) + (voff)[_i]), (LAS unsigned*)(lds + (bufoff) + ldsw + _i * 8192), 16, 0, 0); } while (0)
; #define PG8_LDA(dst, b, h) do { _Pragma("unroll") for (int m = 0; m < 4; ++m) _Pragma("unroll") for (int k = 0; k < 2; ++k) dst[m][k] = *(const LAS bf16x8*)(lds + PG8_SA(b, h) + aoff + m * 2048 + k * 1024); } while (0)
; #define PG8_LDB(dst, b, h) do { _Pragma("unroll") for (int n = 0; n < 2; ++n) _Pragma("unroll") for (int k = 0; k < 2; ++k) dst[n][k] = *(const LAS bf16x8*)(lds + PG8_SB(b, h) + boff + n * 2048 + k * 1024); } while (0)
; #define PG8_MMA(ai, bj, At, Bt) do { __builtin_amdgcn_s_setprio(1); _Pragma("unroll") for (int m = 0; m < 4; ++m) _Pragma("unroll") for (int n = 0; n < 2; ++n) _Pragma("unroll") for (int k = 0; k < 2; ++k) \
;         acc[ai][bj][m][n] = __builtin_amdgcn_mfma_f32_16x16x32_bf16(Bt[n][k], At[m][k], acc[ai][bj][m][n], 0, 0, 0); __builtin_amdgcn_s_setprio(0); } while (0)
; #define PG8_WAIT_V(n) asm volatile("s_waitcnt vmcnt(" #n ")" ::: "memory")
; #define PG8_WAIT_L(n) asm volatile("s_waitcnt lgkmcnt(" #n ")" ::: "memory")
; #define PG8_BAR __builtin_amdgcn_s_barrier()
; #define PG8_SCHED __builtin_amdgcn_sched_barrier(0)
; template <class Epi>
; __device__ __forceinline__ void gemm_phase(LAS unsigned char* lds, const Gemm g, const StaticOrder& S, const Epi& E) {
;     ...
;             PG8_LDB(B0, 1, 0); PG8_LDB(B1, 1, 1); PG8_SCHED; PG8_LDA(At, 1, 0); PG8_STAGE(PG8_SA(0, 1), a2 + hstepA, voffA);
;             PG8_WAIT_V(8); PG8_WAIT_L(0); PG8_BAR; PG8_MMA(0, 0, At, B0); PG8_MMA(0, 1, At, B1); PG8_BAR; PG8_SCHED;
	s_add_i32 s47, 0, 0x18000
	s_add_i32 s48, 0, 0x1c000
	v_add_u32_e32 v162, s47, v149
	v_add_u32_e32 v178, s48, v149
	ds_read_b128 v[142:145], v162
	ds_read_b128 v[154:157], v162 offset:1024
	ds_read_b128 v[158:161], v162 offset:2048
	ds_read_b128 v[162:165], v162 offset:3072
	ds_read_b128 v[166:169], v178
	ds_read_b128 v[170:173], v178 offset:1024
	ds_read_b128 v[174:177], v178 offset:2048
	ds_read_b128 v[178:181], v178 offset:3072
	s_add_u32 s20, s20, 0x40000
	s_addc_u32 s21, s21, 0
	s_mov_b32 m0, s27
	v_lshl_add_u64 v[224:225], s[20:21], 0, v[128:129]
	ds_read_b128 v[182:185], v153 offset:32768
	ds_read_b128 v[190:193], v153 offset:33792
	ds_read_b128 v[198:201], v153 offset:34816
	ds_read_b128 v[202:205], v153 offset:35840
	ds_read_b128 v[206:209], v153 offset:36864
	ds_read_b128 v[210:213], v153 offset:37888
	ds_read_b128 v[214:217], v153 offset:38912
	ds_read_b128 v[218:221], v153 offset:39936
	global_load_lds_dwordx4 v[224:225], off
	v_lshl_add_u64 v[224:225], s[20:21], 0, v[132:133]
	s_mov_b32 m0, s28
	s_nop 0
	global_load_lds_dwordx4 v[224:225], off
	s_waitcnt vmcnt(8)
	s_waitcnt lgkmcnt(0)
	s_barrier
	s_waitcnt lgkmcnt(0)
	v_mfma_f32_16x16x32_bf16 v[124:127], v[142:145], v[182:185], v[124:127]
	v_mfma_f32_16x16x32_bf16 v[120:123], v[158:161], v[182:185], v[120:123]
	v_mfma_f32_16x16x32_bf16 v[112:115], v[158:161], v[198:201], v[112:115]
	v_mfma_f32_16x16x32_bf16 v[116:119], v[142:145], v[198:201], v[116:119]
	v_mfma_f32_16x16x32_bf16 v[96:99], v[142:145], v[206:209], v[96:99]
	v_mfma_f32_16x16x32_bf16 v[88:91], v[158:161], v[206:209], v[88:91]
	v_mfma_f32_16x16x32_bf16 v[72:75], v[158:161], v[214:217], v[72:75]
	v_mfma_f32_16x16x32_bf16 v[80:83], v[142:145], v[214:217], v[80:83]
	v_mfma_f32_16x16x32_bf16 v[124:127], v[154:157], v[190:193], v[124:127]
	v_mfma_f32_16x16x32_bf16 v[120:123], v[162:165], v[190:193], v[120:123]
	v_mfma_f32_16x16x32_bf16 v[112:115], v[162:165], v[202:205], v[112:115]
	v_mfma_f32_16x16x32_bf16 v[116:119], v[154:157], v[202:205], v[116:119]
	v_mfma_f32_16x16x32_bf16 v[96:99], v[154:157], v[210:213], v[96:99]
	v_mfma_f32_16x16x32_bf16 v[88:91], v[162:165], v[210:213], v[88:91]
	v_mfma_f32_16x16x32_bf16 v[72:75], v[162:165], v[218:221], v[72:75]
	v_mfma_f32_16x16x32_bf16 v[80:83], v[154:157], v[218:221], v[80:83]
	v_mfma_f32_16x16x32_bf16 v[108:111], v[166:169], v[182:185], v[108:111]
	v_mfma_f32_16x16x32_bf16 v[104:107], v[174:177], v[182:185], v[104:107]
	v_mfma_f32_16x16x32_bf16 v[92:95], v[174:177], v[198:201], v[92:95]
	v_mfma_f32_16x16x32_bf16 v[100:103], v[166:169], v[198:201], v[100:103]
	v_mfma_f32_16x16x32_bf16 v[84:87], v[166:169], v[206:209], v[84:87]
	v_mfma_f32_16x16x32_bf16 v[76:79], v[174:177], v[206:209], v[76:79]
	v_mfma_f32_16x16x32_bf16 v[64:67], v[174:177], v[214:217], v[64:67]
	v_mfma_f32_16x16x32_bf16 v[68:71], v[166:169], v[214:217], v[68:71]
	v_mfma_f32_16x16x32_bf16 v[108:111], v[170:173], v[190:193], v[108:111]
	v_mfma_f32_16x16x32_bf16 v[104:107], v[178:181], v[190:193], v[104:107]
	v_mfma_f32_16x16x32_bf16 v[92:95], v[178:181], v[202:205], v[92:95]
	v_mfma_f32_16x16x32_bf16 v[100:103], v[170:173], v[202:205], v[100:103]
	v_mfma_f32_16x16x32_bf16 v[84:87], v[170:173], v[210:213], v[84:87]
	v_mfma_f32_16x16x32_bf16 v[76:79], v[178:181], v[210:213], v[76:79]
	v_mfma_f32_16x16x32_bf16 v[64:67], v[178:181], v[218:221], v[64:67]
	v_mfma_f32_16x16x32_bf16 v[68:71], v[170:173], v[218:221], v[68:71]
	s_barrier
; #define PG8_STAGE(bufoff, gbase, voff) do { _Pragma("unroll") for (int _i = 0; _i < 2; ++_i) \
;         __builtin_amdgcn_global_load_lds((const unsigned*)((const char*)(gbase) + (voff)[_i]), (LAS unsigned*)(lds + (bufoff) + ldsw + _i * 8192), 16, 0, 0); } while (0)
; #define PG8_LDA(dst, b, h) do { _Pragma("unroll") for (int m = 0; m < 4; ++m) _Pragma("unroll") for (int k = 0; k < 2; ++k) dst[m][k] = *(const LAS bf16x8*)(lds + PG8_SA(b, h) + aoff + m * 2048 + k * 1024); } while (0)
; #define PG8_MMA(ai, bj, At, Bt) do { __builtin_amdgcn_s_setprio(1); _Pragma("unroll") for (int m = 0; m < 4; ++m) _Pragma("unroll") for (int n = 0; n < 2; ++n) _Pragma("unroll") for (int k = 0; k < 2; ++k) \
;         acc[ai][bj][m][n] = __builtin_amdgcn_mfma_f32_16x16x32_bf16(Bt[n][k], At[m][k], acc[ai][bj][m][n], 0, 0, 0); __builtin_amdgcn_s_setprio(0); } while (0)
; #define PG8_WAIT_V(n) asm volatile("s_waitcnt vmcnt(" #n ")" ::: "memory")
; #define PG8_WAIT_L(n) asm volatile("s_waitcnt lgkmcnt(" #n ")" ::: "memory")
; #define PG8_BAR __builtin_amdgcn_s_barrier()
; #define PG8_SCHED __builtin_amdgcn_sched_barrier(0)
; template <class Epi>
; __device__ __forceinline__ void gemm_phase(LAS unsigned char* lds, const Gemm g, const StaticOrder& S, const Epi& E) {
;     ...
;             PG8_LDA(At, 1, 1); PG8_STAGE(PG8_SB(1, 0), b3, voffB); PG8_STAGE(PG8_SB(1, 1), b3 + hstepB, voffB); PG8_STAGE(PG8_SA(1, 0), a3, voffA);
;             PG8_WAIT_V(8); PG8_WAIT_L(0); PG8_BAR; PG8_MMA(1, 0, At, B0); PG8_MMA(1, 1, At, B1); PG8_BAR; PG8_SCHED;
;         }
;         if (wr == 0) PG8_BAR;
	s_add_i32 s20, s47, s22
	v_lshl_add_u64 v[146:147], v[146:147], 0, s[8:9]
	s_mov_b32 m0, s20
	ds_read_b128 v[182:185], v153 offset:49152
	ds_read_b128 v[190:193], v153 offset:50176
	ds_read_b128 v[198:201], v153 offset:51200
	ds_read_b128 v[202:205], v153 offset:52224
	ds_read_b128 v[206:209], v153 offset:53248
	ds_read_b128 v[210:213], v153 offset:54272
	ds_read_b128 v[214:217], v153 offset:55296
	ds_read_b128 v[218:221], v153 offset:56320
	global_load_lds_dwordx4 v[146:147], off
	s_add_i32 m0, s20, 0x2000
	s_add_u32 s2, s2, 0x20080
	v_lshl_add_u64 v[146:147], v[186:187], 0, s[8:9]
	s_addc_u32 s3, s3, 0
	s_add_i32 s20, s48, s22
	global_load_lds_dwordx4 v[146:147], off
	v_lshl_add_u64 v[146:147], s[2:3], 0, v[130:131]
	s_mov_b32 m0, s20
	s_nop 0
	global_load_lds_dwordx4 v[146:147], off
	v_lshl_add_u64 v[146:147], s[2:3], 0, v[134:135]
	s_add_i32 m0, s20, 0x2000
	s_nop 0
	global_load_lds_dwordx4 v[146:147], off
	v_lshl_add_u64 v[146:147], v[194:195], 0, s[8:9]
	s_mov_b32 m0, s30
	s_nop 0
	global_load_lds_dwordx4 v[146:147], off
	v_lshl_add_u64 v[146:147], v[222:223], 0, s[8:9]
	s_mov_b32 m0, s31
	s_nop 0
	global_load_lds_dwordx4 v[146:147], off
	s_waitcnt vmcnt(8)
	s_waitcnt lgkmcnt(0)
	s_barrier
	s_waitcnt lgkmcnt(0)
	v_mfma_f32_16x16x32_bf16 v[60:63], v[142:145], v[182:185], v[60:63]
	v_mfma_f32_16x16x32_bf16 v[56:59], v[158:161], v[182:185], v[56:59]
	v_mfma_f32_16x16x32_bf16 v[40:43], v[158:161], v[198:201], v[40:43]
	v_mfma_f32_16x16x32_bf16 v[48:51], v[142:145], v[198:201], v[48:51]
	v_mfma_f32_16x16x32_bf16 v[32:35], v[142:145], v[206:209], v[32:35]
	v_mfma_f32_16x16x32_bf16 v[24:27], v[158:161], v[206:209], v[24:27]
	v_mfma_f32_16x16x32_bf16 v[8:11], v[158:161], v[214:217], v[8:11]
	v_mfma_f32_16x16x32_bf16 v[16:19], v[142:145], v[214:217], v[16:19]
	v_mfma_f32_16x16x32_bf16 v[60:63], v[154:157], v[190:193], v[60:63]
	v_mfma_f32_16x16x32_bf16 v[56:59], v[162:165], v[190:193], v[56:59]
	v_mfma_f32_16x16x32_bf16 v[40:43], v[162:165], v[202:205], v[40:43]
	v_mfma_f32_16x16x32_bf16 v[48:51], v[154:157], v[202:205], v[48:51]
	v_mfma_f32_16x16x32_bf16 v[32:35], v[154:157], v[210:213], v[32:35]
	v_mfma_f32_16x16x32_bf16 v[24:27], v[162:165], v[210:213], v[24:27]
	v_mfma_f32_16x16x32_bf16 v[8:11], v[162:165], v[218:221], v[8:11]
	v_mfma_f32_16x16x32_bf16 v[16:19], v[154:157], v[218:221], v[16:19]
	v_mfma_f32_16x16x32_bf16 v[52:55], v[166:169], v[182:185], v[52:55]
	v_mfma_f32_16x16x32_bf16 v[44:47], v[174:177], v[182:185], v[44:47]
	v_mfma_f32_16x16x32_bf16 v[28:31], v[174:177], v[198:201], v[28:31]
	v_mfma_f32_16x16x32_bf16 v[36:39], v[166:169], v[198:201], v[36:39]
	v_mfma_f32_16x16x32_bf16 v[20:23], v[166:169], v[206:209], v[20:23]
	v_mfma_f32_16x16x32_bf16 v[12:15], v[174:177], v[206:209], v[12:15]
	v_mfma_f32_16x16x32_bf16 v[0:3], v[174:177], v[214:217], v[0:3]
	v_mfma_f32_16x16x32_bf16 v[4:7], v[166:169], v[214:217], v[4:7]
	v_mfma_f32_16x16x32_bf16 v[52:55], v[170:173], v[190:193], v[52:55]
	v_mfma_f32_16x16x32_bf16 v[44:47], v[178:181], v[190:193], v[44:47]
	v_mfma_f32_16x16x32_bf16 v[28:31], v[178:181], v[202:205], v[28:31]
	v_mfma_f32_16x16x32_bf16 v[36:39], v[170:173], v[202:205], v[36:39]
	v_mfma_f32_16x16x32_bf16 v[20:23], v[170:173], v[210:213], v[20:23]
	v_mfma_f32_16x16x32_bf16 v[12:15], v[178:181], v[210:213], v[12:15]
	v_mfma_f32_16x16x32_bf16 v[0:3], v[178:181], v[218:221], v[0:3]
	v_mfma_f32_16x16x32_bf16 v[4:7], v[170:173], v[218:221], v[4:7]
	s_barrier
	s_add_i32 s46, s46, 2
	s_add_u32 s18, s18, 0x100
	s_addc_u32 s19, s19, 0
	s_add_u32 s44, s44, 0x100
	s_addc_u32 s45, s45, 0
	s_cmp_gt_u32 s46, 5
	s_cbranch_scc0 .LBB0_697
	s_and_b64 vcc, exec, s[10:11]
	s_cbranch_vccz .LBB0_700
	s_barrier

; #define PG8_STAGE(bufoff, gbase, voff) do { _Pragma("unroll") for (int _i = 0; _i < 2; ++_i) \
;         __builtin_amdgcn_global_load_lds((const unsigned*)((const char*)(gbase) + (voff)[_i]), (LAS unsigned*)(lds + (bufoff) + ldsw + _i * 8192), 16, 0, 0); } while (0)
; #define PG8_LDA(dst, b, h) do { _Pragma("unroll") for (int m = 0; m < 4; ++m) _Pragma("unroll") for (int k = 0; k < 2; ++k) dst[m][k] = *(const LAS bf16x8*)(lds + PG8_SA(b, h) + aoff + m * 2048 + k * 1024); } while (0)
; #define PG8_LDB(dst, b, h) do { _Pragma("unroll") for (int n = 0; n < 2; ++n) _Pragma("unroll") for (int k = 0; k < 2; ++k) dst[n][k] = *(const LAS bf16x8*)(lds + PG8_SB(b, h) + boff + n * 2048 + k * 1024); } while (0)
; #define PG8_MMA(ai, bj, At, Bt) do { __builtin_amdgcn_s_setprio(1); _Pragma("unroll") for (int m = 0; m < 4; ++m) _Pragma("unroll") for (int n = 0; n < 2; ++n) _Pragma("unroll") for (int k = 0; k < 2; ++k) \
;         acc[ai][bj][m][n] = __builtin_amdgcn_mfma_f32_16x16x32_bf16(Bt[n][k], At[m][k], acc[ai][bj][m][n], 0, 0, 0); __builtin_amdgcn_s_setprio(0); } while (0)
; #define PG8_WAIT_V(n) asm volatile("s_waitcnt vmcnt(" #n ")" ::: "memory")
; #define PG8_WAIT_L(n) asm volatile("s_waitcnt lgkmcnt(" #n ")" ::: "memory")
; #define PG8_BAR __builtin_amdgcn_s_barrier()
; #define PG8_SCHED __builtin_amdgcn_sched_barrier(0)
; template <class Epi>
; __device__ __forceinline__ void gemm_phase(LAS unsigned char* lds, const Gemm g, const StaticOrder& S, const Epi& E) {
;     ...
;         const char* nA = has_next ? (const char*)g.A + (size_t)(nxt.pm >> 5) * aslab + (size_t)(nxt.pm & 31) * tstepA : cA; const char* nB = has_next ? (const char*)g.Bt + (size_t)nxt.pn * tstepB : cB;
;         for (int t = 0; t < nt; t += 2) {
;             const bool last = (t == nt - 2);
;             const char* a1 = cA + (size_t)(t + 1) * kstep;
;             const char* a2 = last ? nA : cA + (size_t)(t + 2) * kstep; const char* b2 = last ? nB : cB + (size_t)(t + 2) * kstep;
;             const char* a3 = a2 + kstep; const char* b3 = b2 + kstep;
;             PG8_LDB(B0, 0, 0); PG8_LDB(B1, 0, 1); PG8_SCHED; PG8_LDA(At, 0, 0); PG8_STAGE(PG8_SA(1, 1), a1 + hstepA, voffA);
;             PG8_WAIT_V(8); PG8_WAIT_L(0); PG8_BAR; PG8_MMA(0, 0, At, B0); PG8_MMA(0, 1, At, B1); PG8_BAR; PG8_SCHED;
.LBB0_720:
	s_ashr_i32 s16, s41, 5
	s_ashr_i32 s17, s16, 31
	s_lshl_b64 s[16:17], s[16:17], 24
	s_add_u32 s15, s24, s16
	s_addc_u32 s17, s25, s17
	s_lshl_b32 s16, s41, 19
	s_and_b32 s16, s16, 0xf80000
	s_add_u32 s16, s15, s16
	s_addc_u32 s17, s17, 0
	s_and_b64 s[18:19], s[4:5], exec
	s_cselect_b32 s44, s17, s21
	s_cselect_b32 s45, s16, s20
	s_ashr_i32 s15, s14, 31
	s_lshl_b64 s[18:19], s[14:15], 18
	v_readlane_b32 s22, v235, 27
	v_readlane_b32 s23, v235, 28
	s_add_u32 s18, s22, s18
	s_addc_u32 s19, s23, s19
	s_and_b64 s[22:23], s[4:5], exec
	s_cselect_b32 s15, s19, s3
	s_cselect_b32 s46, s18, s2
	s_add_u32 s20, s20, 0x40080
	s_addc_u32 s21, s21, 0
	s_add_u32 s47, s2, 0x100
	s_addc_u32 s48, s3, 0
	s_mov_b32 s49, -2
	s_waitcnt vmcnt(0)
	ds_read_b128 v[128:131], v167
	ds_read_b128 v[132:135], v167 offset:1024
	ds_read_b128 v[136:139], v167 offset:2048
	ds_read_b128 v[140:143], v167 offset:3072
	ds_read_b128 v[158:161], v168
	ds_read_b128 v[170:173], v168 offset:1024
	ds_read_b128 v[174:177], v168 offset:2048
	ds_read_b128 v[178:181], v168 offset:3072
	s_add_u32 s2, s20, 0xfffc0080
	s_addc_u32 s3, s21, -1
	s_cmp_eq_u32 s49, 4
	s_cselect_b32 s23, s44, s3
	s_cselect_b32 s22, s45, s2
	s_cselect_b32 s3, s15, s48
	s_cselect_b32 s2, s46, s47
	v_lshl_add_u64 v[162:163], s[20:21], 0, v[152:153]
	s_add_i32 m0, s27, 0xc000
	ds_read_b128 v[182:185], v169
	ds_read_b128 v[190:193], v169 offset:1024
	ds_read_b128 v[198:201], v169 offset:2048
	ds_read_b128 v[202:205], v169 offset:3072
	ds_read_b128 v[206:209], v169 offset:4096
	ds_read_b128 v[210:213], v169 offset:5120
	ds_read_b128 v[214:217], v169 offset:6144
	ds_read_b128 v[218:221], v169 offset:7168
	global_load_lds_dwordx4 v[162:163], off
	v_lshl_add_u64 v[162:163], s[20:21], 0, v[154:155]
	s_add_i32 m0, s27, 0xe000
	s_nop 0
	global_load_lds_dwordx4 v[162:163], off
	s_waitcnt vmcnt(8)
	s_waitcnt lgkmcnt(0)
	s_barrier
	s_waitcnt lgkmcnt(0)
	v_mfma_f32_16x16x32_bf16 v[124:127], v[128:131], v[182:185], 0
	v_mfma_f32_16x16x32_bf16 v[120:123], v[136:139], v[182:185], 0
	v_mfma_f32_16x16x32_bf16 v[104:107], v[136:139], v[198:201], 0
	v_mfma_f32_16x16x32_bf16 v[112:115], v[128:131], v[198:201], 0
	v_mfma_f32_16x16x32_bf16 v[96:99], v[128:131], v[206:209], 0
	v_mfma_f32_16x16x32_bf16 v[88:91], v[136:139], v[206:209], 0
	v_mfma_f32_16x16x32_bf16 v[72:75], v[136:139], v[214:217], 0
	v_mfma_f32_16x16x32_bf16 v[80:83], v[128:131], v[214:217], 0
	v_mfma_f32_16x16x32_bf16 v[124:127], v[132:135], v[190:193], v[124:127]
	v_mfma_f32_16x16x32_bf16 v[120:123], v[140:143], v[190:193], v[120:123]
	v_mfma_f32_16x16x32_bf16 v[104:107], v[140:143], v[202:205], v[104:107]
	v_mfma_f32_16x16x32_bf16 v[112:115], v[132:135], v[202:205], v[112:115]
	v_mfma_f32_16x16x32_bf16 v[96:99], v[132:135], v[210:213], v[96:99]
	v_mfma_f32_16x16x32_bf16 v[88:91], v[140:143], v[210:213], v[88:91]
	v_mfma_f32_16x16x32_bf16 v[72:75], v[140:143], v[218:221], v[72:75]
	v_mfma_f32_16x16x32_bf16 v[80:83], v[132:135], v[218:221], v[80:83]
	v_mfma_f32_16x16x32_bf16 v[116:119], v[158:161], v[182:185], 0
	v_mfma_f32_16x16x32_bf16 v[108:111], v[174:177], v[182:185], 0
	v_mfma_f32_16x16x32_bf16 v[92:95], v[174:177], v[198:201], 0
	v_mfma_f32_16x16x32_bf16 v[100:103], v[158:161], v[198:201], 0
	v_mfma_f32_16x16x32_bf16 v[84:87], v[158:161], v[206:209], 0
	v_mfma_f32_16x16x32_bf16 v[76:79], v[174:177], v[206:209], 0
	v_mfma_f32_16x16x32_bf16 v[64:67], v[174:177], v[214:217], 0
	v_mfma_f32_16x16x32_bf16 v[68:71], v[158:161], v[214:217], 0
	v_mfma_f32_16x16x32_bf16 v[116:119], v[170:173], v[190:193], v[116:119]
	v_mfma_f32_16x16x32_bf16 v[108:111], v[178:181], v[190:193], v[108:111]
	v_mfma_f32_16x16x32_bf16 v[92:95], v[178:181], v[202:205], v[92:95]
	v_mfma_f32_16x16x32_bf16 v[100:103], v[170:173], v[202:205], v[100:103]
	v_mfma_f32_16x16x32_bf16 v[84:87], v[170:173], v[210:213], v[84:87]
	v_mfma_f32_16x16x32_bf16 v[76:79], v[178:181], v[210:213], v[76:79]
	v_mfma_f32_16x16x32_bf16 v[64:67], v[178:181], v[218:221], v[64:67]
	v_mfma_f32_16x16x32_bf16 v[68:71], v[170:173], v[218:221], v[68:71]
	s_barrier
	s_add_i32 s50, s37, s26
	v_lshl_add_u64 v[162:163], s[2:3], 0, v[146:147]
	s_mov_b32 m0, s50
	ds_read_b128 v[182:185], v169 offset:16384
	ds_read_b128 v[190:193], v169 offset:17408
	ds_read_b128 v[198:201], v169 offset:18432
	ds_read_b128 v[202:205], v169 offset:19456
	ds_read_b128 v[206:209], v169 offset:20480
	ds_read_b128 v[210:213], v169 offset:21504
	ds_read_b128 v[214:217], v169 offset:22528
	ds_read_b128 v[218:221], v169 offset:23552
	global_load_lds_dwordx4 v[162:163], off
	s_add_i32 m0, s50, 0x2000
	s_add_u32 s50, s2, 0x20000
	v_lshl_add_u64 v[186:187], s[2:3], 0, v[150:151]
	s_addc_u32 s51, s3, 0
	s_add_i32 s52, s38, s26
	global_load_lds_dwordx4 v[186:187], off
	v_lshl_add_u64 v[194:195], s[50:51], 0, v[146:147]
	s_mov_b32 m0, s52
	v_lshl_add_u64 v[222:223], s[22:23], 0, v[148:149]
	global_load_lds_dwordx4 v[194:195], off
	v_lshl_add_u64 v[194:195], s[50:51], 0, v[150:151]
	s_add_i32 m0, s52, 0x2000
	s_nop 0
	global_load_lds_dwordx4 v[194:195], off
	v_lshl_add_u64 v[194:195], s[22:23], 0, v[144:145]
	s_mov_b32 m0, s27
	s_nop 0
	global_load_lds_dwordx4 v[194:195], off
	s_mov_b32 m0, s28
	s_nop 0
	global_load_lds_dwordx4 v[222:223], off
	s_waitcnt vmcnt(8)
	s_waitcnt lgkmcnt(0)
	s_barrier
; #define PG8_STAGE(bufoff, gbase, voff) do { _Pragma("unroll") for (int _i = 0; _i < 2; ++_i) \
;         __builtin_amdgcn_global_load_lds((const unsigned*)((const char*)(gbase) + (voff)[_i]), (LAS unsigned*)(lds + (bufoff) + ldsw + _i * 8192), 16, 0, 0); } while (0)
; #define PG8_LDA(dst, b, h) do { _Pragma("unroll") for (int m = 0; m < 4; ++m) _Pragma("unroll") for (int k = 0; k < 2; ++k) dst[m][k] = *(const LAS bf16x8*)(lds + PG8_SA(b, h) + aoff + m * 2048 + k * 1024); } while (0)
; #define PG8_LDB(dst, b, h) do { _Pragma("unroll") for (int n = 0; n < 2; ++n) _Pragma("unroll") for (int k = 0; k < 2; ++k) dst[n][k] = *(const LAS bf16x8*)(lds + PG8_SB(b, h) + boff + n * 2048 + k * 1024); } while (0)
; #define PG8_MMA(ai, bj, At, Bt) do { __builtin_amdgcn_s_setprio(1); _Pragma("unroll") for (int m = 0; m < 4; ++m) _Pragma("unroll") for (int n = 0; n < 2; ++n) _Pragma("unroll") for (int k = 0; k < 2; ++k) \
;         acc[ai][bj][m][n] = __builtin_amdgcn_mfma_f32_16x16x32_bf16(Bt[n][k], At[m][k], acc[ai][bj][m][n], 0, 0, 0); __builtin_amdgcn_s_setprio(0); } while (0)
; #define PG8_WAIT_V(n) asm volatile("s_waitcnt vmcnt(" #n ")" ::: "memory")
; #define PG8_WAIT_L(n) asm volatile("s_waitcnt lgkmcnt(" #n ")" ::: "memory")
; #define PG8_BAR __builtin_amdgcn_s_barrier()
; #define PG8_SCHED __builtin_amdgcn_sched_barrier(0)
; template <class Epi>
; __device__ __forceinline__ void gemm_phase(LAS unsigned char* lds, const Gemm g, const StaticOrder& S, const Epi& E) {
;     ...
;             PG8_WAIT_V(8); PG8_WAIT_L(0); PG8_BAR; PG8_MMA(0, 0, At, B0); PG8_MMA(0, 1, At, B1); PG8_BAR; PG8_SCHED;
;             PG8_LDA(At, 0, 1); PG8_STAGE(PG8_SB(0, 0), b2, voffB); PG8_STAGE(PG8_SB(0, 1), b2 + hstepB, voffB); PG8_STAGE(PG8_SA(0, 0), a2, voffA);
;             PG8_WAIT_V(8); PG8_WAIT_L(0); PG8_BAR; PG8_MMA(1, 0, At, B0); PG8_MMA(1, 1, At, B1); PG8_BAR; PG8_SCHED;
;             PG8_LDB(B0, 1, 0); PG8_LDB(B1, 1, 1); PG8_SCHED; PG8_LDA(At, 1, 0); PG8_STAGE(PG8_SA(0, 1), a2 + hstepA, voffA);
;             PG8_WAIT_V(8); PG8_WAIT_L(0); PG8_BAR; PG8_MMA(0, 0, At, B0); PG8_MMA(0, 1, At, B1); PG8_BAR; PG8_SCHED;
	s_waitcnt lgkmcnt(0)
	v_mfma_f32_16x16x32_bf16 v[60:63], v[128:131], v[182:185], 0
	v_mfma_f32_16x16x32_bf16 v[56:59], v[136:139], v[182:185], 0
	v_mfma_f32_16x16x32_bf16 v[40:43], v[136:139], v[198:201], 0
	v_mfma_f32_16x16x32_bf16 v[48:51], v[128:131], v[198:201], 0
	v_mfma_f32_16x16x32_bf16 v[32:35], v[128:131], v[206:209], 0
	v_mfma_f32_16x16x32_bf16 v[24:27], v[136:139], v[206:209], 0
	v_mfma_f32_16x16x32_bf16 v[8:11], v[136:139], v[214:217], 0
	v_mfma_f32_16x16x32_bf16 v[16:19], v[128:131], v[214:217], 0
	v_mfma_f32_16x16x32_bf16 v[60:63], v[132:135], v[190:193], v[60:63]
	v_mfma_f32_16x16x32_bf16 v[56:59], v[140:143], v[190:193], v[56:59]
	v_mfma_f32_16x16x32_bf16 v[40:43], v[140:143], v[202:205], v[40:43]
	v_mfma_f32_16x16x32_bf16 v[48:51], v[132:135], v[202:205], v[48:51]
	v_mfma_f32_16x16x32_bf16 v[32:35], v[132:135], v[210:213], v[32:35]
	v_mfma_f32_16x16x32_bf16 v[24:27], v[140:143], v[210:213], v[24:27]
	v_mfma_f32_16x16x32_bf16 v[8:11], v[140:143], v[218:221], v[8:11]
	v_mfma_f32_16x16x32_bf16 v[16:19], v[132:135], v[218:221], v[16:19]
	v_mfma_f32_16x16x32_bf16 v[52:55], v[158:161], v[182:185], 0
	v_mfma_f32_16x16x32_bf16 v[44:47], v[174:177], v[182:185], 0
	v_mfma_f32_16x16x32_bf16 v[28:31], v[174:177], v[198:201], 0
	v_mfma_f32_16x16x32_bf16 v[36:39], v[158:161], v[198:201], 0
	v_mfma_f32_16x16x32_bf16 v[20:23], v[158:161], v[206:209], 0
	v_mfma_f32_16x16x32_bf16 v[12:15], v[174:177], v[206:209], 0
	v_mfma_f32_16x16x32_bf16 v[0:3], v[174:177], v[214:217], 0
	v_mfma_f32_16x16x32_bf16 v[4:7], v[158:161], v[214:217], 0
	v_mfma_f32_16x16x32_bf16 v[52:55], v[170:173], v[190:193], v[52:55]
	v_mfma_f32_16x16x32_bf16 v[44:47], v[178:181], v[190:193], v[44:47]
	v_mfma_f32_16x16x32_bf16 v[28:31], v[178:181], v[202:205], v[28:31]
	v_mfma_f32_16x16x32_bf16 v[36:39], v[170:173], v[202:205], v[36:39]
	v_mfma_f32_16x16x32_bf16 v[20:23], v[170:173], v[210:213], v[20:23]
	v_mfma_f32_16x16x32_bf16 v[12:15], v[178:181], v[210:213], v[12:15]
	v_mfma_f32_16x16x32_bf16 v[0:3], v[178:181], v[218:221], v[0:3]
	v_mfma_f32_16x16x32_bf16 v[4:7], v[170:173], v[218:221], v[4:7]
	s_barrier
	s_add_i32 s50, 0, 0x18000
	s_add_i32 s51, 0, 0x1c000
	v_add_u32_e32 v140, s50, v165
	v_add_u32_e32 v178, s51, v165
	ds_read_b128 v[128:131], v140
	ds_read_b128 v[132:135], v140 offset:1024
	ds_read_b128 v[136:139], v140 offset:2048
	ds_read_b128 v[140:143], v140 offset:3072
	ds_read_b128 v[158:161], v178
	ds_read_b128 v[170:173], v178 offset:1024
	ds_read_b128 v[174:177], v178 offset:2048
	ds_read_b128 v[178:181], v178 offset:3072
	s_add_u32 s22, s22, 0x40000
	s_addc_u32 s23, s23, 0
	s_mov_b32 m0, s29
	v_lshl_add_u64 v[224:225], s[22:23], 0, v[144:145]
	ds_read_b128 v[182:185], v169 offset:32768
	ds_read_b128 v[190:193], v169 offset:33792
	ds_read_b128 v[198:201], v169 offset:34816
	ds_read_b128 v[202:205], v169 offset:35840
	ds_read_b128 v[206:209], v169 offset:36864
	ds_read_b128 v[210:213], v169 offset:37888
	ds_read_b128 v[214:217], v169 offset:38912
	ds_read_b128 v[218:221], v169 offset:39936
	global_load_lds_dwordx4 v[224:225], off
	v_lshl_add_u64 v[224:225], s[22:23], 0, v[148:149]
	s_mov_b32 m0, s30
	s_nop 0
	global_load_lds_dwordx4 v[224:225], off
	s_waitcnt vmcnt(8)
	s_waitcnt lgkmcnt(0)
	s_barrier
	s_waitcnt lgkmcnt(0)
	v_mfma_f32_16x16x32_bf16 v[124:127], v[128:131], v[182:185], v[124:127]
	v_mfma_f32_16x16x32_bf16 v[120:123], v[136:139], v[182:185], v[120:123]
	v_mfma_f32_16x16x32_bf16 v[104:107], v[136:139], v[198:201], v[104:107]
	v_mfma_f32_16x16x32_bf16 v[112:115], v[128:131], v[198:201], v[112:115]
	v_mfma_f32_16x16x32_bf16 v[96:99], v[128:131], v[206:209], v[96:99]
	v_mfma_f32_16x16x32_bf16 v[88:91], v[136:139], v[206:209], v[88:91]
	v_mfma_f32_16x16x32_bf16 v[72:75], v[136:139], v[214:217], v[72:75]
	v_mfma_f32_16x16x32_bf16 v[80:83], v[128:131], v[214:217], v[80:83]
	v_mfma_f32_16x16x32_bf16 v[124:127], v[132:135], v[190:193], v[124:127]
	v_mfma_f32_16x16x32_bf16 v[120:123], v[140:143], v[190:193], v[120:123]
	v_mfma_f32_16x16x32_bf16 v[104:107], v[140:143], v[202:205], v[104:107]
	v_mfma_f32_16x16x32_bf16 v[112:115], v[132:135], v[202:205], v[112:115]
	v_mfma_f32_16x16x32_bf16 v[96:99], v[132:135], v[210:213], v[96:99]
	v_mfma_f32_16x16x32_bf16 v[88:91], v[140:143], v[210:213], v[88:91]
	v_mfma_f32_16x16x32_bf16 v[72:75], v[140:143], v[218:221], v[72:75]
	v_mfma_f32_16x16x32_bf16 v[80:83], v[132:135], v[218:221], v[80:83]
	v_mfma_f32_16x16x32_bf16 v[116:119], v[158:161], v[182:185], v[116:119]
	v_mfma_f32_16x16x32_bf16 v[108:111], v[174:177], v[182:185], v[108:111]
	v_mfma_f32_16x16x32_bf16 v[92:95], v[174:177], v[198:201], v[92:95]
	v_mfma_f32_16x16x32_bf16 v[100:103], v[158:161], v[198:201], v[100:103]
	v_mfma_f32_16x16x32_bf16 v[84:87], v[158:161], v[206:209], v[84:87]
	v_mfma_f32_16x16x32_bf16 v[76:79], v[174:177], v[206:209], v[76:79]
	v_mfma_f32_16x16x32_bf16 v[64:67], v[174:177], v[214:217], v[64:67]
	v_mfma_f32_16x16x32_bf16 v[68:71], v[158:161], v[214:217], v[68:71]
	v_mfma_f32_16x16x32_bf16 v[116:119], v[170:173], v[190:193], v[116:119]
	v_mfma_f32_16x16x32_bf16 v[108:111], v[178:181], v[190:193], v[108:111]
	v_mfma_f32_16x16x32_bf16 v[92:95], v[178:181], v[202:205], v[92:95]
	v_mfma_f32_16x16x32_bf16 v[100:103], v[170:173], v[202:205], v[100:103]
	v_mfma_f32_16x16x32_bf16 v[84:87], v[170:173], v[210:213], v[84:87]
	v_mfma_f32_16x16x32_bf16 v[76:79], v[178:181], v[210:213], v[76:79]
	v_mfma_f32_16x16x32_bf16 v[64:67], v[178:181], v[218:221], v[64:67]
	v_mfma_f32_16x16x32_bf16 v[68:71], v[170:173], v[218:221], v[68:71]
	s_barrier
; #define PG8_STAGE(bufoff, gbase, voff) do { _Pragma("unroll") for (int _i = 0; _i < 2; ++_i) \
;         __builtin_amdgcn_global_load_lds((const unsigned*)((const char*)(gbase) + (voff)[_i]), (LAS unsigned*)(lds + (bufoff) + ldsw + _i * 8192), 16, 0, 0); } while (0)
; #define PG8_LDA(dst, b, h) do { _Pragma("unroll") for (int m = 0; m < 4; ++m) _Pragma("unroll") for (int k = 0; k < 2; ++k) dst[m][k] = *(const LAS bf16x8*)(lds + PG8_SA(b, h) + aoff + m * 2048 + k * 1024); } while (0)
; #define PG8_LDB(dst, b, h) do { _Pragma("unroll") for (int n = 0; n < 2; ++n) _Pragma("unroll") for (int k = 0; k < 2; ++k) dst[n][k] = *(const LAS bf16x8*)(lds + PG8_SB(b, h) + boff + n * 2048 + k * 1024); } while (0)
; #define PG8_WAIT_V(n) asm volatile("s_waitcnt vmcnt(" #n ")" ::: "memory")
; #define PG8_WAIT_L(n) asm volatile("s_waitcnt lgkmcnt(" #n ")" ::: "memory")
; template <class Epi>
; __device__ __forceinline__ void gemm_phase(LAS unsigned char* lds, const Gemm g, const StaticOrder& S, const Epi& E) {
;     ...
;         for (int t = 0; t < nt; t += 2) {
;             const bool last = (t == nt - 2);
;             const char* a1 = cA + (size_t)(t + 1) * kstep;
;             const char* a2 = last ? nA : cA + (size_t)(t + 2) * kstep; const char* b2 = last ? nB : cB + (size_t)(t + 2) * kstep;
;             const char* a3 = a2 + kstep; const char* b3 = b2 + kstep;
;             PG8_LDB(B0, 0, 0); PG8_LDB(B1, 0, 1); PG8_SCHED; PG8_LDA(At, 0, 0); PG8_STAGE(PG8_SA(1, 1), a1 + hstepA, voffA);
;             PG8_WAIT_V(8); PG8_WAIT_L(0); PG8_BAR; PG8_MMA(0, 0, At, B0); PG8_MMA(0, 1, At, B1); PG8_BAR; PG8_SCHED;
;             PG8_LDA(At, 0, 1); PG8_STAGE(PG8_SB(0, 0), b2, voffB); PG8_STAGE(PG8_SB(0, 1), b2 + hstepB, voffB); PG8_STAGE(PG8_SA(0, 0), a2, voffA);
;             PG8_WAIT_V(8); PG8_WAIT_L(0); PG8_BAR; PG8_MMA(1, 0, At, B0); PG8_MMA(1, 1, At, B1); PG8_BAR; PG8_SCHED;
;             PG8_LDB(B0, 1, 0); PG8_LDB(B1, 1, 1); PG8_SCHED; PG8_LDA(At, 1, 0); PG8_STAGE(PG8_SA(0, 1), a2 + hstepA, voffA);
;             PG8_WAIT_V(8); PG8_WAIT_L(0); PG8_BAR; PG8_MMA(0, 0, At, B0); PG8_MMA(0, 1, At, B1); PG8_BAR; PG8_SCHED;
;             PG8_LDA(At, 1, 1); PG8_STAGE(PG8_SB(1, 0), b3, voffB); PG8_STAGE(PG8_SB(1, 1), b3 + hstepB, voffB); PG8_STAGE(PG8_SA(1, 0), a3, voffA);
;             PG8_WAIT_V(8); PG8_WAIT_L(0); PG8_BAR; PG8_MMA(1, 0, At, B0); PG8_MMA(1, 1, At, B1); PG8_BAR; PG8_SCHED;
	s_add_i32 s22, s50, s26
	v_lshl_add_u64 v[162:163], v[162:163], 0, s[10:11]
	s_mov_b32 m0, s22
	ds_read_b128 v[182:185], v169 offset:49152
	ds_read_b128 v[190:193], v169 offset:50176
	ds_read_b128 v[198:201], v169 offset:51200
	ds_read_b128 v[202:205], v169 offset:52224
	ds_read_b128 v[206:209], v169 offset:53248
	ds_read_b128 v[210:213], v169 offset:54272
	ds_read_b128 v[214:217], v169 offset:55296
	ds_read_b128 v[218:221], v169 offset:56320
	global_load_lds_dwordx4 v[162:163], off
	s_add_i32 m0, s22, 0x2000
	s_add_u32 s2, s2, 0x20080
	v_lshl_add_u64 v[162:163], v[186:187], 0, s[10:11]
	s_addc_u32 s3, s3, 0
	s_add_i32 s22, s51, s26
	global_load_lds_dwordx4 v[162:163], off
	v_lshl_add_u64 v[162:163], s[2:3], 0, v[146:147]
	s_mov_b32 m0, s22
	s_nop 0
	global_load_lds_dwordx4 v[162:163], off
	v_lshl_add_u64 v[162:163], s[2:3], 0, v[150:151]
	s_add_i32 m0, s22, 0x2000
	s_nop 0
	global_load_lds_dwordx4 v[162:163], off
	v_lshl_add_u64 v[162:163], v[194:195], 0, s[10:11]
	s_mov_b32 m0, s33
	s_nop 0
	global_load_lds_dwordx4 v[162:163], off
	v_lshl_add_u64 v[162:163], v[222:223], 0, s[10:11]
	s_mov_b32 m0, s34
	s_nop 0
	global_load_lds_dwordx4 v[162:163], off
	s_waitcnt vmcnt(8)
	s_waitcnt lgkmcnt(0)
	s_barrier
	s_waitcnt lgkmcnt(0)
	v_mfma_f32_16x16x32_bf16 v[60:63], v[128:131], v[182:185], v[60:63]
	v_mfma_f32_16x16x32_bf16 v[56:59], v[136:139], v[182:185], v[56:59]
	v_mfma_f32_16x16x32_bf16 v[40:43], v[136:139], v[198:201], v[40:43]
	v_mfma_f32_16x16x32_bf16 v[48:51], v[128:131], v[198:201], v[48:51]
	v_mfma_f32_16x16x32_bf16 v[32:35], v[128:131], v[206:209], v[32:35]
	v_mfma_f32_16x16x32_bf16 v[24:27], v[136:139], v[206:209], v[24:27]
	v_mfma_f32_16x16x32_bf16 v[8:11], v[136:139], v[214:217], v[8:11]
	v_mfma_f32_16x16x32_bf16 v[16:19], v[128:131], v[214:217], v[16:19]
	v_mfma_f32_16x16x32_bf16 v[60:63], v[132:135], v[190:193], v[60:63]
	v_mfma_f32_16x16x32_bf16 v[56:59], v[140:143], v[190:193], v[56:59]
	v_mfma_f32_16x16x32_bf16 v[40:43], v[140:143], v[202:205], v[40:43]
	v_mfma_f32_16x16x32_bf16 v[48:51], v[132:135], v[202:205], v[48:51]
	v_mfma_f32_16x16x32_bf16 v[32:35], v[132:135], v[210:213], v[32:35]
	v_mfma_f32_16x16x32_bf16 v[24:27], v[140:143], v[210:213], v[24:27]
	v_mfma_f32_16x16x32_bf16 v[8:11], v[140:143], v[218:221], v[8:11]
	v_mfma_f32_16x16x32_bf16 v[16:19], v[132:135], v[218:221], v[16:19]
	v_mfma_f32_16x16x32_bf16 v[52:55], v[158:161], v[182:185], v[52:55]
	v_mfma_f32_16x16x32_bf16 v[44:47], v[174:177], v[182:185], v[44:47]
	v_mfma_f32_16x16x32_bf16 v[28:31], v[174:177], v[198:201], v[28:31]
	v_mfma_f32_16x16x32_bf16 v[36:39], v[158:161], v[198:201], v[36:39]
	v_mfma_f32_16x16x32_bf16 v[20:23], v[158:161], v[206:209], v[20:23]
	v_mfma_f32_16x16x32_bf16 v[12:15], v[174:177], v[206:209], v[12:15]
	v_mfma_f32_16x16x32_bf16 v[0:3], v[174:177], v[214:217], v[0:3]
	v_mfma_f32_16x16x32_bf16 v[4:7], v[158:161], v[214:217], v[4:7]
	v_mfma_f32_16x16x32_bf16 v[52:55], v[170:173], v[190:193], v[52:55]
	v_mfma_f32_16x16x32_bf16 v[44:47], v[178:181], v[190:193], v[44:47]
	v_mfma_f32_16x16x32_bf16 v[28:31], v[178:181], v[202:205], v[28:31]
	v_mfma_f32_16x16x32_bf16 v[36:39], v[170:173], v[202:205], v[36:39]
	v_mfma_f32_16x16x32_bf16 v[20:23], v[170:173], v[210:213], v[20:23]
	v_mfma_f32_16x16x32_bf16 v[12:15], v[178:181], v[210:213], v[12:15]
	v_mfma_f32_16x16x32_bf16 v[0:3], v[178:181], v[218:221], v[0:3]
	v_mfma_f32_16x16x32_bf16 v[4:7], v[170:173], v[218:221], v[4:7]
	s_barrier
	s_add_i32 s49, s49, 2
	s_add_u32 s20, s20, 0x100
	s_addc_u32 s21, s21, 0
	s_add_u32 s47, s47, 0x100
	s_addc_u32 s48, s48, 0
	s_cmp_gt_u32 s49, 5
	s_cbranch_scc0 .LBB0_721
.LBB0_721:
	ds_read_b128 v[128:131], v167
	ds_read_b128 v[132:135], v167 offset:1024
	ds_read_b128 v[136:139], v167 offset:2048
	ds_read_b128 v[140:143], v167 offset:3072
	ds_read_b128 v[158:161], v168
	ds_read_b128 v[170:173], v168 offset:1024
	ds_read_b128 v[174:177], v168 offset:2048
	ds_read_b128 v[178:181], v168 offset:3072
	s_add_u32 s2, s20, 0xfffc0080
	s_addc_u32 s3, s21, -1
	s_cmp_eq_u32 s49, 4
	s_cselect_b32 s23, s44, s3
	s_cselect_b32 s22, s45, s2
	s_cselect_b32 s3, s15, s48
	s_cselect_b32 s2, s46, s47
	v_lshl_add_u64 v[162:163], s[20:21], 0, v[152:153]
	s_add_i32 m0, s27, 0xc000
	ds_read_b128 v[182:185], v169
	ds_read_b128 v[190:193], v169 offset:1024
	ds_read_b128 v[198:201], v169 offset:2048
	ds_read_b128 v[202:205], v169 offset:3072
	ds_read_b128 v[206:209], v169 offset:4096
	ds_read_b128 v[210:213], v169 offset:5120
	ds_read_b128 v[214:217], v169 offset:6144
	ds_read_b128 v[218:221], v169 offset:7168
	global_load_lds_dwordx4 v[162:163], off
	v_lshl_add_u64 v[162:163], s[20:21], 0, v[154:155]
	s_add_i32 m0, s27, 0xe000
	s_nop 0
	global_load_lds_dwordx4 v[162:163], off
	s_waitcnt vmcnt(8)
	s_waitcnt lgkmcnt(0)
	s_barrier
; #define PG8_STAGE(bufoff, gbase, voff) do { _Pragma("unroll") for (int _i = 0; _i < 2; ++_i) \
;         __builtin_amdgcn_global_load_lds((const unsigned*)((const char*)(gbase) + (voff)[_i]), (LAS unsigned*)(lds + (bufoff) + ldsw + _i * 8192), 16, 0, 0); } while (0)
; #define PG8_LDA(dst, b, h) do { _Pragma("unroll") for (int m = 0; m < 4; ++m) _Pragma("unroll") for (int k = 0; k < 2; ++k) dst[m][k] = *(const LAS bf16x8*)(lds + PG8_SA(b, h) + aoff + m * 2048 + k * 1024); } while (0)
; #define PG8_MMA(ai, bj, At, Bt) do { __builtin_amdgcn_s_setprio(1); _Pragma("unroll") for (int m = 0; m < 4; ++m) _Pragma("unroll") for (int n = 0; n < 2; ++n) _Pragma("unroll") for (int k = 0; k < 2; ++k) \
;         acc[ai][bj][m][n] = __builtin_amdgcn_mfma_f32_16x16x32_bf16(Bt[n][k], At[m][k], acc[ai][bj][m][n], 0, 0, 0); __builtin_amdgcn_s_setprio(0); } while (0)
; #define PG8_WAIT_V(n) asm volatile("s_waitcnt vmcnt(" #n ")" ::: "memory")
; #define PG8_WAIT_L(n) asm volatile("s_waitcnt lgkmcnt(" #n ")" ::: "memory")
; #define PG8_BAR __builtin_amdgcn_s_barrier()
; #define PG8_SCHED __builtin_amdgcn_sched_barrier(0)
; template <class Epi>
; __device__ __forceinline__ void gemm_phase(LAS unsigned char* lds, const Gemm g, const StaticOrder& S, const Epi& E) {
;     ...
;             PG8_WAIT_V(8); PG8_WAIT_L(0); PG8_BAR; PG8_MMA(0, 0, At, B0); PG8_MMA(0, 1, At, B1); PG8_BAR; PG8_SCHED;
;             PG8_LDA(At, 0, 1); PG8_STAGE(PG8_SB(0, 0), b2, voffB); PG8_STAGE(PG8_SB(0, 1), b2 + hstepB, voffB); PG8_STAGE(PG8_SA(0, 0), a2, voffA);
;             PG8_WAIT_V(8); PG8_WAIT_L(0); PG8_BAR; PG8_MMA(1, 0, At, B0); PG8_MMA(1, 1, At, B1); PG8_BAR; PG8_SCHED;
	s_waitcnt lgkmcnt(0)
	v_mfma_f32_16x16x32_bf16 v[124:127], v[128:131], v[182:185], v[124:127]
	v_mfma_f32_16x16x32_bf16 v[120:123], v[136:139], v[182:185], v[120:123]
	v_mfma_f32_16x16x32_bf16 v[104:107], v[136:139], v[198:201], v[104:107]
	v_mfma_f32_16x16x32_bf16 v[112:115], v[128:131], v[198:201], v[112:115]
	v_mfma_f32_16x16x32_bf16 v[96:99], v[128:131], v[206:209], v[96:99]
	v_mfma_f32_16x16x32_bf16 v[88:91], v[136:139], v[206:209], v[88:91]
	v_mfma_f32_16x16x32_bf16 v[72:75], v[136:139], v[214:217], v[72:75]
	v_mfma_f32_16x16x32_bf16 v[80:83], v[128:131], v[214:217], v[80:83]
	v_mfma_f32_16x16x32_bf16 v[124:127], v[132:135], v[190:193], v[124:127]
	v_mfma_f32_16x16x32_bf16 v[120:123], v[140:143], v[190:193], v[120:123]
	v_mfma_f32_16x16x32_bf16 v[104:107], v[140:143], v[202:205], v[104:107]
	v_mfma_f32_16x16x32_bf16 v[112:115], v[132:135], v[202:205], v[112:115]
	v_mfma_f32_16x16x32_bf16 v[96:99], v[132:135], v[210:213], v[96:99]
	v_mfma_f32_16x16x32_bf16 v[88:91], v[140:143], v[210:213], v[88:91]
	v_mfma_f32_16x16x32_bf16 v[72:75], v[140:143], v[218:221], v[72:75]
	v_mfma_f32_16x16x32_bf16 v[80:83], v[132:135], v[218:221], v[80:83]
	v_mfma_f32_16x16x32_bf16 v[116:119], v[158:161], v[182:185], v[116:119]
	v_mfma_f32_16x16x32_bf16 v[108:111], v[174:177], v[182:185], v[108:111]
	v_mfma_f32_16x16x32_bf16 v[92:95], v[174:177], v[198:201], v[92:95]
	v_mfma_f32_16x16x32_bf16 v[100:103], v[158:161], v[198:201], v[100:103]
	v_mfma_f32_16x16x32_bf16 v[84:87], v[158:161], v[206:209], v[84:87]
	v_mfma_f32_16x16x32_bf16 v[76:79], v[174:177], v[206:209], v[76:79]
	v_mfma_f32_16x16x32_bf16 v[64:67], v[174:177], v[214:217], v[64:67]
	v_mfma_f32_16x16x32_bf16 v[68:71], v[158:161], v[214:217], v[68:71]
	v_mfma_f32_16x16x32_bf16 v[116:119], v[170:173], v[190:193], v[116:119]
	v_mfma_f32_16x16x32_bf16 v[108:111], v[178:181], v[190:193], v[108:111]
	v_mfma_f32_16x16x32_bf16 v[92:95], v[178:181], v[202:205], v[92:95]
	v_mfma_f32_16x16x32_bf16 v[100:103], v[170:173], v[202:205], v[100:103]
	v_mfma_f32_16x16x32_bf16 v[84:87], v[170:173], v[210:213], v[84:87]
	v_mfma_f32_16x16x32_bf16 v[76:79], v[178:181], v[210:213], v[76:79]
	v_mfma_f32_16x16x32_bf16 v[64:67], v[178:181], v[218:221], v[64:67]
	v_mfma_f32_16x16x32_bf16 v[68:71], v[170:173], v[218:221], v[68:71]
	s_barrier
	s_add_i32 s50, s37, s26
	v_lshl_add_u64 v[162:163], s[2:3], 0, v[146:147]
	s_mov_b32 m0, s50
	ds_read_b128 v[182:185], v169 offset:16384
	ds_read_b128 v[190:193], v169 offset:17408
	ds_read_b128 v[198:201], v169 offset:18432
	ds_read_b128 v[202:205], v169 offset:19456
	ds_read_b128 v[206:209], v169 offset:20480
	ds_read_b128 v[210:213], v169 offset:21504
	ds_read_b128 v[214:217], v169 offset:22528
	ds_read_b128 v[218:221], v169 offset:23552
	global_load_lds_dwordx4 v[162:163], off
	s_add_i32 m0, s50, 0x2000
	s_add_u32 s50, s2, 0x20000
	v_lshl_add_u64 v[186:187], s[2:3], 0, v[150:151]
	s_addc_u32 s51, s3, 0
	s_add_i32 s52, s38, s26
	global_load_lds_dwordx4 v[186:187], off
	v_lshl_add_u64 v[194:195], s[50:51], 0, v[146:147]
	s_mov_b32 m0, s52
	v_lshl_add_u64 v[222:223], s[22:23], 0, v[148:149]
	global_load_lds_dwordx4 v[194:195], off
	v_lshl_add_u64 v[194:195], s[50:51], 0, v[150:151]
	s_add_i32 m0, s52, 0x2000
	s_nop 0
	global_load_lds_dwordx4 v[194:195], off
	v_lshl_add_u64 v[194:195], s[22:23], 0, v[144:145]
	s_mov_b32 m0, s27
	s_nop 0
	global_load_lds_dwordx4 v[194:195], off
	s_mov_b32 m0, s28
	s_nop 0
	global_load_lds_dwordx4 v[222:223], off
	s_waitcnt vmcnt(8)
	s_waitcnt lgkmcnt(0)
	s_barrier
	s_waitcnt lgkmcnt(0)
	v_mfma_f32_16x16x32_bf16 v[60:63], v[128:131], v[182:185], v[60:63]
	v_mfma_f32_16x16x32_bf16 v[56:59], v[136:139], v[182:185], v[56:59]
	v_mfma_f32_16x16x32_bf16 v[40:43], v[136:139], v[198:201], v[40:43]
	v_mfma_f32_16x16x32_bf16 v[48:51], v[128:131], v[198:201], v[48:51]
	v_mfma_f32_16x16x32_bf16 v[32:35], v[128:131], v[206:209], v[32:35]
	v_mfma_f32_16x16x32_bf16 v[24:27], v[136:139], v[206:209], v[24:27]
	v_mfma_f32_16x16x32_bf16 v[8:11], v[136:139], v[214:217], v[8:11]
	v_mfma_f32_16x16x32_bf16 v[16:19], v[128:131], v[214:217], v[16:19]
	v_mfma_f32_16x16x32_bf16 v[60:63], v[132:135], v[190:193], v[60:63]
	v_mfma_f32_16x16x32_bf16 v[56:59], v[140:143], v[190:193], v[56:59]
	v_mfma_f32_16x16x32_bf16 v[40:43], v[140:143], v[202:205], v[40:43]
	v_mfma_f32_16x16x32_bf16 v[48:51], v[132:135], v[202:205], v[48:51]
	v_mfma_f32_16x16x32_bf16 v[32:35], v[132:135], v[210:213], v[32:35]
	v_mfma_f32_16x16x32_bf16 v[24:27], v[140:143], v[210:213], v[24:27]
	v_mfma_f32_16x16x32_bf16 v[8:11], v[140:143], v[218:221], v[8:11]
	v_mfma_f32_16x16x32_bf16 v[16:19], v[132:135], v[218:221], v[16:19]
	v_mfma_f32_16x16x32_bf16 v[52:55], v[158:161], v[182:185], v[52:55]
	v_mfma_f32_16x16x32_bf16 v[44:47], v[174:177], v[182:185], v[44:47]
	v_mfma_f32_16x16x32_bf16 v[28:31], v[174:177], v[198:201], v[28:31]
	v_mfma_f32_16x16x32_bf16 v[36:39], v[158:161], v[198:201], v[36:39]
	v_mfma_f32_16x16x32_bf16 v[20:23], v[158:161], v[206:209], v[20:23]
	v_mfma_f32_16x16x32_bf16 v[12:15], v[174:177], v[206:209], v[12:15]
	v_mfma_f32_16x16x32_bf16 v[0:3], v[174:177], v[214:217], v[0:3]
	v_mfma_f32_16x16x32_bf16 v[4:7], v[158:161], v[214:217], v[4:7]
	v_mfma_f32_16x16x32_bf16 v[52:55], v[170:173], v[190:193], v[52:55]
	v_mfma_f32_16x16x32_bf16 v[44:47], v[178:181], v[190:193], v[44:47]
	v_mfma_f32_16x16x32_bf16 v[28:31], v[178:181], v[202:205], v[28:31]
	v_mfma_f32_16x16x32_bf16 v[36:39], v[170:173], v[202:205], v[36:39]
	v_mfma_f32_16x16x32_bf16 v[20:23], v[170:173], v[210:213], v[20:23]
	v_mfma_f32_16x16x32_bf16 v[12:15], v[178:181], v[210:213], v[12:15]
	v_mfma_f32_16x16x32_bf16 v[0:3], v[178:181], v[218:221], v[0:3]
	v_mfma_f32_16x16x32_bf16 v[4:7], v[170:173], v[218:221], v[4:7]
	s_barrier
; #define PG8_STAGE(bufoff, gbase, voff) do { _Pragma("unroll") for (int _i = 0; _i < 2; ++_i) \
;         __builtin_amdgcn_global_load_lds((const unsigned*)((const char*)(gbase) + (voff)[_i]), (LAS unsigned*)(lds + (bufoff) + ldsw + _i * 8192), 16, 0, 0); } while (0)
; #define PG8_LDA(dst, b, h) do { _Pragma("unroll") for (int m = 0; m < 4; ++m) _Pragma("unroll") for (int k = 0; k < 2; ++k) dst[m][k] = *(const LAS bf16x8*)(lds + PG8_SA(b, h) + aoff + m * 2048 + k * 1024); } while (0)
; #define PG8_LDB(dst, b, h) do { _Pragma("unroll") for (int n = 0; n < 2; ++n) _Pragma("unroll") for (int k = 0; k < 2; ++k) dst[n][k] = *(const LAS bf16x8*)(lds + PG8_SB(b, h) + boff + n * 2048 + k * 1024); } while (0)
; #define PG8_MMA(ai, bj, At, Bt) do { __builtin_amdgcn_s_setprio(1); _Pragma("unroll") for (int m = 0; m < 4; ++m) _Pragma("unroll") for (int n = 0; n < 2; ++n) _Pragma("unroll") for (int k = 0; k < 2; ++k) \
;         acc[ai][bj][m][n] = __builtin_amdgcn_mfma_f32_16x16x32_bf16(Bt[n][k], At[m][k], acc[ai][bj][m][n], 0, 0, 0); __builtin_amdgcn_s_setprio(0); } while (0)
; #define PG8_WAIT_V(n) asm volatile("s_waitcnt vmcnt(" #n ")" ::: "memory")
; #define PG8_WAIT_L(n) asm volatile("s_waitcnt lgkmcnt(" #n ")" ::: "memory")
; #define PG8_BAR __builtin_amdgcn_s_barrier()
; #define PG8_SCHED __builtin_amdgcn_sched_barrier(0)
; template <class Epi>
; __device__ __forceinline__ void gemm_phase(LAS unsigned char* lds, const Gemm g, const StaticOrder& S, const Epi& E) {
;     ...
;             PG8_LDB(B0, 1, 0); PG8_LDB(B1, 1, 1); PG8_SCHED; PG8_LDA(At, 1, 0); PG8_STAGE(PG8_SA(0, 1), a2 + hstepA, voffA);
;             PG8_WAIT_V(8); PG8_WAIT_L(0); PG8_BAR; PG8_MMA(0, 0, At, B0); PG8_MMA(0, 1, At, B1); PG8_BAR; PG8_SCHED;
	s_add_i32 s50, 0, 0x18000
	s_add_i32 s51, 0, 0x1c000
	v_add_u32_e32 v140, s50, v165
	v_add_u32_e32 v178, s51, v165
	ds_read_b128 v[128:131], v140
	ds_read_b128 v[132:135], v140 offset:1024
	ds_read_b128 v[136:139], v140 offset:2048
	ds_read_b128 v[140:143], v140 offset:3072
	ds_read_b128 v[158:161], v178
	ds_read_b128 v[170:173], v178 offset:1024
	ds_read_b128 v[174:177], v178 offset:2048
	ds_read_b128 v[178:181], v178 offset:3072
	s_add_u32 s22, s22, 0x40000
	s_addc_u32 s23, s23, 0
	s_mov_b32 m0, s29
	v_lshl_add_u64 v[224:225], s[22:23], 0, v[144:145]
	ds_read_b128 v[182:185], v169 offset:32768
	ds_read_b128 v[190:193], v169 offset:33792
	ds_read_b128 v[198:201], v169 offset:34816
	ds_read_b128 v[202:205], v169 offset:35840
	ds_read_b128 v[206:209], v169 offset:36864
	ds_read_b128 v[210:213], v169 offset:37888
	ds_read_b128 v[214:217], v169 offset:38912
	ds_read_b128 v[218:221], v169 offset:39936
	global_load_lds_dwordx4 v[224:225], off
	v_lshl_add_u64 v[224:225], s[22:23], 0, v[148:149]
	s_mov_b32 m0, s30
	s_nop 0
	global_load_lds_dwordx4 v[224:225], off
	s_waitcnt vmcnt(8)
	s_waitcnt lgkmcnt(0)
	s_barrier
	s_waitcnt lgkmcnt(0)
	v_mfma_f32_16x16x32_bf16 v[124:127], v[128:131], v[182:185], v[124:127]
	v_mfma_f32_16x16x32_bf16 v[120:123], v[136:139], v[182:185], v[120:123]
	v_mfma_f32_16x16x32_bf16 v[104:107], v[136:139], v[198:201], v[104:107]
	v_mfma_f32_16x16x32_bf16 v[112:115], v[128:131], v[198:201], v[112:115]
	v_mfma_f32_16x16x32_bf16 v[96:99], v[128:131], v[206:209], v[96:99]
	v_mfma_f32_16x16x32_bf16 v[88:91], v[136:139], v[206:209], v[88:91]
	v_mfma_f32_16x16x32_bf16 v[72:75], v[136:139], v[214:217], v[72:75]
	v_mfma_f32_16x16x32_bf16 v[80:83], v[128:131], v[214:217], v[80:83]
	v_mfma_f32_16x16x32_bf16 v[124:127], v[132:135], v[190:193], v[124:127]
	v_mfma_f32_16x16x32_bf16 v[120:123], v[140:143], v[190:193], v[120:123]
	v_mfma_f32_16x16x32_bf16 v[104:107], v[140:143], v[202:205], v[104:107]
	v_mfma_f32_16x16x32_bf16 v[112:115], v[132:135], v[202:205], v[112:115]
	v_mfma_f32_16x16x32_bf16 v[96:99], v[132:135], v[210:213], v[96:99]
	v_mfma_f32_16x16x32_bf16 v[88:91], v[140:143], v[210:213], v[88:91]
	v_mfma_f32_16x16x32_bf16 v[72:75], v[140:143], v[218:221], v[72:75]
	v_mfma_f32_16x16x32_bf16 v[80:83], v[132:135], v[218:221], v[80:83]
	v_mfma_f32_16x16x32_bf16 v[116:119], v[158:161], v[182:185], v[116:119]
	v_mfma_f32_16x16x32_bf16 v[108:111], v[174:177], v[182:185], v[108:111]
	v_mfma_f32_16x16x32_bf16 v[92:95], v[174:177], v[198:201], v[92:95]
	v_mfma_f32_16x16x32_bf16 v[100:103], v[158:161], v[198:201], v[100:103]
	v_mfma_f32_16x16x32_bf16 v[84:87], v[158:161], v[206:209], v[84:87]
	v_mfma_f32_16x16x32_bf16 v[76:79], v[174:177], v[206:209], v[76:79]
	v_mfma_f32_16x16x32_bf16 v[64:67], v[174:177], v[214:217], v[64:67]
	v_mfma_f32_16x16x32_bf16 v[68:71], v[158:161], v[214:217], v[68:71]
	v_mfma_f32_16x16x32_bf16 v[116:119], v[170:173], v[190:193], v[116:119]
	v_mfma_f32_16x16x32_bf16 v[108:111], v[178:181], v[190:193], v[108:111]
	v_mfma_f32_16x16x32_bf16 v[92:95], v[178:181], v[202:205], v[92:95]
	v_mfma_f32_16x16x32_bf16 v[100:103], v[170:173], v[202:205], v[100:103]
	v_mfma_f32_16x16x32_bf16 v[84:87], v[170:173], v[210:213], v[84:87]
	v_mfma_f32_16x16x32_bf16 v[76:79], v[178:181], v[210:213], v[76:79]
	v_mfma_f32_16x16x32_bf16 v[64:67], v[178:181], v[218:221], v[64:67]
	v_mfma_f32_16x16x32_bf16 v[68:71], v[170:173], v[218:221], v[68:71]
	s_barrier
; #define PG8_STAGE(bufoff, gbase, voff) do { _Pragma("unroll") for (int _i = 0; _i < 2; ++_i) \
;         __builtin_amdgcn_global_load_lds((const unsigned*)((const char*)(gbase) + (voff)[_i]), (LAS unsigned*)(lds + (bufoff) + ldsw + _i * 8192), 16, 0, 0); } while (0)
; #define PG8_LDA(dst, b, h) do { _Pragma("unroll") for (int m = 0; m < 4; ++m) _Pragma("unroll") for (int k = 0; k < 2; ++k) dst[m][k] = *(const LAS bf16x8*)(lds + PG8_SA(b, h) + aoff + m * 2048 + k * 1024); } while (0)
; #define PG8_MMA(ai, bj, At, Bt) do { __builtin_amdgcn_s_setprio(1); _Pragma("unroll") for (int m = 0; m < 4; ++m) _Pragma("unroll") for (int n = 0; n < 2; ++n) _Pragma("unroll") for (int k = 0; k < 2; ++k) \
;         acc[ai][bj][m][n] = __builtin_amdgcn_mfma_f32_16x16x32_bf16(Bt[n][k], At[m][k], acc[ai][bj][m][n], 0, 0, 0); __builtin_amdgcn_s_setprio(0); } while (0)
; #define PG8_WAIT_V(n) asm volatile("s_waitcnt vmcnt(" #n ")" ::: "memory")
; #define PG8_WAIT_L(n) asm volatile("s_waitcnt lgkmcnt(" #n ")" ::: "memory")
; #define PG8_BAR __builtin_amdgcn_s_barrier()
; #define PG8_SCHED __builtin_amdgcn_sched_barrier(0)
; template <class Epi>
; __device__ __forceinline__ void gemm_phase(LAS unsigned char* lds, const Gemm g, const StaticOrder& S, const Epi& E) {
;     ...
;             PG8_LDA(At, 1, 1); PG8_STAGE(PG8_SB(1, 0), b3, voffB); PG8_STAGE(PG8_SB(1, 1), b3 + hstepB, voffB); PG8_STAGE(PG8_SA(1, 0), a3, voffA);
;             PG8_WAIT_V(8); PG8_WAIT_L(0); PG8_BAR; PG8_MMA(1, 0, At, B0); PG8_MMA(1, 1, At, B1); PG8_BAR; PG8_SCHED;
;         }
;         if (wr == 0) PG8_BAR;
	s_add_i32 s22, s50, s26
	v_lshl_add_u64 v[162:163], v[162:163], 0, s[10:11]
	s_mov_b32 m0, s22
	ds_read_b128 v[182:185], v169 offset:49152
	ds_read_b128 v[190:193], v169 offset:50176
	ds_read_b128 v[198:201], v169 offset:51200
	ds_read_b128 v[202:205], v169 offset:52224
	ds_read_b128 v[206:209], v169 offset:53248
	ds_read_b128 v[210:213], v169 offset:54272
	ds_read_b128 v[214:217], v169 offset:55296
	ds_read_b128 v[218:221], v169 offset:56320
	global_load_lds_dwordx4 v[162:163], off
	s_add_i32 m0, s22, 0x2000
	s_add_u32 s2, s2, 0x20080
	v_lshl_add_u64 v[162:163], v[186:187], 0, s[10:11]
	s_addc_u32 s3, s3, 0
	s_add_i32 s22, s51, s26
	global_load_lds_dwordx4 v[162:163], off
	v_lshl_add_u64 v[162:163], s[2:3], 0, v[146:147]
	s_mov_b32 m0, s22
	s_nop 0
	global_load_lds_dwordx4 v[162:163], off
	v_lshl_add_u64 v[162:163], s[2:3], 0, v[150:151]
	s_add_i32 m0, s22, 0x2000
	s_nop 0
	global_load_lds_dwordx4 v[162:163], off
	v_lshl_add_u64 v[162:163], v[194:195], 0, s[10:11]
	s_mov_b32 m0, s33
	s_nop 0
	global_load_lds_dwordx4 v[162:163], off
	v_lshl_add_u64 v[162:163], v[222:223], 0, s[10:11]
	s_mov_b32 m0, s34
	s_nop 0
	global_load_lds_dwordx4 v[162:163], off
	s_waitcnt vmcnt(8)
	s_waitcnt lgkmcnt(0)
	s_barrier
	s_waitcnt lgkmcnt(0)
	v_mfma_f32_16x16x32_bf16 v[60:63], v[128:131], v[182:185], v[60:63]
	v_mfma_f32_16x16x32_bf16 v[56:59], v[136:139], v[182:185], v[56:59]
	v_mfma_f32_16x16x32_bf16 v[40:43], v[136:139], v[198:201], v[40:43]
	v_mfma_f32_16x16x32_bf16 v[48:51], v[128:131], v[198:201], v[48:51]
	v_mfma_f32_16x16x32_bf16 v[32:35], v[128:131], v[206:209], v[32:35]
	v_mfma_f32_16x16x32_bf16 v[24:27], v[136:139], v[206:209], v[24:27]
	v_mfma_f32_16x16x32_bf16 v[8:11], v[136:139], v[214:217], v[8:11]
	v_mfma_f32_16x16x32_bf16 v[16:19], v[128:131], v[214:217], v[16:19]
	v_mfma_f32_16x16x32_bf16 v[60:63], v[132:135], v[190:193], v[60:63]
	v_mfma_f32_16x16x32_bf16 v[56:59], v[140:143], v[190:193], v[56:59]
	v_mfma_f32_16x16x32_bf16 v[40:43], v[140:143], v[202:205], v[40:43]
	v_mfma_f32_16x16x32_bf16 v[48:51], v[132:135], v[202:205], v[48:51]
	v_mfma_f32_16x16x32_bf16 v[32:35], v[132:135], v[210:213], v[32:35]
	v_mfma_f32_16x16x32_bf16 v[24:27], v[140:143], v[210:213], v[24:27]
	v_mfma_f32_16x16x32_bf16 v[8:11], v[140:143], v[218:221], v[8:11]
	v_mfma_f32_16x16x32_bf16 v[16:19], v[132:135], v[218:221], v[16:19]
	v_mfma_f32_16x16x32_bf16 v[52:55], v[158:161], v[182:185], v[52:55]
	v_mfma_f32_16x16x32_bf16 v[44:47], v[174:177], v[182:185], v[44:47]
	v_mfma_f32_16x16x32_bf16 v[28:31], v[174:177], v[198:201], v[28:31]
	v_mfma_f32_16x16x32_bf16 v[36:39], v[158:161], v[198:201], v[36:39]
	v_mfma_f32_16x16x32_bf16 v[20:23], v[158:161], v[206:209], v[20:23]
	v_mfma_f32_16x16x32_bf16 v[12:15], v[174:177], v[206:209], v[12:15]
	v_mfma_f32_16x16x32_bf16 v[0:3], v[174:177], v[214:217], v[0:3]
	v_mfma_f32_16x16x32_bf16 v[4:7], v[158:161], v[214:217], v[4:7]
	v_mfma_f32_16x16x32_bf16 v[52:55], v[170:173], v[190:193], v[52:55]
	v_mfma_f32_16x16x32_bf16 v[44:47], v[178:181], v[190:193], v[44:47]
	v_mfma_f32_16x16x32_bf16 v[28:31], v[178:181], v[202:205], v[28:31]
	v_mfma_f32_16x16x32_bf16 v[36:39], v[170:173], v[202:205], v[36:39]
	v_mfma_f32_16x16x32_bf16 v[20:23], v[170:173], v[210:213], v[20:23]
	v_mfma_f32_16x16x32_bf16 v[12:15], v[178:181], v[210:213], v[12:15]
	v_mfma_f32_16x16x32_bf16 v[0:3], v[178:181], v[218:221], v[0:3]
	v_mfma_f32_16x16x32_bf16 v[4:7], v[170:173], v[218:221], v[4:7]
	s_barrier
	s_add_i32 s49, s49, 2
	s_add_u32 s20, s20, 0x100
	s_addc_u32 s21, s21, 0
	s_add_u32 s47, s47, 0x100
	s_addc_u32 s48, s48, 0
	s_cmp_gt_u32 s49, 5
	s_cbranch_scc0 .LBB0_721
	s_and_b64 vcc, exec, s[12:13]
	s_cbranch_vccz .LBB0_724
	s_barrier

; #define PG8_STAGE(bufoff, gbase, voff) do { _Pragma("unroll") for (int _i = 0; _i < 2; ++_i) \
;         __builtin_amdgcn_global_load_lds((const unsigned*)((const char*)(gbase) + (voff)[_i]), (LAS unsigned*)(lds + (bufoff) + ldsw + _i * 8192), 16, 0, 0); } while (0)
; #define PG8_LDA(dst, b, h) do { _Pragma("unroll") for (int m = 0; m < 4; ++m) _Pragma("unroll") for (int k = 0; k < 2; ++k) dst[m][k] = *(const LAS bf16x8*)(lds + PG8_SA(b, h) + aoff + m * 2048 + k * 1024); } while (0)
; #define PG8_LDB(dst, b, h) do { _Pragma("unroll") for (int n = 0; n < 2; ++n) _Pragma("unroll") for (int k = 0; k < 2; ++k) dst[n][k] = *(const LAS bf16x8*)(lds + PG8_SB(b, h) + boff + n * 2048 + k * 1024); } while (0)
; #define PG8_MMA(ai, bj, At, Bt) do { __builtin_amdgcn_s_setprio(1); _Pragma("unroll") for (int m = 0; m < 4; ++m) _Pragma("unroll") for (int n = 0; n < 2; ++n) _Pragma("unroll") for (int k = 0; k < 2; ++k) \
;         acc[ai][bj][m][n] = __builtin_amdgcn_mfma_f32_16x16x32_bf16(Bt[n][k], At[m][k], acc[ai][bj][m][n], 0, 0, 0); __builtin_amdgcn_s_setprio(0); } while (0)
; template <class Epi>
; __device__ __forceinline__ void gemm_phase(LAS unsigned char* lds, const Gemm g, const StaticOrder& S, const Epi& E) {
;     ...
;         const bool has_next = S.next(ui + 1, nxt);
;         const char* nA = has_next ? (const char*)g.A + (size_t)(nxt.pm >> 5) * aslab + (size_t)(nxt.pm & 31) * tstepA : cA; const char* nB = has_next ? (const char*)g.Bt + (size_t)nxt.pn * tstepB : cB;
;         for (int t = 0; t < nt; t += 2) {
;             const bool last = (t == nt - 2);
;             const char* a1 = cA + (size_t)(t + 1) * kstep;
;             const char* a2 = last ? nA : cA + (size_t)(t + 2) * kstep; const char* b2 = last ? nB : cB + (size_t)(t + 2) * kstep;
;             const char* a3 = a2 + kstep; const char* b3 = b2 + kstep;
;             PG8_LDB(B0, 0, 0); PG8_LDB(B1, 0, 1); PG8_SCHED; PG8_LDA(At, 0, 0); PG8_STAGE(PG8_SA(1, 1), a1 + hstepA, voffA);
;             PG8_WAIT_V(8); PG8_WAIT_L(0); PG8_BAR; PG8_MMA(0, 0, At, B0); PG8_MMA(0, 1, At, B1); PG8_BAR; PG8_SCHED;
;             PG8_LDA(At, 0, 1); PG8_STAGE(PG8_SB(0, 0), b2, voffB); PG8_STAGE(PG8_SB(0, 1), b2 + hstepB, voffB); PG8_STAGE(PG8_SA(0, 0), a2, voffA);
;             PG8_WAIT_V(8); PG8_WAIT_L(0); PG8_BAR; PG8_MMA(1, 0, At, B0); PG8_MMA(1, 1, At, B1); PG8_BAR; PG8_SCHED;
.LBB0_822:
	s_ashr_i32 s21, s20, 31
	s_lshl_b64 s[24:25], s[20:21], 19
	v_readlane_b32 s28, v235, 29
	v_readlane_b32 s29, v235, 30
	s_add_u32 s24, s28, s24
	s_addc_u32 s25, s29, s25
	s_and_b64 s[8:9], s[8:9], exec
	s_cselect_b32 s21, s25, s27
	s_cselect_b32 s46, s24, s26
	s_add_u32 s47, s26, 0x100
	s_addc_u32 s48, s27, 0
	s_mov_b32 s49, -2
	s_waitcnt lgkmcnt(0)
	s_waitcnt vmcnt(0)
	ds_read_b128 v[128:131], v187
	ds_read_b128 v[132:135], v187 offset:1024
	ds_read_b128 v[136:139], v187 offset:2048
	ds_read_b128 v[140:143], v187 offset:3072
	ds_read_b128 v[144:147], v188
	ds_read_b128 v[148:151], v188 offset:1024
	ds_read_b128 v[166:169], v188 offset:2048
	ds_read_b128 v[170:173], v188 offset:3072
	s_add_u32 s8, s2, 0x100
	s_addc_u32 s9, s3, 0
	s_cmp_eq_u32 s49, 12
	s_cselect_b32 s29, s23, s9
	s_cselect_b32 s28, s22, s8
	s_cselect_b32 s27, s21, s48
	s_cselect_b32 s26, s46, s47
	v_lshl_add_u64 v[182:183], s[2:3], 0, v[160:161]
	s_add_i32 m0, s31, 0xc000
	ds_read_b128 v[174:177], v190
	ds_read_b128 v[178:181], v190 offset:1024
	ds_read_b128 v[192:195], v190 offset:2048
	ds_read_b128 v[198:201], v190 offset:3072
	ds_read_b128 v[202:205], v190 offset:4096
	ds_read_b128 v[206:209], v190 offset:5120
	ds_read_b128 v[210:213], v190 offset:6144
	ds_read_b128 v[214:217], v190 offset:7168
	global_load_lds_dwordx4 v[182:183], off
	v_lshl_add_u64 v[182:183], s[2:3], 0, v[162:163]
	s_add_i32 m0, s31, 0xe000
	s_nop 0
	global_load_lds_dwordx4 v[182:183], off
	s_waitcnt vmcnt(8)
	s_waitcnt lgkmcnt(0)
	s_barrier
	s_waitcnt lgkmcnt(0)
	v_mfma_f32_16x16x32_bf16 v[124:127], v[128:131], v[174:177], 0
	v_mfma_f32_16x16x32_bf16 v[120:123], v[136:139], v[174:177], 0
	v_mfma_f32_16x16x32_bf16 v[104:107], v[136:139], v[192:195], 0
	v_mfma_f32_16x16x32_bf16 v[108:111], v[128:131], v[192:195], 0
	v_mfma_f32_16x16x32_bf16 v[92:95], v[128:131], v[202:205], 0
	v_mfma_f32_16x16x32_bf16 v[88:91], v[136:139], v[202:205], 0
	v_mfma_f32_16x16x32_bf16 v[72:75], v[136:139], v[210:213], 0
	v_mfma_f32_16x16x32_bf16 v[76:79], v[128:131], v[210:213], 0
	v_mfma_f32_16x16x32_bf16 v[124:127], v[132:135], v[178:181], v[124:127]
	v_mfma_f32_16x16x32_bf16 v[120:123], v[140:143], v[178:181], v[120:123]
	v_mfma_f32_16x16x32_bf16 v[104:107], v[140:143], v[198:201], v[104:107]
	v_mfma_f32_16x16x32_bf16 v[108:111], v[132:135], v[198:201], v[108:111]
	v_mfma_f32_16x16x32_bf16 v[92:95], v[132:135], v[206:209], v[92:95]
	v_mfma_f32_16x16x32_bf16 v[88:91], v[140:143], v[206:209], v[88:91]
	v_mfma_f32_16x16x32_bf16 v[72:75], v[140:143], v[214:217], v[72:75]
	v_mfma_f32_16x16x32_bf16 v[76:79], v[132:135], v[214:217], v[76:79]
	v_mfma_f32_16x16x32_bf16 v[116:119], v[144:147], v[174:177], 0
	v_mfma_f32_16x16x32_bf16 v[112:115], v[166:169], v[174:177], 0
	v_mfma_f32_16x16x32_bf16 v[96:99], v[166:169], v[192:195], 0
	v_mfma_f32_16x16x32_bf16 v[100:103], v[144:147], v[192:195], 0
	v_mfma_f32_16x16x32_bf16 v[84:87], v[144:147], v[202:205], 0
	v_mfma_f32_16x16x32_bf16 v[80:83], v[166:169], v[202:205], 0
	v_mfma_f32_16x16x32_bf16 v[64:67], v[166:169], v[210:213], 0
	v_mfma_f32_16x16x32_bf16 v[68:71], v[144:147], v[210:213], 0
	v_mfma_f32_16x16x32_bf16 v[116:119], v[148:151], v[178:181], v[116:119]
	v_mfma_f32_16x16x32_bf16 v[112:115], v[170:173], v[178:181], v[112:115]
	v_mfma_f32_16x16x32_bf16 v[96:99], v[170:173], v[198:201], v[96:99]
	v_mfma_f32_16x16x32_bf16 v[100:103], v[148:151], v[198:201], v[100:103]
	v_mfma_f32_16x16x32_bf16 v[84:87], v[148:151], v[206:209], v[84:87]
	v_mfma_f32_16x16x32_bf16 v[80:83], v[170:173], v[206:209], v[80:83]
	v_mfma_f32_16x16x32_bf16 v[64:67], v[170:173], v[214:217], v[64:67]
	v_mfma_f32_16x16x32_bf16 v[68:71], v[148:151], v[214:217], v[68:71]
	s_barrier
	s_add_i32 s2, s41, s30
	v_lshl_add_u64 v[182:183], s[26:27], 0, v[154:155]
	s_mov_b32 m0, s2
	ds_read_b128 v[174:177], v190 offset:16384
	ds_read_b128 v[178:181], v190 offset:17408
	ds_read_b128 v[192:195], v190 offset:18432
	ds_read_b128 v[198:201], v190 offset:19456
	ds_read_b128 v[202:205], v190 offset:20480
	ds_read_b128 v[206:209], v190 offset:21504
	ds_read_b128 v[210:213], v190 offset:22528
	ds_read_b128 v[214:217], v190 offset:23552
	global_load_lds_dwordx4 v[182:183], off
	s_add_i32 m0, s2, 0x2000
	s_add_u32 s2, s26, 0x40000
	v_lshl_add_u64 v[218:219], s[26:27], 0, v[158:159]
	s_addc_u32 s3, s27, 0
	s_add_i32 s50, s42, s30
	global_load_lds_dwordx4 v[218:219], off
	v_lshl_add_u64 v[220:221], s[2:3], 0, v[154:155]
	s_mov_b32 m0, s50
	v_lshl_add_u64 v[222:223], s[28:29], 0, v[156:157]
	global_load_lds_dwordx4 v[220:221], off
	v_lshl_add_u64 v[220:221], s[2:3], 0, v[158:159]
	s_add_i32 m0, s50, 0x2000
	s_nop 0
	global_load_lds_dwordx4 v[220:221], off
	v_lshl_add_u64 v[220:221], s[28:29], 0, v[152:153]
	s_mov_b32 m0, s31
	s_nop 0
	global_load_lds_dwordx4 v[220:221], off
	s_mov_b32 m0, s33
	s_nop 0
	global_load_lds_dwordx4 v[222:223], off
	s_waitcnt vmcnt(8)
	s_waitcnt lgkmcnt(0)
	s_barrier
; #define PG8_STAGE(bufoff, gbase, voff) do { _Pragma("unroll") for (int _i = 0; _i < 2; ++_i) \
;         __builtin_amdgcn_global_load_lds((const unsigned*)((const char*)(gbase) + (voff)[_i]), (LAS unsigned*)(lds + (bufoff) + ldsw + _i * 8192), 16, 0, 0); } while (0)
; #define PG8_LDA(dst, b, h) do { _Pragma("unroll") for (int m = 0; m < 4; ++m) _Pragma("unroll") for (int k = 0; k < 2; ++k) dst[m][k] = *(const LAS bf16x8*)(lds + PG8_SA(b, h) + aoff + m * 2048 + k * 1024); } while (0)
; #define PG8_LDB(dst, b, h) do { _Pragma("unroll") for (int n = 0; n < 2; ++n) _Pragma("unroll") for (int k = 0; k < 2; ++k) dst[n][k] = *(const LAS bf16x8*)(lds + PG8_SB(b, h) + boff + n * 2048 + k * 1024); } while (0)
; #define PG8_MMA(ai, bj, At, Bt) do { __builtin_amdgcn_s_setprio(1); _Pragma("unroll") for (int m = 0; m < 4; ++m) _Pragma("unroll") for (int n = 0; n < 2; ++n) _Pragma("unroll") for (int k = 0; k < 2; ++k) \
;         acc[ai][bj][m][n] = __builtin_amdgcn_mfma_f32_16x16x32_bf16(Bt[n][k], At[m][k], acc[ai][bj][m][n], 0, 0, 0); __builtin_amdgcn_s_setprio(0); } while (0)
; #define PG8_WAIT_V(n) asm volatile("s_waitcnt vmcnt(" #n ")" ::: "memory")
; #define PG8_WAIT_L(n) asm volatile("s_waitcnt lgkmcnt(" #n ")" ::: "memory")
; #define PG8_BAR __builtin_amdgcn_s_barrier()
; #define PG8_SCHED __builtin_amdgcn_sched_barrier(0)
; template <class Epi>
; __device__ __forceinline__ void gemm_phase(LAS unsigned char* lds, const Gemm g, const StaticOrder& S, const Epi& E) {
;     ...
;             PG8_WAIT_V(8); PG8_WAIT_L(0); PG8_BAR; PG8_MMA(1, 0, At, B0); PG8_MMA(1, 1, At, B1); PG8_BAR; PG8_SCHED;
;             PG8_LDB(B0, 1, 0); PG8_LDB(B1, 1, 1); PG8_SCHED; PG8_LDA(At, 1, 0); PG8_STAGE(PG8_SA(0, 1), a2 + hstepA, voffA);
;             PG8_WAIT_V(8); PG8_WAIT_L(0); PG8_BAR; PG8_MMA(0, 0, At, B0); PG8_MMA(0, 1, At, B1); PG8_BAR; PG8_SCHED;
	s_waitcnt lgkmcnt(0)
	v_mfma_f32_16x16x32_bf16 v[60:63], v[128:131], v[174:177], 0
	v_mfma_f32_16x16x32_bf16 v[56:59], v[136:139], v[174:177], 0
	v_mfma_f32_16x16x32_bf16 v[40:43], v[136:139], v[192:195], 0
	v_mfma_f32_16x16x32_bf16 v[44:47], v[128:131], v[192:195], 0
	v_mfma_f32_16x16x32_bf16 v[28:31], v[128:131], v[202:205], 0
	v_mfma_f32_16x16x32_bf16 v[24:27], v[136:139], v[202:205], 0
	v_mfma_f32_16x16x32_bf16 v[8:11], v[136:139], v[210:213], 0
	v_mfma_f32_16x16x32_bf16 v[12:15], v[128:131], v[210:213], 0
	v_mfma_f32_16x16x32_bf16 v[60:63], v[132:135], v[178:181], v[60:63]
	v_mfma_f32_16x16x32_bf16 v[56:59], v[140:143], v[178:181], v[56:59]
	v_mfma_f32_16x16x32_bf16 v[40:43], v[140:143], v[198:201], v[40:43]
	v_mfma_f32_16x16x32_bf16 v[44:47], v[132:135], v[198:201], v[44:47]
	v_mfma_f32_16x16x32_bf16 v[28:31], v[132:135], v[206:209], v[28:31]
	v_mfma_f32_16x16x32_bf16 v[24:27], v[140:143], v[206:209], v[24:27]
	v_mfma_f32_16x16x32_bf16 v[8:11], v[140:143], v[214:217], v[8:11]
	v_mfma_f32_16x16x32_bf16 v[12:15], v[132:135], v[214:217], v[12:15]
	v_mfma_f32_16x16x32_bf16 v[52:55], v[144:147], v[174:177], 0
	v_mfma_f32_16x16x32_bf16 v[48:51], v[166:169], v[174:177], 0
	v_mfma_f32_16x16x32_bf16 v[32:35], v[166:169], v[192:195], 0
	v_mfma_f32_16x16x32_bf16 v[36:39], v[144:147], v[192:195], 0
	v_mfma_f32_16x16x32_bf16 v[20:23], v[144:147], v[202:205], 0
	v_mfma_f32_16x16x32_bf16 v[16:19], v[166:169], v[202:205], 0
	v_mfma_f32_16x16x32_bf16 v[0:3], v[166:169], v[210:213], 0
	v_mfma_f32_16x16x32_bf16 v[4:7], v[144:147], v[210:213], 0
	v_mfma_f32_16x16x32_bf16 v[52:55], v[148:151], v[178:181], v[52:55]
	v_mfma_f32_16x16x32_bf16 v[48:51], v[170:173], v[178:181], v[48:51]
	v_mfma_f32_16x16x32_bf16 v[32:35], v[170:173], v[198:201], v[32:35]
	v_mfma_f32_16x16x32_bf16 v[36:39], v[148:151], v[198:201], v[36:39]
	v_mfma_f32_16x16x32_bf16 v[20:23], v[148:151], v[206:209], v[20:23]
	v_mfma_f32_16x16x32_bf16 v[16:19], v[170:173], v[206:209], v[16:19]
	v_mfma_f32_16x16x32_bf16 v[0:3], v[170:173], v[214:217], v[0:3]
	v_mfma_f32_16x16x32_bf16 v[4:7], v[148:151], v[214:217], v[4:7]
	s_barrier
	s_add_i32 s50, 0, 0x18000
	s_add_i32 s51, 0, 0x1c000
	v_add_u32_e32 v140, s50, v185
	v_add_u32_e32 v170, s51, v185
	ds_read_b128 v[128:131], v140
	ds_read_b128 v[132:135], v140 offset:1024
	ds_read_b128 v[136:139], v140 offset:2048
	ds_read_b128 v[140:143], v140 offset:3072
	ds_read_b128 v[144:147], v170
	ds_read_b128 v[148:151], v170 offset:1024
	ds_read_b128 v[166:169], v170 offset:2048
	ds_read_b128 v[170:173], v170 offset:3072
	s_add_u32 s2, s28, 0x110000
	s_addc_u32 s3, s29, 0
	s_mov_b32 m0, s34
	v_lshl_add_u64 v[224:225], s[2:3], 0, v[152:153]
	ds_read_b128 v[174:177], v190 offset:32768
	ds_read_b128 v[178:181], v190 offset:33792
	ds_read_b128 v[192:195], v190 offset:34816
	ds_read_b128 v[198:201], v190 offset:35840
	ds_read_b128 v[202:205], v190 offset:36864
	ds_read_b128 v[206:209], v190 offset:37888
	ds_read_b128 v[210:213], v190 offset:38912
	ds_read_b128 v[214:217], v190 offset:39936
	global_load_lds_dwordx4 v[224:225], off
	v_lshl_add_u64 v[224:225], s[2:3], 0, v[156:157]
	s_mov_b32 m0, s35
	s_nop 0
	global_load_lds_dwordx4 v[224:225], off
	s_waitcnt vmcnt(8)
	s_waitcnt lgkmcnt(0)
	s_barrier
	s_waitcnt lgkmcnt(0)
	v_mfma_f32_16x16x32_bf16 v[124:127], v[128:131], v[174:177], v[124:127]
	v_mfma_f32_16x16x32_bf16 v[120:123], v[136:139], v[174:177], v[120:123]
	v_mfma_f32_16x16x32_bf16 v[104:107], v[136:139], v[192:195], v[104:107]
	v_mfma_f32_16x16x32_bf16 v[108:111], v[128:131], v[192:195], v[108:111]
	v_mfma_f32_16x16x32_bf16 v[92:95], v[128:131], v[202:205], v[92:95]
	v_mfma_f32_16x16x32_bf16 v[88:91], v[136:139], v[202:205], v[88:91]
	v_mfma_f32_16x16x32_bf16 v[72:75], v[136:139], v[210:213], v[72:75]
	v_mfma_f32_16x16x32_bf16 v[76:79], v[128:131], v[210:213], v[76:79]
	v_mfma_f32_16x16x32_bf16 v[124:127], v[132:135], v[178:181], v[124:127]
	v_mfma_f32_16x16x32_bf16 v[120:123], v[140:143], v[178:181], v[120:123]
	v_mfma_f32_16x16x32_bf16 v[104:107], v[140:143], v[198:201], v[104:107]
	v_mfma_f32_16x16x32_bf16 v[108:111], v[132:135], v[198:201], v[108:111]
	v_mfma_f32_16x16x32_bf16 v[92:95], v[132:135], v[206:209], v[92:95]
	v_mfma_f32_16x16x32_bf16 v[88:91], v[140:143], v[206:209], v[88:91]
	v_mfma_f32_16x16x32_bf16 v[72:75], v[140:143], v[214:217], v[72:75]
	v_mfma_f32_16x16x32_bf16 v[76:79], v[132:135], v[214:217], v[76:79]
	v_mfma_f32_16x16x32_bf16 v[116:119], v[144:147], v[174:177], v[116:119]
	v_mfma_f32_16x16x32_bf16 v[112:115], v[166:169], v[174:177], v[112:115]
	v_mfma_f32_16x16x32_bf16 v[96:99], v[166:169], v[192:195], v[96:99]
	v_mfma_f32_16x16x32_bf16 v[100:103], v[144:147], v[192:195], v[100:103]
	v_mfma_f32_16x16x32_bf16 v[84:87], v[144:147], v[202:205], v[84:87]
	v_mfma_f32_16x16x32_bf16 v[80:83], v[166:169], v[202:205], v[80:83]
	v_mfma_f32_16x16x32_bf16 v[64:67], v[166:169], v[210:213], v[64:67]
	v_mfma_f32_16x16x32_bf16 v[68:71], v[144:147], v[210:213], v[68:71]
	v_mfma_f32_16x16x32_bf16 v[116:119], v[148:151], v[178:181], v[116:119]
	v_mfma_f32_16x16x32_bf16 v[112:115], v[170:173], v[178:181], v[112:115]
	v_mfma_f32_16x16x32_bf16 v[96:99], v[170:173], v[198:201], v[96:99]
	v_mfma_f32_16x16x32_bf16 v[100:103], v[148:151], v[198:201], v[100:103]
	v_mfma_f32_16x16x32_bf16 v[84:87], v[148:151], v[206:209], v[84:87]
	v_mfma_f32_16x16x32_bf16 v[80:83], v[170:173], v[206:209], v[80:83]
	v_mfma_f32_16x16x32_bf16 v[64:67], v[170:173], v[214:217], v[64:67]
	v_mfma_f32_16x16x32_bf16 v[68:71], v[148:151], v[214:217], v[68:71]
	s_barrier
; #define PG8_STAGE(bufoff, gbase, voff) do { _Pragma("unroll") for (int _i = 0; _i < 2; ++_i) \
;         __builtin_amdgcn_global_load_lds((const unsigned*)((const char*)(gbase) + (voff)[_i]), (LAS unsigned*)(lds + (bufoff) + ldsw + _i * 8192), 16, 0, 0); } while (0)
; #define PG8_LDA(dst, b, h) do { _Pragma("unroll") for (int m = 0; m < 4; ++m) _Pragma("unroll") for (int k = 0; k < 2; ++k) dst[m][k] = *(const LAS bf16x8*)(lds + PG8_SA(b, h) + aoff + m * 2048 + k * 1024); } while (0)
; #define PG8_LDB(dst, b, h) do { _Pragma("unroll") for (int n = 0; n < 2; ++n) _Pragma("unroll") for (int k = 0; k < 2; ++k) dst[n][k] = *(const LAS bf16x8*)(lds + PG8_SB(b, h) + boff + n * 2048 + k * 1024); } while (0)
; #define PG8_MMA(ai, bj, At, Bt) do { __builtin_amdgcn_s_setprio(1); _Pragma("unroll") for (int m = 0; m < 4; ++m) _Pragma("unroll") for (int n = 0; n < 2; ++n) _Pragma("unroll") for (int k = 0; k < 2; ++k) \
;         acc[ai][bj][m][n] = __builtin_amdgcn_mfma_f32_16x16x32_bf16(Bt[n][k], At[m][k], acc[ai][bj][m][n], 0, 0, 0); __builtin_amdgcn_s_setprio(0); } while (0)
; #define PG8_WAIT_V(n) asm volatile("s_waitcnt vmcnt(" #n ")" ::: "memory")
; #define PG8_WAIT_L(n) asm volatile("s_waitcnt lgkmcnt(" #n ")" ::: "memory")
; #define PG8_BAR __builtin_amdgcn_s_barrier()
; #define PG8_SCHED __builtin_amdgcn_sched_barrier(0)
; template <class Epi>
; __device__ __forceinline__ void gemm_phase(LAS unsigned char* lds, const Gemm g, const StaticOrder& S, const Epi& E) {
;     ...
;         for (int t = 0; t < nt; t += 2) {
;             const bool last = (t == nt - 2);
;             const char* a1 = cA + (size_t)(t + 1) * kstep;
;             const char* a2 = last ? nA : cA + (size_t)(t + 2) * kstep; const char* b2 = last ? nB : cB + (size_t)(t + 2) * kstep;
;             const char* a3 = a2 + kstep; const char* b3 = b2 + kstep;
;             PG8_LDB(B0, 0, 0); PG8_LDB(B1, 0, 1); PG8_SCHED; PG8_LDA(At, 0, 0); PG8_STAGE(PG8_SA(1, 1), a1 + hstepA, voffA);
;             PG8_WAIT_V(8); PG8_WAIT_L(0); PG8_BAR; PG8_MMA(0, 0, At, B0); PG8_MMA(0, 1, At, B1); PG8_BAR; PG8_SCHED;
;     ...
;             PG8_LDA(At, 1, 1); PG8_STAGE(PG8_SB(1, 0), b3, voffB); PG8_STAGE(PG8_SB(1, 1), b3 + hstepB, voffB); PG8_STAGE(PG8_SA(1, 0), a3, voffA);
;             PG8_WAIT_V(8); PG8_WAIT_L(0); PG8_BAR; PG8_MMA(1, 0, At, B0); PG8_MMA(1, 1, At, B1); PG8_BAR; PG8_SCHED;
	s_add_i32 s2, s50, s30
	v_lshl_add_u64 v[182:183], v[182:183], 0, s[16:17]
	s_mov_b32 m0, s2
	ds_read_b128 v[174:177], v190 offset:49152
	ds_read_b128 v[178:181], v190 offset:50176
	ds_read_b128 v[192:195], v190 offset:51200
	ds_read_b128 v[198:201], v190 offset:52224
	ds_read_b128 v[202:205], v190 offset:53248
	ds_read_b128 v[206:209], v190 offset:54272
	ds_read_b128 v[210:213], v190 offset:55296
	ds_read_b128 v[214:217], v190 offset:56320
	global_load_lds_dwordx4 v[182:183], off
	s_add_i32 m0, s2, 0x2000
	s_add_u32 s2, s26, 0x40080
	v_lshl_add_u64 v[182:183], v[218:219], 0, s[16:17]
	s_addc_u32 s3, s27, 0
	s_add_i32 s26, s51, s30
	global_load_lds_dwordx4 v[182:183], off
	v_lshl_add_u64 v[182:183], s[2:3], 0, v[154:155]
	s_mov_b32 m0, s26
	s_nop 0
	global_load_lds_dwordx4 v[182:183], off
	v_lshl_add_u64 v[182:183], s[2:3], 0, v[158:159]
	s_add_i32 m0, s26, 0x2000
	s_nop 0
	global_load_lds_dwordx4 v[182:183], off
	v_lshl_add_u64 v[182:183], v[220:221], 0, s[16:17]
	s_mov_b32 m0, s37
	s_nop 0
	global_load_lds_dwordx4 v[182:183], off
	v_lshl_add_u64 v[182:183], v[222:223], 0, s[16:17]
	s_mov_b32 m0, s38
	s_nop 0
	global_load_lds_dwordx4 v[182:183], off
	s_waitcnt vmcnt(8)
	s_waitcnt lgkmcnt(0)
	s_barrier
	s_waitcnt lgkmcnt(0)
	v_mfma_f32_16x16x32_bf16 v[60:63], v[128:131], v[174:177], v[60:63]
	v_mfma_f32_16x16x32_bf16 v[56:59], v[136:139], v[174:177], v[56:59]
	v_mfma_f32_16x16x32_bf16 v[40:43], v[136:139], v[192:195], v[40:43]
	v_mfma_f32_16x16x32_bf16 v[44:47], v[128:131], v[192:195], v[44:47]
	v_mfma_f32_16x16x32_bf16 v[28:31], v[128:131], v[202:205], v[28:31]
	v_mfma_f32_16x16x32_bf16 v[24:27], v[136:139], v[202:205], v[24:27]
	v_mfma_f32_16x16x32_bf16 v[8:11], v[136:139], v[210:213], v[8:11]
	v_mfma_f32_16x16x32_bf16 v[12:15], v[128:131], v[210:213], v[12:15]
	v_mfma_f32_16x16x32_bf16 v[60:63], v[132:135], v[178:181], v[60:63]
	v_mfma_f32_16x16x32_bf16 v[56:59], v[140:143], v[178:181], v[56:59]
	v_mfma_f32_16x16x32_bf16 v[40:43], v[140:143], v[198:201], v[40:43]
	v_mfma_f32_16x16x32_bf16 v[44:47], v[132:135], v[198:201], v[44:47]
	v_mfma_f32_16x16x32_bf16 v[28:31], v[132:135], v[206:209], v[28:31]
	v_mfma_f32_16x16x32_bf16 v[24:27], v[140:143], v[206:209], v[24:27]
	v_mfma_f32_16x16x32_bf16 v[8:11], v[140:143], v[214:217], v[8:11]
	v_mfma_f32_16x16x32_bf16 v[12:15], v[132:135], v[214:217], v[12:15]
	v_mfma_f32_16x16x32_bf16 v[52:55], v[144:147], v[174:177], v[52:55]
	v_mfma_f32_16x16x32_bf16 v[48:51], v[166:169], v[174:177], v[48:51]
	v_mfma_f32_16x16x32_bf16 v[32:35], v[166:169], v[192:195], v[32:35]
	v_mfma_f32_16x16x32_bf16 v[36:39], v[144:147], v[192:195], v[36:39]
	v_mfma_f32_16x16x32_bf16 v[20:23], v[144:147], v[202:205], v[20:23]
	v_mfma_f32_16x16x32_bf16 v[16:19], v[166:169], v[202:205], v[16:19]
	v_mfma_f32_16x16x32_bf16 v[0:3], v[166:169], v[210:213], v[0:3]
	v_mfma_f32_16x16x32_bf16 v[4:7], v[144:147], v[210:213], v[4:7]
	v_mfma_f32_16x16x32_bf16 v[52:55], v[148:151], v[178:181], v[52:55]
	v_mfma_f32_16x16x32_bf16 v[48:51], v[170:173], v[178:181], v[48:51]
	v_mfma_f32_16x16x32_bf16 v[32:35], v[170:173], v[198:201], v[32:35]
	v_mfma_f32_16x16x32_bf16 v[36:39], v[148:151], v[198:201], v[36:39]
	v_mfma_f32_16x16x32_bf16 v[20:23], v[148:151], v[206:209], v[20:23]
	v_mfma_f32_16x16x32_bf16 v[16:19], v[170:173], v[206:209], v[16:19]
	v_mfma_f32_16x16x32_bf16 v[0:3], v[170:173], v[214:217], v[0:3]
	v_mfma_f32_16x16x32_bf16 v[4:7], v[148:151], v[214:217], v[4:7]
	s_barrier
	s_add_i32 s49, s49, 2
	s_add_u32 s47, s47, 0x100
	s_addc_u32 s48, s48, 0
	s_cmp_gt_u32 s49, 13
	s_mov_b64 s[2:3], s[8:9]
	s_cbranch_scc0 .LBB0_823
.LBB0_823:
	ds_read_b128 v[128:131], v187
	ds_read_b128 v[132:135], v187 offset:1024
	ds_read_b128 v[136:139], v187 offset:2048
	ds_read_b128 v[140:143], v187 offset:3072
	ds_read_b128 v[144:147], v188
	ds_read_b128 v[148:151], v188 offset:1024
	ds_read_b128 v[166:169], v188 offset:2048
	ds_read_b128 v[170:173], v188 offset:3072
	s_add_u32 s8, s2, 0x100
	s_addc_u32 s9, s3, 0
	s_cmp_eq_u32 s49, 12
	s_cselect_b32 s29, s23, s9
	s_cselect_b32 s28, s22, s8
	s_cselect_b32 s27, s21, s48
	s_cselect_b32 s26, s46, s47
	v_lshl_add_u64 v[182:183], s[2:3], 0, v[160:161]
	s_add_i32 m0, s31, 0xc000
	ds_read_b128 v[174:177], v190
	ds_read_b128 v[178:181], v190 offset:1024
	ds_read_b128 v[192:195], v190 offset:2048
	ds_read_b128 v[198:201], v190 offset:3072
	ds_read_b128 v[202:205], v190 offset:4096
	ds_read_b128 v[206:209], v190 offset:5120
	ds_read_b128 v[210:213], v190 offset:6144
	ds_read_b128 v[214:217], v190 offset:7168
	global_load_lds_dwordx4 v[182:183], off
	v_lshl_add_u64 v[182:183], s[2:3], 0, v[162:163]
	s_add_i32 m0, s31, 0xe000
	s_nop 0
	global_load_lds_dwordx4 v[182:183], off
	s_waitcnt vmcnt(8)
	s_waitcnt lgkmcnt(0)
	s_barrier
; #define PG8_STAGE(bufoff, gbase, voff) do { _Pragma("unroll") for (int _i = 0; _i < 2; ++_i) \
;         __builtin_amdgcn_global_load_lds((const unsigned*)((const char*)(gbase) + (voff)[_i]), (LAS unsigned*)(lds + (bufoff) + ldsw + _i * 8192), 16, 0, 0); } while (0)
; #define PG8_LDA(dst, b, h) do { _Pragma("unroll") for (int m = 0; m < 4; ++m) _Pragma("unroll") for (int k = 0; k < 2; ++k) dst[m][k] = *(const LAS bf16x8*)(lds + PG8_SA(b, h) + aoff + m * 2048 + k * 1024); } while (0)
; #define PG8_MMA(ai, bj, At, Bt) do { __builtin_amdgcn_s_setprio(1); _Pragma("unroll") for (int m = 0; m < 4; ++m) _Pragma("unroll") for (int n = 0; n < 2; ++n) _Pragma("unroll") for (int k = 0; k < 2; ++k) \
;         acc[ai][bj][m][n] = __builtin_amdgcn_mfma_f32_16x16x32_bf16(Bt[n][k], At[m][k], acc[ai][bj][m][n], 0, 0, 0); __builtin_amdgcn_s_setprio(0); } while (0)
; #define PG8_WAIT_V(n) asm volatile("s_waitcnt vmcnt(" #n ")" ::: "memory")
; #define PG8_WAIT_L(n) asm volatile("s_waitcnt lgkmcnt(" #n ")" ::: "memory")
; #define PG8_BAR __builtin_amdgcn_s_barrier()
; #define PG8_SCHED __builtin_amdgcn_sched_barrier(0)
; template <class Epi>
; __device__ __forceinline__ void gemm_phase(LAS unsigned char* lds, const Gemm g, const StaticOrder& S, const Epi& E) {
;     ...
;             PG8_WAIT_V(8); PG8_WAIT_L(0); PG8_BAR; PG8_MMA(0, 0, At, B0); PG8_MMA(0, 1, At, B1); PG8_BAR; PG8_SCHED;
;             PG8_LDA(At, 0, 1); PG8_STAGE(PG8_SB(0, 0), b2, voffB); PG8_STAGE(PG8_SB(0, 1), b2 + hstepB, voffB); PG8_STAGE(PG8_SA(0, 0), a2, voffA);
;             PG8_WAIT_V(8); PG8_WAIT_L(0); PG8_BAR; PG8_MMA(1, 0, At, B0); PG8_MMA(1, 1, At, B1); PG8_BAR; PG8_SCHED;
	s_waitcnt lgkmcnt(0)
	v_mfma_f32_16x16x32_bf16 v[124:127], v[128:131], v[174:177], v[124:127]
	v_mfma_f32_16x16x32_bf16 v[120:123], v[136:139], v[174:177], v[120:123]
	v_mfma_f32_16x16x32_bf16 v[104:107], v[136:139], v[192:195], v[104:107]
	v_mfma_f32_16x16x32_bf16 v[108:111], v[128:131], v[192:195], v[108:111]
	v_mfma_f32_16x16x32_bf16 v[92:95], v[128:131], v[202:205], v[92:95]
	v_mfma_f32_16x16x32_bf16 v[88:91], v[136:139], v[202:205], v[88:91]
	v_mfma_f32_16x16x32_bf16 v[72:75], v[136:139], v[210:213], v[72:75]
	v_mfma_f32_16x16x32_bf16 v[76:79], v[128:131], v[210:213], v[76:79]
	v_mfma_f32_16x16x32_bf16 v[124:127], v[132:135], v[178:181], v[124:127]
	v_mfma_f32_16x16x32_bf16 v[120:123], v[140:143], v[178:181], v[120:123]
	v_mfma_f32_16x16x32_bf16 v[104:107], v[140:143], v[198:201], v[104:107]
	v_mfma_f32_16x16x32_bf16 v[108:111], v[132:135], v[198:201], v[108:111]
	v_mfma_f32_16x16x32_bf16 v[92:95], v[132:135], v[206:209], v[92:95]
	v_mfma_f32_16x16x32_bf16 v[88:91], v[140:143], v[206:209], v[88:91]
	v_mfma_f32_16x16x32_bf16 v[72:75], v[140:143], v[214:217], v[72:75]
	v_mfma_f32_16x16x32_bf16 v[76:79], v[132:135], v[214:217], v[76:79]
	v_mfma_f32_16x16x32_bf16 v[116:119], v[144:147], v[174:177], v[116:119]
	v_mfma_f32_16x16x32_bf16 v[112:115], v[166:169], v[174:177], v[112:115]
	v_mfma_f32_16x16x32_bf16 v[96:99], v[166:169], v[192:195], v[96:99]
	v_mfma_f32_16x16x32_bf16 v[100:103], v[144:147], v[192:195], v[100:103]
	v_mfma_f32_16x16x32_bf16 v[84:87], v[144:147], v[202:205], v[84:87]
	v_mfma_f32_16x16x32_bf16 v[80:83], v[166:169], v[202:205], v[80:83]
	v_mfma_f32_16x16x32_bf16 v[64:67], v[166:169], v[210:213], v[64:67]
	v_mfma_f32_16x16x32_bf16 v[68:71], v[144:147], v[210:213], v[68:71]
	v_mfma_f32_16x16x32_bf16 v[116:119], v[148:151], v[178:181], v[116:119]
	v_mfma_f32_16x16x32_bf16 v[112:115], v[170:173], v[178:181], v[112:115]
	v_mfma_f32_16x16x32_bf16 v[96:99], v[170:173], v[198:201], v[96:99]
	v_mfma_f32_16x16x32_bf16 v[100:103], v[148:151], v[198:201], v[100:103]
	v_mfma_f32_16x16x32_bf16 v[84:87], v[148:151], v[206:209], v[84:87]
	v_mfma_f32_16x16x32_bf16 v[80:83], v[170:173], v[206:209], v[80:83]
	v_mfma_f32_16x16x32_bf16 v[64:67], v[170:173], v[214:217], v[64:67]
	v_mfma_f32_16x16x32_bf16 v[68:71], v[148:151], v[214:217], v[68:71]
	s_barrier
	s_add_i32 s2, s41, s30
	v_lshl_add_u64 v[182:183], s[26:27], 0, v[154:155]
	s_mov_b32 m0, s2
	ds_read_b128 v[174:177], v190 offset:16384
	ds_read_b128 v[178:181], v190 offset:17408
	ds_read_b128 v[192:195], v190 offset:18432
	ds_read_b128 v[198:201], v190 offset:19456
	ds_read_b128 v[202:205], v190 offset:20480
	ds_read_b128 v[206:209], v190 offset:21504
	ds_read_b128 v[210:213], v190 offset:22528
	ds_read_b128 v[214:217], v190 offset:23552
	global_load_lds_dwordx4 v[182:183], off
	s_add_i32 m0, s2, 0x2000
	s_add_u32 s2, s26, 0x40000
	v_lshl_add_u64 v[218:219], s[26:27], 0, v[158:159]
	s_addc_u32 s3, s27, 0
	s_add_i32 s50, s42, s30
	global_load_lds_dwordx4 v[218:219], off
	v_lshl_add_u64 v[220:221], s[2:3], 0, v[154:155]
	s_mov_b32 m0, s50
	v_lshl_add_u64 v[222:223], s[28:29], 0, v[156:157]
	global_load_lds_dwordx4 v[220:221], off
	v_lshl_add_u64 v[220:221], s[2:3], 0, v[158:159]
	s_add_i32 m0, s50, 0x2000
	s_nop 0
	global_load_lds_dwordx4 v[220:221], off
	v_lshl_add_u64 v[220:221], s[28:29], 0, v[152:153]
	s_mov_b32 m0, s31
	s_nop 0
	global_load_lds_dwordx4 v[220:221], off
	s_mov_b32 m0, s33
	s_nop 0
	global_load_lds_dwordx4 v[222:223], off
	s_waitcnt vmcnt(8)
	s_waitcnt lgkmcnt(0)
	s_barrier
	s_waitcnt lgkmcnt(0)
	v_mfma_f32_16x16x32_bf16 v[60:63], v[128:131], v[174:177], v[60:63]
	v_mfma_f32_16x16x32_bf16 v[56:59], v[136:139], v[174:177], v[56:59]
	v_mfma_f32_16x16x32_bf16 v[40:43], v[136:139], v[192:195], v[40:43]
	v_mfma_f32_16x16x32_bf16 v[44:47], v[128:131], v[192:195], v[44:47]
	v_mfma_f32_16x16x32_bf16 v[28:31], v[128:131], v[202:205], v[28:31]
	v_mfma_f32_16x16x32_bf16 v[24:27], v[136:139], v[202:205], v[24:27]
	v_mfma_f32_16x16x32_bf16 v[8:11], v[136:139], v[210:213], v[8:11]
	v_mfma_f32_16x16x32_bf16 v[12:15], v[128:131], v[210:213], v[12:15]
	v_mfma_f32_16x16x32_bf16 v[60:63], v[132:135], v[178:181], v[60:63]
	v_mfma_f32_16x16x32_bf16 v[56:59], v[140:143], v[178:181], v[56:59]
	v_mfma_f32_16x16x32_bf16 v[40:43], v[140:143], v[198:201], v[40:43]
	v_mfma_f32_16x16x32_bf16 v[44:47], v[132:135], v[198:201], v[44:47]
	v_mfma_f32_16x16x32_bf16 v[28:31], v[132:135], v[206:209], v[28:31]
	v_mfma_f32_16x16x32_bf16 v[24:27], v[140:143], v[206:209], v[24:27]
	v_mfma_f32_16x16x32_bf16 v[8:11], v[140:143], v[214:217], v[8:11]
	v_mfma_f32_16x16x32_bf16 v[12:15], v[132:135], v[214:217], v[12:15]
	v_mfma_f32_16x16x32_bf16 v[52:55], v[144:147], v[174:177], v[52:55]
	v_mfma_f32_16x16x32_bf16 v[48:51], v[166:169], v[174:177], v[48:51]
	v_mfma_f32_16x16x32_bf16 v[32:35], v[166:169], v[192:195], v[32:35]
	v_mfma_f32_16x16x32_bf16 v[36:39], v[144:147], v[192:195], v[36:39]
	v_mfma_f32_16x16x32_bf16 v[20:23], v[144:147], v[202:205], v[20:23]
	v_mfma_f32_16x16x32_bf16 v[16:19], v[166:169], v[202:205], v[16:19]
	v_mfma_f32_16x16x32_bf16 v[0:3], v[166:169], v[210:213], v[0:3]
	v_mfma_f32_16x16x32_bf16 v[4:7], v[144:147], v[210:213], v[4:7]
	v_mfma_f32_16x16x32_bf16 v[52:55], v[148:151], v[178:181], v[52:55]
	v_mfma_f32_16x16x32_bf16 v[48:51], v[170:173], v[178:181], v[48:51]
	v_mfma_f32_16x16x32_bf16 v[32:35], v[170:173], v[198:201], v[32:35]
	v_mfma_f32_16x16x32_bf16 v[36:39], v[148:151], v[198:201], v[36:39]
	v_mfma_f32_16x16x32_bf16 v[20:23], v[148:151], v[206:209], v[20:23]
	v_mfma_f32_16x16x32_bf16 v[16:19], v[170:173], v[206:209], v[16:19]
	v_mfma_f32_16x16x32_bf16 v[0:3], v[170:173], v[214:217], v[0:3]
	v_mfma_f32_16x16x32_bf16 v[4:7], v[148:151], v[214:217], v[4:7]
	s_barrier
; #define PG8_STAGE(bufoff, gbase, voff) do { _Pragma("unroll") for (int _i = 0; _i < 2; ++_i) \
;         __builtin_amdgcn_global_load_lds((const unsigned*)((const char*)(gbase) + (voff)[_i]), (LAS unsigned*)(lds + (bufoff) + ldsw + _i * 8192), 16, 0, 0); } while (0)
; #define PG8_LDA(dst, b, h) do { _Pragma("unroll") for (int m = 0; m < 4; ++m) _Pragma("unroll") for (int k = 0; k < 2; ++k) dst[m][k] = *(const LAS bf16x8*)(lds + PG8_SA(b, h) + aoff + m * 2048 + k * 1024); } while (0)
; #define PG8_LDB(dst, b, h) do { _Pragma("unroll") for (int n = 0; n < 2; ++n) _Pragma("unroll") for (int k = 0; k < 2; ++k) dst[n][k] = *(const LAS bf16x8*)(lds + PG8_SB(b, h) + boff + n * 2048 + k * 1024); } while (0)
; #define PG8_MMA(ai, bj, At, Bt) do { __builtin_amdgcn_s_setprio(1); _Pragma("unroll") for (int m = 0; m < 4; ++m) _Pragma("unroll") for (int n = 0; n < 2; ++n) _Pragma("unroll") for (int k = 0; k < 2; ++k) \
;         acc[ai][bj][m][n] = __builtin_amdgcn_mfma_f32_16x16x32_bf16(Bt[n][k], At[m][k], acc[ai][bj][m][n], 0, 0, 0); __builtin_amdgcn_s_setprio(0); } while (0)
; #define PG8_WAIT_V(n) asm volatile("s_waitcnt vmcnt(" #n ")" ::: "memory")
; #define PG8_WAIT_L(n) asm volatile("s_waitcnt lgkmcnt(" #n ")" ::: "memory")
; #define PG8_BAR __builtin_amdgcn_s_barrier()
; #define PG8_SCHED __builtin_amdgcn_sched_barrier(0)
; template <class Epi>
; __device__ __forceinline__ void gemm_phase(LAS unsigned char* lds, const Gemm g, const StaticOrder& S, const Epi& E) {
;     ...
;             PG8_LDB(B0, 1, 0); PG8_LDB(B1, 1, 1); PG8_SCHED; PG8_LDA(At, 1, 0); PG8_STAGE(PG8_SA(0, 1), a2 + hstepA, voffA);
;             PG8_WAIT_V(8); PG8_WAIT_L(0); PG8_BAR; PG8_MMA(0, 0, At, B0); PG8_MMA(0, 1, At, B1); PG8_BAR; PG8_SCHED;
	s_add_i32 s50, 0, 0x18000
	s_add_i32 s51, 0, 0x1c000
	v_add_u32_e32 v140, s50, v185
	v_add_u32_e32 v170, s51, v185
	ds_read_b128 v[128:131], v140
	ds_read_b128 v[132:135], v140 offset:1024
	ds_read_b128 v[136:139], v140 offset:2048
	ds_read_b128 v[140:143], v140 offset:3072
	ds_read_b128 v[144:147], v170
	ds_read_b128 v[148:151], v170 offset:1024
	ds_read_b128 v[166:169], v170 offset:2048
	ds_read_b128 v[170:173], v170 offset:3072
	s_add_u32 s2, s28, 0x110000
	s_addc_u32 s3, s29, 0
	s_mov_b32 m0, s34
	v_lshl_add_u64 v[224:225], s[2:3], 0, v[152:153]
	ds_read_b128 v[174:177], v190 offset:32768
	ds_read_b128 v[178:181], v190 offset:33792
	ds_read_b128 v[192:195], v190 offset:34816
	ds_read_b128 v[198:201], v190 offset:35840
	ds_read_b128 v[202:205], v190 offset:36864
	ds_read_b128 v[206:209], v190 offset:37888
	ds_read_b128 v[210:213], v190 offset:38912
	ds_read_b128 v[214:217], v190 offset:39936
	global_load_lds_dwordx4 v[224:225], off
	v_lshl_add_u64 v[224:225], s[2:3], 0, v[156:157]
	s_mov_b32 m0, s35
	s_nop 0
	global_load_lds_dwordx4 v[224:225], off
	s_waitcnt vmcnt(8)
	s_waitcnt lgkmcnt(0)
	s_barrier
	s_waitcnt lgkmcnt(0)
	v_mfma_f32_16x16x32_bf16 v[124:127], v[128:131], v[174:177], v[124:127]
	v_mfma_f32_16x16x32_bf16 v[120:123], v[136:139], v[174:177], v[120:123]
	v_mfma_f32_16x16x32_bf16 v[104:107], v[136:139], v[192:195], v[104:107]
	v_mfma_f32_16x16x32_bf16 v[108:111], v[128:131], v[192:195], v[108:111]
	v_mfma_f32_16x16x32_bf16 v[92:95], v[128:131], v[202:205], v[92:95]
	v_mfma_f32_16x16x32_bf16 v[88:91], v[136:139], v[202:205], v[88:91]
	v_mfma_f32_16x16x32_bf16 v[72:75], v[136:139], v[210:213], v[72:75]
	v_mfma_f32_16x16x32_bf16 v[76:79], v[128:131], v[210:213], v[76:79]
	v_mfma_f32_16x16x32_bf16 v[124:127], v[132:135], v[178:181], v[124:127]
	v_mfma_f32_16x16x32_bf16 v[120:123], v[140:143], v[178:181], v[120:123]
	v_mfma_f32_16x16x32_bf16 v[104:107], v[140:143], v[198:201], v[104:107]
	v_mfma_f32_16x16x32_bf16 v[108:111], v[132:135], v[198:201], v[108:111]
	v_mfma_f32_16x16x32_bf16 v[92:95], v[132:135], v[206:209], v[92:95]
	v_mfma_f32_16x16x32_bf16 v[88:91], v[140:143], v[206:209], v[88:91]
	v_mfma_f32_16x16x32_bf16 v[72:75], v[140:143], v[214:217], v[72:75]
	v_mfma_f32_16x16x32_bf16 v[76:79], v[132:135], v[214:217], v[76:79]
	v_mfma_f32_16x16x32_bf16 v[116:119], v[144:147], v[174:177], v[116:119]
	v_mfma_f32_16x16x32_bf16 v[112:115], v[166:169], v[174:177], v[112:115]
	v_mfma_f32_16x16x32_bf16 v[96:99], v[166:169], v[192:195], v[96:99]
	v_mfma_f32_16x16x32_bf16 v[100:103], v[144:147], v[192:195], v[100:103]
	v_mfma_f32_16x16x32_bf16 v[84:87], v[144:147], v[202:205], v[84:87]
	v_mfma_f32_16x16x32_bf16 v[80:83], v[166:169], v[202:205], v[80:83]
	v_mfma_f32_16x16x32_bf16 v[64:67], v[166:169], v[210:213], v[64:67]
	v_mfma_f32_16x16x32_bf16 v[68:71], v[144:147], v[210:213], v[68:71]
	v_mfma_f32_16x16x32_bf16 v[116:119], v[148:151], v[178:181], v[116:119]
	v_mfma_f32_16x16x32_bf16 v[112:115], v[170:173], v[178:181], v[112:115]
	v_mfma_f32_16x16x32_bf16 v[96:99], v[170:173], v[198:201], v[96:99]
	v_mfma_f32_16x16x32_bf16 v[100:103], v[148:151], v[198:201], v[100:103]
	v_mfma_f32_16x16x32_bf16 v[84:87], v[148:151], v[206:209], v[84:87]
	v_mfma_f32_16x16x32_bf16 v[80:83], v[170:173], v[206:209], v[80:83]
	v_mfma_f32_16x16x32_bf16 v[64:67], v[170:173], v[214:217], v[64:67]
	v_mfma_f32_16x16x32_bf16 v[68:71], v[148:151], v[214:217], v[68:71]
	s_barrier
; #define PG8_STAGE(bufoff, gbase, voff) do { _Pragma("unroll") for (int _i = 0; _i < 2; ++_i) \
;         __builtin_amdgcn_global_load_lds((const unsigned*)((const char*)(gbase) + (voff)[_i]), (LAS unsigned*)(lds + (bufoff) + ldsw + _i * 8192), 16, 0, 0); } while (0)
; #define PG8_LDA(dst, b, h) do { _Pragma("unroll") for (int m = 0; m < 4; ++m) _Pragma("unroll") for (int k = 0; k < 2; ++k) dst[m][k] = *(const LAS bf16x8*)(lds + PG8_SA(b, h) + aoff + m * 2048 + k * 1024); } while (0)
; #define PG8_MMA(ai, bj, At, Bt) do { __builtin_amdgcn_s_setprio(1); _Pragma("unroll") for (int m = 0; m < 4; ++m) _Pragma("unroll") for (int n = 0; n < 2; ++n) _Pragma("unroll") for (int k = 0; k < 2; ++k) \
;         acc[ai][bj][m][n] = __builtin_amdgcn_mfma_f32_16x16x32_bf16(Bt[n][k], At[m][k], acc[ai][bj][m][n], 0, 0, 0); __builtin_amdgcn_s_setprio(0); } while (0)
; #define PG8_WAIT_V(n) asm volatile("s_waitcnt vmcnt(" #n ")" ::: "memory")
; #define PG8_WAIT_L(n) asm volatile("s_waitcnt lgkmcnt(" #n ")" ::: "memory")
; #define PG8_BAR __builtin_amdgcn_s_barrier()
; #define PG8_SCHED __builtin_amdgcn_sched_barrier(0)
; template <class Epi>
; __device__ __forceinline__ void gemm_phase(LAS unsigned char* lds, const Gemm g, const StaticOrder& S, const Epi& E) {
;     ...
;             PG8_LDA(At, 1, 1); PG8_STAGE(PG8_SB(1, 0), b3, voffB); PG8_STAGE(PG8_SB(1, 1), b3 + hstepB, voffB); PG8_STAGE(PG8_SA(1, 0), a3, voffA);
;             PG8_WAIT_V(8); PG8_WAIT_L(0); PG8_BAR; PG8_MMA(1, 0, At, B0); PG8_MMA(1, 1, At, B1); PG8_BAR; PG8_SCHED;
;         }
;         if (wr == 0) PG8_BAR;
	s_add_i32 s2, s50, s30
	v_lshl_add_u64 v[182:183], v[182:183], 0, s[16:17]
	s_mov_b32 m0, s2
	ds_read_b128 v[174:177], v190 offset:49152
	ds_read_b128 v[178:181], v190 offset:50176
	ds_read_b128 v[192:195], v190 offset:51200
	ds_read_b128 v[198:201], v190 offset:52224
	ds_read_b128 v[202:205], v190 offset:53248
	ds_read_b128 v[206:209], v190 offset:54272
	ds_read_b128 v[210:213], v190 offset:55296
	ds_read_b128 v[214:217], v190 offset:56320
	global_load_lds_dwordx4 v[182:183], off
	s_add_i32 m0, s2, 0x2000
	s_add_u32 s2, s26, 0x40080
	v_lshl_add_u64 v[182:183], v[218:219], 0, s[16:17]
	s_addc_u32 s3, s27, 0
	s_add_i32 s26, s51, s30
	global_load_lds_dwordx4 v[182:183], off
	v_lshl_add_u64 v[182:183], s[2:3], 0, v[154:155]
	s_mov_b32 m0, s26
	s_nop 0
	global_load_lds_dwordx4 v[182:183], off
	v_lshl_add_u64 v[182:183], s[2:3], 0, v[158:159]
	s_add_i32 m0, s26, 0x2000
	s_nop 0
	global_load_lds_dwordx4 v[182:183], off
	v_lshl_add_u64 v[182:183], v[220:221], 0, s[16:17]
	s_mov_b32 m0, s37
	s_nop 0
	global_load_lds_dwordx4 v[182:183], off
	v_lshl_add_u64 v[182:183], v[222:223], 0, s[16:17]
	s_mov_b32 m0, s38
	s_nop 0
	global_load_lds_dwordx4 v[182:183], off
	s_waitcnt vmcnt(8)
	s_waitcnt lgkmcnt(0)
	s_barrier
	s_waitcnt lgkmcnt(0)
	v_mfma_f32_16x16x32_bf16 v[60:63], v[128:131], v[174:177], v[60:63]
	v_mfma_f32_16x16x32_bf16 v[56:59], v[136:139], v[174:177], v[56:59]
	v_mfma_f32_16x16x32_bf16 v[40:43], v[136:139], v[192:195], v[40:43]
	v_mfma_f32_16x16x32_bf16 v[44:47], v[128:131], v[192:195], v[44:47]
	v_mfma_f32_16x16x32_bf16 v[28:31], v[128:131], v[202:205], v[28:31]
	v_mfma_f32_16x16x32_bf16 v[24:27], v[136:139], v[202:205], v[24:27]
	v_mfma_f32_16x16x32_bf16 v[8:11], v[136:139], v[210:213], v[8:11]
	v_mfma_f32_16x16x32_bf16 v[12:15], v[128:131], v[210:213], v[12:15]
	v_mfma_f32_16x16x32_bf16 v[60:63], v[132:135], v[178:181], v[60:63]
	v_mfma_f32_16x16x32_bf16 v[56:59], v[140:143], v[178:181], v[56:59]
	v_mfma_f32_16x16x32_bf16 v[40:43], v[140:143], v[198:201], v[40:43]
	v_mfma_f32_16x16x32_bf16 v[44:47], v[132:135], v[198:201], v[44:47]
	v_mfma_f32_16x16x32_bf16 v[28:31], v[132:135], v[206:209], v[28:31]
	v_mfma_f32_16x16x32_bf16 v[24:27], v[140:143], v[206:209], v[24:27]
	v_mfma_f32_16x16x32_bf16 v[8:11], v[140:143], v[214:217], v[8:11]
	v_mfma_f32_16x16x32_bf16 v[12:15], v[132:135], v[214:217], v[12:15]
	v_mfma_f32_16x16x32_bf16 v[52:55], v[144:147], v[174:177], v[52:55]
	v_mfma_f32_16x16x32_bf16 v[48:51], v[166:169], v[174:177], v[48:51]
	v_mfma_f32_16x16x32_bf16 v[32:35], v[166:169], v[192:195], v[32:35]
	v_mfma_f32_16x16x32_bf16 v[36:39], v[144:147], v[192:195], v[36:39]
	v_mfma_f32_16x16x32_bf16 v[20:23], v[144:147], v[202:205], v[20:23]
	v_mfma_f32_16x16x32_bf16 v[16:19], v[166:169], v[202:205], v[16:19]
	v_mfma_f32_16x16x32_bf16 v[0:3], v[166:169], v[210:213], v[0:3]
	v_mfma_f32_16x16x32_bf16 v[4:7], v[144:147], v[210:213], v[4:7]
	v_mfma_f32_16x16x32_bf16 v[52:55], v[148:151], v[178:181], v[52:55]
	v_mfma_f32_16x16x32_bf16 v[48:51], v[170:173], v[178:181], v[48:51]
	v_mfma_f32_16x16x32_bf16 v[32:35], v[170:173], v[198:201], v[32:35]
	v_mfma_f32_16x16x32_bf16 v[36:39], v[148:151], v[198:201], v[36:39]
	v_mfma_f32_16x16x32_bf16 v[20:23], v[148:151], v[206:209], v[20:23]
	v_mfma_f32_16x16x32_bf16 v[16:19], v[170:173], v[206:209], v[16:19]
	v_mfma_f32_16x16x32_bf16 v[0:3], v[170:173], v[214:217], v[0:3]
	v_mfma_f32_16x16x32_bf16 v[4:7], v[148:151], v[214:217], v[4:7]
	s_barrier
	s_add_i32 s49, s49, 2
	s_add_u32 s47, s47, 0x100
	s_addc_u32 s48, s48, 0
	s_cmp_gt_u32 s49, 13
	s_mov_b64 s[2:3], s[8:9]
	s_cbranch_scc0 .LBB0_823
	s_and_b64 vcc, exec, s[18:19]
	s_cbranch_vccz .LBB0_826
	s_barrier

; #define PG8_STAGE(bufoff, gbase, voff) do { _Pragma("unroll") for (int _i = 0; _i < 2; ++_i) \
;         __builtin_amdgcn_global_load_lds((const unsigned*)((const char*)(gbase) + (voff)[_i]), (LAS unsigned*)(lds + (bufoff) + ldsw + _i * 8192), 16, 0, 0); } while (0)
; #define PG8_LDA(dst, b, h) do { _Pragma("unroll") for (int m = 0; m < 4; ++m) _Pragma("unroll") for (int k = 0; k < 2; ++k) dst[m][k] = *(const LAS bf16x8*)(lds + PG8_SA(b, h) + aoff + m * 2048 + k * 1024); } while (0)
; #define PG8_LDB(dst, b, h) do { _Pragma("unroll") for (int n = 0; n < 2; ++n) _Pragma("unroll") for (int k = 0; k < 2; ++k) dst[n][k] = *(const LAS bf16x8*)(lds + PG8_SB(b, h) + boff + n * 2048 + k * 1024); } while (0)
; #define PG8_MMA(ai, bj, At, Bt) do { __builtin_amdgcn_s_setprio(1); _Pragma("unroll") for (int m = 0; m < 4; ++m) _Pragma("unroll") for (int n = 0; n < 2; ++n) _Pragma("unroll") for (int k = 0; k < 2; ++k) \
;         acc[ai][bj][m][n] = __builtin_amdgcn_mfma_f32_16x16x32_bf16(Bt[n][k], At[m][k], acc[ai][bj][m][n], 0, 0, 0); __builtin_amdgcn_s_setprio(0); } while (0)
; template <class Epi>
; __device__ __forceinline__ void gemm_phase(LAS unsigned char* lds, const Gemm g, const StaticOrder& S, const Epi& E) {
;     ...
;         const bool has_next = S.next(ui + 1, nxt);
;         const char* nA = has_next ? (const char*)g.A + (size_t)(nxt.pm >> 5) * aslab + (size_t)(nxt.pm & 31) * tstepA : cA; const char* nB = has_next ? (const char*)g.Bt + (size_t)nxt.pn * tstepB : cB;
;         for (int t = 0; t < nt; t += 2) {
;             const bool last = (t == nt - 2);
;             const char* a1 = cA + (size_t)(t + 1) * kstep;
;             const char* a2 = last ? nA : cA + (size_t)(t + 2) * kstep; const char* b2 = last ? nB : cB + (size_t)(t + 2) * kstep;
;             const char* a3 = a2 + kstep; const char* b3 = b2 + kstep;
;             PG8_LDB(B0, 0, 0); PG8_LDB(B1, 0, 1); PG8_SCHED; PG8_LDA(At, 0, 0); PG8_STAGE(PG8_SA(1, 1), a1 + hstepA, voffA);
;             PG8_WAIT_V(8); PG8_WAIT_L(0); PG8_BAR; PG8_MMA(0, 0, At, B0); PG8_MMA(0, 1, At, B1); PG8_BAR; PG8_SCHED;
;             PG8_LDA(At, 0, 1); PG8_STAGE(PG8_SB(0, 0), b2, voffB); PG8_STAGE(PG8_SB(0, 1), b2 + hstepB, voffB); PG8_STAGE(PG8_SA(0, 0), a2, voffA);
;             PG8_WAIT_V(8); PG8_WAIT_L(0); PG8_BAR; PG8_MMA(1, 0, At, B0); PG8_MMA(1, 1, At, B1); PG8_BAR; PG8_SCHED;
.LBB0_928:
	s_ashr_i32 s12, s40, 5
	s_ashr_i32 s13, s12, 31
	s_lshl_b64 s[12:13], s[12:13], 24
	v_readlane_b32 s14, v235, 38
	v_readlane_b32 s15, v235, 39
	s_add_u32 s11, s14, s12
	s_addc_u32 s13, s15, s13
	s_lshl_b32 s12, s40, 19
	s_and_b32 s12, s12, 0xf80000
	s_add_u32 s12, s11, s12
	s_addc_u32 s13, s13, 0
	s_and_b64 s[14:15], s[4:5], exec
	s_cselect_b32 s43, s13, s17
	s_cselect_b32 s44, s12, s16
	s_ashr_i32 s11, s10, 31
	s_lshl_b64 s[14:15], s[10:11], 19
	v_readlane_b32 s18, v235, 31
	v_readlane_b32 s19, v235, 32
	s_add_u32 s14, s18, s14
	s_addc_u32 s15, s19, s15
	s_and_b64 s[18:19], s[4:5], exec
	s_cselect_b32 s11, s15, s3
	s_cselect_b32 s45, s14, s2
	s_add_u32 s16, s16, 0x40080
	s_addc_u32 s17, s17, 0
	s_add_u32 s46, s2, 0x100
	s_addc_u32 s47, s3, 0
	s_mov_b32 s48, -2
	s_waitcnt vmcnt(0)
	ds_read_b128 v[146:149], v153
	ds_read_b128 v[160:163], v153 offset:1024
	ds_read_b128 v[164:167], v153 offset:2048
	ds_read_b128 v[168:171], v153 offset:3072
	ds_read_b128 v[172:175], v154
	ds_read_b128 v[176:179], v154 offset:1024
	ds_read_b128 v[180:183], v154 offset:2048
	ds_read_b128 v[184:187], v154 offset:3072
	s_add_u32 s2, s16, 0xfffc0080
	s_addc_u32 s3, s17, -1
	s_cmp_eq_u32 s48, 12
	s_cselect_b32 s19, s43, s3
	s_cselect_b32 s18, s44, s2
	s_cselect_b32 s3, s11, s47
	s_cselect_b32 s2, s45, s46
	v_lshl_add_u64 v[194:195], s[16:17], 0, v[140:141]
	s_add_i32 m0, s22, 0xc000
	ds_read_b128 v[190:193], v155
	ds_read_b128 v[198:201], v155 offset:1024
	ds_read_b128 v[202:205], v155 offset:2048
	ds_read_b128 v[206:209], v155 offset:3072
	ds_read_b128 v[210:213], v155 offset:4096
	ds_read_b128 v[214:217], v155 offset:5120
	ds_read_b128 v[218:221], v155 offset:6144
	ds_read_b128 v[222:225], v155 offset:7168
	global_load_lds_dwordx4 v[194:195], off
	v_lshl_add_u64 v[194:195], s[16:17], 0, v[142:143]
	s_add_i32 m0, s22, 0xe000
	s_nop 0
	global_load_lds_dwordx4 v[194:195], off
	s_waitcnt vmcnt(8)
	s_waitcnt lgkmcnt(0)
	s_barrier
	s_waitcnt lgkmcnt(0)
	v_mfma_f32_16x16x32_bf16 v[124:127], v[146:149], v[190:193], 0
	v_mfma_f32_16x16x32_bf16 v[116:119], v[164:167], v[190:193], 0
	v_mfma_f32_16x16x32_bf16 v[100:103], v[164:167], v[202:205], 0
	v_mfma_f32_16x16x32_bf16 v[108:111], v[146:149], v[202:205], 0
	v_mfma_f32_16x16x32_bf16 v[92:95], v[146:149], v[210:213], 0
	v_mfma_f32_16x16x32_bf16 v[84:87], v[164:167], v[210:213], 0
	v_mfma_f32_16x16x32_bf16 v[68:71], v[164:167], v[218:221], 0
	v_mfma_f32_16x16x32_bf16 v[76:79], v[146:149], v[218:221], 0
	v_mfma_f32_16x16x32_bf16 v[124:127], v[160:163], v[198:201], v[124:127]
	v_mfma_f32_16x16x32_bf16 v[116:119], v[168:171], v[198:201], v[116:119]
	v_mfma_f32_16x16x32_bf16 v[100:103], v[168:171], v[206:209], v[100:103]
	v_mfma_f32_16x16x32_bf16 v[108:111], v[160:163], v[206:209], v[108:111]
	v_mfma_f32_16x16x32_bf16 v[92:95], v[160:163], v[214:217], v[92:95]
	v_mfma_f32_16x16x32_bf16 v[84:87], v[168:171], v[214:217], v[84:87]
	v_mfma_f32_16x16x32_bf16 v[68:71], v[168:171], v[222:225], v[68:71]
	v_mfma_f32_16x16x32_bf16 v[76:79], v[160:163], v[222:225], v[76:79]
	v_mfma_f32_16x16x32_bf16 v[120:123], v[172:175], v[190:193], 0
	v_mfma_f32_16x16x32_bf16 v[112:115], v[180:183], v[190:193], 0
	v_mfma_f32_16x16x32_bf16 v[96:99], v[180:183], v[202:205], 0
	v_mfma_f32_16x16x32_bf16 v[104:107], v[172:175], v[202:205], 0
	v_mfma_f32_16x16x32_bf16 v[88:91], v[172:175], v[210:213], 0
	v_mfma_f32_16x16x32_bf16 v[80:83], v[180:183], v[210:213], 0
	v_mfma_f32_16x16x32_bf16 v[64:67], v[180:183], v[218:221], 0
	v_mfma_f32_16x16x32_bf16 v[72:75], v[172:175], v[218:221], 0
	v_mfma_f32_16x16x32_bf16 v[120:123], v[176:179], v[198:201], v[120:123]
	v_mfma_f32_16x16x32_bf16 v[112:115], v[184:187], v[198:201], v[112:115]
	v_mfma_f32_16x16x32_bf16 v[96:99], v[184:187], v[206:209], v[96:99]
	v_mfma_f32_16x16x32_bf16 v[104:107], v[176:179], v[206:209], v[104:107]
	v_mfma_f32_16x16x32_bf16 v[88:91], v[176:179], v[214:217], v[88:91]
	v_mfma_f32_16x16x32_bf16 v[80:83], v[184:187], v[214:217], v[80:83]
	v_mfma_f32_16x16x32_bf16 v[64:67], v[184:187], v[222:225], v[64:67]
	v_mfma_f32_16x16x32_bf16 v[72:75], v[176:179], v[222:225], v[72:75]
	s_barrier
	s_add_i32 s49, s35, s20
	v_lshl_add_u64 v[194:195], s[2:3], 0, v[132:133]
	s_mov_b32 m0, s49
	ds_read_b128 v[190:193], v155 offset:16384
	ds_read_b128 v[198:201], v155 offset:17408
	ds_read_b128 v[202:205], v155 offset:18432
	ds_read_b128 v[206:209], v155 offset:19456
	ds_read_b128 v[210:213], v155 offset:20480
	ds_read_b128 v[214:217], v155 offset:21504
	ds_read_b128 v[218:221], v155 offset:22528
	ds_read_b128 v[222:225], v155 offset:23552
	global_load_lds_dwordx4 v[194:195], off
	s_add_i32 m0, s49, 0x2000
	s_add_u32 s50, s2, 0x40000
	v_lshl_add_u64 v[226:227], s[2:3], 0, v[128:129]
	s_addc_u32 s51, s3, 0
	s_add_i32 s49, s36, s20
	global_load_lds_dwordx4 v[226:227], off
	v_lshl_add_u64 v[228:229], s[50:51], 0, v[132:133]
	s_mov_b32 m0, s49
	v_lshl_add_u64 v[230:231], s[18:19], 0, v[130:131]
	global_load_lds_dwordx4 v[228:229], off
	v_lshl_add_u64 v[228:229], s[50:51], 0, v[128:129]
	s_add_i32 m0, s49, 0x2000
	s_nop 0
	global_load_lds_dwordx4 v[228:229], off
	v_lshl_add_u64 v[228:229], s[18:19], 0, v[134:135]
	s_mov_b32 m0, s22
	s_nop 0
	global_load_lds_dwordx4 v[228:229], off
	s_mov_b32 m0, s23
	s_nop 0
	global_load_lds_dwordx4 v[230:231], off
	s_waitcnt vmcnt(8)
	s_waitcnt lgkmcnt(0)
	s_barrier
; #define PG8_STAGE(bufoff, gbase, voff) do { _Pragma("unroll") for (int _i = 0; _i < 2; ++_i) \
;         __builtin_amdgcn_global_load_lds((const unsigned*)((const char*)(gbase) + (voff)[_i]), (LAS unsigned*)(lds + (bufoff) + ldsw + _i * 8192), 16, 0, 0); } while (0)
; #define PG8_LDA(dst, b, h) do { _Pragma("unroll") for (int m = 0; m < 4; ++m) _Pragma("unroll") for (int k = 0; k < 2; ++k) dst[m][k] = *(const LAS bf16x8*)(lds + PG8_SA(b, h) + aoff + m * 2048 + k * 1024); } while (0)
; #define PG8_LDB(dst, b, h) do { _Pragma("unroll") for (int n = 0; n < 2; ++n) _Pragma("unroll") for (int k = 0; k < 2; ++k) dst[n][k] = *(const LAS bf16x8*)(lds + PG8_SB(b, h) + boff + n * 2048 + k * 1024); } while (0)
; #define PG8_MMA(ai, bj, At, Bt) do { __builtin_amdgcn_s_setprio(1); _Pragma("unroll") for (int m = 0; m < 4; ++m) _Pragma("unroll") for (int n = 0; n < 2; ++n) _Pragma("unroll") for (int k = 0; k < 2; ++k) \
;         acc[ai][bj][m][n] = __builtin_amdgcn_mfma_f32_16x16x32_bf16(Bt[n][k], At[m][k], acc[ai][bj][m][n], 0, 0, 0); __builtin_amdgcn_s_setprio(0); } while (0)
; #define PG8_WAIT_V(n) asm volatile("s_waitcnt vmcnt(" #n ")" ::: "memory")
; #define PG8_WAIT_L(n) asm volatile("s_waitcnt lgkmcnt(" #n ")" ::: "memory")
; #define PG8_BAR __builtin_amdgcn_s_barrier()
; #define PG8_SCHED __builtin_amdgcn_sched_barrier(0)
; template <class Epi>
; __device__ __forceinline__ void gemm_phase(LAS unsigned char* lds, const Gemm g, const StaticOrder& S, const Epi& E) {
;     ...
;             PG8_WAIT_V(8); PG8_WAIT_L(0); PG8_BAR; PG8_MMA(1, 0, At, B0); PG8_MMA(1, 1, At, B1); PG8_BAR; PG8_SCHED;
;             PG8_LDB(B0, 1, 0); PG8_LDB(B1, 1, 1); PG8_SCHED; PG8_LDA(At, 1, 0); PG8_STAGE(PG8_SA(0, 1), a2 + hstepA, voffA);
;             PG8_WAIT_V(8); PG8_WAIT_L(0); PG8_BAR; PG8_MMA(0, 0, At, B0); PG8_MMA(0, 1, At, B1); PG8_BAR; PG8_SCHED;
	s_waitcnt lgkmcnt(0)
	v_mfma_f32_16x16x32_bf16 v[60:63], v[146:149], v[190:193], 0
	v_mfma_f32_16x16x32_bf16 v[52:55], v[164:167], v[190:193], 0
	v_mfma_f32_16x16x32_bf16 v[36:39], v[164:167], v[202:205], 0
	v_mfma_f32_16x16x32_bf16 v[44:47], v[146:149], v[202:205], 0
	v_mfma_f32_16x16x32_bf16 v[28:31], v[146:149], v[210:213], 0
	v_mfma_f32_16x16x32_bf16 v[20:23], v[164:167], v[210:213], 0
	v_mfma_f32_16x16x32_bf16 v[4:7], v[164:167], v[218:221], 0
	v_mfma_f32_16x16x32_bf16 v[12:15], v[146:149], v[218:221], 0
	v_mfma_f32_16x16x32_bf16 v[60:63], v[160:163], v[198:201], v[60:63]
	v_mfma_f32_16x16x32_bf16 v[52:55], v[168:171], v[198:201], v[52:55]
	v_mfma_f32_16x16x32_bf16 v[36:39], v[168:171], v[206:209], v[36:39]
	v_mfma_f32_16x16x32_bf16 v[44:47], v[160:163], v[206:209], v[44:47]
	v_mfma_f32_16x16x32_bf16 v[28:31], v[160:163], v[214:217], v[28:31]
	v_mfma_f32_16x16x32_bf16 v[20:23], v[168:171], v[214:217], v[20:23]
	v_mfma_f32_16x16x32_bf16 v[4:7], v[168:171], v[222:225], v[4:7]
	v_mfma_f32_16x16x32_bf16 v[12:15], v[160:163], v[222:225], v[12:15]
	v_mfma_f32_16x16x32_bf16 v[56:59], v[172:175], v[190:193], 0
	v_mfma_f32_16x16x32_bf16 v[48:51], v[180:183], v[190:193], 0
	v_mfma_f32_16x16x32_bf16 v[32:35], v[180:183], v[202:205], 0
	v_mfma_f32_16x16x32_bf16 v[40:43], v[172:175], v[202:205], 0
	v_mfma_f32_16x16x32_bf16 v[24:27], v[172:175], v[210:213], 0
	v_mfma_f32_16x16x32_bf16 v[16:19], v[180:183], v[210:213], 0
	v_mfma_f32_16x16x32_bf16 v[0:3], v[180:183], v[218:221], 0
	v_mfma_f32_16x16x32_bf16 v[8:11], v[172:175], v[218:221], 0
	v_mfma_f32_16x16x32_bf16 v[56:59], v[176:179], v[198:201], v[56:59]
	v_mfma_f32_16x16x32_bf16 v[48:51], v[184:187], v[198:201], v[48:51]
	v_mfma_f32_16x16x32_bf16 v[32:35], v[184:187], v[206:209], v[32:35]
	v_mfma_f32_16x16x32_bf16 v[40:43], v[176:179], v[206:209], v[40:43]
	v_mfma_f32_16x16x32_bf16 v[24:27], v[176:179], v[214:217], v[24:27]
	v_mfma_f32_16x16x32_bf16 v[16:19], v[184:187], v[214:217], v[16:19]
	v_mfma_f32_16x16x32_bf16 v[0:3], v[184:187], v[222:225], v[0:3]
	v_mfma_f32_16x16x32_bf16 v[8:11], v[176:179], v[222:225], v[8:11]
	s_barrier
	s_add_i32 s49, 0, 0x18000
	v_add_u32_e32 v136, s49, v151
	s_add_i32 s50, 0, 0x1c000
	ds_read_b128 v[146:149], v136
	ds_read_b128 v[160:163], v136 offset:1024
	ds_read_b128 v[164:167], v136 offset:2048
	ds_read_b128 v[168:171], v136 offset:3072
	v_add_u32_e32 v136, s50, v151
	ds_read_b128 v[172:175], v136
	ds_read_b128 v[176:179], v136 offset:1024
	ds_read_b128 v[180:183], v136 offset:2048
	ds_read_b128 v[184:187], v136 offset:3072
	s_add_u32 s18, s18, 0x40000
	s_addc_u32 s19, s19, 0
	s_mov_b32 m0, s24
	v_lshl_add_u64 v[232:233], s[18:19], 0, v[134:135]
	ds_read_b128 v[190:193], v155 offset:32768
	ds_read_b128 v[198:201], v155 offset:33792
	ds_read_b128 v[202:205], v155 offset:34816
	ds_read_b128 v[206:209], v155 offset:35840
	ds_read_b128 v[210:213], v155 offset:36864
	ds_read_b128 v[214:217], v155 offset:37888
	ds_read_b128 v[218:221], v155 offset:38912
	ds_read_b128 v[222:225], v155 offset:39936
	global_load_lds_dwordx4 v[232:233], off
	v_lshl_add_u64 v[232:233], s[18:19], 0, v[130:131]
	s_mov_b32 m0, s25
	s_nop 0
	global_load_lds_dwordx4 v[232:233], off
	s_waitcnt vmcnt(8)
	s_waitcnt lgkmcnt(0)
	s_barrier
	s_waitcnt lgkmcnt(0)
	v_mfma_f32_16x16x32_bf16 v[124:127], v[146:149], v[190:193], v[124:127]
	v_mfma_f32_16x16x32_bf16 v[116:119], v[164:167], v[190:193], v[116:119]
	v_mfma_f32_16x16x32_bf16 v[100:103], v[164:167], v[202:205], v[100:103]
	v_mfma_f32_16x16x32_bf16 v[108:111], v[146:149], v[202:205], v[108:111]
	v_mfma_f32_16x16x32_bf16 v[92:95], v[146:149], v[210:213], v[92:95]
	v_mfma_f32_16x16x32_bf16 v[84:87], v[164:167], v[210:213], v[84:87]
	v_mfma_f32_16x16x32_bf16 v[68:71], v[164:167], v[218:221], v[68:71]
	v_mfma_f32_16x16x32_bf16 v[76:79], v[146:149], v[218:221], v[76:79]
	v_mfma_f32_16x16x32_bf16 v[124:127], v[160:163], v[198:201], v[124:127]
	v_mfma_f32_16x16x32_bf16 v[116:119], v[168:171], v[198:201], v[116:119]
	v_mfma_f32_16x16x32_bf16 v[100:103], v[168:171], v[206:209], v[100:103]
	v_mfma_f32_16x16x32_bf16 v[108:111], v[160:163], v[206:209], v[108:111]
	v_mfma_f32_16x16x32_bf16 v[92:95], v[160:163], v[214:217], v[92:95]
	v_mfma_f32_16x16x32_bf16 v[84:87], v[168:171], v[214:217], v[84:87]
	v_mfma_f32_16x16x32_bf16 v[68:71], v[168:171], v[222:225], v[68:71]
	v_mfma_f32_16x16x32_bf16 v[76:79], v[160:163], v[222:225], v[76:79]
	v_mfma_f32_16x16x32_bf16 v[120:123], v[172:175], v[190:193], v[120:123]
	v_mfma_f32_16x16x32_bf16 v[112:115], v[180:183], v[190:193], v[112:115]
	v_mfma_f32_16x16x32_bf16 v[96:99], v[180:183], v[202:205], v[96:99]
	v_mfma_f32_16x16x32_bf16 v[104:107], v[172:175], v[202:205], v[104:107]
	v_mfma_f32_16x16x32_bf16 v[88:91], v[172:175], v[210:213], v[88:91]
	v_mfma_f32_16x16x32_bf16 v[80:83], v[180:183], v[210:213], v[80:83]
	v_mfma_f32_16x16x32_bf16 v[64:67], v[180:183], v[218:221], v[64:67]
	v_mfma_f32_16x16x32_bf16 v[72:75], v[172:175], v[218:221], v[72:75]
	v_mfma_f32_16x16x32_bf16 v[120:123], v[176:179], v[198:201], v[120:123]
	v_mfma_f32_16x16x32_bf16 v[112:115], v[184:187], v[198:201], v[112:115]
	v_mfma_f32_16x16x32_bf16 v[96:99], v[184:187], v[206:209], v[96:99]
	v_mfma_f32_16x16x32_bf16 v[104:107], v[176:179], v[206:209], v[104:107]
	v_mfma_f32_16x16x32_bf16 v[88:91], v[176:179], v[214:217], v[88:91]
	v_mfma_f32_16x16x32_bf16 v[80:83], v[184:187], v[214:217], v[80:83]
	v_mfma_f32_16x16x32_bf16 v[64:67], v[184:187], v[222:225], v[64:67]
	v_mfma_f32_16x16x32_bf16 v[72:75], v[176:179], v[222:225], v[72:75]
	s_barrier
; #define PG8_STAGE(bufoff, gbase, voff) do { _Pragma("unroll") for (int _i = 0; _i < 2; ++_i) \
;         __builtin_amdgcn_global_load_lds((const unsigned*)((const char*)(gbase) + (voff)[_i]), (LAS unsigned*)(lds + (bufoff) + ldsw + _i * 8192), 16, 0, 0); } while (0)
; #define PG8_LDA(dst, b, h) do { _Pragma("unroll") for (int m = 0; m < 4; ++m) _Pragma("unroll") for (int k = 0; k < 2; ++k) dst[m][k] = *(const LAS bf16x8*)(lds + PG8_SA(b, h) + aoff + m * 2048 + k * 1024); } while (0)
; #define PG8_LDB(dst, b, h) do { _Pragma("unroll") for (int n = 0; n < 2; ++n) _Pragma("unroll") for (int k = 0; k < 2; ++k) dst[n][k] = *(const LAS bf16x8*)(lds + PG8_SB(b, h) + boff + n * 2048 + k * 1024); } while (0)
; #define PG8_MMA(ai, bj, At, Bt) do { __builtin_amdgcn_s_setprio(1); _Pragma("unroll") for (int m = 0; m < 4; ++m) _Pragma("unroll") for (int n = 0; n < 2; ++n) _Pragma("unroll") for (int k = 0; k < 2; ++k) \
;         acc[ai][bj][m][n] = __builtin_amdgcn_mfma_f32_16x16x32_bf16(Bt[n][k], At[m][k], acc[ai][bj][m][n], 0, 0, 0); __builtin_amdgcn_s_setprio(0); } while (0)
; #define PG8_WAIT_V(n) asm volatile("s_waitcnt vmcnt(" #n ")" ::: "memory")
; #define PG8_WAIT_L(n) asm volatile("s_waitcnt lgkmcnt(" #n ")" ::: "memory")
; #define PG8_BAR __builtin_amdgcn_s_barrier()
; #define PG8_SCHED __builtin_amdgcn_sched_barrier(0)
; template <class Epi>
; __device__ __forceinline__ void gemm_phase(LAS unsigned char* lds, const Gemm g, const StaticOrder& S, const Epi& E) {
;     ...
;         for (int t = 0; t < nt; t += 2) {
;             const bool last = (t == nt - 2);
;             const char* a1 = cA + (size_t)(t + 1) * kstep;
;             const char* a2 = last ? nA : cA + (size_t)(t + 2) * kstep; const char* b2 = last ? nB : cB + (size_t)(t + 2) * kstep;
;             const char* a3 = a2 + kstep; const char* b3 = b2 + kstep;
;             PG8_LDB(B0, 0, 0); PG8_LDB(B1, 0, 1); PG8_SCHED; PG8_LDA(At, 0, 0); PG8_STAGE(PG8_SA(1, 1), a1 + hstepA, voffA);
;             PG8_WAIT_V(8); PG8_WAIT_L(0); PG8_BAR; PG8_MMA(0, 0, At, B0); PG8_MMA(0, 1, At, B1); PG8_BAR; PG8_SCHED;
;     ...
;             PG8_LDA(At, 1, 1); PG8_STAGE(PG8_SB(1, 0), b3, voffB); PG8_STAGE(PG8_SB(1, 1), b3 + hstepB, voffB); PG8_STAGE(PG8_SA(1, 0), a3, voffA);
;             PG8_WAIT_V(8); PG8_WAIT_L(0); PG8_BAR; PG8_MMA(1, 0, At, B0); PG8_MMA(1, 1, At, B1); PG8_BAR; PG8_SCHED;
	s_add_i32 s18, s49, s20
	v_lshl_add_u64 v[194:195], v[194:195], 0, s[6:7]
	s_mov_b32 m0, s18
	ds_read_b128 v[190:193], v155 offset:49152
	ds_read_b128 v[198:201], v155 offset:50176
	ds_read_b128 v[202:205], v155 offset:51200
	ds_read_b128 v[206:209], v155 offset:52224
	ds_read_b128 v[210:213], v155 offset:53248
	ds_read_b128 v[214:217], v155 offset:54272
	ds_read_b128 v[218:221], v155 offset:55296
	ds_read_b128 v[222:225], v155 offset:56320
	global_load_lds_dwordx4 v[194:195], off
	s_add_i32 m0, s18, 0x2000
	s_add_u32 s2, s2, 0x40080
	v_lshl_add_u64 v[194:195], v[226:227], 0, s[6:7]
	s_addc_u32 s3, s3, 0
	s_add_i32 s18, s50, s20
	global_load_lds_dwordx4 v[194:195], off
	v_lshl_add_u64 v[194:195], s[2:3], 0, v[132:133]
	s_mov_b32 m0, s18
	s_nop 0
	global_load_lds_dwordx4 v[194:195], off
	v_lshl_add_u64 v[194:195], s[2:3], 0, v[128:129]
	s_add_i32 m0, s18, 0x2000
	s_nop 0
	global_load_lds_dwordx4 v[194:195], off
	v_lshl_add_u64 v[194:195], v[228:229], 0, s[6:7]
	s_mov_b32 m0, s30
	s_nop 0
	global_load_lds_dwordx4 v[194:195], off
	v_lshl_add_u64 v[194:195], v[230:231], 0, s[6:7]
	s_mov_b32 m0, s31
	s_nop 0
	global_load_lds_dwordx4 v[194:195], off
	s_waitcnt vmcnt(8)
	s_waitcnt lgkmcnt(0)
	s_barrier
	s_waitcnt lgkmcnt(0)
	v_mfma_f32_16x16x32_bf16 v[60:63], v[146:149], v[190:193], v[60:63]
	v_mfma_f32_16x16x32_bf16 v[52:55], v[164:167], v[190:193], v[52:55]
	v_mfma_f32_16x16x32_bf16 v[36:39], v[164:167], v[202:205], v[36:39]
	v_mfma_f32_16x16x32_bf16 v[44:47], v[146:149], v[202:205], v[44:47]
	v_mfma_f32_16x16x32_bf16 v[28:31], v[146:149], v[210:213], v[28:31]
	v_mfma_f32_16x16x32_bf16 v[20:23], v[164:167], v[210:213], v[20:23]
	v_mfma_f32_16x16x32_bf16 v[4:7], v[164:167], v[218:221], v[4:7]
	v_mfma_f32_16x16x32_bf16 v[12:15], v[146:149], v[218:221], v[12:15]
	v_mfma_f32_16x16x32_bf16 v[60:63], v[160:163], v[198:201], v[60:63]
	v_mfma_f32_16x16x32_bf16 v[52:55], v[168:171], v[198:201], v[52:55]
	v_mfma_f32_16x16x32_bf16 v[36:39], v[168:171], v[206:209], v[36:39]
	v_mfma_f32_16x16x32_bf16 v[44:47], v[160:163], v[206:209], v[44:47]
	v_mfma_f32_16x16x32_bf16 v[28:31], v[160:163], v[214:217], v[28:31]
	v_mfma_f32_16x16x32_bf16 v[20:23], v[168:171], v[214:217], v[20:23]
	v_mfma_f32_16x16x32_bf16 v[4:7], v[168:171], v[222:225], v[4:7]
	v_mfma_f32_16x16x32_bf16 v[12:15], v[160:163], v[222:225], v[12:15]
	v_mfma_f32_16x16x32_bf16 v[56:59], v[172:175], v[190:193], v[56:59]
	v_mfma_f32_16x16x32_bf16 v[48:51], v[180:183], v[190:193], v[48:51]
	v_mfma_f32_16x16x32_bf16 v[32:35], v[180:183], v[202:205], v[32:35]
	v_mfma_f32_16x16x32_bf16 v[40:43], v[172:175], v[202:205], v[40:43]
	v_mfma_f32_16x16x32_bf16 v[24:27], v[172:175], v[210:213], v[24:27]
	v_mfma_f32_16x16x32_bf16 v[16:19], v[180:183], v[210:213], v[16:19]
	v_mfma_f32_16x16x32_bf16 v[0:3], v[180:183], v[218:221], v[0:3]
	v_mfma_f32_16x16x32_bf16 v[8:11], v[172:175], v[218:221], v[8:11]
	v_mfma_f32_16x16x32_bf16 v[56:59], v[176:179], v[198:201], v[56:59]
	v_mfma_f32_16x16x32_bf16 v[48:51], v[184:187], v[198:201], v[48:51]
	v_mfma_f32_16x16x32_bf16 v[32:35], v[184:187], v[206:209], v[32:35]
	v_mfma_f32_16x16x32_bf16 v[40:43], v[176:179], v[206:209], v[40:43]
	v_mfma_f32_16x16x32_bf16 v[24:27], v[176:179], v[214:217], v[24:27]
	v_mfma_f32_16x16x32_bf16 v[16:19], v[184:187], v[214:217], v[16:19]
	v_mfma_f32_16x16x32_bf16 v[0:3], v[184:187], v[222:225], v[0:3]
	v_mfma_f32_16x16x32_bf16 v[8:11], v[176:179], v[222:225], v[8:11]
	s_barrier
	s_add_i32 s48, s48, 2
	s_add_u32 s16, s16, 0x100
	s_addc_u32 s17, s17, 0
	s_add_u32 s46, s46, 0x100
	s_addc_u32 s47, s47, 0
	s_cmp_gt_u32 s48, 13
	s_cbranch_scc0 .LBB0_929
.LBB0_929:
	ds_read_b128 v[146:149], v153
	ds_read_b128 v[160:163], v153 offset:1024
	ds_read_b128 v[164:167], v153 offset:2048
	ds_read_b128 v[168:171], v153 offset:3072
	ds_read_b128 v[172:175], v154
	ds_read_b128 v[176:179], v154 offset:1024
	ds_read_b128 v[180:183], v154 offset:2048
	ds_read_b128 v[184:187], v154 offset:3072
	s_add_u32 s2, s16, 0xfffc0080
	s_addc_u32 s3, s17, -1
	s_cmp_eq_u32 s48, 12
	s_cselect_b32 s19, s43, s3
	s_cselect_b32 s18, s44, s2
	s_cselect_b32 s3, s11, s47
	s_cselect_b32 s2, s45, s46
	v_lshl_add_u64 v[194:195], s[16:17], 0, v[140:141]
	s_add_i32 m0, s22, 0xc000
	ds_read_b128 v[190:193], v155
	ds_read_b128 v[198:201], v155 offset:1024
	ds_read_b128 v[202:205], v155 offset:2048
	ds_read_b128 v[206:209], v155 offset:3072
	ds_read_b128 v[210:213], v155 offset:4096
	ds_read_b128 v[214:217], v155 offset:5120
	ds_read_b128 v[218:221], v155 offset:6144
	ds_read_b128 v[222:225], v155 offset:7168
	global_load_lds_dwordx4 v[194:195], off
	v_lshl_add_u64 v[194:195], s[16:17], 0, v[142:143]
	s_add_i32 m0, s22, 0xe000
	s_nop 0
	global_load_lds_dwordx4 v[194:195], off
	s_waitcnt vmcnt(8)
	s_waitcnt lgkmcnt(0)
	s_barrier
; #define PG8_STAGE(bufoff, gbase, voff) do { _Pragma("unroll") for (int _i = 0; _i < 2; ++_i) \
;         __builtin_amdgcn_global_load_lds((const unsigned*)((const char*)(gbase) + (voff)[_i]), (LAS unsigned*)(lds + (bufoff) + ldsw + _i * 8192), 16, 0, 0); } while (0)
; #define PG8_LDA(dst, b, h) do { _Pragma("unroll") for (int m = 0; m < 4; ++m) _Pragma("unroll") for (int k = 0; k < 2; ++k) dst[m][k] = *(const LAS bf16x8*)(lds + PG8_SA(b, h) + aoff + m * 2048 + k * 1024); } while (0)
; #define PG8_MMA(ai, bj, At, Bt) do { __builtin_amdgcn_s_setprio(1); _Pragma("unroll") for (int m = 0; m < 4; ++m) _Pragma("unroll") for (int n = 0; n < 2; ++n) _Pragma("unroll") for (int k = 0; k < 2; ++k) \
;         acc[ai][bj][m][n] = __builtin_amdgcn_mfma_f32_16x16x32_bf16(Bt[n][k], At[m][k], acc[ai][bj][m][n], 0, 0, 0); __builtin_amdgcn_s_setprio(0); } while (0)
; #define PG8_WAIT_V(n) asm volatile("s_waitcnt vmcnt(" #n ")" ::: "memory")
; #define PG8_WAIT_L(n) asm volatile("s_waitcnt lgkmcnt(" #n ")" ::: "memory")
; #define PG8_BAR __builtin_amdgcn_s_barrier()
; #define PG8_SCHED __builtin_amdgcn_sched_barrier(0)
; template <class Epi>
; __device__ __forceinline__ void gemm_phase(LAS unsigned char* lds, const Gemm g, const StaticOrder& S, const Epi& E) {
;     ...
;             PG8_WAIT_V(8); PG8_WAIT_L(0); PG8_BAR; PG8_MMA(0, 0, At, B0); PG8_MMA(0, 1, At, B1); PG8_BAR; PG8_SCHED;
;             PG8_LDA(At, 0, 1); PG8_STAGE(PG8_SB(0, 0), b2, voffB); PG8_STAGE(PG8_SB(0, 1), b2 + hstepB, voffB); PG8_STAGE(PG8_SA(0, 0), a2, voffA);
;             PG8_WAIT_V(8); PG8_WAIT_L(0); PG8_BAR; PG8_MMA(1, 0, At, B0); PG8_MMA(1, 1, At, B1); PG8_BAR; PG8_SCHED;
	s_waitcnt lgkmcnt(0)
	v_mfma_f32_16x16x32_bf16 v[124:127], v[146:149], v[190:193], v[124:127]
	v_mfma_f32_16x16x32_bf16 v[116:119], v[164:167], v[190:193], v[116:119]
	v_mfma_f32_16x16x32_bf16 v[100:103], v[164:167], v[202:205], v[100:103]
	v_mfma_f32_16x16x32_bf16 v[108:111], v[146:149], v[202:205], v[108:111]
	v_mfma_f32_16x16x32_bf16 v[92:95], v[146:149], v[210:213], v[92:95]
	v_mfma_f32_16x16x32_bf16 v[84:87], v[164:167], v[210:213], v[84:87]
	v_mfma_f32_16x16x32_bf16 v[68:71], v[164:167], v[218:221], v[68:71]
	v_mfma_f32_16x16x32_bf16 v[76:79], v[146:149], v[218:221], v[76:79]
	v_mfma_f32_16x16x32_bf16 v[124:127], v[160:163], v[198:201], v[124:127]
	v_mfma_f32_16x16x32_bf16 v[116:119], v[168:171], v[198:201], v[116:119]
	v_mfma_f32_16x16x32_bf16 v[100:103], v[168:171], v[206:209], v[100:103]
	v_mfma_f32_16x16x32_bf16 v[108:111], v[160:163], v[206:209], v[108:111]
	v_mfma_f32_16x16x32_bf16 v[92:95], v[160:163], v[214:217], v[92:95]
	v_mfma_f32_16x16x32_bf16 v[84:87], v[168:171], v[214:217], v[84:87]
	v_mfma_f32_16x16x32_bf16 v[68:71], v[168:171], v[222:225], v[68:71]
	v_mfma_f32_16x16x32_bf16 v[76:79], v[160:163], v[222:225], v[76:79]
	v_mfma_f32_16x16x32_bf16 v[120:123], v[172:175], v[190:193], v[120:123]
	v_mfma_f32_16x16x32_bf16 v[112:115], v[180:183], v[190:193], v[112:115]
	v_mfma_f32_16x16x32_bf16 v[96:99], v[180:183], v[202:205], v[96:99]
	v_mfma_f32_16x16x32_bf16 v[104:107], v[172:175], v[202:205], v[104:107]
	v_mfma_f32_16x16x32_bf16 v[88:91], v[172:175], v[210:213], v[88:91]
	v_mfma_f32_16x16x32_bf16 v[80:83], v[180:183], v[210:213], v[80:83]
	v_mfma_f32_16x16x32_bf16 v[64:67], v[180:183], v[218:221], v[64:67]
	v_mfma_f32_16x16x32_bf16 v[72:75], v[172:175], v[218:221], v[72:75]
	v_mfma_f32_16x16x32_bf16 v[120:123], v[176:179], v[198:201], v[120:123]
	v_mfma_f32_16x16x32_bf16 v[112:115], v[184:187], v[198:201], v[112:115]
	v_mfma_f32_16x16x32_bf16 v[96:99], v[184:187], v[206:209], v[96:99]
	v_mfma_f32_16x16x32_bf16 v[104:107], v[176:179], v[206:209], v[104:107]
	v_mfma_f32_16x16x32_bf16 v[88:91], v[176:179], v[214:217], v[88:91]
	v_mfma_f32_16x16x32_bf16 v[80:83], v[184:187], v[214:217], v[80:83]
	v_mfma_f32_16x16x32_bf16 v[64:67], v[184:187], v[222:225], v[64:67]
	v_mfma_f32_16x16x32_bf16 v[72:75], v[176:179], v[222:225], v[72:75]
	s_barrier
	s_add_i32 s49, s35, s20
	v_lshl_add_u64 v[194:195], s[2:3], 0, v[132:133]
	s_mov_b32 m0, s49
	ds_read_b128 v[190:193], v155 offset:16384
	ds_read_b128 v[198:201], v155 offset:17408
	ds_read_b128 v[202:205], v155 offset:18432
	ds_read_b128 v[206:209], v155 offset:19456
	ds_read_b128 v[210:213], v155 offset:20480
	ds_read_b128 v[214:217], v155 offset:21504
	ds_read_b128 v[218:221], v155 offset:22528
	ds_read_b128 v[222:225], v155 offset:23552
	global_load_lds_dwordx4 v[194:195], off
	s_add_i32 m0, s49, 0x2000
	s_add_u32 s50, s2, 0x40000
	v_lshl_add_u64 v[226:227], s[2:3], 0, v[128:129]
	s_addc_u32 s51, s3, 0
	s_add_i32 s49, s36, s20
	global_load_lds_dwordx4 v[226:227], off
	v_lshl_add_u64 v[228:229], s[50:51], 0, v[132:133]
	s_mov_b32 m0, s49
	v_lshl_add_u64 v[230:231], s[18:19], 0, v[130:131]
	global_load_lds_dwordx4 v[228:229], off
	v_lshl_add_u64 v[228:229], s[50:51], 0, v[128:129]
	s_add_i32 m0, s49, 0x2000
	s_nop 0
	global_load_lds_dwordx4 v[228:229], off
	v_lshl_add_u64 v[228:229], s[18:19], 0, v[134:135]
	s_mov_b32 m0, s22
	s_nop 0
	global_load_lds_dwordx4 v[228:229], off
	s_mov_b32 m0, s23
	s_nop 0
	global_load_lds_dwordx4 v[230:231], off
	s_waitcnt vmcnt(8)
	s_waitcnt lgkmcnt(0)
	s_barrier
	s_waitcnt lgkmcnt(0)
	v_mfma_f32_16x16x32_bf16 v[60:63], v[146:149], v[190:193], v[60:63]
	v_mfma_f32_16x16x32_bf16 v[52:55], v[164:167], v[190:193], v[52:55]
	v_mfma_f32_16x16x32_bf16 v[36:39], v[164:167], v[202:205], v[36:39]
	v_mfma_f32_16x16x32_bf16 v[44:47], v[146:149], v[202:205], v[44:47]
	v_mfma_f32_16x16x32_bf16 v[28:31], v[146:149], v[210:213], v[28:31]
	v_mfma_f32_16x16x32_bf16 v[20:23], v[164:167], v[210:213], v[20:23]
	v_mfma_f32_16x16x32_bf16 v[4:7], v[164:167], v[218:221], v[4:7]
	v_mfma_f32_16x16x32_bf16 v[12:15], v[146:149], v[218:221], v[12:15]
	v_mfma_f32_16x16x32_bf16 v[60:63], v[160:163], v[198:201], v[60:63]
	v_mfma_f32_16x16x32_bf16 v[52:55], v[168:171], v[198:201], v[52:55]
	v_mfma_f32_16x16x32_bf16 v[36:39], v[168:171], v[206:209], v[36:39]
	v_mfma_f32_16x16x32_bf16 v[44:47], v[160:163], v[206:209], v[44:47]
	v_mfma_f32_16x16x32_bf16 v[28:31], v[160:163], v[214:217], v[28:31]
	v_mfma_f32_16x16x32_bf16 v[20:23], v[168:171], v[214:217], v[20:23]
	v_mfma_f32_16x16x32_bf16 v[4:7], v[168:171], v[222:225], v[4:7]
	v_mfma_f32_16x16x32_bf16 v[12:15], v[160:163], v[222:225], v[12:15]
	v_mfma_f32_16x16x32_bf16 v[56:59], v[172:175], v[190:193], v[56:59]
	v_mfma_f32_16x16x32_bf16 v[48:51], v[180:183], v[190:193], v[48:51]
	v_mfma_f32_16x16x32_bf16 v[32:35], v[180:183], v[202:205], v[32:35]
	v_mfma_f32_16x16x32_bf16 v[40:43], v[172:175], v[202:205], v[40:43]
	v_mfma_f32_16x16x32_bf16 v[24:27], v[172:175], v[210:213], v[24:27]
	v_mfma_f32_16x16x32_bf16 v[16:19], v[180:183], v[210:213], v[16:19]
	v_mfma_f32_16x16x32_bf16 v[0:3], v[180:183], v[218:221], v[0:3]
	v_mfma_f32_16x16x32_bf16 v[8:11], v[172:175], v[218:221], v[8:11]
	v_mfma_f32_16x16x32_bf16 v[56:59], v[176:179], v[198:201], v[56:59]
	v_mfma_f32_16x16x32_bf16 v[48:51], v[184:187], v[198:201], v[48:51]
	v_mfma_f32_16x16x32_bf16 v[32:35], v[184:187], v[206:209], v[32:35]
	v_mfma_f32_16x16x32_bf16 v[40:43], v[176:179], v[206:209], v[40:43]
	v_mfma_f32_16x16x32_bf16 v[24:27], v[176:179], v[214:217], v[24:27]
	v_mfma_f32_16x16x32_bf16 v[16:19], v[184:187], v[214:217], v[16:19]
	v_mfma_f32_16x16x32_bf16 v[0:3], v[184:187], v[222:225], v[0:3]
	v_mfma_f32_16x16x32_bf16 v[8:11], v[176:179], v[222:225], v[8:11]
	s_barrier
; #define PG8_STAGE(bufoff, gbase, voff) do { _Pragma("unroll") for (int _i = 0; _i < 2; ++_i) \
;         __builtin_amdgcn_global_load_lds((const unsigned*)((const char*)(gbase) + (voff)[_i]), (LAS unsigned*)(lds + (bufoff) + ldsw + _i * 8192), 16, 0, 0); } while (0)
; #define PG8_LDA(dst, b, h) do { _Pragma("unroll") for (int m = 0; m < 4; ++m) _Pragma("unroll") for (int k = 0; k < 2; ++k) dst[m][k] = *(const LAS bf16x8*)(lds + PG8_SA(b, h) + aoff + m * 2048 + k * 1024); } while (0)
; #define PG8_LDB(dst, b, h) do { _Pragma("unroll") for (int n = 0; n < 2; ++n) _Pragma("unroll") for (int k = 0; k < 2; ++k) dst[n][k] = *(const LAS bf16x8*)(lds + PG8_SB(b, h) + boff + n * 2048 + k * 1024); } while (0)
; #define PG8_MMA(ai, bj, At, Bt) do { __builtin_amdgcn_s_setprio(1); _Pragma("unroll") for (int m = 0; m < 4; ++m) _Pragma("unroll") for (int n = 0; n < 2; ++n) _Pragma("unroll") for (int k = 0; k < 2; ++k) \
;         acc[ai][bj][m][n] = __builtin_amdgcn_mfma_f32_16x16x32_bf16(Bt[n][k], At[m][k], acc[ai][bj][m][n], 0, 0, 0); __builtin_amdgcn_s_setprio(0); } while (0)
; #define PG8_WAIT_V(n) asm volatile("s_waitcnt vmcnt(" #n ")" ::: "memory")
; #define PG8_WAIT_L(n) asm volatile("s_waitcnt lgkmcnt(" #n ")" ::: "memory")
; #define PG8_BAR __builtin_amdgcn_s_barrier()
; #define PG8_SCHED __builtin_amdgcn_sched_barrier(0)
; template <class Epi>
; __device__ __forceinline__ void gemm_phase(LAS unsigned char* lds, const Gemm g, const StaticOrder& S, const Epi& E) {
;     ...
;             PG8_LDB(B0, 1, 0); PG8_LDB(B1, 1, 1); PG8_SCHED; PG8_LDA(At, 1, 0); PG8_STAGE(PG8_SA(0, 1), a2 + hstepA, voffA);
;             PG8_WAIT_V(8); PG8_WAIT_L(0); PG8_BAR; PG8_MMA(0, 0, At, B0); PG8_MMA(0, 1, At, B1); PG8_BAR; PG8_SCHED;
	s_add_i32 s49, 0, 0x18000
	v_add_u32_e32 v136, s49, v151
	s_add_i32 s50, 0, 0x1c000
	ds_read_b128 v[146:149], v136
	ds_read_b128 v[160:163], v136 offset:1024
	ds_read_b128 v[164:167], v136 offset:2048
	ds_read_b128 v[168:171], v136 offset:3072
	v_add_u32_e32 v136, s50, v151
	ds_read_b128 v[172:175], v136
	ds_read_b128 v[176:179], v136 offset:1024
	ds_read_b128 v[180:183], v136 offset:2048
	ds_read_b128 v[184:187], v136 offset:3072
	s_add_u32 s18, s18, 0x40000
	s_addc_u32 s19, s19, 0
	s_mov_b32 m0, s24
	v_lshl_add_u64 v[232:233], s[18:19], 0, v[134:135]
	ds_read_b128 v[190:193], v155 offset:32768
	ds_read_b128 v[198:201], v155 offset:33792
	ds_read_b128 v[202:205], v155 offset:34816
	ds_read_b128 v[206:209], v155 offset:35840
	ds_read_b128 v[210:213], v155 offset:36864
	ds_read_b128 v[214:217], v155 offset:37888
	ds_read_b128 v[218:221], v155 offset:38912
	ds_read_b128 v[222:225], v155 offset:39936
	global_load_lds_dwordx4 v[232:233], off
	v_lshl_add_u64 v[232:233], s[18:19], 0, v[130:131]
	s_mov_b32 m0, s25
	s_nop 0
	global_load_lds_dwordx4 v[232:233], off
	s_waitcnt vmcnt(8)
	s_waitcnt lgkmcnt(0)
	s_barrier
	s_waitcnt lgkmcnt(0)
	v_mfma_f32_16x16x32_bf16 v[124:127], v[146:149], v[190:193], v[124:127]
	v_mfma_f32_16x16x32_bf16 v[116:119], v[164:167], v[190:193], v[116:119]
	v_mfma_f32_16x16x32_bf16 v[100:103], v[164:167], v[202:205], v[100:103]
	v_mfma_f32_16x16x32_bf16 v[108:111], v[146:149], v[202:205], v[108:111]
	v_mfma_f32_16x16x32_bf16 v[92:95], v[146:149], v[210:213], v[92:95]
	v_mfma_f32_16x16x32_bf16 v[84:87], v[164:167], v[210:213], v[84:87]
	v_mfma_f32_16x16x32_bf16 v[68:71], v[164:167], v[218:221], v[68:71]
	v_mfma_f32_16x16x32_bf16 v[76:79], v[146:149], v[218:221], v[76:79]
	v_mfma_f32_16x16x32_bf16 v[124:127], v[160:163], v[198:201], v[124:127]
	v_mfma_f32_16x16x32_bf16 v[116:119], v[168:171], v[198:201], v[116:119]
	v_mfma_f32_16x16x32_bf16 v[100:103], v[168:171], v[206:209], v[100:103]
	v_mfma_f32_16x16x32_bf16 v[108:111], v[160:163], v[206:209], v[108:111]
	v_mfma_f32_16x16x32_bf16 v[92:95], v[160:163], v[214:217], v[92:95]
	v_mfma_f32_16x16x32_bf16 v[84:87], v[168:171], v[214:217], v[84:87]
	v_mfma_f32_16x16x32_bf16 v[68:71], v[168:171], v[222:225], v[68:71]
	v_mfma_f32_16x16x32_bf16 v[76:79], v[160:163], v[222:225], v[76:79]
	v_mfma_f32_16x16x32_bf16 v[120:123], v[172:175], v[190:193], v[120:123]
	v_mfma_f32_16x16x32_bf16 v[112:115], v[180:183], v[190:193], v[112:115]
	v_mfma_f32_16x16x32_bf16 v[96:99], v[180:183], v[202:205], v[96:99]
	v_mfma_f32_16x16x32_bf16 v[104:107], v[172:175], v[202:205], v[104:107]
	v_mfma_f32_16x16x32_bf16 v[88:91], v[172:175], v[210:213], v[88:91]
	v_mfma_f32_16x16x32_bf16 v[80:83], v[180:183], v[210:213], v[80:83]
	v_mfma_f32_16x16x32_bf16 v[64:67], v[180:183], v[218:221], v[64:67]
	v_mfma_f32_16x16x32_bf16 v[72:75], v[172:175], v[218:221], v[72:75]
	v_mfma_f32_16x16x32_bf16 v[120:123], v[176:179], v[198:201], v[120:123]
	v_mfma_f32_16x16x32_bf16 v[112:115], v[184:187], v[198:201], v[112:115]
	v_mfma_f32_16x16x32_bf16 v[96:99], v[184:187], v[206:209], v[96:99]
	v_mfma_f32_16x16x32_bf16 v[104:107], v[176:179], v[206:209], v[104:107]
	v_mfma_f32_16x16x32_bf16 v[88:91], v[176:179], v[214:217], v[88:91]
	v_mfma_f32_16x16x32_bf16 v[80:83], v[184:187], v[214:217], v[80:83]
	v_mfma_f32_16x16x32_bf16 v[64:67], v[184:187], v[222:225], v[64:67]
	v_mfma_f32_16x16x32_bf16 v[72:75], v[176:179], v[222:225], v[72:75]
	s_barrier
; #define PG8_STAGE(bufoff, gbase, voff) do { _Pragma("unroll") for (int _i = 0; _i < 2; ++_i) \
;         __builtin_amdgcn_global_load_lds((const unsigned*)((const char*)(gbase) + (voff)[_i]), (LAS unsigned*)(lds + (bufoff) + ldsw + _i * 8192), 16, 0, 0); } while (0)
; #define PG8_LDA(dst, b, h) do { _Pragma("unroll") for (int m = 0; m < 4; ++m) _Pragma("unroll") for (int k = 0; k < 2; ++k) dst[m][k] = *(const LAS bf16x8*)(lds + PG8_SA(b, h) + aoff + m * 2048 + k * 1024); } while (0)
; #define PG8_MMA(ai, bj, At, Bt) do { __builtin_amdgcn_s_setprio(1); _Pragma("unroll") for (int m = 0; m < 4; ++m) _Pragma("unroll") for (int n = 0; n < 2; ++n) _Pragma("unroll") for (int k = 0; k < 2; ++k) \
;         acc[ai][bj][m][n] = __builtin_amdgcn_mfma_f32_16x16x32_bf16(Bt[n][k], At[m][k], acc[ai][bj][m][n], 0, 0, 0); __builtin_amdgcn_s_setprio(0); } while (0)
; #define PG8_WAIT_V(n) asm volatile("s_waitcnt vmcnt(" #n ")" ::: "memory")
; #define PG8_WAIT_L(n) asm volatile("s_waitcnt lgkmcnt(" #n ")" ::: "memory")
; #define PG8_BAR __builtin_amdgcn_s_barrier()
; #define PG8_SCHED __builtin_amdgcn_sched_barrier(0)
; template <class Epi>
; __device__ __forceinline__ void gemm_phase(LAS unsigned char* lds, const Gemm g, const StaticOrder& S, const Epi& E) {
;     ...
;             PG8_LDA(At, 1, 1); PG8_STAGE(PG8_SB(1, 0), b3, voffB); PG8_STAGE(PG8_SB(1, 1), b3 + hstepB, voffB); PG8_STAGE(PG8_SA(1, 0), a3, voffA);
;             PG8_WAIT_V(8); PG8_WAIT_L(0); PG8_BAR; PG8_MMA(1, 0, At, B0); PG8_MMA(1, 1, At, B1); PG8_BAR; PG8_SCHED;
;         }
;         if (wr == 0) PG8_BAR;
	s_add_i32 s18, s49, s20
	v_lshl_add_u64 v[194:195], v[194:195], 0, s[6:7]
	s_mov_b32 m0, s18
	ds_read_b128 v[190:193], v155 offset:49152
	ds_read_b128 v[198:201], v155 offset:50176
	ds_read_b128 v[202:205], v155 offset:51200
	ds_read_b128 v[206:209], v155 offset:52224
	ds_read_b128 v[210:213], v155 offset:53248
	ds_read_b128 v[214:217], v155 offset:54272
	ds_read_b128 v[218:221], v155 offset:55296
	ds_read_b128 v[222:225], v155 offset:56320
	global_load_lds_dwordx4 v[194:195], off
	s_add_i32 m0, s18, 0x2000
	s_add_u32 s2, s2, 0x40080
	v_lshl_add_u64 v[194:195], v[226:227], 0, s[6:7]
	s_addc_u32 s3, s3, 0
	s_add_i32 s18, s50, s20
	global_load_lds_dwordx4 v[194:195], off
	v_lshl_add_u64 v[194:195], s[2:3], 0, v[132:133]
	s_mov_b32 m0, s18
	s_nop 0
	global_load_lds_dwordx4 v[194:195], off
	v_lshl_add_u64 v[194:195], s[2:3], 0, v[128:129]
	s_add_i32 m0, s18, 0x2000
	s_nop 0
	global_load_lds_dwordx4 v[194:195], off
	v_lshl_add_u64 v[194:195], v[228:229], 0, s[6:7]
	s_mov_b32 m0, s30
	s_nop 0
	global_load_lds_dwordx4 v[194:195], off
	v_lshl_add_u64 v[194:195], v[230:231], 0, s[6:7]
	s_mov_b32 m0, s31
	s_nop 0
	global_load_lds_dwordx4 v[194:195], off
	s_waitcnt vmcnt(8)
	s_waitcnt lgkmcnt(0)
	s_barrier
	s_waitcnt lgkmcnt(0)
	v_mfma_f32_16x16x32_bf16 v[60:63], v[146:149], v[190:193], v[60:63]
	v_mfma_f32_16x16x32_bf16 v[52:55], v[164:167], v[190:193], v[52:55]
	v_mfma_f32_16x16x32_bf16 v[36:39], v[164:167], v[202:205], v[36:39]
	v_mfma_f32_16x16x32_bf16 v[44:47], v[146:149], v[202:205], v[44:47]
	v_mfma_f32_16x16x32_bf16 v[28:31], v[146:149], v[210:213], v[28:31]
	v_mfma_f32_16x16x32_bf16 v[20:23], v[164:167], v[210:213], v[20:23]
	v_mfma_f32_16x16x32_bf16 v[4:7], v[164:167], v[218:221], v[4:7]
	v_mfma_f32_16x16x32_bf16 v[12:15], v[146:149], v[218:221], v[12:15]
	v_mfma_f32_16x16x32_bf16 v[60:63], v[160:163], v[198:201], v[60:63]
	v_mfma_f32_16x16x32_bf16 v[52:55], v[168:171], v[198:201], v[52:55]
	v_mfma_f32_16x16x32_bf16 v[36:39], v[168:171], v[206:209], v[36:39]
	v_mfma_f32_16x16x32_bf16 v[44:47], v[160:163], v[206:209], v[44:47]
	v_mfma_f32_16x16x32_bf16 v[28:31], v[160:163], v[214:217], v[28:31]
	v_mfma_f32_16x16x32_bf16 v[20:23], v[168:171], v[214:217], v[20:23]
	v_mfma_f32_16x16x32_bf16 v[4:7], v[168:171], v[222:225], v[4:7]
	v_mfma_f32_16x16x32_bf16 v[12:15], v[160:163], v[222:225], v[12:15]
	v_mfma_f32_16x16x32_bf16 v[56:59], v[172:175], v[190:193], v[56:59]
	v_mfma_f32_16x16x32_bf16 v[48:51], v[180:183], v[190:193], v[48:51]
	v_mfma_f32_16x16x32_bf16 v[32:35], v[180:183], v[202:205], v[32:35]
	v_mfma_f32_16x16x32_bf16 v[40:43], v[172:175], v[202:205], v[40:43]
	v_mfma_f32_16x16x32_bf16 v[24:27], v[172:175], v[210:213], v[24:27]
	v_mfma_f32_16x16x32_bf16 v[16:19], v[180:183], v[210:213], v[16:19]
	v_mfma_f32_16x16x32_bf16 v[0:3], v[180:183], v[218:221], v[0:3]
	v_mfma_f32_16x16x32_bf16 v[8:11], v[172:175], v[218:221], v[8:11]
	v_mfma_f32_16x16x32_bf16 v[56:59], v[176:179], v[198:201], v[56:59]
	v_mfma_f32_16x16x32_bf16 v[48:51], v[184:187], v[198:201], v[48:51]
	v_mfma_f32_16x16x32_bf16 v[32:35], v[184:187], v[206:209], v[32:35]
	v_mfma_f32_16x16x32_bf16 v[40:43], v[176:179], v[206:209], v[40:43]
	v_mfma_f32_16x16x32_bf16 v[24:27], v[176:179], v[214:217], v[24:27]
	v_mfma_f32_16x16x32_bf16 v[16:19], v[184:187], v[214:217], v[16:19]
	v_mfma_f32_16x16x32_bf16 v[0:3], v[184:187], v[222:225], v[0:3]
	v_mfma_f32_16x16x32_bf16 v[8:11], v[176:179], v[222:225], v[8:11]
	s_barrier
	s_add_i32 s48, s48, 2
	s_add_u32 s16, s16, 0x100
	s_addc_u32 s17, s17, 0
	s_add_u32 s46, s46, 0x100
	s_addc_u32 s47, s47, 0
	s_cmp_gt_u32 s48, 13
	s_cbranch_scc0 .LBB0_929
	s_and_b64 vcc, exec, s[8:9]
	s_cbranch_vccz .LBB0_932
	s_barrier

; #define PG8_STAGE(bufoff, gbase, voff) do { _Pragma("unroll") for (int _i = 0; _i < 2; ++_i) \
;         __builtin_amdgcn_global_load_lds((const unsigned*)((const char*)(gbase) + (voff)[_i]), (LAS unsigned*)(lds + (bufoff) + ldsw + _i * 8192), 16, 0, 0); } while (0)
; #define PG8_LDA(dst, b, h) do { _Pragma("unroll") for (int m = 0; m < 4; ++m) _Pragma("unroll") for (int k = 0; k < 2; ++k) dst[m][k] = *(const LAS bf16x8*)(lds + PG8_SA(b, h) + aoff + m * 2048 + k * 1024); } while (0)
; #define PG8_LDB(dst, b, h) do { _Pragma("unroll") for (int n = 0; n < 2; ++n) _Pragma("unroll") for (int k = 0; k < 2; ++k) dst[n][k] = *(const LAS bf16x8*)(lds + PG8_SB(b, h) + boff + n * 2048 + k * 1024); } while (0)
; #define PG8_MMA(ai, bj, At, Bt) do { __builtin_amdgcn_s_setprio(1); _Pragma("unroll") for (int m = 0; m < 4; ++m) _Pragma("unroll") for (int n = 0; n < 2; ++n) _Pragma("unroll") for (int k = 0; k < 2; ++k) \
;         acc[ai][bj][m][n] = __builtin_amdgcn_mfma_f32_16x16x32_bf16(Bt[n][k], At[m][k], acc[ai][bj][m][n], 0, 0, 0); __builtin_amdgcn_s_setprio(0); } while (0)
; template <class Epi>
; __device__ __forceinline__ void gemm_phase(LAS unsigned char* lds, const Gemm g, const StaticOrder& S, const Epi& E) {
;     ...
;         const bool has_next = S.next(ui + 1, nxt);
;         const char* nA = has_next ? (const char*)g.A + (size_t)(nxt.pm >> 5) * aslab + (size_t)(nxt.pm & 31) * tstepA : cA; const char* nB = has_next ? (const char*)g.Bt + (size_t)nxt.pn * tstepB : cB;
;         for (int t = 0; t < nt; t += 2) {
;             const bool last = (t == nt - 2);
;             const char* a1 = cA + (size_t)(t + 1) * kstep;
;             const char* a2 = last ? nA : cA + (size_t)(t + 2) * kstep; const char* b2 = last ? nB : cB + (size_t)(t + 2) * kstep;
;             const char* a3 = a2 + kstep; const char* b3 = b2 + kstep;
;             PG8_LDB(B0, 0, 0); PG8_LDB(B1, 0, 1); PG8_SCHED; PG8_LDA(At, 0, 0); PG8_STAGE(PG8_SA(1, 1), a1 + hstepA, voffA);
;             PG8_WAIT_V(8); PG8_WAIT_L(0); PG8_BAR; PG8_MMA(0, 0, At, B0); PG8_MMA(0, 1, At, B1); PG8_BAR; PG8_SCHED;
;             PG8_LDA(At, 0, 1); PG8_STAGE(PG8_SB(0, 0), b2, voffB); PG8_STAGE(PG8_SB(0, 1), b2 + hstepB, voffB); PG8_STAGE(PG8_SA(0, 0), a2, voffA);
;             PG8_WAIT_V(8); PG8_WAIT_L(0); PG8_BAR; PG8_MMA(1, 0, At, B0); PG8_MMA(1, 1, At, B1); PG8_BAR; PG8_SCHED;
.LBB0_1033:
	s_add_u32 s42, s8, 0x100
	s_addc_u32 s43, s9, 0
	s_mov_b32 s44, -2
	s_waitcnt lgkmcnt(0)
	s_waitcnt vmcnt(0)
	ds_read_b128 v[128:131], v187
	ds_read_b128 v[132:135], v187 offset:1024
	ds_read_b128 v[136:139], v187 offset:2048
	ds_read_b128 v[140:143], v187 offset:3072
	ds_read_b128 v[144:147], v188
	ds_read_b128 v[148:151], v188 offset:1024
	ds_read_b128 v[166:169], v188 offset:2048
	ds_read_b128 v[170:173], v188 offset:3072
	s_add_u32 s8, s2, 0x100
	s_addc_u32 s9, s3, 0
	s_cmp_eq_u32 s44, 40
	s_cselect_b32 s23, s1, s9
	s_cselect_b32 s22, s0, s8
	s_cselect_b32 s21, s19, s43
	s_cselect_b32 s20, s18, s42
	v_lshl_add_u64 v[182:183], s[2:3], 0, v[160:161]
	s_add_i32 m0, s25, 0xc000
	ds_read_b128 v[174:177], v190
	ds_read_b128 v[178:181], v190 offset:1024
	ds_read_b128 v[192:195], v190 offset:2048
	ds_read_b128 v[198:201], v190 offset:3072
	ds_read_b128 v[202:205], v190 offset:4096
	ds_read_b128 v[206:209], v190 offset:5120
	ds_read_b128 v[210:213], v190 offset:6144
	ds_read_b128 v[214:217], v190 offset:7168
	global_load_lds_dwordx4 v[182:183], off
	v_lshl_add_u64 v[182:183], s[2:3], 0, v[162:163]
	s_add_i32 m0, s25, 0xe000
	s_nop 0
	global_load_lds_dwordx4 v[182:183], off
	s_waitcnt vmcnt(8)
	s_waitcnt lgkmcnt(0)
	s_barrier
	s_waitcnt lgkmcnt(0)
	v_mfma_f32_16x16x32_bf16 v[124:127], v[128:131], v[174:177], 0
	v_mfma_f32_16x16x32_bf16 v[120:123], v[136:139], v[174:177], 0
	v_mfma_f32_16x16x32_bf16 v[104:107], v[136:139], v[192:195], 0
	v_mfma_f32_16x16x32_bf16 v[108:111], v[128:131], v[192:195], 0
	v_mfma_f32_16x16x32_bf16 v[92:95], v[128:131], v[202:205], 0
	v_mfma_f32_16x16x32_bf16 v[88:91], v[136:139], v[202:205], 0
	v_mfma_f32_16x16x32_bf16 v[72:75], v[136:139], v[210:213], 0
	v_mfma_f32_16x16x32_bf16 v[76:79], v[128:131], v[210:213], 0
	v_mfma_f32_16x16x32_bf16 v[124:127], v[132:135], v[178:181], v[124:127]
	v_mfma_f32_16x16x32_bf16 v[120:123], v[140:143], v[178:181], v[120:123]
	v_mfma_f32_16x16x32_bf16 v[104:107], v[140:143], v[198:201], v[104:107]
	v_mfma_f32_16x16x32_bf16 v[108:111], v[132:135], v[198:201], v[108:111]
	v_mfma_f32_16x16x32_bf16 v[92:95], v[132:135], v[206:209], v[92:95]
	v_mfma_f32_16x16x32_bf16 v[88:91], v[140:143], v[206:209], v[88:91]
	v_mfma_f32_16x16x32_bf16 v[72:75], v[140:143], v[214:217], v[72:75]
	v_mfma_f32_16x16x32_bf16 v[76:79], v[132:135], v[214:217], v[76:79]
	v_mfma_f32_16x16x32_bf16 v[116:119], v[144:147], v[174:177], 0
	v_mfma_f32_16x16x32_bf16 v[112:115], v[166:169], v[174:177], 0
	v_mfma_f32_16x16x32_bf16 v[96:99], v[166:169], v[192:195], 0
	v_mfma_f32_16x16x32_bf16 v[100:103], v[144:147], v[192:195], 0
	v_mfma_f32_16x16x32_bf16 v[84:87], v[144:147], v[202:205], 0
	v_mfma_f32_16x16x32_bf16 v[80:83], v[166:169], v[202:205], 0
	v_mfma_f32_16x16x32_bf16 v[64:67], v[166:169], v[210:213], 0
	v_mfma_f32_16x16x32_bf16 v[68:71], v[144:147], v[210:213], 0
	v_mfma_f32_16x16x32_bf16 v[116:119], v[148:151], v[178:181], v[116:119]
	v_mfma_f32_16x16x32_bf16 v[112:115], v[170:173], v[178:181], v[112:115]
	v_mfma_f32_16x16x32_bf16 v[96:99], v[170:173], v[198:201], v[96:99]
	v_mfma_f32_16x16x32_bf16 v[100:103], v[148:151], v[198:201], v[100:103]
	v_mfma_f32_16x16x32_bf16 v[84:87], v[148:151], v[206:209], v[84:87]
	v_mfma_f32_16x16x32_bf16 v[80:83], v[170:173], v[206:209], v[80:83]
	v_mfma_f32_16x16x32_bf16 v[64:67], v[170:173], v[214:217], v[64:67]
	v_mfma_f32_16x16x32_bf16 v[68:71], v[148:151], v[214:217], v[68:71]
	s_barrier
	s_add_i32 s2, s36, s24
	v_lshl_add_u64 v[182:183], s[20:21], 0, v[154:155]
	s_mov_b32 m0, s2
	ds_read_b128 v[174:177], v190 offset:16384
	ds_read_b128 v[178:181], v190 offset:17408
	ds_read_b128 v[192:195], v190 offset:18432
	ds_read_b128 v[198:201], v190 offset:19456
	ds_read_b128 v[202:205], v190 offset:20480
	ds_read_b128 v[206:209], v190 offset:21504
	ds_read_b128 v[210:213], v190 offset:22528
	ds_read_b128 v[214:217], v190 offset:23552
	global_load_lds_dwordx4 v[182:183], off
	s_add_i32 m0, s2, 0x2000
	s_add_u32 s2, s20, 0xb0000
	v_lshl_add_u64 v[218:219], s[20:21], 0, v[158:159]
	s_addc_u32 s3, s21, 0
	s_add_i32 s45, s37, s24
	global_load_lds_dwordx4 v[218:219], off
	v_lshl_add_u64 v[220:221], s[2:3], 0, v[154:155]
	s_mov_b32 m0, s45
	v_lshl_add_u64 v[222:223], s[22:23], 0, v[156:157]
	global_load_lds_dwordx4 v[220:221], off
	v_lshl_add_u64 v[220:221], s[2:3], 0, v[158:159]
	s_add_i32 m0, s45, 0x2000
	s_nop 0
	global_load_lds_dwordx4 v[220:221], off
	v_lshl_add_u64 v[220:221], s[22:23], 0, v[152:153]
	s_mov_b32 m0, s25
	s_nop 0
	global_load_lds_dwordx4 v[220:221], off
	s_mov_b32 m0, s26
	s_nop 0
	global_load_lds_dwordx4 v[222:223], off
	s_waitcnt vmcnt(8)
	s_waitcnt lgkmcnt(0)
	s_barrier
; #define PG8_STAGE(bufoff, gbase, voff) do { _Pragma("unroll") for (int _i = 0; _i < 2; ++_i) \
;         __builtin_amdgcn_global_load_lds((const unsigned*)((const char*)(gbase) + (voff)[_i]), (LAS unsigned*)(lds + (bufoff) + ldsw + _i * 8192), 16, 0, 0); } while (0)
; #define PG8_LDA(dst, b, h) do { _Pragma("unroll") for (int m = 0; m < 4; ++m) _Pragma("unroll") for (int k = 0; k < 2; ++k) dst[m][k] = *(const LAS bf16x8*)(lds + PG8_SA(b, h) + aoff + m * 2048 + k * 1024); } while (0)
; #define PG8_LDB(dst, b, h) do { _Pragma("unroll") for (int n = 0; n < 2; ++n) _Pragma("unroll") for (int k = 0; k < 2; ++k) dst[n][k] = *(const LAS bf16x8*)(lds + PG8_SB(b, h) + boff + n * 2048 + k * 1024); } while (0)
; #define PG8_MMA(ai, bj, At, Bt) do { __builtin_amdgcn_s_setprio(1); _Pragma("unroll") for (int m = 0; m < 4; ++m) _Pragma("unroll") for (int n = 0; n < 2; ++n) _Pragma("unroll") for (int k = 0; k < 2; ++k) \
;         acc[ai][bj][m][n] = __builtin_amdgcn_mfma_f32_16x16x32_bf16(Bt[n][k], At[m][k], acc[ai][bj][m][n], 0, 0, 0); __builtin_amdgcn_s_setprio(0); } while (0)
; #define PG8_WAIT_V(n) asm volatile("s_waitcnt vmcnt(" #n ")" ::: "memory")
; #define PG8_WAIT_L(n) asm volatile("s_waitcnt lgkmcnt(" #n ")" ::: "memory")
; #define PG8_BAR __builtin_amdgcn_s_barrier()
; #define PG8_SCHED __builtin_amdgcn_sched_barrier(0)
; template <class Epi>
; __device__ __forceinline__ void gemm_phase(LAS unsigned char* lds, const Gemm g, const StaticOrder& S, const Epi& E) {
;     ...
;             PG8_WAIT_V(8); PG8_WAIT_L(0); PG8_BAR; PG8_MMA(1, 0, At, B0); PG8_MMA(1, 1, At, B1); PG8_BAR; PG8_SCHED;
;             PG8_LDB(B0, 1, 0); PG8_LDB(B1, 1, 1); PG8_SCHED; PG8_LDA(At, 1, 0); PG8_STAGE(PG8_SA(0, 1), a2 + hstepA, voffA);
;             PG8_WAIT_V(8); PG8_WAIT_L(0); PG8_BAR; PG8_MMA(0, 0, At, B0); PG8_MMA(0, 1, At, B1); PG8_BAR; PG8_SCHED;
	s_waitcnt lgkmcnt(0)
	v_mfma_f32_16x16x32_bf16 v[60:63], v[128:131], v[174:177], 0
	v_mfma_f32_16x16x32_bf16 v[56:59], v[136:139], v[174:177], 0
	v_mfma_f32_16x16x32_bf16 v[40:43], v[136:139], v[192:195], 0
	v_mfma_f32_16x16x32_bf16 v[44:47], v[128:131], v[192:195], 0
	v_mfma_f32_16x16x32_bf16 v[28:31], v[128:131], v[202:205], 0
	v_mfma_f32_16x16x32_bf16 v[24:27], v[136:139], v[202:205], 0
	v_mfma_f32_16x16x32_bf16 v[8:11], v[136:139], v[210:213], 0
	v_mfma_f32_16x16x32_bf16 v[12:15], v[128:131], v[210:213], 0
	v_mfma_f32_16x16x32_bf16 v[60:63], v[132:135], v[178:181], v[60:63]
	v_mfma_f32_16x16x32_bf16 v[56:59], v[140:143], v[178:181], v[56:59]
	v_mfma_f32_16x16x32_bf16 v[40:43], v[140:143], v[198:201], v[40:43]
	v_mfma_f32_16x16x32_bf16 v[44:47], v[132:135], v[198:201], v[44:47]
	v_mfma_f32_16x16x32_bf16 v[28:31], v[132:135], v[206:209], v[28:31]
	v_mfma_f32_16x16x32_bf16 v[24:27], v[140:143], v[206:209], v[24:27]
	v_mfma_f32_16x16x32_bf16 v[8:11], v[140:143], v[214:217], v[8:11]
	v_mfma_f32_16x16x32_bf16 v[12:15], v[132:135], v[214:217], v[12:15]
	v_mfma_f32_16x16x32_bf16 v[52:55], v[144:147], v[174:177], 0
	v_mfma_f32_16x16x32_bf16 v[48:51], v[166:169], v[174:177], 0
	v_mfma_f32_16x16x32_bf16 v[32:35], v[166:169], v[192:195], 0
	v_mfma_f32_16x16x32_bf16 v[36:39], v[144:147], v[192:195], 0
	v_mfma_f32_16x16x32_bf16 v[20:23], v[144:147], v[202:205], 0
	v_mfma_f32_16x16x32_bf16 v[16:19], v[166:169], v[202:205], 0
	v_mfma_f32_16x16x32_bf16 v[0:3], v[166:169], v[210:213], 0
	v_mfma_f32_16x16x32_bf16 v[4:7], v[144:147], v[210:213], 0
	v_mfma_f32_16x16x32_bf16 v[52:55], v[148:151], v[178:181], v[52:55]
	v_mfma_f32_16x16x32_bf16 v[48:51], v[170:173], v[178:181], v[48:51]
	v_mfma_f32_16x16x32_bf16 v[32:35], v[170:173], v[198:201], v[32:35]
	v_mfma_f32_16x16x32_bf16 v[36:39], v[148:151], v[198:201], v[36:39]
	v_mfma_f32_16x16x32_bf16 v[20:23], v[148:151], v[206:209], v[20:23]
	v_mfma_f32_16x16x32_bf16 v[16:19], v[170:173], v[206:209], v[16:19]
	v_mfma_f32_16x16x32_bf16 v[0:3], v[170:173], v[214:217], v[0:3]
	v_mfma_f32_16x16x32_bf16 v[4:7], v[148:151], v[214:217], v[4:7]
	s_barrier
	s_add_i32 s45, 0, 0x18000
	s_add_i32 s46, 0, 0x1c000
	v_add_u32_e32 v140, s45, v185
	v_add_u32_e32 v170, s46, v185
	ds_read_b128 v[128:131], v140
	ds_read_b128 v[132:135], v140 offset:1024
	ds_read_b128 v[136:139], v140 offset:2048
	ds_read_b128 v[140:143], v140 offset:3072
	ds_read_b128 v[144:147], v170
	ds_read_b128 v[148:151], v170 offset:1024
	ds_read_b128 v[166:169], v170 offset:2048
	ds_read_b128 v[170:173], v170 offset:3072
	s_add_u32 s2, s22, 0xb4000
	s_addc_u32 s3, s23, 0
	s_mov_b32 m0, s27
	v_lshl_add_u64 v[224:225], s[2:3], 0, v[152:153]
	ds_read_b128 v[174:177], v190 offset:32768
	ds_read_b128 v[178:181], v190 offset:33792
	ds_read_b128 v[192:195], v190 offset:34816
	ds_read_b128 v[198:201], v190 offset:35840
	ds_read_b128 v[202:205], v190 offset:36864
	ds_read_b128 v[206:209], v190 offset:37888
	ds_read_b128 v[210:213], v190 offset:38912
	ds_read_b128 v[214:217], v190 offset:39936
	global_load_lds_dwordx4 v[224:225], off
	v_lshl_add_u64 v[224:225], s[2:3], 0, v[156:157]
	s_mov_b32 m0, s28
	s_nop 0
	global_load_lds_dwordx4 v[224:225], off
	s_waitcnt vmcnt(8)
	s_waitcnt lgkmcnt(0)
	s_barrier
	s_waitcnt lgkmcnt(0)
	v_mfma_f32_16x16x32_bf16 v[124:127], v[128:131], v[174:177], v[124:127]
	v_mfma_f32_16x16x32_bf16 v[120:123], v[136:139], v[174:177], v[120:123]
	v_mfma_f32_16x16x32_bf16 v[104:107], v[136:139], v[192:195], v[104:107]
	v_mfma_f32_16x16x32_bf16 v[108:111], v[128:131], v[192:195], v[108:111]
	v_mfma_f32_16x16x32_bf16 v[92:95], v[128:131], v[202:205], v[92:95]
	v_mfma_f32_16x16x32_bf16 v[88:91], v[136:139], v[202:205], v[88:91]
	v_mfma_f32_16x16x32_bf16 v[72:75], v[136:139], v[210:213], v[72:75]
	v_mfma_f32_16x16x32_bf16 v[76:79], v[128:131], v[210:213], v[76:79]
	v_mfma_f32_16x16x32_bf16 v[124:127], v[132:135], v[178:181], v[124:127]
	v_mfma_f32_16x16x32_bf16 v[120:123], v[140:143], v[178:181], v[120:123]
	v_mfma_f32_16x16x32_bf16 v[104:107], v[140:143], v[198:201], v[104:107]
	v_mfma_f32_16x16x32_bf16 v[108:111], v[132:135], v[198:201], v[108:111]
	v_mfma_f32_16x16x32_bf16 v[92:95], v[132:135], v[206:209], v[92:95]
	v_mfma_f32_16x16x32_bf16 v[88:91], v[140:143], v[206:209], v[88:91]
	v_mfma_f32_16x16x32_bf16 v[72:75], v[140:143], v[214:217], v[72:75]
	v_mfma_f32_16x16x32_bf16 v[76:79], v[132:135], v[214:217], v[76:79]
	v_mfma_f32_16x16x32_bf16 v[116:119], v[144:147], v[174:177], v[116:119]
	v_mfma_f32_16x16x32_bf16 v[112:115], v[166:169], v[174:177], v[112:115]
	v_mfma_f32_16x16x32_bf16 v[96:99], v[166:169], v[192:195], v[96:99]
	v_mfma_f32_16x16x32_bf16 v[100:103], v[144:147], v[192:195], v[100:103]
	v_mfma_f32_16x16x32_bf16 v[84:87], v[144:147], v[202:205], v[84:87]
	v_mfma_f32_16x16x32_bf16 v[80:83], v[166:169], v[202:205], v[80:83]
	v_mfma_f32_16x16x32_bf16 v[64:67], v[166:169], v[210:213], v[64:67]
	v_mfma_f32_16x16x32_bf16 v[68:71], v[144:147], v[210:213], v[68:71]
	v_mfma_f32_16x16x32_bf16 v[116:119], v[148:151], v[178:181], v[116:119]
	v_mfma_f32_16x16x32_bf16 v[112:115], v[170:173], v[178:181], v[112:115]
	v_mfma_f32_16x16x32_bf16 v[96:99], v[170:173], v[198:201], v[96:99]
	v_mfma_f32_16x16x32_bf16 v[100:103], v[148:151], v[198:201], v[100:103]
	v_mfma_f32_16x16x32_bf16 v[84:87], v[148:151], v[206:209], v[84:87]
	v_mfma_f32_16x16x32_bf16 v[80:83], v[170:173], v[206:209], v[80:83]
	v_mfma_f32_16x16x32_bf16 v[64:67], v[170:173], v[214:217], v[64:67]
	v_mfma_f32_16x16x32_bf16 v[68:71], v[148:151], v[214:217], v[68:71]
	s_barrier
; #define PG8_STAGE(bufoff, gbase, voff) do { _Pragma("unroll") for (int _i = 0; _i < 2; ++_i) \
;         __builtin_amdgcn_global_load_lds((const unsigned*)((const char*)(gbase) + (voff)[_i]), (LAS unsigned*)(lds + (bufoff) + ldsw + _i * 8192), 16, 0, 0); } while (0)
; #define PG8_LDA(dst, b, h) do { _Pragma("unroll") for (int m = 0; m < 4; ++m) _Pragma("unroll") for (int k = 0; k < 2; ++k) dst[m][k] = *(const LAS bf16x8*)(lds + PG8_SA(b, h) + aoff + m * 2048 + k * 1024); } while (0)
; #define PG8_LDB(dst, b, h) do { _Pragma("unroll") for (int n = 0; n < 2; ++n) _Pragma("unroll") for (int k = 0; k < 2; ++k) dst[n][k] = *(const LAS bf16x8*)(lds + PG8_SB(b, h) + boff + n * 2048 + k * 1024); } while (0)
; #define PG8_MMA(ai, bj, At, Bt) do { __builtin_amdgcn_s_setprio(1); _Pragma("unroll") for (int m = 0; m < 4; ++m) _Pragma("unroll") for (int n = 0; n < 2; ++n) _Pragma("unroll") for (int k = 0; k < 2; ++k) \
;         acc[ai][bj][m][n] = __builtin_amdgcn_mfma_f32_16x16x32_bf16(Bt[n][k], At[m][k], acc[ai][bj][m][n], 0, 0, 0); __builtin_amdgcn_s_setprio(0); } while (0)
; #define PG8_WAIT_V(n) asm volatile("s_waitcnt vmcnt(" #n ")" ::: "memory")
; #define PG8_WAIT_L(n) asm volatile("s_waitcnt lgkmcnt(" #n ")" ::: "memory")
; #define PG8_BAR __builtin_amdgcn_s_barrier()
; #define PG8_SCHED __builtin_amdgcn_sched_barrier(0)
; template <class Epi>
; __device__ __forceinline__ void gemm_phase(LAS unsigned char* lds, const Gemm g, const StaticOrder& S, const Epi& E) {
;     ...
;         for (int t = 0; t < nt; t += 2) {
;             const bool last = (t == nt - 2);
;             const char* a1 = cA + (size_t)(t + 1) * kstep;
;             const char* a2 = last ? nA : cA + (size_t)(t + 2) * kstep; const char* b2 = last ? nB : cB + (size_t)(t + 2) * kstep;
;             const char* a3 = a2 + kstep; const char* b3 = b2 + kstep;
;             PG8_LDB(B0, 0, 0); PG8_LDB(B1, 0, 1); PG8_SCHED; PG8_LDA(At, 0, 0); PG8_STAGE(PG8_SA(1, 1), a1 + hstepA, voffA);
;             PG8_WAIT_V(8); PG8_WAIT_L(0); PG8_BAR; PG8_MMA(0, 0, At, B0); PG8_MMA(0, 1, At, B1); PG8_BAR; PG8_SCHED;
;     ...
;             PG8_LDA(At, 1, 1); PG8_STAGE(PG8_SB(1, 0), b3, voffB); PG8_STAGE(PG8_SB(1, 1), b3 + hstepB, voffB); PG8_STAGE(PG8_SA(1, 0), a3, voffA);
;             PG8_WAIT_V(8); PG8_WAIT_L(0); PG8_BAR; PG8_MMA(1, 0, At, B0); PG8_MMA(1, 1, At, B1); PG8_BAR; PG8_SCHED;
	s_add_i32 s2, s45, s24
	v_lshl_add_u64 v[182:183], v[182:183], 0, s[14:15]
	s_mov_b32 m0, s2
	ds_read_b128 v[174:177], v190 offset:49152
	ds_read_b128 v[178:181], v190 offset:50176
	ds_read_b128 v[192:195], v190 offset:51200
	ds_read_b128 v[198:201], v190 offset:52224
	ds_read_b128 v[202:205], v190 offset:53248
	ds_read_b128 v[206:209], v190 offset:54272
	ds_read_b128 v[210:213], v190 offset:55296
	ds_read_b128 v[214:217], v190 offset:56320
	global_load_lds_dwordx4 v[182:183], off
	s_add_i32 m0, s2, 0x2000
	s_add_u32 s2, s20, 0xb0080
	v_lshl_add_u64 v[182:183], v[218:219], 0, s[14:15]
	s_addc_u32 s3, s21, 0
	s_add_i32 s20, s46, s24
	global_load_lds_dwordx4 v[182:183], off
	v_lshl_add_u64 v[182:183], s[2:3], 0, v[154:155]
	s_mov_b32 m0, s20
	s_nop 0
	global_load_lds_dwordx4 v[182:183], off
	v_lshl_add_u64 v[182:183], s[2:3], 0, v[158:159]
	s_add_i32 m0, s20, 0x2000
	s_nop 0
	global_load_lds_dwordx4 v[182:183], off
	v_lshl_add_u64 v[182:183], v[220:221], 0, s[14:15]
	s_mov_b32 m0, s30
	s_nop 0
	global_load_lds_dwordx4 v[182:183], off
	v_lshl_add_u64 v[182:183], v[222:223], 0, s[14:15]
	s_mov_b32 m0, s31
	s_nop 0
	global_load_lds_dwordx4 v[182:183], off
	s_waitcnt vmcnt(8)
	s_waitcnt lgkmcnt(0)
	s_barrier
	s_waitcnt lgkmcnt(0)
	v_mfma_f32_16x16x32_bf16 v[60:63], v[128:131], v[174:177], v[60:63]
	v_mfma_f32_16x16x32_bf16 v[56:59], v[136:139], v[174:177], v[56:59]
	v_mfma_f32_16x16x32_bf16 v[40:43], v[136:139], v[192:195], v[40:43]
	v_mfma_f32_16x16x32_bf16 v[44:47], v[128:131], v[192:195], v[44:47]
	v_mfma_f32_16x16x32_bf16 v[28:31], v[128:131], v[202:205], v[28:31]
	v_mfma_f32_16x16x32_bf16 v[24:27], v[136:139], v[202:205], v[24:27]
	v_mfma_f32_16x16x32_bf16 v[8:11], v[136:139], v[210:213], v[8:11]
	v_mfma_f32_16x16x32_bf16 v[12:15], v[128:131], v[210:213], v[12:15]
	v_mfma_f32_16x16x32_bf16 v[60:63], v[132:135], v[178:181], v[60:63]
	v_mfma_f32_16x16x32_bf16 v[56:59], v[140:143], v[178:181], v[56:59]
	v_mfma_f32_16x16x32_bf16 v[40:43], v[140:143], v[198:201], v[40:43]
	v_mfma_f32_16x16x32_bf16 v[44:47], v[132:135], v[198:201], v[44:47]
	v_mfma_f32_16x16x32_bf16 v[28:31], v[132:135], v[206:209], v[28:31]
	v_mfma_f32_16x16x32_bf16 v[24:27], v[140:143], v[206:209], v[24:27]
	v_mfma_f32_16x16x32_bf16 v[8:11], v[140:143], v[214:217], v[8:11]
	v_mfma_f32_16x16x32_bf16 v[12:15], v[132:135], v[214:217], v[12:15]
	v_mfma_f32_16x16x32_bf16 v[52:55], v[144:147], v[174:177], v[52:55]
	v_mfma_f32_16x16x32_bf16 v[48:51], v[166:169], v[174:177], v[48:51]
	v_mfma_f32_16x16x32_bf16 v[32:35], v[166:169], v[192:195], v[32:35]
	v_mfma_f32_16x16x32_bf16 v[36:39], v[144:147], v[192:195], v[36:39]
	v_mfma_f32_16x16x32_bf16 v[20:23], v[144:147], v[202:205], v[20:23]
	v_mfma_f32_16x16x32_bf16 v[16:19], v[166:169], v[202:205], v[16:19]
	v_mfma_f32_16x16x32_bf16 v[0:3], v[166:169], v[210:213], v[0:3]
	v_mfma_f32_16x16x32_bf16 v[4:7], v[144:147], v[210:213], v[4:7]
	v_mfma_f32_16x16x32_bf16 v[52:55], v[148:151], v[178:181], v[52:55]
	v_mfma_f32_16x16x32_bf16 v[48:51], v[170:173], v[178:181], v[48:51]
	v_mfma_f32_16x16x32_bf16 v[32:35], v[170:173], v[198:201], v[32:35]
	v_mfma_f32_16x16x32_bf16 v[36:39], v[148:151], v[198:201], v[36:39]
	v_mfma_f32_16x16x32_bf16 v[20:23], v[148:151], v[206:209], v[20:23]
	v_mfma_f32_16x16x32_bf16 v[16:19], v[170:173], v[206:209], v[16:19]
	v_mfma_f32_16x16x32_bf16 v[0:3], v[170:173], v[214:217], v[0:3]
	v_mfma_f32_16x16x32_bf16 v[4:7], v[148:151], v[214:217], v[4:7]
	s_barrier
	s_add_i32 s44, s44, 2
	s_add_u32 s42, s42, 0x100
	s_addc_u32 s43, s43, 0
	s_cmp_gt_u32 s44, 41
	s_mov_b64 s[2:3], s[8:9]
	s_cbranch_scc0 .LBB0_1034
.LBB0_1034:
	ds_read_b128 v[128:131], v187
	ds_read_b128 v[132:135], v187 offset:1024
	ds_read_b128 v[136:139], v187 offset:2048
	ds_read_b128 v[140:143], v187 offset:3072
	ds_read_b128 v[144:147], v188
	ds_read_b128 v[148:151], v188 offset:1024
	ds_read_b128 v[166:169], v188 offset:2048
	ds_read_b128 v[170:173], v188 offset:3072
	s_add_u32 s8, s2, 0x100
	s_addc_u32 s9, s3, 0
	s_cmp_eq_u32 s44, 40
	s_cselect_b32 s23, s1, s9
	s_cselect_b32 s22, s0, s8
	s_cselect_b32 s21, s19, s43
	s_cselect_b32 s20, s18, s42
	v_lshl_add_u64 v[182:183], s[2:3], 0, v[160:161]
	s_add_i32 m0, s25, 0xc000
	ds_read_b128 v[174:177], v190
	ds_read_b128 v[178:181], v190 offset:1024
	ds_read_b128 v[192:195], v190 offset:2048
	ds_read_b128 v[198:201], v190 offset:3072
	ds_read_b128 v[202:205], v190 offset:4096
	ds_read_b128 v[206:209], v190 offset:5120
	ds_read_b128 v[210:213], v190 offset:6144
	ds_read_b128 v[214:217], v190 offset:7168
	global_load_lds_dwordx4 v[182:183], off
	v_lshl_add_u64 v[182:183], s[2:3], 0, v[162:163]
	s_add_i32 m0, s25, 0xe000
	s_nop 0
	global_load_lds_dwordx4 v[182:183], off
	s_waitcnt vmcnt(8)
	s_waitcnt lgkmcnt(0)
	s_barrier
; #define PG8_STAGE(bufoff, gbase, voff) do { _Pragma("unroll") for (int _i = 0; _i < 2; ++_i) \
;         __builtin_amdgcn_global_load_lds((const unsigned*)((const char*)(gbase) + (voff)[_i]), (LAS unsigned*)(lds + (bufoff) + ldsw + _i * 8192), 16, 0, 0); } while (0)
; #define PG8_LDA(dst, b, h) do { _Pragma("unroll") for (int m = 0; m < 4; ++m) _Pragma("unroll") for (int k = 0; k < 2; ++k) dst[m][k] = *(const LAS bf16x8*)(lds + PG8_SA(b, h) + aoff + m * 2048 + k * 1024); } while (0)
; #define PG8_MMA(ai, bj, At, Bt) do { __builtin_amdgcn_s_setprio(1); _Pragma("unroll") for (int m = 0; m < 4; ++m) _Pragma("unroll") for (int n = 0; n < 2; ++n) _Pragma("unroll") for (int k = 0; k < 2; ++k) \
;         acc[ai][bj][m][n] = __builtin_amdgcn_mfma_f32_16x16x32_bf16(Bt[n][k], At[m][k], acc[ai][bj][m][n], 0, 0, 0); __builtin_amdgcn_s_setprio(0); } while (0)
; #define PG8_WAIT_V(n) asm volatile("s_waitcnt vmcnt(" #n ")" ::: "memory")
; #define PG8_WAIT_L(n) asm volatile("s_waitcnt lgkmcnt(" #n ")" ::: "memory")
; #define PG8_BAR __builtin_amdgcn_s_barrier()
; #define PG8_SCHED __builtin_amdgcn_sched_barrier(0)
; template <class Epi>
; __device__ __forceinline__ void gemm_phase(LAS unsigned char* lds, const Gemm g, const StaticOrder& S, const Epi& E) {
;     ...
;             PG8_WAIT_V(8); PG8_WAIT_L(0); PG8_BAR; PG8_MMA(0, 0, At, B0); PG8_MMA(0, 1, At, B1); PG8_BAR; PG8_SCHED;
;             PG8_LDA(At, 0, 1); PG8_STAGE(PG8_SB(0, 0), b2, voffB); PG8_STAGE(PG8_SB(0, 1), b2 + hstepB, voffB); PG8_STAGE(PG8_SA(0, 0), a2, voffA);
;             PG8_WAIT_V(8); PG8_WAIT_L(0); PG8_BAR; PG8_MMA(1, 0, At, B0); PG8_MMA(1, 1, At, B1); PG8_BAR; PG8_SCHED;
	s_waitcnt lgkmcnt(0)
	v_mfma_f32_16x16x32_bf16 v[124:127], v[128:131], v[174:177], v[124:127]
	v_mfma_f32_16x16x32_bf16 v[120:123], v[136:139], v[174:177], v[120:123]
	v_mfma_f32_16x16x32_bf16 v[104:107], v[136:139], v[192:195], v[104:107]
	v_mfma_f32_16x16x32_bf16 v[108:111], v[128:131], v[192:195], v[108:111]
	v_mfma_f32_16x16x32_bf16 v[92:95], v[128:131], v[202:205], v[92:95]
	v_mfma_f32_16x16x32_bf16 v[88:91], v[136:139], v[202:205], v[88:91]
	v_mfma_f32_16x16x32_bf16 v[72:75], v[136:139], v[210:213], v[72:75]
	v_mfma_f32_16x16x32_bf16 v[76:79], v[128:131], v[210:213], v[76:79]
	v_mfma_f32_16x16x32_bf16 v[124:127], v[132:135], v[178:181], v[124:127]
	v_mfma_f32_16x16x32_bf16 v[120:123], v[140:143], v[178:181], v[120:123]
	v_mfma_f32_16x16x32_bf16 v[104:107], v[140:143], v[198:201], v[104:107]
	v_mfma_f32_16x16x32_bf16 v[108:111], v[132:135], v[198:201], v[108:111]
	v_mfma_f32_16x16x32_bf16 v[92:95], v[132:135], v[206:209], v[92:95]
	v_mfma_f32_16x16x32_bf16 v[88:91], v[140:143], v[206:209], v[88:91]
	v_mfma_f32_16x16x32_bf16 v[72:75], v[140:143], v[214:217], v[72:75]
	v_mfma_f32_16x16x32_bf16 v[76:79], v[132:135], v[214:217], v[76:79]
	v_mfma_f32_16x16x32_bf16 v[116:119], v[144:147], v[174:177], v[116:119]
	v_mfma_f32_16x16x32_bf16 v[112:115], v[166:169], v[174:177], v[112:115]
	v_mfma_f32_16x16x32_bf16 v[96:99], v[166:169], v[192:195], v[96:99]
	v_mfma_f32_16x16x32_bf16 v[100:103], v[144:147], v[192:195], v[100:103]
	v_mfma_f32_16x16x32_bf16 v[84:87], v[144:147], v[202:205], v[84:87]
	v_mfma_f32_16x16x32_bf16 v[80:83], v[166:169], v[202:205], v[80:83]
	v_mfma_f32_16x16x32_bf16 v[64:67], v[166:169], v[210:213], v[64:67]
	v_mfma_f32_16x16x32_bf16 v[68:71], v[144:147], v[210:213], v[68:71]
	v_mfma_f32_16x16x32_bf16 v[116:119], v[148:151], v[178:181], v[116:119]
	v_mfma_f32_16x16x32_bf16 v[112:115], v[170:173], v[178:181], v[112:115]
	v_mfma_f32_16x16x32_bf16 v[96:99], v[170:173], v[198:201], v[96:99]
	v_mfma_f32_16x16x32_bf16 v[100:103], v[148:151], v[198:201], v[100:103]
	v_mfma_f32_16x16x32_bf16 v[84:87], v[148:151], v[206:209], v[84:87]
	v_mfma_f32_16x16x32_bf16 v[80:83], v[170:173], v[206:209], v[80:83]
	v_mfma_f32_16x16x32_bf16 v[64:67], v[170:173], v[214:217], v[64:67]
	v_mfma_f32_16x16x32_bf16 v[68:71], v[148:151], v[214:217], v[68:71]
	s_barrier
	s_add_i32 s2, s36, s24
	v_lshl_add_u64 v[182:183], s[20:21], 0, v[154:155]
	s_mov_b32 m0, s2
	ds_read_b128 v[174:177], v190 offset:16384
	ds_read_b128 v[178:181], v190 offset:17408
	ds_read_b128 v[192:195], v190 offset:18432
	ds_read_b128 v[198:201], v190 offset:19456
	ds_read_b128 v[202:205], v190 offset:20480
	ds_read_b128 v[206:209], v190 offset:21504
	ds_read_b128 v[210:213], v190 offset:22528
	ds_read_b128 v[214:217], v190 offset:23552
	global_load_lds_dwordx4 v[182:183], off
	s_add_i32 m0, s2, 0x2000
	s_add_u32 s2, s20, 0xb0000
	v_lshl_add_u64 v[218:219], s[20:21], 0, v[158:159]
	s_addc_u32 s3, s21, 0
	s_add_i32 s45, s37, s24
	global_load_lds_dwordx4 v[218:219], off
	v_lshl_add_u64 v[220:221], s[2:3], 0, v[154:155]
	s_mov_b32 m0, s45
	v_lshl_add_u64 v[222:223], s[22:23], 0, v[156:157]
	global_load_lds_dwordx4 v[220:221], off
	v_lshl_add_u64 v[220:221], s[2:3], 0, v[158:159]
	s_add_i32 m0, s45, 0x2000
	s_nop 0
	global_load_lds_dwordx4 v[220:221], off
	v_lshl_add_u64 v[220:221], s[22:23], 0, v[152:153]
	s_mov_b32 m0, s25
	s_nop 0
	global_load_lds_dwordx4 v[220:221], off
	s_mov_b32 m0, s26
	s_nop 0
	global_load_lds_dwordx4 v[222:223], off
	s_waitcnt vmcnt(8)
	s_waitcnt lgkmcnt(0)
	s_barrier
	s_waitcnt lgkmcnt(0)
	v_mfma_f32_16x16x32_bf16 v[60:63], v[128:131], v[174:177], v[60:63]
	v_mfma_f32_16x16x32_bf16 v[56:59], v[136:139], v[174:177], v[56:59]
	v_mfma_f32_16x16x32_bf16 v[40:43], v[136:139], v[192:195], v[40:43]
	v_mfma_f32_16x16x32_bf16 v[44:47], v[128:131], v[192:195], v[44:47]
	v_mfma_f32_16x16x32_bf16 v[28:31], v[128:131], v[202:205], v[28:31]
	v_mfma_f32_16x16x32_bf16 v[24:27], v[136:139], v[202:205], v[24:27]
	v_mfma_f32_16x16x32_bf16 v[8:11], v[136:139], v[210:213], v[8:11]
	v_mfma_f32_16x16x32_bf16 v[12:15], v[128:131], v[210:213], v[12:15]
	v_mfma_f32_16x16x32_bf16 v[60:63], v[132:135], v[178:181], v[60:63]
	v_mfma_f32_16x16x32_bf16 v[56:59], v[140:143], v[178:181], v[56:59]
	v_mfma_f32_16x16x32_bf16 v[40:43], v[140:143], v[198:201], v[40:43]
	v_mfma_f32_16x16x32_bf16 v[44:47], v[132:135], v[198:201], v[44:47]
	v_mfma_f32_16x16x32_bf16 v[28:31], v[132:135], v[206:209], v[28:31]
	v_mfma_f32_16x16x32_bf16 v[24:27], v[140:143], v[206:209], v[24:27]
	v_mfma_f32_16x16x32_bf16 v[8:11], v[140:143], v[214:217], v[8:11]
	v_mfma_f32_16x16x32_bf16 v[12:15], v[132:135], v[214:217], v[12:15]
	v_mfma_f32_16x16x32_bf16 v[52:55], v[144:147], v[174:177], v[52:55]
	v_mfma_f32_16x16x32_bf16 v[48:51], v[166:169], v[174:177], v[48:51]
	v_mfma_f32_16x16x32_bf16 v[32:35], v[166:169], v[192:195], v[32:35]
	v_mfma_f32_16x16x32_bf16 v[36:39], v[144:147], v[192:195], v[36:39]
	v_mfma_f32_16x16x32_bf16 v[20:23], v[144:147], v[202:205], v[20:23]
	v_mfma_f32_16x16x32_bf16 v[16:19], v[166:169], v[202:205], v[16:19]
	v_mfma_f32_16x16x32_bf16 v[0:3], v[166:169], v[210:213], v[0:3]
	v_mfma_f32_16x16x32_bf16 v[4:7], v[144:147], v[210:213], v[4:7]
	v_mfma_f32_16x16x32_bf16 v[52:55], v[148:151], v[178:181], v[52:55]
	v_mfma_f32_16x16x32_bf16 v[48:51], v[170:173], v[178:181], v[48:51]
	v_mfma_f32_16x16x32_bf16 v[32:35], v[170:173], v[198:201], v[32:35]
	v_mfma_f32_16x16x32_bf16 v[36:39], v[148:151], v[198:201], v[36:39]
	v_mfma_f32_16x16x32_bf16 v[20:23], v[148:151], v[206:209], v[20:23]
	v_mfma_f32_16x16x32_bf16 v[16:19], v[170:173], v[206:209], v[16:19]
	v_mfma_f32_16x16x32_bf16 v[0:3], v[170:173], v[214:217], v[0:3]
	v_mfma_f32_16x16x32_bf16 v[4:7], v[148:151], v[214:217], v[4:7]
	s_barrier
; #define PG8_STAGE(bufoff, gbase, voff) do { _Pragma("unroll") for (int _i = 0; _i < 2; ++_i) \
;         __builtin_amdgcn_global_load_lds((const unsigned*)((const char*)(gbase) + (voff)[_i]), (LAS unsigned*)(lds + (bufoff) + ldsw + _i * 8192), 16, 0, 0); } while (0)
; #define PG8_LDA(dst, b, h) do { _Pragma("unroll") for (int m = 0; m < 4; ++m) _Pragma("unroll") for (int k = 0; k < 2; ++k) dst[m][k] = *(const LAS bf16x8*)(lds + PG8_SA(b, h) + aoff + m * 2048 + k * 1024); } while (0)
; #define PG8_LDB(dst, b, h) do { _Pragma("unroll") for (int n = 0; n < 2; ++n) _Pragma("unroll") for (int k = 0; k < 2; ++k) dst[n][k] = *(const LAS bf16x8*)(lds + PG8_SB(b, h) + boff + n * 2048 + k * 1024); } while (0)
; #define PG8_MMA(ai, bj, At, Bt) do { __builtin_amdgcn_s_setprio(1); _Pragma("unroll") for (int m = 0; m < 4; ++m) _Pragma("unroll") for (int n = 0; n < 2; ++n) _Pragma("unroll") for (int k = 0; k < 2; ++k) \
;         acc[ai][bj][m][n] = __builtin_amdgcn_mfma_f32_16x16x32_bf16(Bt[n][k], At[m][k], acc[ai][bj][m][n], 0, 0, 0); __builtin_amdgcn_s_setprio(0); } while (0)
; #define PG8_WAIT_V(n) asm volatile("s_waitcnt vmcnt(" #n ")" ::: "memory")
; #define PG8_WAIT_L(n) asm volatile("s_waitcnt lgkmcnt(" #n ")" ::: "memory")
; #define PG8_BAR __builtin_amdgcn_s_barrier()
; #define PG8_SCHED __builtin_amdgcn_sched_barrier(0)
; template <class Epi>
; __device__ __forceinline__ void gemm_phase(LAS unsigned char* lds, const Gemm g, const StaticOrder& S, const Epi& E) {
;     ...
;             PG8_LDB(B0, 1, 0); PG8_LDB(B1, 1, 1); PG8_SCHED; PG8_LDA(At, 1, 0); PG8_STAGE(PG8_SA(0, 1), a2 + hstepA, voffA);
;             PG8_WAIT_V(8); PG8_WAIT_L(0); PG8_BAR; PG8_MMA(0, 0, At, B0); PG8_MMA(0, 1, At, B1); PG8_BAR; PG8_SCHED;
	s_add_i32 s45, 0, 0x18000
	s_add_i32 s46, 0, 0x1c000
	v_add_u32_e32 v140, s45, v185
	v_add_u32_e32 v170, s46, v185
	ds_read_b128 v[128:131], v140
	ds_read_b128 v[132:135], v140 offset:1024
	ds_read_b128 v[136:139], v140 offset:2048
	ds_read_b128 v[140:143], v140 offset:3072
	ds_read_b128 v[144:147], v170
	ds_read_b128 v[148:151], v170 offset:1024
	ds_read_b128 v[166:169], v170 offset:2048
	ds_read_b128 v[170:173], v170 offset:3072
	s_add_u32 s2, s22, 0xb4000
	s_addc_u32 s3, s23, 0
	s_mov_b32 m0, s27
	v_lshl_add_u64 v[224:225], s[2:3], 0, v[152:153]
	ds_read_b128 v[174:177], v190 offset:32768
	ds_read_b128 v[178:181], v190 offset:33792
	ds_read_b128 v[192:195], v190 offset:34816
	ds_read_b128 v[198:201], v190 offset:35840
	ds_read_b128 v[202:205], v190 offset:36864
	ds_read_b128 v[206:209], v190 offset:37888
	ds_read_b128 v[210:213], v190 offset:38912
	ds_read_b128 v[214:217], v190 offset:39936
	global_load_lds_dwordx4 v[224:225], off
	v_lshl_add_u64 v[224:225], s[2:3], 0, v[156:157]
	s_mov_b32 m0, s28
	s_nop 0
	global_load_lds_dwordx4 v[224:225], off
	s_waitcnt vmcnt(8)
	s_waitcnt lgkmcnt(0)
	s_barrier
	s_waitcnt lgkmcnt(0)
	v_mfma_f32_16x16x32_bf16 v[124:127], v[128:131], v[174:177], v[124:127]
	v_mfma_f32_16x16x32_bf16 v[120:123], v[136:139], v[174:177], v[120:123]
	v_mfma_f32_16x16x32_bf16 v[104:107], v[136:139], v[192:195], v[104:107]
	v_mfma_f32_16x16x32_bf16 v[108:111], v[128:131], v[192:195], v[108:111]
	v_mfma_f32_16x16x32_bf16 v[92:95], v[128:131], v[202:205], v[92:95]
	v_mfma_f32_16x16x32_bf16 v[88:91], v[136:139], v[202:205], v[88:91]
	v_mfma_f32_16x16x32_bf16 v[72:75], v[136:139], v[210:213], v[72:75]
	v_mfma_f32_16x16x32_bf16 v[76:79], v[128:131], v[210:213], v[76:79]
	v_mfma_f32_16x16x32_bf16 v[124:127], v[132:135], v[178:181], v[124:127]
	v_mfma_f32_16x16x32_bf16 v[120:123], v[140:143], v[178:181], v[120:123]
	v_mfma_f32_16x16x32_bf16 v[104:107], v[140:143], v[198:201], v[104:107]
	v_mfma_f32_16x16x32_bf16 v[108:111], v[132:135], v[198:201], v[108:111]
	v_mfma_f32_16x16x32_bf16 v[92:95], v[132:135], v[206:209], v[92:95]
	v_mfma_f32_16x16x32_bf16 v[88:91], v[140:143], v[206:209], v[88:91]
	v_mfma_f32_16x16x32_bf16 v[72:75], v[140:143], v[214:217], v[72:75]
	v_mfma_f32_16x16x32_bf16 v[76:79], v[132:135], v[214:217], v[76:79]
	v_mfma_f32_16x16x32_bf16 v[116:119], v[144:147], v[174:177], v[116:119]
	v_mfma_f32_16x16x32_bf16 v[112:115], v[166:169], v[174:177], v[112:115]
	v_mfma_f32_16x16x32_bf16 v[96:99], v[166:169], v[192:195], v[96:99]
	v_mfma_f32_16x16x32_bf16 v[100:103], v[144:147], v[192:195], v[100:103]
	v_mfma_f32_16x16x32_bf16 v[84:87], v[144:147], v[202:205], v[84:87]
	v_mfma_f32_16x16x32_bf16 v[80:83], v[166:169], v[202:205], v[80:83]
	v_mfma_f32_16x16x32_bf16 v[64:67], v[166:169], v[210:213], v[64:67]
	v_mfma_f32_16x16x32_bf16 v[68:71], v[144:147], v[210:213], v[68:71]
	v_mfma_f32_16x16x32_bf16 v[116:119], v[148:151], v[178:181], v[116:119]
	v_mfma_f32_16x16x32_bf16 v[112:115], v[170:173], v[178:181], v[112:115]
	v_mfma_f32_16x16x32_bf16 v[96:99], v[170:173], v[198:201], v[96:99]
	v_mfma_f32_16x16x32_bf16 v[100:103], v[148:151], v[198:201], v[100:103]
	v_mfma_f32_16x16x32_bf16 v[84:87], v[148:151], v[206:209], v[84:87]
	v_mfma_f32_16x16x32_bf16 v[80:83], v[170:173], v[206:209], v[80:83]
	v_mfma_f32_16x16x32_bf16 v[64:67], v[170:173], v[214:217], v[64:67]
	v_mfma_f32_16x16x32_bf16 v[68:71], v[148:151], v[214:217], v[68:71]
	s_barrier
; #define PG8_STAGE(bufoff, gbase, voff) do { _Pragma("unroll") for (int _i = 0; _i < 2; ++_i) \
;         __builtin_amdgcn_global_load_lds((const unsigned*)((const char*)(gbase) + (voff)[_i]), (LAS unsigned*)(lds + (bufoff) + ldsw + _i * 8192), 16, 0, 0); } while (0)
; #define PG8_LDA(dst, b, h) do { _Pragma("unroll") for (int m = 0; m < 4; ++m) _Pragma("unroll") for (int k = 0; k < 2; ++k) dst[m][k] = *(const LAS bf16x8*)(lds + PG8_SA(b, h) + aoff + m * 2048 + k * 1024); } while (0)
; #define PG8_MMA(ai, bj, At, Bt) do { __builtin_amdgcn_s_setprio(1); _Pragma("unroll") for (int m = 0; m < 4; ++m) _Pragma("unroll") for (int n = 0; n < 2; ++n) _Pragma("unroll") for (int k = 0; k < 2; ++k) \
;         acc[ai][bj][m][n] = __builtin_amdgcn_mfma_f32_16x16x32_bf16(Bt[n][k], At[m][k], acc[ai][bj][m][n], 0, 0, 0); __builtin_amdgcn_s_setprio(0); } while (0)
; #define PG8_WAIT_V(n) asm volatile("s_waitcnt vmcnt(" #n ")" ::: "memory")
; #define PG8_WAIT_L(n) asm volatile("s_waitcnt lgkmcnt(" #n ")" ::: "memory")
; #define PG8_BAR __builtin_amdgcn_s_barrier()
; #define PG8_SCHED __builtin_amdgcn_sched_barrier(0)
; template <class Epi>
; __device__ __forceinline__ void gemm_phase(LAS unsigned char* lds, const Gemm g, const StaticOrder& S, const Epi& E) {
;     ...
;             PG8_LDA(At, 1, 1); PG8_STAGE(PG8_SB(1, 0), b3, voffB); PG8_STAGE(PG8_SB(1, 1), b3 + hstepB, voffB); PG8_STAGE(PG8_SA(1, 0), a3, voffA);
;             PG8_WAIT_V(8); PG8_WAIT_L(0); PG8_BAR; PG8_MMA(1, 0, At, B0); PG8_MMA(1, 1, At, B1); PG8_BAR; PG8_SCHED;
;         }
;         if (wr == 0) PG8_BAR;
	s_add_i32 s2, s45, s24
	v_lshl_add_u64 v[182:183], v[182:183], 0, s[14:15]
	s_mov_b32 m0, s2
	ds_read_b128 v[174:177], v190 offset:49152
	ds_read_b128 v[178:181], v190 offset:50176
	ds_read_b128 v[192:195], v190 offset:51200
	ds_read_b128 v[198:201], v190 offset:52224
	ds_read_b128 v[202:205], v190 offset:53248
	ds_read_b128 v[206:209], v190 offset:54272
	ds_read_b128 v[210:213], v190 offset:55296
	ds_read_b128 v[214:217], v190 offset:56320
	global_load_lds_dwordx4 v[182:183], off
	s_add_i32 m0, s2, 0x2000
	s_add_u32 s2, s20, 0xb0080
	v_lshl_add_u64 v[182:183], v[218:219], 0, s[14:15]
	s_addc_u32 s3, s21, 0
	s_add_i32 s20, s46, s24
	global_load_lds_dwordx4 v[182:183], off
	v_lshl_add_u64 v[182:183], s[2:3], 0, v[154:155]
	s_mov_b32 m0, s20
	s_nop 0
	global_load_lds_dwordx4 v[182:183], off
	v_lshl_add_u64 v[182:183], s[2:3], 0, v[158:159]
	s_add_i32 m0, s20, 0x2000
	s_nop 0
	global_load_lds_dwordx4 v[182:183], off
	v_lshl_add_u64 v[182:183], v[220:221], 0, s[14:15]
	s_mov_b32 m0, s30
	s_nop 0
	global_load_lds_dwordx4 v[182:183], off
	v_lshl_add_u64 v[182:183], v[222:223], 0, s[14:15]
	s_mov_b32 m0, s31
	s_nop 0
	global_load_lds_dwordx4 v[182:183], off
	s_waitcnt vmcnt(8)
	s_waitcnt lgkmcnt(0)
	s_barrier
	s_waitcnt lgkmcnt(0)
	v_mfma_f32_16x16x32_bf16 v[60:63], v[128:131], v[174:177], v[60:63]
	v_mfma_f32_16x16x32_bf16 v[56:59], v[136:139], v[174:177], v[56:59]
	v_mfma_f32_16x16x32_bf16 v[40:43], v[136:139], v[192:195], v[40:43]
	v_mfma_f32_16x16x32_bf16 v[44:47], v[128:131], v[192:195], v[44:47]
	v_mfma_f32_16x16x32_bf16 v[28:31], v[128:131], v[202:205], v[28:31]
	v_mfma_f32_16x16x32_bf16 v[24:27], v[136:139], v[202:205], v[24:27]
	v_mfma_f32_16x16x32_bf16 v[8:11], v[136:139], v[210:213], v[8:11]
	v_mfma_f32_16x16x32_bf16 v[12:15], v[128:131], v[210:213], v[12:15]
	v_mfma_f32_16x16x32_bf16 v[60:63], v[132:135], v[178:181], v[60:63]
	v_mfma_f32_16x16x32_bf16 v[56:59], v[140:143], v[178:181], v[56:59]
	v_mfma_f32_16x16x32_bf16 v[40:43], v[140:143], v[198:201], v[40:43]
	v_mfma_f32_16x16x32_bf16 v[44:47], v[132:135], v[198:201], v[44:47]
	v_mfma_f32_16x16x32_bf16 v[28:31], v[132:135], v[206:209], v[28:31]
	v_mfma_f32_16x16x32_bf16 v[24:27], v[140:143], v[206:209], v[24:27]
	v_mfma_f32_16x16x32_bf16 v[8:11], v[140:143], v[214:217], v[8:11]
	v_mfma_f32_16x16x32_bf16 v[12:15], v[132:135], v[214:217], v[12:15]
	v_mfma_f32_16x16x32_bf16 v[52:55], v[144:147], v[174:177], v[52:55]
	v_mfma_f32_16x16x32_bf16 v[48:51], v[166:169], v[174:177], v[48:51]
	v_mfma_f32_16x16x32_bf16 v[32:35], v[166:169], v[192:195], v[32:35]
	v_mfma_f32_16x16x32_bf16 v[36:39], v[144:147], v[192:195], v[36:39]
	v_mfma_f32_16x16x32_bf16 v[20:23], v[144:147], v[202:205], v[20:23]
	v_mfma_f32_16x16x32_bf16 v[16:19], v[166:169], v[202:205], v[16:19]
	v_mfma_f32_16x16x32_bf16 v[0:3], v[166:169], v[210:213], v[0:3]
	v_mfma_f32_16x16x32_bf16 v[4:7], v[144:147], v[210:213], v[4:7]
	v_mfma_f32_16x16x32_bf16 v[52:55], v[148:151], v[178:181], v[52:55]
	v_mfma_f32_16x16x32_bf16 v[48:51], v[170:173], v[178:181], v[48:51]
	v_mfma_f32_16x16x32_bf16 v[32:35], v[170:173], v[198:201], v[32:35]
	v_mfma_f32_16x16x32_bf16 v[36:39], v[148:151], v[198:201], v[36:39]
	v_mfma_f32_16x16x32_bf16 v[20:23], v[148:151], v[206:209], v[20:23]
	v_mfma_f32_16x16x32_bf16 v[16:19], v[170:173], v[206:209], v[16:19]
	v_mfma_f32_16x16x32_bf16 v[0:3], v[170:173], v[214:217], v[0:3]
	v_mfma_f32_16x16x32_bf16 v[4:7], v[148:151], v[214:217], v[4:7]
	s_barrier
	s_add_i32 s44, s44, 2
	s_add_u32 s42, s42, 0x100
	s_addc_u32 s43, s43, 0
	s_cmp_gt_u32 s44, 41
	s_mov_b64 s[2:3], s[8:9]
	s_cbranch_scc0 .LBB0_1034
	s_and_b64 vcc, exec, s[16:17]
	s_cbranch_vccz .LBB0_1037
	s_barrier

; #define PG8_STAGE(bufoff, gbase, voff) do { _Pragma("unroll") for (int _i = 0; _i < 2; ++_i) \
;         __builtin_amdgcn_global_load_lds((const unsigned*)((const char*)(gbase) + (voff)[_i]), (LAS unsigned*)(lds + (bufoff) + ldsw + _i * 8192), 16, 0, 0); } while (0)
; #define PG8_LDA(dst, b, h) do { _Pragma("unroll") for (int m = 0; m < 4; ++m) _Pragma("unroll") for (int k = 0; k < 2; ++k) dst[m][k] = *(const LAS bf16x8*)(lds + PG8_SA(b, h) + aoff + m * 2048 + k * 1024); } while (0)
; #define PG8_LDB(dst, b, h) do { _Pragma("unroll") for (int n = 0; n < 2; ++n) _Pragma("unroll") for (int k = 0; k < 2; ++k) dst[n][k] = *(const LAS bf16x8*)(lds + PG8_SB(b, h) + boff + n * 2048 + k * 1024); } while (0)
; #define PG8_MMA(ai, bj, At, Bt) do { __builtin_amdgcn_s_setprio(1); _Pragma("unroll") for (int m = 0; m < 4; ++m) _Pragma("unroll") for (int n = 0; n < 2; ++n) _Pragma("unroll") for (int k = 0; k < 2; ++k) \
;         acc[ai][bj][m][n] = __builtin_amdgcn_mfma_f32_16x16x32_bf16(Bt[n][k], At[m][k], acc[ai][bj][m][n], 0, 0, 0); __builtin_amdgcn_s_setprio(0); } while (0)
; template <class Epi>
; __device__ __forceinline__ void gemm_phase(LAS unsigned char* lds, const Gemm g, const StaticOrder& S, const Epi& E) {
;     ...
;         const bool has_next = S.next(ui + 1, nxt);
;         const char* nA = has_next ? (const char*)g.A + (size_t)(nxt.pm >> 5) * aslab + (size_t)(nxt.pm & 31) * tstepA : cA; const char* nB = has_next ? (const char*)g.Bt + (size_t)nxt.pn * tstepB : cB;
;         for (int t = 0; t < nt; t += 2) {
;             const bool last = (t == nt - 2);
;             const char* a1 = cA + (size_t)(t + 1) * kstep;
;             const char* a2 = last ? nA : cA + (size_t)(t + 2) * kstep; const char* b2 = last ? nB : cB + (size_t)(t + 2) * kstep;
;             const char* a3 = a2 + kstep; const char* b3 = b2 + kstep;
;             PG8_LDB(B0, 0, 0); PG8_LDB(B1, 0, 1); PG8_SCHED; PG8_LDA(At, 0, 0); PG8_STAGE(PG8_SA(1, 1), a1 + hstepA, voffA);
;             PG8_WAIT_V(8); PG8_WAIT_L(0); PG8_BAR; PG8_MMA(0, 0, At, B0); PG8_MMA(0, 1, At, B1); PG8_BAR; PG8_SCHED;
;             PG8_LDA(At, 0, 1); PG8_STAGE(PG8_SB(0, 0), b2, voffB); PG8_STAGE(PG8_SB(0, 1), b2 + hstepB, voffB); PG8_STAGE(PG8_SA(0, 0), a2, voffA);
;             PG8_WAIT_V(8); PG8_WAIT_L(0); PG8_BAR; PG8_MMA(1, 0, At, B0); PG8_MMA(1, 1, At, B1); PG8_BAR; PG8_SCHED;
.LBB0_1176:
	s_add_u32 s44, s20, 0x100
	s_addc_u32 s45, s21, 0
	s_mov_b32 s46, -2
	ds_read_b128 v[128:131], v200
	ds_read_b128 v[132:135], v200 offset:1024
	ds_read_b128 v[136:139], v200 offset:2048
	ds_read_b128 v[140:143], v200 offset:3072
	ds_read_b128 v[144:147], v201
	ds_read_b128 v[148:151], v201 offset:1024
	ds_read_b128 v[168:171], v201 offset:2048
	ds_read_b128 v[172:175], v201 offset:3072
	s_add_u32 s20, s2, 0x100
	s_addc_u32 s21, s3, 0
	s_cmp_eq_u32 s46, 40
	s_cselect_b32 s25, s7, s21
	s_cselect_b32 s24, s6, s20
	s_cselect_b32 s23, s19, s45
	s_cselect_b32 s22, s18, s44
	v_lshl_add_u64 v[218:219], s[2:3], 0, v[162:163]
	s_add_i32 m0, s27, 0xc000
	ds_read_b128 v[176:179], v202
	ds_read_b128 v[180:183], v202 offset:1024
	ds_read_b128 v[184:187], v202 offset:2048
	ds_read_b128 v[188:191], v202 offset:3072
	ds_read_b128 v[192:195], v202 offset:4096
	ds_read_b128 v[206:209], v202 offset:5120
	ds_read_b128 v[210:213], v202 offset:6144
	ds_read_b128 v[214:217], v202 offset:7168
	global_load_lds_dwordx4 v[218:219], off
	v_lshl_add_u64 v[218:219], s[2:3], 0, v[164:165]
	s_add_i32 m0, s27, 0xe000
	s_nop 0
	global_load_lds_dwordx4 v[218:219], off
	s_waitcnt vmcnt(8)
	s_waitcnt lgkmcnt(0)
	s_barrier
	s_waitcnt lgkmcnt(0)
	v_mfma_f32_16x16x32_bf16 v[124:127], v[128:131], v[176:179], 0
	v_mfma_f32_16x16x32_bf16 v[120:123], v[136:139], v[176:179], 0
	v_mfma_f32_16x16x32_bf16 v[104:107], v[136:139], v[184:187], 0
	v_mfma_f32_16x16x32_bf16 v[108:111], v[128:131], v[184:187], 0
	v_mfma_f32_16x16x32_bf16 v[92:95], v[128:131], v[192:195], 0
	v_mfma_f32_16x16x32_bf16 v[88:91], v[136:139], v[192:195], 0
	v_mfma_f32_16x16x32_bf16 v[72:75], v[136:139], v[210:213], 0
	v_mfma_f32_16x16x32_bf16 v[76:79], v[128:131], v[210:213], 0
	v_mfma_f32_16x16x32_bf16 v[124:127], v[132:135], v[180:183], v[124:127]
	v_mfma_f32_16x16x32_bf16 v[120:123], v[140:143], v[180:183], v[120:123]
	v_mfma_f32_16x16x32_bf16 v[104:107], v[140:143], v[188:191], v[104:107]
	v_mfma_f32_16x16x32_bf16 v[108:111], v[132:135], v[188:191], v[108:111]
	v_mfma_f32_16x16x32_bf16 v[92:95], v[132:135], v[206:209], v[92:95]
	v_mfma_f32_16x16x32_bf16 v[88:91], v[140:143], v[206:209], v[88:91]
	v_mfma_f32_16x16x32_bf16 v[72:75], v[140:143], v[214:217], v[72:75]
	v_mfma_f32_16x16x32_bf16 v[76:79], v[132:135], v[214:217], v[76:79]
	v_mfma_f32_16x16x32_bf16 v[116:119], v[144:147], v[176:179], 0
	v_mfma_f32_16x16x32_bf16 v[112:115], v[168:171], v[176:179], 0
	v_mfma_f32_16x16x32_bf16 v[96:99], v[168:171], v[184:187], 0
	v_mfma_f32_16x16x32_bf16 v[100:103], v[144:147], v[184:187], 0
	v_mfma_f32_16x16x32_bf16 v[84:87], v[144:147], v[192:195], 0
	v_mfma_f32_16x16x32_bf16 v[80:83], v[168:171], v[192:195], 0
	v_mfma_f32_16x16x32_bf16 v[64:67], v[168:171], v[210:213], 0
	v_mfma_f32_16x16x32_bf16 v[68:71], v[144:147], v[210:213], 0
	v_mfma_f32_16x16x32_bf16 v[116:119], v[148:151], v[180:183], v[116:119]
	v_mfma_f32_16x16x32_bf16 v[112:115], v[172:175], v[180:183], v[112:115]
	v_mfma_f32_16x16x32_bf16 v[96:99], v[172:175], v[188:191], v[96:99]
	v_mfma_f32_16x16x32_bf16 v[100:103], v[148:151], v[188:191], v[100:103]
	v_mfma_f32_16x16x32_bf16 v[84:87], v[148:151], v[206:209], v[84:87]
	v_mfma_f32_16x16x32_bf16 v[80:83], v[172:175], v[206:209], v[80:83]
	v_mfma_f32_16x16x32_bf16 v[64:67], v[172:175], v[214:217], v[64:67]
	v_mfma_f32_16x16x32_bf16 v[68:71], v[148:151], v[214:217], v[68:71]
	s_barrier
	s_add_i32 s2, s38, s26
	v_lshl_add_u64 v[218:219], s[22:23], 0, v[154:155]
	s_mov_b32 m0, s2
	ds_read_b128 v[176:179], v202 offset:16384
	ds_read_b128 v[180:183], v202 offset:17408
	ds_read_b128 v[184:187], v202 offset:18432
	ds_read_b128 v[188:191], v202 offset:19456
	ds_read_b128 v[192:195], v202 offset:20480
	ds_read_b128 v[206:209], v202 offset:21504
	ds_read_b128 v[210:213], v202 offset:22528
	ds_read_b128 v[214:217], v202 offset:23552
	global_load_lds_dwordx4 v[218:219], off
	s_add_i32 m0, s2, 0x2000
	s_add_u32 s2, s22, 0xb0000
	v_lshl_add_u64 v[220:221], s[22:23], 0, v[158:159]
	s_addc_u32 s3, s23, 0
	s_add_i32 s47, s39, s26
	global_load_lds_dwordx4 v[220:221], off
	v_lshl_add_u64 v[222:223], s[2:3], 0, v[154:155]
	s_mov_b32 m0, s47
	v_lshl_add_u64 v[224:225], s[24:25], 0, v[156:157]
	global_load_lds_dwordx4 v[222:223], off
	v_lshl_add_u64 v[222:223], s[2:3], 0, v[158:159]
	s_add_i32 m0, s47, 0x2000
	s_nop 0
	global_load_lds_dwordx4 v[222:223], off
	v_lshl_add_u64 v[222:223], s[24:25], 0, v[152:153]
	s_mov_b32 m0, s27
	s_nop 0
	global_load_lds_dwordx4 v[222:223], off
	s_mov_b32 m0, s28
	s_nop 0
	global_load_lds_dwordx4 v[224:225], off
	s_waitcnt vmcnt(8)
	s_waitcnt lgkmcnt(0)
	s_barrier
; #define PG8_STAGE(bufoff, gbase, voff) do { _Pragma("unroll") for (int _i = 0; _i < 2; ++_i) \
;         __builtin_amdgcn_global_load_lds((const unsigned*)((const char*)(gbase) + (voff)[_i]), (LAS unsigned*)(lds + (bufoff) + ldsw + _i * 8192), 16, 0, 0); } while (0)
; #define PG8_LDA(dst, b, h) do { _Pragma("unroll") for (int m = 0; m < 4; ++m) _Pragma("unroll") for (int k = 0; k < 2; ++k) dst[m][k] = *(const LAS bf16x8*)(lds + PG8_SA(b, h) + aoff + m * 2048 + k * 1024); } while (0)
; #define PG8_LDB(dst, b, h) do { _Pragma("unroll") for (int n = 0; n < 2; ++n) _Pragma("unroll") for (int k = 0; k < 2; ++k) dst[n][k] = *(const LAS bf16x8*)(lds + PG8_SB(b, h) + boff + n * 2048 + k * 1024); } while (0)
; #define PG8_MMA(ai, bj, At, Bt) do { __builtin_amdgcn_s_setprio(1); _Pragma("unroll") for (int m = 0; m < 4; ++m) _Pragma("unroll") for (int n = 0; n < 2; ++n) _Pragma("unroll") for (int k = 0; k < 2; ++k) \
;         acc[ai][bj][m][n] = __builtin_amdgcn_mfma_f32_16x16x32_bf16(Bt[n][k], At[m][k], acc[ai][bj][m][n], 0, 0, 0); __builtin_amdgcn_s_setprio(0); } while (0)
; #define PG8_WAIT_V(n) asm volatile("s_waitcnt vmcnt(" #n ")" ::: "memory")
; #define PG8_WAIT_L(n) asm volatile("s_waitcnt lgkmcnt(" #n ")" ::: "memory")
; #define PG8_BAR __builtin_amdgcn_s_barrier()
; #define PG8_SCHED __builtin_amdgcn_sched_barrier(0)
; template <class Epi>
; __device__ __forceinline__ void gemm_phase(LAS unsigned char* lds, const Gemm g, const StaticOrder& S, const Epi& E) {
;     ...
;             PG8_WAIT_V(8); PG8_WAIT_L(0); PG8_BAR; PG8_MMA(1, 0, At, B0); PG8_MMA(1, 1, At, B1); PG8_BAR; PG8_SCHED;
;             PG8_LDB(B0, 1, 0); PG8_LDB(B1, 1, 1); PG8_SCHED; PG8_LDA(At, 1, 0); PG8_STAGE(PG8_SA(0, 1), a2 + hstepA, voffA);
;             PG8_WAIT_V(8); PG8_WAIT_L(0); PG8_BAR; PG8_MMA(0, 0, At, B0); PG8_MMA(0, 1, At, B1); PG8_BAR; PG8_SCHED;
	s_waitcnt lgkmcnt(0)
	v_mfma_f32_16x16x32_bf16 v[60:63], v[128:131], v[176:179], 0
	v_mfma_f32_16x16x32_bf16 v[56:59], v[136:139], v[176:179], 0
	v_mfma_f32_16x16x32_bf16 v[40:43], v[136:139], v[184:187], 0
	v_mfma_f32_16x16x32_bf16 v[44:47], v[128:131], v[184:187], 0
	v_mfma_f32_16x16x32_bf16 v[28:31], v[128:131], v[192:195], 0
	v_mfma_f32_16x16x32_bf16 v[24:27], v[136:139], v[192:195], 0
	v_mfma_f32_16x16x32_bf16 v[8:11], v[136:139], v[210:213], 0
	v_mfma_f32_16x16x32_bf16 v[12:15], v[128:131], v[210:213], 0
	v_mfma_f32_16x16x32_bf16 v[60:63], v[132:135], v[180:183], v[60:63]
	v_mfma_f32_16x16x32_bf16 v[56:59], v[140:143], v[180:183], v[56:59]
	v_mfma_f32_16x16x32_bf16 v[40:43], v[140:143], v[188:191], v[40:43]
	v_mfma_f32_16x16x32_bf16 v[44:47], v[132:135], v[188:191], v[44:47]
	v_mfma_f32_16x16x32_bf16 v[28:31], v[132:135], v[206:209], v[28:31]
	v_mfma_f32_16x16x32_bf16 v[24:27], v[140:143], v[206:209], v[24:27]
	v_mfma_f32_16x16x32_bf16 v[8:11], v[140:143], v[214:217], v[8:11]
	v_mfma_f32_16x16x32_bf16 v[12:15], v[132:135], v[214:217], v[12:15]
	v_mfma_f32_16x16x32_bf16 v[52:55], v[144:147], v[176:179], 0
	v_mfma_f32_16x16x32_bf16 v[48:51], v[168:171], v[176:179], 0
	v_mfma_f32_16x16x32_bf16 v[32:35], v[168:171], v[184:187], 0
	v_mfma_f32_16x16x32_bf16 v[36:39], v[144:147], v[184:187], 0
	v_mfma_f32_16x16x32_bf16 v[20:23], v[144:147], v[192:195], 0
	v_mfma_f32_16x16x32_bf16 v[16:19], v[168:171], v[192:195], 0
	v_mfma_f32_16x16x32_bf16 v[0:3], v[168:171], v[210:213], 0
	v_mfma_f32_16x16x32_bf16 v[4:7], v[144:147], v[210:213], 0
	v_mfma_f32_16x16x32_bf16 v[52:55], v[148:151], v[180:183], v[52:55]
	v_mfma_f32_16x16x32_bf16 v[48:51], v[172:175], v[180:183], v[48:51]
	v_mfma_f32_16x16x32_bf16 v[32:35], v[172:175], v[188:191], v[32:35]
	v_mfma_f32_16x16x32_bf16 v[36:39], v[148:151], v[188:191], v[36:39]
	v_mfma_f32_16x16x32_bf16 v[20:23], v[148:151], v[206:209], v[20:23]
	v_mfma_f32_16x16x32_bf16 v[16:19], v[172:175], v[206:209], v[16:19]
	v_mfma_f32_16x16x32_bf16 v[0:3], v[172:175], v[214:217], v[0:3]
	v_mfma_f32_16x16x32_bf16 v[4:7], v[148:151], v[214:217], v[4:7]
	s_barrier
	s_add_i32 s47, 0, 0x18000
	s_add_i32 s48, 0, 0x1c000
	v_add_u32_e32 v140, s47, v198
	v_add_u32_e32 v172, s48, v198
	ds_read_b128 v[128:131], v140
	ds_read_b128 v[132:135], v140 offset:1024
	ds_read_b128 v[136:139], v140 offset:2048
	ds_read_b128 v[140:143], v140 offset:3072
	ds_read_b128 v[144:147], v172
	ds_read_b128 v[148:151], v172 offset:1024
	ds_read_b128 v[168:171], v172 offset:2048
	ds_read_b128 v[172:175], v172 offset:3072
	s_add_u32 s2, s24, 0xb4000
	s_addc_u32 s3, s25, 0
	s_mov_b32 m0, s29
	v_lshl_add_u64 v[226:227], s[2:3], 0, v[152:153]
	ds_read_b128 v[176:179], v202 offset:32768
	ds_read_b128 v[180:183], v202 offset:33792
	ds_read_b128 v[184:187], v202 offset:34816
	ds_read_b128 v[188:191], v202 offset:35840
	ds_read_b128 v[192:195], v202 offset:36864
	ds_read_b128 v[206:209], v202 offset:37888
	ds_read_b128 v[210:213], v202 offset:38912
	ds_read_b128 v[214:217], v202 offset:39936
	global_load_lds_dwordx4 v[226:227], off
	v_lshl_add_u64 v[226:227], s[2:3], 0, v[156:157]
	s_mov_b32 m0, s30
	s_nop 0
	global_load_lds_dwordx4 v[226:227], off
	s_waitcnt vmcnt(8)
	s_waitcnt lgkmcnt(0)
	s_barrier
	s_waitcnt lgkmcnt(0)
	v_mfma_f32_16x16x32_bf16 v[124:127], v[128:131], v[176:179], v[124:127]
	v_mfma_f32_16x16x32_bf16 v[120:123], v[136:139], v[176:179], v[120:123]
	v_mfma_f32_16x16x32_bf16 v[104:107], v[136:139], v[184:187], v[104:107]
	v_mfma_f32_16x16x32_bf16 v[108:111], v[128:131], v[184:187], v[108:111]
	v_mfma_f32_16x16x32_bf16 v[92:95], v[128:131], v[192:195], v[92:95]
	v_mfma_f32_16x16x32_bf16 v[88:91], v[136:139], v[192:195], v[88:91]
	v_mfma_f32_16x16x32_bf16 v[72:75], v[136:139], v[210:213], v[72:75]
	v_mfma_f32_16x16x32_bf16 v[76:79], v[128:131], v[210:213], v[76:79]
	v_mfma_f32_16x16x32_bf16 v[124:127], v[132:135], v[180:183], v[124:127]
	v_mfma_f32_16x16x32_bf16 v[120:123], v[140:143], v[180:183], v[120:123]
	v_mfma_f32_16x16x32_bf16 v[104:107], v[140:143], v[188:191], v[104:107]
	v_mfma_f32_16x16x32_bf16 v[108:111], v[132:135], v[188:191], v[108:111]
	v_mfma_f32_16x16x32_bf16 v[92:95], v[132:135], v[206:209], v[92:95]
	v_mfma_f32_16x16x32_bf16 v[88:91], v[140:143], v[206:209], v[88:91]
	v_mfma_f32_16x16x32_bf16 v[72:75], v[140:143], v[214:217], v[72:75]
	v_mfma_f32_16x16x32_bf16 v[76:79], v[132:135], v[214:217], v[76:79]
	v_mfma_f32_16x16x32_bf16 v[116:119], v[144:147], v[176:179], v[116:119]
	v_mfma_f32_16x16x32_bf16 v[112:115], v[168:171], v[176:179], v[112:115]
	v_mfma_f32_16x16x32_bf16 v[96:99], v[168:171], v[184:187], v[96:99]
	v_mfma_f32_16x16x32_bf16 v[100:103], v[144:147], v[184:187], v[100:103]
	v_mfma_f32_16x16x32_bf16 v[84:87], v[144:147], v[192:195], v[84:87]
	v_mfma_f32_16x16x32_bf16 v[80:83], v[168:171], v[192:195], v[80:83]
	v_mfma_f32_16x16x32_bf16 v[64:67], v[168:171], v[210:213], v[64:67]
	v_mfma_f32_16x16x32_bf16 v[68:71], v[144:147], v[210:213], v[68:71]
	v_mfma_f32_16x16x32_bf16 v[116:119], v[148:151], v[180:183], v[116:119]
	v_mfma_f32_16x16x32_bf16 v[112:115], v[172:175], v[180:183], v[112:115]
	v_mfma_f32_16x16x32_bf16 v[96:99], v[172:175], v[188:191], v[96:99]
	v_mfma_f32_16x16x32_bf16 v[100:103], v[148:151], v[188:191], v[100:103]
	v_mfma_f32_16x16x32_bf16 v[84:87], v[148:151], v[206:209], v[84:87]
	v_mfma_f32_16x16x32_bf16 v[80:83], v[172:175], v[206:209], v[80:83]
	v_mfma_f32_16x16x32_bf16 v[64:67], v[172:175], v[214:217], v[64:67]
	v_mfma_f32_16x16x32_bf16 v[68:71], v[148:151], v[214:217], v[68:71]
	s_barrier
; #define PG8_STAGE(bufoff, gbase, voff) do { _Pragma("unroll") for (int _i = 0; _i < 2; ++_i) \
;         __builtin_amdgcn_global_load_lds((const unsigned*)((const char*)(gbase) + (voff)[_i]), (LAS unsigned*)(lds + (bufoff) + ldsw + _i * 8192), 16, 0, 0); } while (0)
; #define PG8_LDA(dst, b, h) do { _Pragma("unroll") for (int m = 0; m < 4; ++m) _Pragma("unroll") for (int k = 0; k < 2; ++k) dst[m][k] = *(const LAS bf16x8*)(lds + PG8_SA(b, h) + aoff + m * 2048 + k * 1024); } while (0)
; #define PG8_LDB(dst, b, h) do { _Pragma("unroll") for (int n = 0; n < 2; ++n) _Pragma("unroll") for (int k = 0; k < 2; ++k) dst[n][k] = *(const LAS bf16x8*)(lds + PG8_SB(b, h) + boff + n * 2048 + k * 1024); } while (0)
; #define PG8_MMA(ai, bj, At, Bt) do { __builtin_amdgcn_s_setprio(1); _Pragma("unroll") for (int m = 0; m < 4; ++m) _Pragma("unroll") for (int n = 0; n < 2; ++n) _Pragma("unroll") for (int k = 0; k < 2; ++k) \
;         acc[ai][bj][m][n] = __builtin_amdgcn_mfma_f32_16x16x32_bf16(Bt[n][k], At[m][k], acc[ai][bj][m][n], 0, 0, 0); __builtin_amdgcn_s_setprio(0); } while (0)
; #define PG8_WAIT_V(n) asm volatile("s_waitcnt vmcnt(" #n ")" ::: "memory")
; #define PG8_WAIT_L(n) asm volatile("s_waitcnt lgkmcnt(" #n ")" ::: "memory")
; #define PG8_BAR __builtin_amdgcn_s_barrier()
; #define PG8_SCHED __builtin_amdgcn_sched_barrier(0)
; template <class Epi>
; __device__ __forceinline__ void gemm_phase(LAS unsigned char* lds, const Gemm g, const StaticOrder& S, const Epi& E) {
;     ...
;         for (int t = 0; t < nt; t += 2) {
;             const bool last = (t == nt - 2);
;             const char* a1 = cA + (size_t)(t + 1) * kstep;
;             const char* a2 = last ? nA : cA + (size_t)(t + 2) * kstep; const char* b2 = last ? nB : cB + (size_t)(t + 2) * kstep;
;             const char* a3 = a2 + kstep; const char* b3 = b2 + kstep;
;             PG8_LDB(B0, 0, 0); PG8_LDB(B1, 0, 1); PG8_SCHED; PG8_LDA(At, 0, 0); PG8_STAGE(PG8_SA(1, 1), a1 + hstepA, voffA);
;             PG8_WAIT_V(8); PG8_WAIT_L(0); PG8_BAR; PG8_MMA(0, 0, At, B0); PG8_MMA(0, 1, At, B1); PG8_BAR; PG8_SCHED;
;     ...
;             PG8_LDA(At, 1, 1); PG8_STAGE(PG8_SB(1, 0), b3, voffB); PG8_STAGE(PG8_SB(1, 1), b3 + hstepB, voffB); PG8_STAGE(PG8_SA(1, 0), a3, voffA);
;             PG8_WAIT_V(8); PG8_WAIT_L(0); PG8_BAR; PG8_MMA(1, 0, At, B0); PG8_MMA(1, 1, At, B1); PG8_BAR; PG8_SCHED;
	s_add_i32 s2, s47, s26
	v_lshl_add_u64 v[218:219], v[218:219], 0, s[14:15]
	s_mov_b32 m0, s2
	ds_read_b128 v[176:179], v202 offset:49152
	ds_read_b128 v[180:183], v202 offset:50176
	ds_read_b128 v[184:187], v202 offset:51200
	ds_read_b128 v[188:191], v202 offset:52224
	ds_read_b128 v[192:195], v202 offset:53248
	ds_read_b128 v[206:209], v202 offset:54272
	ds_read_b128 v[210:213], v202 offset:55296
	ds_read_b128 v[214:217], v202 offset:56320
	global_load_lds_dwordx4 v[218:219], off
	s_add_i32 m0, s2, 0x2000
	s_add_u32 s2, s22, 0xb0080
	v_lshl_add_u64 v[218:219], v[220:221], 0, s[14:15]
	s_addc_u32 s3, s23, 0
	s_add_i32 s22, s48, s26
	global_load_lds_dwordx4 v[218:219], off
	v_lshl_add_u64 v[218:219], s[2:3], 0, v[154:155]
	s_mov_b32 m0, s22
	s_nop 0
	global_load_lds_dwordx4 v[218:219], off
	v_lshl_add_u64 v[218:219], s[2:3], 0, v[158:159]
	s_add_i32 m0, s22, 0x2000
	s_nop 0
	global_load_lds_dwordx4 v[218:219], off
	v_lshl_add_u64 v[218:219], v[222:223], 0, s[14:15]
	s_mov_b32 m0, s34
	s_nop 0
	global_load_lds_dwordx4 v[218:219], off
	v_lshl_add_u64 v[218:219], v[224:225], 0, s[14:15]
	s_mov_b32 m0, s35
	s_nop 0
	global_load_lds_dwordx4 v[218:219], off
	s_waitcnt vmcnt(8)
	s_waitcnt lgkmcnt(0)
	s_barrier
	s_waitcnt lgkmcnt(0)
	v_mfma_f32_16x16x32_bf16 v[60:63], v[128:131], v[176:179], v[60:63]
	v_mfma_f32_16x16x32_bf16 v[56:59], v[136:139], v[176:179], v[56:59]
	v_mfma_f32_16x16x32_bf16 v[40:43], v[136:139], v[184:187], v[40:43]
	v_mfma_f32_16x16x32_bf16 v[44:47], v[128:131], v[184:187], v[44:47]
	v_mfma_f32_16x16x32_bf16 v[28:31], v[128:131], v[192:195], v[28:31]
	v_mfma_f32_16x16x32_bf16 v[24:27], v[136:139], v[192:195], v[24:27]
	v_mfma_f32_16x16x32_bf16 v[8:11], v[136:139], v[210:213], v[8:11]
	v_mfma_f32_16x16x32_bf16 v[12:15], v[128:131], v[210:213], v[12:15]
	v_mfma_f32_16x16x32_bf16 v[60:63], v[132:135], v[180:183], v[60:63]
	v_mfma_f32_16x16x32_bf16 v[56:59], v[140:143], v[180:183], v[56:59]
	v_mfma_f32_16x16x32_bf16 v[40:43], v[140:143], v[188:191], v[40:43]
	v_mfma_f32_16x16x32_bf16 v[44:47], v[132:135], v[188:191], v[44:47]
	v_mfma_f32_16x16x32_bf16 v[28:31], v[132:135], v[206:209], v[28:31]
	v_mfma_f32_16x16x32_bf16 v[24:27], v[140:143], v[206:209], v[24:27]
	v_mfma_f32_16x16x32_bf16 v[8:11], v[140:143], v[214:217], v[8:11]
	v_mfma_f32_16x16x32_bf16 v[12:15], v[132:135], v[214:217], v[12:15]
	v_mfma_f32_16x16x32_bf16 v[52:55], v[144:147], v[176:179], v[52:55]
	v_mfma_f32_16x16x32_bf16 v[48:51], v[168:171], v[176:179], v[48:51]
	v_mfma_f32_16x16x32_bf16 v[32:35], v[168:171], v[184:187], v[32:35]
	v_mfma_f32_16x16x32_bf16 v[36:39], v[144:147], v[184:187], v[36:39]
	v_mfma_f32_16x16x32_bf16 v[20:23], v[144:147], v[192:195], v[20:23]
	v_mfma_f32_16x16x32_bf16 v[16:19], v[168:171], v[192:195], v[16:19]
	v_mfma_f32_16x16x32_bf16 v[0:3], v[168:171], v[210:213], v[0:3]
	v_mfma_f32_16x16x32_bf16 v[4:7], v[144:147], v[210:213], v[4:7]
	v_mfma_f32_16x16x32_bf16 v[52:55], v[148:151], v[180:183], v[52:55]
	v_mfma_f32_16x16x32_bf16 v[48:51], v[172:175], v[180:183], v[48:51]
	v_mfma_f32_16x16x32_bf16 v[32:35], v[172:175], v[188:191], v[32:35]
	v_mfma_f32_16x16x32_bf16 v[36:39], v[148:151], v[188:191], v[36:39]
	v_mfma_f32_16x16x32_bf16 v[20:23], v[148:151], v[206:209], v[20:23]
	v_mfma_f32_16x16x32_bf16 v[16:19], v[172:175], v[206:209], v[16:19]
	v_mfma_f32_16x16x32_bf16 v[0:3], v[172:175], v[214:217], v[0:3]
	v_mfma_f32_16x16x32_bf16 v[4:7], v[148:151], v[214:217], v[4:7]
	s_barrier
	s_add_i32 s46, s46, 2
	s_add_u32 s44, s44, 0x100
	s_addc_u32 s45, s45, 0
	s_cmp_gt_u32 s46, 41
	s_mov_b64 s[2:3], s[20:21]
	s_cbranch_scc0 .LBB0_1177
.LBB0_1177:
	ds_read_b128 v[128:131], v200
	ds_read_b128 v[132:135], v200 offset:1024
	ds_read_b128 v[136:139], v200 offset:2048
	ds_read_b128 v[140:143], v200 offset:3072
	ds_read_b128 v[144:147], v201
	ds_read_b128 v[148:151], v201 offset:1024
	ds_read_b128 v[168:171], v201 offset:2048
	ds_read_b128 v[172:175], v201 offset:3072
	s_add_u32 s20, s2, 0x100
	s_addc_u32 s21, s3, 0
	s_cmp_eq_u32 s46, 40
	s_cselect_b32 s25, s7, s21
	s_cselect_b32 s24, s6, s20
	s_cselect_b32 s23, s19, s45
	s_cselect_b32 s22, s18, s44
	v_lshl_add_u64 v[218:219], s[2:3], 0, v[162:163]
	s_add_i32 m0, s27, 0xc000
	ds_read_b128 v[176:179], v202
	ds_read_b128 v[180:183], v202 offset:1024
	ds_read_b128 v[184:187], v202 offset:2048
	ds_read_b128 v[188:191], v202 offset:3072
	ds_read_b128 v[192:195], v202 offset:4096
	ds_read_b128 v[206:209], v202 offset:5120
	ds_read_b128 v[210:213], v202 offset:6144
	ds_read_b128 v[214:217], v202 offset:7168
	global_load_lds_dwordx4 v[218:219], off
	v_lshl_add_u64 v[218:219], s[2:3], 0, v[164:165]
	s_add_i32 m0, s27, 0xe000
	s_nop 0
	global_load_lds_dwordx4 v[218:219], off
	s_waitcnt vmcnt(8)
	s_waitcnt lgkmcnt(0)
	s_barrier
; #define PG8_STAGE(bufoff, gbase, voff) do { _Pragma("unroll") for (int _i = 0; _i < 2; ++_i) \
;         __builtin_amdgcn_global_load_lds((const unsigned*)((const char*)(gbase) + (voff)[_i]), (LAS unsigned*)(lds + (bufoff) + ldsw + _i * 8192), 16, 0, 0); } while (0)
; #define PG8_LDA(dst, b, h) do { _Pragma("unroll") for (int m = 0; m < 4; ++m) _Pragma("unroll") for (int k = 0; k < 2; ++k) dst[m][k] = *(const LAS bf16x8*)(lds + PG8_SA(b, h) + aoff + m * 2048 + k * 1024); } while (0)
; #define PG8_LDB(dst, b, h) do { _Pragma("unroll") for (int n = 0; n < 2; ++n) _Pragma("unroll") for (int k = 0; k < 2; ++k) dst[n][k] = *(const LAS bf16x8*)(lds + PG8_SB(b, h) + boff + n * 2048 + k * 1024); } while (0)
; #define PG8_MMA(ai, bj, At, Bt) do { __builtin_amdgcn_s_setprio(1); _Pragma("unroll") for (int m = 0; m < 4; ++m) _Pragma("unroll") for (int n = 0; n < 2; ++n) _Pragma("unroll") for (int k = 0; k < 2; ++k) \
;         acc[ai][bj][m][n] = __builtin_amdgcn_mfma_f32_16x16x32_bf16(Bt[n][k], At[m][k], acc[ai][bj][m][n], 0, 0, 0); __builtin_amdgcn_s_setprio(0); } while (0)
; #define PG8_WAIT_V(n) asm volatile("s_waitcnt vmcnt(" #n ")" ::: "memory")
; #define PG8_WAIT_L(n) asm volatile("s_waitcnt lgkmcnt(" #n ")" ::: "memory")
; #define PG8_BAR __builtin_amdgcn_s_barrier()
; #define PG8_SCHED __builtin_amdgcn_sched_barrier(0)
; template <class Epi>
; __device__ __forceinline__ void gemm_phase(LAS unsigned char* lds, const Gemm g, const StaticOrder& S, const Epi& E) {
;     ...
;             PG8_LDB(B0, 0, 0); PG8_LDB(B1, 0, 1); PG8_SCHED; PG8_LDA(At, 0, 0); PG8_STAGE(PG8_SA(1, 1), a1 + hstepA, voffA);
;             PG8_WAIT_V(8); PG8_WAIT_L(0); PG8_BAR; PG8_MMA(0, 0, At, B0); PG8_MMA(0, 1, At, B1); PG8_BAR; PG8_SCHED;
;             PG8_LDA(At, 0, 1); PG8_STAGE(PG8_SB(0, 0), b2, voffB); PG8_STAGE(PG8_SB(0, 1), b2 + hstepB, voffB); PG8_STAGE(PG8_SA(0, 0), a2, voffA);
;             PG8_WAIT_V(8); PG8_WAIT_L(0); PG8_BAR; PG8_MMA(1, 0, At, B0); PG8_MMA(1, 1, At, B1); PG8_BAR; PG8_SCHED;
	s_waitcnt lgkmcnt(0)
	v_mfma_f32_16x16x32_bf16 v[124:127], v[128:131], v[176:179], v[124:127]
	v_mfma_f32_16x16x32_bf16 v[120:123], v[136:139], v[176:179], v[120:123]
	v_mfma_f32_16x16x32_bf16 v[104:107], v[136:139], v[184:187], v[104:107]
	v_mfma_f32_16x16x32_bf16 v[108:111], v[128:131], v[184:187], v[108:111]
	v_mfma_f32_16x16x32_bf16 v[92:95], v[128:131], v[192:195], v[92:95]
	v_mfma_f32_16x16x32_bf16 v[88:91], v[136:139], v[192:195], v[88:91]
	v_mfma_f32_16x16x32_bf16 v[72:75], v[136:139], v[210:213], v[72:75]
	v_mfma_f32_16x16x32_bf16 v[76:79], v[128:131], v[210:213], v[76:79]
	v_mfma_f32_16x16x32_bf16 v[124:127], v[132:135], v[180:183], v[124:127]
	v_mfma_f32_16x16x32_bf16 v[120:123], v[140:143], v[180:183], v[120:123]
	v_mfma_f32_16x16x32_bf16 v[104:107], v[140:143], v[188:191], v[104:107]
	v_mfma_f32_16x16x32_bf16 v[108:111], v[132:135], v[188:191], v[108:111]
	v_mfma_f32_16x16x32_bf16 v[92:95], v[132:135], v[206:209], v[92:95]
	v_mfma_f32_16x16x32_bf16 v[88:91], v[140:143], v[206:209], v[88:91]
	v_mfma_f32_16x16x32_bf16 v[72:75], v[140:143], v[214:217], v[72:75]
	v_mfma_f32_16x16x32_bf16 v[76:79], v[132:135], v[214:217], v[76:79]
	v_mfma_f32_16x16x32_bf16 v[116:119], v[144:147], v[176:179], v[116:119]
	v_mfma_f32_16x16x32_bf16 v[112:115], v[168:171], v[176:179], v[112:115]
	v_mfma_f32_16x16x32_bf16 v[96:99], v[168:171], v[184:187], v[96:99]
	v_mfma_f32_16x16x32_bf16 v[100:103], v[144:147], v[184:187], v[100:103]
	v_mfma_f32_16x16x32_bf16 v[84:87], v[144:147], v[192:195], v[84:87]
	v_mfma_f32_16x16x32_bf16 v[80:83], v[168:171], v[192:195], v[80:83]
	v_mfma_f32_16x16x32_bf16 v[64:67], v[168:171], v[210:213], v[64:67]
	v_mfma_f32_16x16x32_bf16 v[68:71], v[144:147], v[210:213], v[68:71]
	v_mfma_f32_16x16x32_bf16 v[116:119], v[148:151], v[180:183], v[116:119]
	v_mfma_f32_16x16x32_bf16 v[112:115], v[172:175], v[180:183], v[112:115]
	v_mfma_f32_16x16x32_bf16 v[96:99], v[172:175], v[188:191], v[96:99]
	v_mfma_f32_16x16x32_bf16 v[100:103], v[148:151], v[188:191], v[100:103]
	v_mfma_f32_16x16x32_bf16 v[84:87], v[148:151], v[206:209], v[84:87]
	v_mfma_f32_16x16x32_bf16 v[80:83], v[172:175], v[206:209], v[80:83]
	v_mfma_f32_16x16x32_bf16 v[64:67], v[172:175], v[214:217], v[64:67]
	v_mfma_f32_16x16x32_bf16 v[68:71], v[148:151], v[214:217], v[68:71]
	s_barrier
	s_add_i32 s2, s38, s26
	v_lshl_add_u64 v[218:219], s[22:23], 0, v[154:155]
	s_mov_b32 m0, s2
	ds_read_b128 v[176:179], v202 offset:16384
	ds_read_b128 v[180:183], v202 offset:17408
	ds_read_b128 v[184:187], v202 offset:18432
	ds_read_b128 v[188:191], v202 offset:19456
	ds_read_b128 v[192:195], v202 offset:20480
	ds_read_b128 v[206:209], v202 offset:21504
	ds_read_b128 v[210:213], v202 offset:22528
	ds_read_b128 v[214:217], v202 offset:23552
	global_load_lds_dwordx4 v[218:219], off
	s_add_i32 m0, s2, 0x2000
	s_add_u32 s2, s22, 0xb0000
	v_lshl_add_u64 v[220:221], s[22:23], 0, v[158:159]
	s_addc_u32 s3, s23, 0
	s_add_i32 s47, s39, s26
	global_load_lds_dwordx4 v[220:221], off
	v_lshl_add_u64 v[222:223], s[2:3], 0, v[154:155]
	s_mov_b32 m0, s47
	v_lshl_add_u64 v[224:225], s[24:25], 0, v[156:157]
	global_load_lds_dwordx4 v[222:223], off
	v_lshl_add_u64 v[222:223], s[2:3], 0, v[158:159]
	s_add_i32 m0, s47, 0x2000
	s_nop 0
	global_load_lds_dwordx4 v[222:223], off
	v_lshl_add_u64 v[222:223], s[24:25], 0, v[152:153]
	s_mov_b32 m0, s27
	s_nop 0
	global_load_lds_dwordx4 v[222:223], off
	s_mov_b32 m0, s28
	s_nop 0
	global_load_lds_dwordx4 v[224:225], off
	s_waitcnt vmcnt(8)
	s_waitcnt lgkmcnt(0)
	s_barrier
	s_waitcnt lgkmcnt(0)
	v_mfma_f32_16x16x32_bf16 v[60:63], v[128:131], v[176:179], v[60:63]
	v_mfma_f32_16x16x32_bf16 v[56:59], v[136:139], v[176:179], v[56:59]
	v_mfma_f32_16x16x32_bf16 v[40:43], v[136:139], v[184:187], v[40:43]
	v_mfma_f32_16x16x32_bf16 v[44:47], v[128:131], v[184:187], v[44:47]
	v_mfma_f32_16x16x32_bf16 v[28:31], v[128:131], v[192:195], v[28:31]
	v_mfma_f32_16x16x32_bf16 v[24:27], v[136:139], v[192:195], v[24:27]
	v_mfma_f32_16x16x32_bf16 v[8:11], v[136:139], v[210:213], v[8:11]
	v_mfma_f32_16x16x32_bf16 v[12:15], v[128:131], v[210:213], v[12:15]
	v_mfma_f32_16x16x32_bf16 v[60:63], v[132:135], v[180:183], v[60:63]
	v_mfma_f32_16x16x32_bf16 v[56:59], v[140:143], v[180:183], v[56:59]
	v_mfma_f32_16x16x32_bf16 v[40:43], v[140:143], v[188:191], v[40:43]
	v_mfma_f32_16x16x32_bf16 v[44:47], v[132:135], v[188:191], v[44:47]
	v_mfma_f32_16x16x32_bf16 v[28:31], v[132:135], v[206:209], v[28:31]
	v_mfma_f32_16x16x32_bf16 v[24:27], v[140:143], v[206:209], v[24:27]
	v_mfma_f32_16x16x32_bf16 v[8:11], v[140:143], v[214:217], v[8:11]
	v_mfma_f32_16x16x32_bf16 v[12:15], v[132:135], v[214:217], v[12:15]
	v_mfma_f32_16x16x32_bf16 v[52:55], v[144:147], v[176:179], v[52:55]
	v_mfma_f32_16x16x32_bf16 v[48:51], v[168:171], v[176:179], v[48:51]
	v_mfma_f32_16x16x32_bf16 v[32:35], v[168:171], v[184:187], v[32:35]
	v_mfma_f32_16x16x32_bf16 v[36:39], v[144:147], v[184:187], v[36:39]
	v_mfma_f32_16x16x32_bf16 v[20:23], v[144:147], v[192:195], v[20:23]
	v_mfma_f32_16x16x32_bf16 v[16:19], v[168:171], v[192:195], v[16:19]
	v_mfma_f32_16x16x32_bf16 v[0:3], v[168:171], v[210:213], v[0:3]
	v_mfma_f32_16x16x32_bf16 v[4:7], v[144:147], v[210:213], v[4:7]
	v_mfma_f32_16x16x32_bf16 v[52:55], v[148:151], v[180:183], v[52:55]
	v_mfma_f32_16x16x32_bf16 v[48:51], v[172:175], v[180:183], v[48:51]
	v_mfma_f32_16x16x32_bf16 v[32:35], v[172:175], v[188:191], v[32:35]
	v_mfma_f32_16x16x32_bf16 v[36:39], v[148:151], v[188:191], v[36:39]
	v_mfma_f32_16x16x32_bf16 v[20:23], v[148:151], v[206:209], v[20:23]
	v_mfma_f32_16x16x32_bf16 v[16:19], v[172:175], v[206:209], v[16:19]
	v_mfma_f32_16x16x32_bf16 v[0:3], v[172:175], v[214:217], v[0:3]
	v_mfma_f32_16x16x32_bf16 v[4:7], v[148:151], v[214:217], v[4:7]
	s_barrier
; #define PG8_STAGE(bufoff, gbase, voff) do { _Pragma("unroll") for (int _i = 0; _i < 2; ++_i) \
;         __builtin_amdgcn_global_load_lds((const unsigned*)((const char*)(gbase) + (voff)[_i]), (LAS unsigned*)(lds + (bufoff) + ldsw + _i * 8192), 16, 0, 0); } while (0)
; #define PG8_LDA(dst, b, h) do { _Pragma("unroll") for (int m = 0; m < 4; ++m) _Pragma("unroll") for (int k = 0; k < 2; ++k) dst[m][k] = *(const LAS bf16x8*)(lds + PG8_SA(b, h) + aoff + m * 2048 + k * 1024); } while (0)
; #define PG8_LDB(dst, b, h) do { _Pragma("unroll") for (int n = 0; n < 2; ++n) _Pragma("unroll") for (int k = 0; k < 2; ++k) dst[n][k] = *(const LAS bf16x8*)(lds + PG8_SB(b, h) + boff + n * 2048 + k * 1024); } while (0)
; #define PG8_MMA(ai, bj, At, Bt) do { __builtin_amdgcn_s_setprio(1); _Pragma("unroll") for (int m = 0; m < 4; ++m) _Pragma("unroll") for (int n = 0; n < 2; ++n) _Pragma("unroll") for (int k = 0; k < 2; ++k) \
;         acc[ai][bj][m][n] = __builtin_amdgcn_mfma_f32_16x16x32_bf16(Bt[n][k], At[m][k], acc[ai][bj][m][n], 0, 0, 0); __builtin_amdgcn_s_setprio(0); } while (0)
; #define PG8_WAIT_V(n) asm volatile("s_waitcnt vmcnt(" #n ")" ::: "memory")
; #define PG8_WAIT_L(n) asm volatile("s_waitcnt lgkmcnt(" #n ")" ::: "memory")
; #define PG8_BAR __builtin_amdgcn_s_barrier()
; #define PG8_SCHED __builtin_amdgcn_sched_barrier(0)
; template <class Epi>
; __device__ __forceinline__ void gemm_phase(LAS unsigned char* lds, const Gemm g, const StaticOrder& S, const Epi& E) {
;     ...
;             PG8_LDB(B0, 1, 0); PG8_LDB(B1, 1, 1); PG8_SCHED; PG8_LDA(At, 1, 0); PG8_STAGE(PG8_SA(0, 1), a2 + hstepA, voffA);
;             PG8_WAIT_V(8); PG8_WAIT_L(0); PG8_BAR; PG8_MMA(0, 0, At, B0); PG8_MMA(0, 1, At, B1); PG8_BAR; PG8_SCHED;
	s_add_i32 s47, 0, 0x18000
	s_add_i32 s48, 0, 0x1c000
	v_add_u32_e32 v140, s47, v198
	v_add_u32_e32 v172, s48, v198
	ds_read_b128 v[128:131], v140
	ds_read_b128 v[132:135], v140 offset:1024
	ds_read_b128 v[136:139], v140 offset:2048
	ds_read_b128 v[140:143], v140 offset:3072
	ds_read_b128 v[144:147], v172
	ds_read_b128 v[148:151], v172 offset:1024
	ds_read_b128 v[168:171], v172 offset:2048
	ds_read_b128 v[172:175], v172 offset:3072
	s_add_u32 s2, s24, 0xb4000
	s_addc_u32 s3, s25, 0
	s_mov_b32 m0, s29
	v_lshl_add_u64 v[226:227], s[2:3], 0, v[152:153]
	ds_read_b128 v[176:179], v202 offset:32768
	ds_read_b128 v[180:183], v202 offset:33792
	ds_read_b128 v[184:187], v202 offset:34816
	ds_read_b128 v[188:191], v202 offset:35840
	ds_read_b128 v[192:195], v202 offset:36864
	ds_read_b128 v[206:209], v202 offset:37888
	ds_read_b128 v[210:213], v202 offset:38912
	ds_read_b128 v[214:217], v202 offset:39936
	global_load_lds_dwordx4 v[226:227], off
	v_lshl_add_u64 v[226:227], s[2:3], 0, v[156:157]
	s_mov_b32 m0, s30
	s_nop 0
	global_load_lds_dwordx4 v[226:227], off
	s_waitcnt vmcnt(8)
	s_waitcnt lgkmcnt(0)
	s_barrier
	s_waitcnt lgkmcnt(0)
	v_mfma_f32_16x16x32_bf16 v[124:127], v[128:131], v[176:179], v[124:127]
	v_mfma_f32_16x16x32_bf16 v[120:123], v[136:139], v[176:179], v[120:123]
	v_mfma_f32_16x16x32_bf16 v[104:107], v[136:139], v[184:187], v[104:107]
	v_mfma_f32_16x16x32_bf16 v[108:111], v[128:131], v[184:187], v[108:111]
	v_mfma_f32_16x16x32_bf16 v[92:95], v[128:131], v[192:195], v[92:95]
	v_mfma_f32_16x16x32_bf16 v[88:91], v[136:139], v[192:195], v[88:91]
	v_mfma_f32_16x16x32_bf16 v[72:75], v[136:139], v[210:213], v[72:75]
	v_mfma_f32_16x16x32_bf16 v[76:79], v[128:131], v[210:213], v[76:79]
	v_mfma_f32_16x16x32_bf16 v[124:127], v[132:135], v[180:183], v[124:127]
	v_mfma_f32_16x16x32_bf16 v[120:123], v[140:143], v[180:183], v[120:123]
	v_mfma_f32_16x16x32_bf16 v[104:107], v[140:143], v[188:191], v[104:107]
	v_mfma_f32_16x16x32_bf16 v[108:111], v[132:135], v[188:191], v[108:111]
	v_mfma_f32_16x16x32_bf16 v[92:95], v[132:135], v[206:209], v[92:95]
	v_mfma_f32_16x16x32_bf16 v[88:91], v[140:143], v[206:209], v[88:91]
	v_mfma_f32_16x16x32_bf16 v[72:75], v[140:143], v[214:217], v[72:75]
	v_mfma_f32_16x16x32_bf16 v[76:79], v[132:135], v[214:217], v[76:79]
	v_mfma_f32_16x16x32_bf16 v[116:119], v[144:147], v[176:179], v[116:119]
	v_mfma_f32_16x16x32_bf16 v[112:115], v[168:171], v[176:179], v[112:115]
	v_mfma_f32_16x16x32_bf16 v[96:99], v[168:171], v[184:187], v[96:99]
	v_mfma_f32_16x16x32_bf16 v[100:103], v[144:147], v[184:187], v[100:103]
	v_mfma_f32_16x16x32_bf16 v[84:87], v[144:147], v[192:195], v[84:87]
	v_mfma_f32_16x16x32_bf16 v[80:83], v[168:171], v[192:195], v[80:83]
	v_mfma_f32_16x16x32_bf16 v[64:67], v[168:171], v[210:213], v[64:67]
	v_mfma_f32_16x16x32_bf16 v[68:71], v[144:147], v[210:213], v[68:71]
	v_mfma_f32_16x16x32_bf16 v[116:119], v[148:151], v[180:183], v[116:119]
	v_mfma_f32_16x16x32_bf16 v[112:115], v[172:175], v[180:183], v[112:115]
	v_mfma_f32_16x16x32_bf16 v[96:99], v[172:175], v[188:191], v[96:99]
	v_mfma_f32_16x16x32_bf16 v[100:103], v[148:151], v[188:191], v[100:103]
	v_mfma_f32_16x16x32_bf16 v[84:87], v[148:151], v[206:209], v[84:87]
	v_mfma_f32_16x16x32_bf16 v[80:83], v[172:175], v[206:209], v[80:83]
	v_mfma_f32_16x16x32_bf16 v[64:67], v[172:175], v[214:217], v[64:67]
	v_mfma_f32_16x16x32_bf16 v[68:71], v[148:151], v[214:217], v[68:71]
	s_barrier
; #define PG8_STAGE(bufoff, gbase, voff) do { _Pragma("unroll") for (int _i = 0; _i < 2; ++_i) \
;         __builtin_amdgcn_global_load_lds((const unsigned*)((const char*)(gbase) + (voff)[_i]), (LAS unsigned*)(lds + (bufoff) + ldsw + _i * 8192), 16, 0, 0); } while (0)
; #define PG8_LDA(dst, b, h) do { _Pragma("unroll") for (int m = 0; m < 4; ++m) _Pragma("unroll") for (int k = 0; k < 2; ++k) dst[m][k] = *(const LAS bf16x8*)(lds + PG8_SA(b, h) + aoff + m * 2048 + k * 1024); } while (0)
; #define PG8_MMA(ai, bj, At, Bt) do { __builtin_amdgcn_s_setprio(1); _Pragma("unroll") for (int m = 0; m < 4; ++m) _Pragma("unroll") for (int n = 0; n < 2; ++n) _Pragma("unroll") for (int k = 0; k < 2; ++k) \
;         acc[ai][bj][m][n] = __builtin_amdgcn_mfma_f32_16x16x32_bf16(Bt[n][k], At[m][k], acc[ai][bj][m][n], 0, 0, 0); __builtin_amdgcn_s_setprio(0); } while (0)
; #define PG8_WAIT_V(n) asm volatile("s_waitcnt vmcnt(" #n ")" ::: "memory")
; #define PG8_WAIT_L(n) asm volatile("s_waitcnt lgkmcnt(" #n ")" ::: "memory")
; #define PG8_BAR __builtin_amdgcn_s_barrier()
; #define PG8_SCHED __builtin_amdgcn_sched_barrier(0)
; template <class Epi>
; __device__ __forceinline__ void gemm_phase(LAS unsigned char* lds, const Gemm g, const StaticOrder& S, const Epi& E) {
;     ...
;             PG8_LDA(At, 1, 1); PG8_STAGE(PG8_SB(1, 0), b3, voffB); PG8_STAGE(PG8_SB(1, 1), b3 + hstepB, voffB); PG8_STAGE(PG8_SA(1, 0), a3, voffA);
;             PG8_WAIT_V(8); PG8_WAIT_L(0); PG8_BAR; PG8_MMA(1, 0, At, B0); PG8_MMA(1, 1, At, B1); PG8_BAR; PG8_SCHED;
;         }
	s_add_i32 s2, s47, s26
	v_lshl_add_u64 v[218:219], v[218:219], 0, s[14:15]
	s_mov_b32 m0, s2
	ds_read_b128 v[176:179], v202 offset:49152
	ds_read_b128 v[180:183], v202 offset:50176
	ds_read_b128 v[184:187], v202 offset:51200
	ds_read_b128 v[188:191], v202 offset:52224
	ds_read_b128 v[192:195], v202 offset:53248
	ds_read_b128 v[206:209], v202 offset:54272
	ds_read_b128 v[210:213], v202 offset:55296
	ds_read_b128 v[214:217], v202 offset:56320
	global_load_lds_dwordx4 v[218:219], off
	s_add_i32 m0, s2, 0x2000
	s_add_u32 s2, s22, 0xb0080
	v_lshl_add_u64 v[218:219], v[220:221], 0, s[14:15]
	s_addc_u32 s3, s23, 0
	s_add_i32 s22, s48, s26
	global_load_lds_dwordx4 v[218:219], off
	v_lshl_add_u64 v[218:219], s[2:3], 0, v[154:155]
	s_mov_b32 m0, s22
	s_nop 0
	global_load_lds_dwordx4 v[218:219], off
	v_lshl_add_u64 v[218:219], s[2:3], 0, v[158:159]
	s_add_i32 m0, s22, 0x2000
	s_nop 0
	global_load_lds_dwordx4 v[218:219], off
	v_lshl_add_u64 v[218:219], v[222:223], 0, s[14:15]
	s_mov_b32 m0, s34
	s_nop 0
	global_load_lds_dwordx4 v[218:219], off
	v_lshl_add_u64 v[218:219], v[224:225], 0, s[14:15]
	s_mov_b32 m0, s35
	s_nop 0
	global_load_lds_dwordx4 v[218:219], off
	s_waitcnt vmcnt(8)
	s_waitcnt lgkmcnt(0)
	s_barrier
	s_waitcnt lgkmcnt(0)
	v_mfma_f32_16x16x32_bf16 v[60:63], v[128:131], v[176:179], v[60:63]
	v_mfma_f32_16x16x32_bf16 v[56:59], v[136:139], v[176:179], v[56:59]
	v_mfma_f32_16x16x32_bf16 v[40:43], v[136:139], v[184:187], v[40:43]
	v_mfma_f32_16x16x32_bf16 v[44:47], v[128:131], v[184:187], v[44:47]
	v_mfma_f32_16x16x32_bf16 v[28:31], v[128:131], v[192:195], v[28:31]
	v_mfma_f32_16x16x32_bf16 v[24:27], v[136:139], v[192:195], v[24:27]
	v_mfma_f32_16x16x32_bf16 v[8:11], v[136:139], v[210:213], v[8:11]
	v_mfma_f32_16x16x32_bf16 v[12:15], v[128:131], v[210:213], v[12:15]
	v_mfma_f32_16x16x32_bf16 v[60:63], v[132:135], v[180:183], v[60:63]
	v_mfma_f32_16x16x32_bf16 v[56:59], v[140:143], v[180:183], v[56:59]
	v_mfma_f32_16x16x32_bf16 v[40:43], v[140:143], v[188:191], v[40:43]
	v_mfma_f32_16x16x32_bf16 v[44:47], v[132:135], v[188:191], v[44:47]
	v_mfma_f32_16x16x32_bf16 v[28:31], v[132:135], v[206:209], v[28:31]
	v_mfma_f32_16x16x32_bf16 v[24:27], v[140:143], v[206:209], v[24:27]
	v_mfma_f32_16x16x32_bf16 v[8:11], v[140:143], v[214:217], v[8:11]
	v_mfma_f32_16x16x32_bf16 v[12:15], v[132:135], v[214:217], v[12:15]
	v_mfma_f32_16x16x32_bf16 v[52:55], v[144:147], v[176:179], v[52:55]
	v_mfma_f32_16x16x32_bf16 v[48:51], v[168:171], v[176:179], v[48:51]
	v_mfma_f32_16x16x32_bf16 v[32:35], v[168:171], v[184:187], v[32:35]
	v_mfma_f32_16x16x32_bf16 v[36:39], v[144:147], v[184:187], v[36:39]
	v_mfma_f32_16x16x32_bf16 v[20:23], v[144:147], v[192:195], v[20:23]
	v_mfma_f32_16x16x32_bf16 v[16:19], v[168:171], v[192:195], v[16:19]
	v_mfma_f32_16x16x32_bf16 v[0:3], v[168:171], v[210:213], v[0:3]
	v_mfma_f32_16x16x32_bf16 v[4:7], v[144:147], v[210:213], v[4:7]
	v_mfma_f32_16x16x32_bf16 v[52:55], v[148:151], v[180:183], v[52:55]
	v_mfma_f32_16x16x32_bf16 v[48:51], v[172:175], v[180:183], v[48:51]
	v_mfma_f32_16x16x32_bf16 v[32:35], v[172:175], v[188:191], v[32:35]
	v_mfma_f32_16x16x32_bf16 v[36:39], v[148:151], v[188:191], v[36:39]
	v_mfma_f32_16x16x32_bf16 v[20:23], v[148:151], v[206:209], v[20:23]
	v_mfma_f32_16x16x32_bf16 v[16:19], v[172:175], v[206:209], v[16:19]
	v_mfma_f32_16x16x32_bf16 v[0:3], v[172:175], v[214:217], v[0:3]
	v_mfma_f32_16x16x32_bf16 v[4:7], v[148:151], v[214:217], v[4:7]
	s_barrier
	s_add_i32 s46, s46, 2
	s_add_u32 s44, s44, 0x100
	s_addc_u32 s45, s45, 0
	s_cmp_gt_u32 s46, 41
	s_mov_b64 s[2:3], s[20:21]
	s_cbranch_scc0 .LBB0_1177
	s_and_b64 vcc, exec, s[16:17]
	s_cbranch_vccz .LBB0_1180
	s_barrier
